# speedup vs baseline: 1.0004x; 1.0004x over previous
; #define P8_STAGE(P,BASE,br,kt) do{const bfr* _ub=(BASE)+((long)(br)*K+(long)(kt)*BK); \
;     __builtin_amdgcn_global_load_lds((const unsigned*)(_ub+so0),(unsigned*)((char*)(P)+wid*1024),16,0,0); \
;     __builtin_amdgcn_global_load_lds((const unsigned*)(_ub+so1),(unsigned*)((char*)(P)+wid*1024+8192),16,0,0);}while(0)
; #define P8_LDA(dst,b,h) _Pragma("unroll") for(int m=0;m<4;++m) _Pragma("unroll") for(int k=0;k<2;++k) \
;     dst[m][k]=*reinterpret_cast<const bf16x8*>((char*)P8_SA(b,h)+lds_byte(wr*64+m*16+fr,k*32+fq*8))
; #define P8_LDB(dst,b,h) _Pragma("unroll") for(int n=0;n<2;++n) _Pragma("unroll") for(int k=0;k<2;++k) \
;     dst[n][k]=*reinterpret_cast<const bf16x8*>((char*)P8_SB(b,h)+lds_byte(wc*32+n*16+fr,k*32+fq*8))
; #define P8_MMA(ai,bj,At,Bt) do{__builtin_amdgcn_s_setprio(1); \
;     _Pragma("unroll") for(int m=0;m<4;++m) _Pragma("unroll") for(int n=0;n<2;++n) _Pragma("unroll") for(int k=0;k<2;++k) \
;       acc[ai][bj][m][n]=__builtin_amdgcn_mfma_f32_16x16x32_bf16(At[m][k],Bt[n][k],acc[ai][bj][m][n],0,0,0); \
;     __builtin_amdgcn_s_setprio(0);}while(0)
; #define P8_WAIT_V(n) asm volatile("s_waitcnt vmcnt(" #n ")":::"memory")
; #define P8_WAIT_L(n) asm volatile("s_waitcnt lgkmcnt(" #n ")":::"memory")
; #define P8_BAR __builtin_amdgcn_s_barrier()
; #define P8_SCHED __builtin_amdgcn_sched_barrier(0)
; template <class EPI>
; DEVI void gemm8_tile(const bfr* __restrict__ A, const bfr* __restrict__ Bt, int K, int brow, int bcol, int nbrow, int nbcol, char* shmc, EPI epi) {
;     ...
;   for(int t=0;t<nt-2;t+=2){
;     P8_LDB(B0,0,0); P8_SCHED; P8_LDA(At,0,0); P8_STAGE(P8_SA(1,1),A,brow+128,t+1);
;     P8_WAIT_L(8); P8_BAR; P8_WAIT_L(0); P8_MMA(0,0,At,B0); P8_BAR; P8_SCHED;
;     P8_LDB(B1,0,1); P8_STAGE(P8_SB(0,0),Bt,bcol,t+2);
;     P8_BAR; P8_WAIT_L(0); P8_MMA(0,1,At,B1); P8_BAR;
;     P8_LDA(At,0,1); P8_STAGE(P8_SA(0,0),A,brow,t+2);
;     P8_BAR; P8_WAIT_L(0); P8_MMA(1,0,At,B0); P8_BAR; P8_SCHED;
;     P8_STAGE(P8_SB(0,1),Bt,bcol+128,t+2);
;     P8_WAIT_V(6); P8_BAR; P8_MMA(1,1,At,B1); P8_BAR;
.LBB0_66:
	ds_read_b128 v[174:177], v172
	ds_read_b128 v[178:181], v172 offset:1024
	ds_read_b128 v[182:185], v172 offset:2048
	ds_read_b128 v[186:189], v172 offset:3072
	v_add_u32_e32 v224, s54, v140
	s_add_i32 m0, s100, 0xc000
	ds_read_b128 v[190:193], v154
	ds_read_b128 v[196:199], v154 offset:1024
	ds_read_b128 v[200:203], v153
	ds_read_b128 v[204:207], v153 offset:1024
	ds_read_b128 v[208:211], v152
	ds_read_b128 v[212:215], v152 offset:1024
	ds_read_b128 v[216:219], v151
	ds_read_b128 v[220:223], v151 offset:1024
	global_load_lds_dwordx4 v224, s[86:87]
	v_add_u32_e32 v224, s54, v138
	s_add_i32 m0, s100, 0xe000
	s_nop 0
	global_load_lds_dwordx4 v224, s[86:87]
	s_waitcnt lgkmcnt(8)
	s_barrier
	s_waitcnt lgkmcnt(0)
	v_mfma_f32_16x16x32_bf16 v[124:127], v[190:193], v[174:177], v[124:127]
	v_mfma_f32_16x16x32_bf16 v[120:123], v[190:193], v[182:185], v[120:123]
	v_mfma_f32_16x16x32_bf16 v[116:119], v[200:203], v[174:177], v[116:119]
	v_mfma_f32_16x16x32_bf16 v[112:115], v[200:203], v[182:185], v[112:115]
	v_mfma_f32_16x16x32_bf16 v[108:111], v[208:211], v[174:177], v[108:111]
	v_mfma_f32_16x16x32_bf16 v[104:107], v[208:211], v[182:185], v[104:107]
	v_mfma_f32_16x16x32_bf16 v[100:103], v[216:219], v[174:177], v[100:103]
	v_mfma_f32_16x16x32_bf16 v[96:99], v[216:219], v[182:185], v[96:99]
	v_mfma_f32_16x16x32_bf16 v[124:127], v[196:199], v[178:181], v[124:127]
	v_mfma_f32_16x16x32_bf16 v[120:123], v[196:199], v[186:189], v[120:123]
	v_mfma_f32_16x16x32_bf16 v[116:119], v[204:207], v[178:181], v[116:119]
	v_mfma_f32_16x16x32_bf16 v[112:115], v[204:207], v[186:189], v[112:115]
	v_mfma_f32_16x16x32_bf16 v[108:111], v[212:215], v[178:181], v[108:111]
	v_mfma_f32_16x16x32_bf16 v[104:107], v[212:215], v[186:189], v[104:107]
	v_mfma_f32_16x16x32_bf16 v[100:103], v[220:223], v[178:181], v[100:103]
	v_mfma_f32_16x16x32_bf16 v[96:99], v[220:223], v[186:189], v[96:99]
	s_barrier
	v_add_u32_e32 v246, s66, v136
	s_add_i32 m0, s100, 0x10000
	ds_read_b128 v[224:227], v162
	ds_read_b128 v[228:231], v162 offset:1024
	ds_read_b128 v[232:235], v162 offset:2048
	ds_read_b128 v[236:239], v162 offset:3072
	global_load_lds_dwordx4 v246, s[86:87]
	v_add_u32_e32 v248, s66, v134
	s_add_i32 m0, s100, 0x12000
	s_nop 0
	global_load_lds_dwordx4 v248, s[86:87]
	s_barrier
	s_waitcnt lgkmcnt(0)
	v_mfma_f32_16x16x32_bf16 v[92:95], v[190:193], v[224:227], v[92:95]
	v_mfma_f32_16x16x32_bf16 v[88:91], v[190:193], v[232:235], v[88:91]
	v_mfma_f32_16x16x32_bf16 v[84:87], v[200:203], v[224:227], v[84:87]
	v_mfma_f32_16x16x32_bf16 v[80:83], v[200:203], v[232:235], v[80:83]
	v_mfma_f32_16x16x32_bf16 v[76:79], v[208:211], v[224:227], v[76:79]
	v_mfma_f32_16x16x32_bf16 v[72:75], v[208:211], v[232:235], v[72:75]
	v_mfma_f32_16x16x32_bf16 v[68:71], v[216:219], v[224:227], v[68:71]
	v_mfma_f32_16x16x32_bf16 v[64:67], v[216:219], v[232:235], v[64:67]
	v_mfma_f32_16x16x32_bf16 v[92:95], v[196:199], v[228:231], v[92:95]
	v_mfma_f32_16x16x32_bf16 v[88:91], v[196:199], v[236:239], v[88:91]
	v_mfma_f32_16x16x32_bf16 v[84:87], v[204:207], v[228:231], v[84:87]
	v_mfma_f32_16x16x32_bf16 v[80:83], v[204:207], v[236:239], v[80:83]
	v_mfma_f32_16x16x32_bf16 v[76:79], v[212:215], v[228:231], v[76:79]
	v_mfma_f32_16x16x32_bf16 v[72:75], v[212:215], v[236:239], v[72:75]
	v_mfma_f32_16x16x32_bf16 v[68:71], v[220:223], v[228:231], v[68:71]
	v_mfma_f32_16x16x32_bf16 v[64:67], v[220:223], v[236:239], v[64:67]
	v_add_u32_e32 v248, s60, v140
	s_mov_b32 m0, s100
	s_barrier
	ds_read_b128 v[190:193], v154 offset:16384
	ds_read_b128 v[196:199], v154 offset:17408
	ds_read_b128 v[200:203], v153 offset:16384
	ds_read_b128 v[204:207], v153 offset:17408
	ds_read_b128 v[208:211], v152 offset:16384
	ds_read_b128 v[212:215], v152 offset:17408
	ds_read_b128 v[216:219], v151 offset:16384
	ds_read_b128 v[220:223], v151 offset:17408
	global_load_lds_dwordx4 v248, s[86:87]
	v_add_u32_e32 v248, s60, v138
	s_add_i32 m0, s100, 0x2000
	s_nop 0
	global_load_lds_dwordx4 v248, s[86:87]
	s_barrier
	s_waitcnt lgkmcnt(0)
	v_mfma_f32_16x16x32_bf16 v[60:63], v[190:193], v[174:177], v[60:63]
	v_mfma_f32_16x16x32_bf16 v[56:59], v[190:193], v[182:185], v[56:59]
	v_mfma_f32_16x16x32_bf16 v[52:55], v[200:203], v[174:177], v[52:55]
	v_mfma_f32_16x16x32_bf16 v[48:51], v[200:203], v[182:185], v[48:51]
	v_mfma_f32_16x16x32_bf16 v[44:47], v[208:211], v[174:177], v[44:47]
	v_mfma_f32_16x16x32_bf16 v[40:43], v[208:211], v[182:185], v[40:43]
	v_mfma_f32_16x16x32_bf16 v[36:39], v[216:219], v[174:177], v[36:39]
	v_mfma_f32_16x16x32_bf16 v[32:35], v[216:219], v[182:185], v[32:35]
	v_mfma_f32_16x16x32_bf16 v[60:63], v[196:199], v[178:181], v[60:63]
	v_mfma_f32_16x16x32_bf16 v[56:59], v[196:199], v[186:189], v[56:59]
	v_mfma_f32_16x16x32_bf16 v[52:55], v[204:207], v[178:181], v[52:55]
	v_mfma_f32_16x16x32_bf16 v[48:51], v[204:207], v[186:189], v[48:51]
	v_mfma_f32_16x16x32_bf16 v[44:47], v[212:215], v[178:181], v[44:47]
	v_mfma_f32_16x16x32_bf16 v[40:43], v[212:215], v[186:189], v[40:43]
	v_mfma_f32_16x16x32_bf16 v[36:39], v[220:223], v[178:181], v[36:39]
	v_mfma_f32_16x16x32_bf16 v[32:35], v[220:223], v[186:189], v[32:35]
	s_barrier
	v_add_u32_e32 v174, s70, v136
	s_add_i32 m0, s100, 0x14000
	s_nop 0
	global_load_lds_dwordx4 v174, s[86:87]
	v_add_u32_e32 v174, s70, v134
	s_add_i32 m0, s100, 0x16000
	s_nop 0
	global_load_lds_dwordx4 v174, s[86:87]
	s_waitcnt vmcnt(6)
	s_barrier
; #define P8_STAGE(P,BASE,br,kt) do{const bfr* _ub=(BASE)+((long)(br)*K+(long)(kt)*BK); \
;     __builtin_amdgcn_global_load_lds((const unsigned*)(_ub+so0),(unsigned*)((char*)(P)+wid*1024),16,0,0); \
;     __builtin_amdgcn_global_load_lds((const unsigned*)(_ub+so1),(unsigned*)((char*)(P)+wid*1024+8192),16,0,0);}while(0)
; #define P8_LDA(dst,b,h) _Pragma("unroll") for(int m=0;m<4;++m) _Pragma("unroll") for(int k=0;k<2;++k) \
;     dst[m][k]=*reinterpret_cast<const bf16x8*>((char*)P8_SA(b,h)+lds_byte(wr*64+m*16+fr,k*32+fq*8))
; #define P8_LDB(dst,b,h) _Pragma("unroll") for(int n=0;n<2;++n) _Pragma("unroll") for(int k=0;k<2;++k) \
;     dst[n][k]=*reinterpret_cast<const bf16x8*>((char*)P8_SB(b,h)+lds_byte(wc*32+n*16+fr,k*32+fq*8))
; #define P8_MMA(ai,bj,At,Bt) do{__builtin_amdgcn_s_setprio(1); \
;     _Pragma("unroll") for(int m=0;m<4;++m) _Pragma("unroll") for(int n=0;n<2;++n) _Pragma("unroll") for(int k=0;k<2;++k) \
;       acc[ai][bj][m][n]=__builtin_amdgcn_mfma_f32_16x16x32_bf16(At[m][k],Bt[n][k],acc[ai][bj][m][n],0,0,0); \
;     __builtin_amdgcn_s_setprio(0);}while(0)
; #define P8_WAIT_V(n) asm volatile("s_waitcnt vmcnt(" #n ")":::"memory")
; #define P8_WAIT_L(n) asm volatile("s_waitcnt lgkmcnt(" #n ")":::"memory")
; #define P8_BAR __builtin_amdgcn_s_barrier()
; #define P8_SCHED __builtin_amdgcn_sched_barrier(0)
; template <class EPI>
; DEVI void gemm8_tile(const bfr* __restrict__ A, const bfr* __restrict__ Bt, int K, int brow, int bcol, int nbrow, int nbcol, char* shmc, EPI epi) {
;     ...
;     P8_WAIT_V(6); P8_BAR; P8_MMA(1,1,At,B1); P8_BAR;
;     P8_LDB(B0,1,0); P8_SCHED; P8_LDA(At,1,0); P8_STAGE(P8_SA(0,1),A,brow+128,t+2);
;     P8_WAIT_L(8); P8_BAR; P8_WAIT_L(0); P8_MMA(0,0,At,B0); P8_BAR; P8_SCHED;
;     P8_LDB(B1,1,1); P8_STAGE(P8_SB(1,0),Bt,bcol,t+3);
;     P8_BAR; P8_WAIT_L(0); P8_MMA(0,1,At,B1); P8_BAR;
;     P8_LDA(At,1,1); P8_STAGE(P8_SA(1,0),A,brow,t+3);
	v_mfma_f32_16x16x32_bf16 v[28:31], v[190:193], v[224:227], v[28:31]
	v_mfma_f32_16x16x32_bf16 v[24:27], v[190:193], v[232:235], v[24:27]
	v_mfma_f32_16x16x32_bf16 v[20:23], v[200:203], v[224:227], v[20:23]
	v_mfma_f32_16x16x32_bf16 v[16:19], v[200:203], v[232:235], v[16:19]
	v_mfma_f32_16x16x32_bf16 v[12:15], v[208:211], v[224:227], v[12:15]
	v_mfma_f32_16x16x32_bf16 v[8:11], v[208:211], v[232:235], v[8:11]
	v_mfma_f32_16x16x32_bf16 v[4:7], v[216:219], v[224:227], v[4:7]
	v_mfma_f32_16x16x32_bf16 v[0:3], v[216:219], v[232:235], v[0:3]
	v_mfma_f32_16x16x32_bf16 v[28:31], v[196:199], v[228:231], v[28:31]
	v_mfma_f32_16x16x32_bf16 v[24:27], v[196:199], v[236:239], v[24:27]
	v_mfma_f32_16x16x32_bf16 v[20:23], v[204:207], v[228:231], v[20:23]
	v_mfma_f32_16x16x32_bf16 v[16:19], v[204:207], v[236:239], v[16:19]
	v_mfma_f32_16x16x32_bf16 v[12:15], v[212:215], v[228:231], v[12:15]
	v_mfma_f32_16x16x32_bf16 v[8:11], v[212:215], v[236:239], v[8:11]
	v_mfma_f32_16x16x32_bf16 v[4:7], v[220:223], v[228:231], v[4:7]
	v_mfma_f32_16x16x32_bf16 v[0:3], v[220:223], v[236:239], v[0:3]
	s_barrier
	ds_read_b128 v[174:177], v156
	ds_read_b128 v[178:181], v156 offset:1024
	ds_read_b128 v[182:185], v156 offset:2048
	ds_read_b128 v[186:189], v156 offset:3072
	v_add_u32_e32 v224, s72, v140
	s_add_i32 m0, s100, 0x4000
	ds_read_b128 v[190:193], v154 offset:32768
	ds_read_b128 v[196:199], v154 offset:33792
	ds_read_b128 v[200:203], v153 offset:32768
	ds_read_b128 v[204:207], v153 offset:33792
	ds_read_b128 v[208:211], v152 offset:32768
	ds_read_b128 v[212:215], v152 offset:33792
	ds_read_b128 v[216:219], v151 offset:32768
	ds_read_b128 v[220:223], v151 offset:33792
	global_load_lds_dwordx4 v224, s[86:87]
	v_add_u32_e32 v224, s72, v138
	s_add_i32 m0, s100, 0x6000
	s_nop 0
	global_load_lds_dwordx4 v224, s[86:87]
	s_waitcnt lgkmcnt(8)
	s_barrier
	s_waitcnt lgkmcnt(0)
	v_mfma_f32_16x16x32_bf16 v[124:127], v[190:193], v[174:177], v[124:127]
	v_mfma_f32_16x16x32_bf16 v[120:123], v[190:193], v[182:185], v[120:123]
	v_mfma_f32_16x16x32_bf16 v[116:119], v[200:203], v[174:177], v[116:119]
	v_mfma_f32_16x16x32_bf16 v[112:115], v[200:203], v[182:185], v[112:115]
	v_mfma_f32_16x16x32_bf16 v[108:111], v[208:211], v[174:177], v[108:111]
	v_mfma_f32_16x16x32_bf16 v[104:107], v[208:211], v[182:185], v[104:107]
	v_mfma_f32_16x16x32_bf16 v[100:103], v[216:219], v[174:177], v[100:103]
	v_mfma_f32_16x16x32_bf16 v[96:99], v[216:219], v[182:185], v[96:99]
	v_mfma_f32_16x16x32_bf16 v[124:127], v[196:199], v[178:181], v[124:127]
	v_mfma_f32_16x16x32_bf16 v[120:123], v[196:199], v[186:189], v[120:123]
	v_mfma_f32_16x16x32_bf16 v[116:119], v[204:207], v[178:181], v[116:119]
	v_mfma_f32_16x16x32_bf16 v[112:115], v[204:207], v[186:189], v[112:115]
	v_mfma_f32_16x16x32_bf16 v[108:111], v[212:215], v[178:181], v[108:111]
	v_mfma_f32_16x16x32_bf16 v[104:107], v[212:215], v[186:189], v[104:107]
	v_mfma_f32_16x16x32_bf16 v[100:103], v[220:223], v[178:181], v[100:103]
	v_mfma_f32_16x16x32_bf16 v[96:99], v[220:223], v[186:189], v[96:99]
	s_barrier
	v_add_u32_e32 v248, s74, v136
	s_add_i32 m0, s100, 0x18000
	ds_read_b128 v[224:227], v155
	ds_read_b128 v[228:231], v155 offset:1024
	ds_read_b128 v[232:235], v155 offset:2048
	ds_read_b128 v[236:239], v155 offset:3072
	global_load_lds_dwordx4 v248, s[86:87]
	v_add_u32_e32 v248, s74, v134
	s_add_i32 m0, s100, 0x1a000
	s_nop 0
	global_load_lds_dwordx4 v248, s[86:87]
	s_barrier
	s_waitcnt lgkmcnt(0)
	v_mfma_f32_16x16x32_bf16 v[92:95], v[190:193], v[224:227], v[92:95]
	v_mfma_f32_16x16x32_bf16 v[88:91], v[190:193], v[232:235], v[88:91]
	v_mfma_f32_16x16x32_bf16 v[84:87], v[200:203], v[224:227], v[84:87]
	v_mfma_f32_16x16x32_bf16 v[80:83], v[200:203], v[232:235], v[80:83]
	v_mfma_f32_16x16x32_bf16 v[76:79], v[208:211], v[224:227], v[76:79]
	v_mfma_f32_16x16x32_bf16 v[72:75], v[208:211], v[232:235], v[72:75]
	v_mfma_f32_16x16x32_bf16 v[68:71], v[216:219], v[224:227], v[68:71]
	v_mfma_f32_16x16x32_bf16 v[64:67], v[216:219], v[232:235], v[64:67]
	v_mfma_f32_16x16x32_bf16 v[92:95], v[196:199], v[228:231], v[92:95]
	v_mfma_f32_16x16x32_bf16 v[88:91], v[196:199], v[236:239], v[88:91]
	v_mfma_f32_16x16x32_bf16 v[84:87], v[204:207], v[228:231], v[84:87]
	v_mfma_f32_16x16x32_bf16 v[80:83], v[204:207], v[236:239], v[80:83]
	v_mfma_f32_16x16x32_bf16 v[76:79], v[212:215], v[228:231], v[76:79]
	v_mfma_f32_16x16x32_bf16 v[72:75], v[212:215], v[236:239], v[72:75]
	v_mfma_f32_16x16x32_bf16 v[68:71], v[220:223], v[228:231], v[68:71]
	v_mfma_f32_16x16x32_bf16 v[64:67], v[220:223], v[236:239], v[64:67]
	v_add_u32_e32 v240, s82, v140
	s_add_i32 m0, s100, 0x8000
	s_barrier
	ds_read_b128 v[190:193], v154 offset:49152
	ds_read_b128 v[196:199], v154 offset:50176
	ds_read_b128 v[200:203], v153 offset:49152
	ds_read_b128 v[204:207], v153 offset:50176
	ds_read_b128 v[208:211], v152 offset:49152
	ds_read_b128 v[212:215], v152 offset:50176
	ds_read_b128 v[216:219], v151 offset:49152
	ds_read_b128 v[220:223], v151 offset:50176
	global_load_lds_dwordx4 v240, s[86:87]
	v_add_u32_e32 v240, s82, v138
	s_add_i32 m0, s100, 0xa000
	s_nop 0
	global_load_lds_dwordx4 v240, s[86:87]
	s_barrier
; #define P8_STAGE(P,BASE,br,kt) do{const bfr* _ub=(BASE)+((long)(br)*K+(long)(kt)*BK); \
;     __builtin_amdgcn_global_load_lds((const unsigned*)(_ub+so0),(unsigned*)((char*)(P)+wid*1024),16,0,0); \
;     __builtin_amdgcn_global_load_lds((const unsigned*)(_ub+so1),(unsigned*)((char*)(P)+wid*1024+8192),16,0,0);}while(0)
; #define P8_LDA(dst,b,h) _Pragma("unroll") for(int m=0;m<4;++m) _Pragma("unroll") for(int k=0;k<2;++k) \
;     dst[m][k]=*reinterpret_cast<const bf16x8*>((char*)P8_SA(b,h)+lds_byte(wr*64+m*16+fr,k*32+fq*8))
; #define P8_LDB(dst,b,h) _Pragma("unroll") for(int n=0;n<2;++n) _Pragma("unroll") for(int k=0;k<2;++k) \
;     dst[n][k]=*reinterpret_cast<const bf16x8*>((char*)P8_SB(b,h)+lds_byte(wc*32+n*16+fr,k*32+fq*8))
; #define P8_MMA(ai,bj,At,Bt) do{__builtin_amdgcn_s_setprio(1); \
;     _Pragma("unroll") for(int m=0;m<4;++m) _Pragma("unroll") for(int n=0;n<2;++n) _Pragma("unroll") for(int k=0;k<2;++k) \
;       acc[ai][bj][m][n]=__builtin_amdgcn_mfma_f32_16x16x32_bf16(At[m][k],Bt[n][k],acc[ai][bj][m][n],0,0,0); \
;     __builtin_amdgcn_s_setprio(0);}while(0)
; #define P8_WAIT_V(n) asm volatile("s_waitcnt vmcnt(" #n ")":::"memory")
; #define P8_WAIT_L(n) asm volatile("s_waitcnt lgkmcnt(" #n ")":::"memory")
; #define P8_BAR __builtin_amdgcn_s_barrier()
; #define P8_SCHED __builtin_amdgcn_sched_barrier(0)
; template <class EPI>
; DEVI void gemm8_tile(const bfr* __restrict__ A, const bfr* __restrict__ Bt, int K, int brow, int bcol, int nbrow, int nbcol, char* shmc, EPI epi) {
;     ...
;     P8_BAR; P8_WAIT_L(0); P8_MMA(1,0,At,B0); P8_BAR; P8_SCHED;
;     P8_STAGE(P8_SB(1,1),Bt,bcol+128,t+3);
;     P8_WAIT_V(6); P8_BAR; P8_MMA(1,1,At,B1); P8_BAR;
;   }
;   { P8_LDB(B0,0,0); P8_LDA(At,0,0); P8_STAGE(P8_SA(1,1),A,brow+128,nt-1);
;     P8_BAR; P8_WAIT_L(0); P8_MMA(0,0,At,B0); P8_BAR;
;     P8_LDB(B1,0,1); P8_BAR; P8_WAIT_L(0); P8_MMA(0,1,At,B1); P8_BAR;
;     P8_LDA(At,0,1); P8_WAIT_V(4); P8_BAR; P8_WAIT_L(0); P8_MMA(1,0,At,B0); P8_MMA(1,1,At,B1); P8_BAR; }
	s_waitcnt lgkmcnt(0)
	v_mfma_f32_16x16x32_bf16 v[60:63], v[190:193], v[174:177], v[60:63]
	v_mfma_f32_16x16x32_bf16 v[56:59], v[190:193], v[182:185], v[56:59]
	v_mfma_f32_16x16x32_bf16 v[52:55], v[200:203], v[174:177], v[52:55]
	v_mfma_f32_16x16x32_bf16 v[48:51], v[200:203], v[182:185], v[48:51]
	v_mfma_f32_16x16x32_bf16 v[44:47], v[208:211], v[174:177], v[44:47]
	v_mfma_f32_16x16x32_bf16 v[40:43], v[208:211], v[182:185], v[40:43]
	v_mfma_f32_16x16x32_bf16 v[36:39], v[216:219], v[174:177], v[36:39]
	v_mfma_f32_16x16x32_bf16 v[32:35], v[216:219], v[182:185], v[32:35]
	v_mfma_f32_16x16x32_bf16 v[60:63], v[196:199], v[178:181], v[60:63]
	v_mfma_f32_16x16x32_bf16 v[56:59], v[196:199], v[186:189], v[56:59]
	v_mfma_f32_16x16x32_bf16 v[52:55], v[204:207], v[178:181], v[52:55]
	v_mfma_f32_16x16x32_bf16 v[48:51], v[204:207], v[186:189], v[48:51]
	v_mfma_f32_16x16x32_bf16 v[44:47], v[212:215], v[178:181], v[44:47]
	v_mfma_f32_16x16x32_bf16 v[40:43], v[212:215], v[186:189], v[40:43]
	v_mfma_f32_16x16x32_bf16 v[36:39], v[220:223], v[178:181], v[36:39]
	v_mfma_f32_16x16x32_bf16 v[32:35], v[220:223], v[186:189], v[32:35]
	s_barrier
	v_add_u32_e32 v174, s78, v136
	s_add_i32 m0, s100, 0x1c000
	s_nop 0
	global_load_lds_dwordx4 v174, s[86:87]
	v_add_u32_e32 v174, s78, v134
	s_add_i32 m0, s100, 0x1e000
	s_nop 0
	global_load_lds_dwordx4 v174, s[86:87]
	s_waitcnt vmcnt(6)
	s_barrier
	v_mfma_f32_16x16x32_bf16 v[28:31], v[190:193], v[224:227], v[28:31]
	v_mfma_f32_16x16x32_bf16 v[24:27], v[190:193], v[232:235], v[24:27]
	v_mfma_f32_16x16x32_bf16 v[20:23], v[200:203], v[224:227], v[20:23]
	v_mfma_f32_16x16x32_bf16 v[16:19], v[200:203], v[232:235], v[16:19]
	v_mfma_f32_16x16x32_bf16 v[12:15], v[208:211], v[224:227], v[12:15]
	v_mfma_f32_16x16x32_bf16 v[8:11], v[208:211], v[232:235], v[8:11]
	v_mfma_f32_16x16x32_bf16 v[4:7], v[216:219], v[224:227], v[4:7]
	v_mfma_f32_16x16x32_bf16 v[0:3], v[216:219], v[232:235], v[0:3]
	v_mfma_f32_16x16x32_bf16 v[28:31], v[196:199], v[228:231], v[28:31]
	v_mfma_f32_16x16x32_bf16 v[24:27], v[196:199], v[236:239], v[24:27]
	v_mfma_f32_16x16x32_bf16 v[20:23], v[204:207], v[228:231], v[20:23]
	v_mfma_f32_16x16x32_bf16 v[16:19], v[204:207], v[236:239], v[16:19]
	v_mfma_f32_16x16x32_bf16 v[12:15], v[212:215], v[228:231], v[12:15]
	v_mfma_f32_16x16x32_bf16 v[8:11], v[212:215], v[236:239], v[8:11]
	v_mfma_f32_16x16x32_bf16 v[4:7], v[220:223], v[228:231], v[4:7]
	v_mfma_f32_16x16x32_bf16 v[0:3], v[220:223], v[236:239], v[0:3]
	s_add_i32 s0, s0, 2
	v_lshl_add_u64 v[134:135], v[134:135], 0, s[80:81]
	v_lshl_add_u64 v[136:137], v[136:137], 0, s[80:81]
	v_lshl_add_u64 v[138:139], v[138:139], 0, s[80:81]
	s_cmp_lt_u32 s0, 28
	v_lshl_add_u64 v[140:141], v[140:141], 0, s[80:81]
	s_barrier
	s_cbranch_scc1 .LBB0_66
	s_or_b32 s0, s8, 0x80
	s_ashr_i32 s1, s0, 31
	s_lshl_b64 s[0:1], s[0:1], 12
	s_add_u32 s0, s28, s0
	s_addc_u32 s1, s29, s1
	v_lshl_add_u64 v[192:193], v[166:167], 1, s[0:1]
	s_mov_b64 s[54:55], 0xf80
	v_lshl_add_u64 v[192:193], v[192:193], 0, s[54:55]
	s_add_i32 m0, s100, 0xc000
	v_lshl_add_u64 v[132:133], v[132:133], 1, s[0:1]
	ds_read_b128 v[134:137], v172
	ds_read_b128 v[138:141], v172 offset:1024
	ds_read_b128 v[158:161], v172 offset:2048
	ds_read_b128 v[172:175], v172 offset:3072
	ds_read_b128 v[176:179], v154
	ds_read_b128 v[180:183], v154 offset:1024
	ds_read_b128 v[184:187], v153
	ds_read_b128 v[188:191], v153 offset:1024
	ds_read_b128 v[196:199], v152
	ds_read_b128 v[200:203], v152 offset:1024
	ds_read_b128 v[204:207], v151
	ds_read_b128 v[208:211], v151 offset:1024
	global_load_lds_dwordx4 v[192:193], off
	v_lshl_add_u64 v[132:133], v[132:133], 0, s[54:55]
	s_add_i32 m0, s100, 0xe000
	s_nop 0
	global_load_lds_dwordx4 v[132:133], off
	s_barrier
	s_waitcnt lgkmcnt(0)
	s_waitcnt lgkmcnt(0)
	v_mfma_f32_16x16x32_bf16 v[124:127], v[176:179], v[134:137], v[124:127]
	v_mfma_f32_16x16x32_bf16 v[116:119], v[184:187], v[134:137], v[116:119]
	v_mfma_f32_16x16x32_bf16 v[112:115], v[184:187], v[158:161], v[112:115]
	v_mfma_f32_16x16x32_bf16 v[96:99], v[204:207], v[158:161], v[96:99]
	v_mfma_f32_16x16x32_bf16 v[124:127], v[180:183], v[138:141], v[124:127]
	v_mfma_f32_16x16x32_bf16 v[120:123], v[176:179], v[158:161], v[120:123]
	v_mfma_f32_16x16x32_bf16 v[116:119], v[188:191], v[138:141], v[116:119]
	v_mfma_f32_16x16x32_bf16 v[112:115], v[188:191], v[172:175], v[112:115]
	v_mfma_f32_16x16x32_bf16 v[108:111], v[196:199], v[134:137], v[108:111]
	v_mfma_f32_16x16x32_bf16 v[104:107], v[196:199], v[158:161], v[104:107]
	v_mfma_f32_16x16x32_bf16 v[100:103], v[204:207], v[134:137], v[100:103]
	v_mfma_f32_16x16x32_bf16 v[96:99], v[208:211], v[172:175], v[96:99]
	v_mfma_f32_16x16x32_bf16 v[212:215], v[180:183], v[172:175], v[120:123]
	v_mfma_f32_16x16x32_bf16 v[216:219], v[200:203], v[138:141], v[108:111]
	v_mfma_f32_16x16x32_bf16 v[220:223], v[200:203], v[172:175], v[104:107]
	v_mfma_f32_16x16x32_bf16 v[224:227], v[208:211], v[138:141], v[100:103]
	s_barrier
	s_nop 0
	ds_read_b128 v[100:103], v162
	ds_read_b128 v[104:107], v162 offset:1024
	ds_read_b128 v[108:111], v162 offset:2048
	ds_read_b128 v[120:123], v162 offset:3072
	s_barrier
; #define P8_LDA(dst,b,h) _Pragma("unroll") for(int m=0;m<4;++m) _Pragma("unroll") for(int k=0;k<2;++k) \
;     dst[m][k]=*reinterpret_cast<const bf16x8*>((char*)P8_SA(b,h)+lds_byte(wr*64+m*16+fr,k*32+fq*8))
; #define P8_LDB(dst,b,h) _Pragma("unroll") for(int n=0;n<2;++n) _Pragma("unroll") for(int k=0;k<2;++k) \
;     dst[n][k]=*reinterpret_cast<const bf16x8*>((char*)P8_SB(b,h)+lds_byte(wc*32+n*16+fr,k*32+fq*8))
; #define P8_MMA(ai,bj,At,Bt) do{__builtin_amdgcn_s_setprio(1); \
;     _Pragma("unroll") for(int m=0;m<4;++m) _Pragma("unroll") for(int n=0;n<2;++n) _Pragma("unroll") for(int k=0;k<2;++k) \
;       acc[ai][bj][m][n]=__builtin_amdgcn_mfma_f32_16x16x32_bf16(At[m][k],Bt[n][k],acc[ai][bj][m][n],0,0,0); \
;     __builtin_amdgcn_s_setprio(0);}while(0)
; #define P8_WAIT_V(n) asm volatile("s_waitcnt vmcnt(" #n ")":::"memory")
; #define P8_WAIT_L(n) asm volatile("s_waitcnt lgkmcnt(" #n ")":::"memory")
; #define P8_BAR __builtin_amdgcn_s_barrier()
; template <class EPI>
; DEVI void gemm8_tile(const bfr* __restrict__ A, const bfr* __restrict__ Bt, int K, int brow, int bcol, int nbrow, int nbcol, char* shmc, EPI epi) {
;     ...
;     P8_LDB(B1,0,1); P8_BAR; P8_WAIT_L(0); P8_MMA(0,1,At,B1); P8_BAR;
;     P8_LDA(At,0,1); P8_WAIT_V(4); P8_BAR; P8_WAIT_L(0); P8_MMA(1,0,At,B0); P8_MMA(1,1,At,B1); P8_BAR; }
;   { P8_LDB(B0,1,0); P8_LDA(At,1,0); P8_WAIT_V(2); P8_BAR; P8_WAIT_L(0); P8_MMA(0,0,At,B0); P8_BAR;
	s_waitcnt lgkmcnt(0)
	s_waitcnt lgkmcnt(0)
	v_mfma_f32_16x16x32_bf16 v[92:95], v[176:179], v[100:103], v[92:95]
	v_mfma_f32_16x16x32_bf16 v[84:87], v[184:187], v[100:103], v[84:87]
	v_mfma_f32_16x16x32_bf16 v[80:83], v[184:187], v[108:111], v[80:83]
	v_mfma_f32_16x16x32_bf16 v[64:67], v[204:207], v[108:111], v[64:67]
	v_mfma_f32_16x16x32_bf16 v[92:95], v[180:183], v[104:107], v[92:95]
	v_mfma_f32_16x16x32_bf16 v[88:91], v[176:179], v[108:111], v[88:91]
	v_mfma_f32_16x16x32_bf16 v[84:87], v[188:191], v[104:107], v[84:87]
	v_mfma_f32_16x16x32_bf16 v[80:83], v[188:191], v[120:123], v[80:83]
	v_mfma_f32_16x16x32_bf16 v[76:79], v[196:199], v[100:103], v[76:79]
	v_mfma_f32_16x16x32_bf16 v[72:75], v[196:199], v[108:111], v[72:75]
	v_mfma_f32_16x16x32_bf16 v[68:71], v[204:207], v[100:103], v[68:71]
	v_mfma_f32_16x16x32_bf16 v[64:67], v[208:211], v[120:123], v[64:67]
	v_mfma_f32_16x16x32_bf16 v[176:179], v[180:183], v[120:123], v[88:91]
	v_mfma_f32_16x16x32_bf16 v[180:183], v[200:203], v[104:107], v[76:79]
	v_mfma_f32_16x16x32_bf16 v[184:187], v[200:203], v[120:123], v[72:75]
	v_mfma_f32_16x16x32_bf16 v[188:191], v[208:211], v[104:107], v[68:71]
	s_barrier
	s_nop 0
	ds_read_b128 v[68:71], v154 offset:16384
	ds_read_b128 v[72:75], v154 offset:17408
	ds_read_b128 v[76:79], v153 offset:16384
	ds_read_b128 v[88:91], v153 offset:17408
	ds_read_b128 v[196:199], v152 offset:16384
	ds_read_b128 v[200:203], v152 offset:17408
	ds_read_b128 v[204:207], v151 offset:16384
	ds_read_b128 v[208:211], v151 offset:17408
	s_waitcnt vmcnt(4)
	s_barrier
	s_waitcnt lgkmcnt(0)
	s_waitcnt lgkmcnt(0)
	v_mfma_f32_16x16x32_bf16 v[60:63], v[68:71], v[134:137], v[60:63]
	v_mfma_f32_16x16x32_bf16 v[52:55], v[76:79], v[134:137], v[52:55]
	v_mfma_f32_16x16x32_bf16 v[48:51], v[76:79], v[158:161], v[48:51]
	v_mfma_f32_16x16x32_bf16 v[32:35], v[204:207], v[158:161], v[32:35]
	v_mfma_f32_16x16x32_bf16 v[60:63], v[72:75], v[138:141], v[60:63]
	v_mfma_f32_16x16x32_bf16 v[56:59], v[68:71], v[158:161], v[56:59]
	v_mfma_f32_16x16x32_bf16 v[52:55], v[88:91], v[138:141], v[52:55]
	v_mfma_f32_16x16x32_bf16 v[48:51], v[88:91], v[172:175], v[48:51]
	v_mfma_f32_16x16x32_bf16 v[44:47], v[196:199], v[134:137], v[44:47]
	v_mfma_f32_16x16x32_bf16 v[40:43], v[196:199], v[158:161], v[40:43]
	v_mfma_f32_16x16x32_bf16 v[36:39], v[204:207], v[134:137], v[36:39]
	v_mfma_f32_16x16x32_bf16 v[32:35], v[208:211], v[172:175], v[32:35]
	v_mfma_f32_16x16x32_bf16 v[228:231], v[72:75], v[172:175], v[56:59]
	v_mfma_f32_16x16x32_bf16 v[232:235], v[200:203], v[138:141], v[44:47]
	v_mfma_f32_16x16x32_bf16 v[236:239], v[200:203], v[172:175], v[40:43]
	v_mfma_f32_16x16x32_bf16 v[132:135], v[208:211], v[138:141], v[36:39]
	s_setprio 0
	s_setprio 1
	v_mfma_f32_16x16x32_bf16 v[28:31], v[68:71], v[100:103], v[28:31]
	v_mfma_f32_16x16x32_bf16 v[20:23], v[76:79], v[100:103], v[20:23]
	v_mfma_f32_16x16x32_bf16 v[16:19], v[76:79], v[108:111], v[16:19]
	v_mfma_f32_16x16x32_bf16 v[0:3], v[204:207], v[108:111], v[0:3]
	v_mfma_f32_16x16x32_bf16 v[28:31], v[72:75], v[104:107], v[28:31]
	v_mfma_f32_16x16x32_bf16 v[24:27], v[68:71], v[108:111], v[24:27]
	v_mfma_f32_16x16x32_bf16 v[20:23], v[88:91], v[104:107], v[20:23]
	v_mfma_f32_16x16x32_bf16 v[16:19], v[88:91], v[120:123], v[16:19]
	v_mfma_f32_16x16x32_bf16 v[12:15], v[196:199], v[100:103], v[12:15]
	v_mfma_f32_16x16x32_bf16 v[8:11], v[196:199], v[108:111], v[8:11]
	v_mfma_f32_16x16x32_bf16 v[4:7], v[204:207], v[100:103], v[4:7]
	v_mfma_f32_16x16x32_bf16 v[0:3], v[208:211], v[120:123], v[0:3]
	v_mfma_f32_16x16x32_bf16 v[136:139], v[72:75], v[120:123], v[24:27]
	v_mfma_f32_16x16x32_bf16 v[158:161], v[200:203], v[104:107], v[12:15]
	v_mfma_f32_16x16x32_bf16 v[170:173], v[200:203], v[120:123], v[8:11]
	v_mfma_f32_16x16x32_bf16 v[196:199], v[208:211], v[104:107], v[4:7]
	s_barrier
	s_nop 0
	ds_read_b128 v[4:7], v156
	ds_read_b128 v[8:11], v156 offset:1024
	ds_read_b128 v[12:15], v156 offset:2048
	ds_read_b128 v[24:27], v156 offset:3072
	ds_read_b128 v[36:39], v154 offset:32768
	ds_read_b128 v[40:43], v154 offset:33792
	ds_read_b128 v[44:47], v153 offset:32768
	ds_read_b128 v[56:59], v153 offset:33792
	ds_read_b128 v[68:71], v152 offset:32768
	ds_read_b128 v[200:203], v152 offset:33792
	ds_read_b128 v[204:207], v151 offset:32768
	ds_read_b128 v[208:211], v151 offset:33792
	s_waitcnt vmcnt(2)
	s_barrier
; #define P8_LDA(dst,b,h) _Pragma("unroll") for(int m=0;m<4;++m) _Pragma("unroll") for(int k=0;k<2;++k) \
;     dst[m][k]=*reinterpret_cast<const bf16x8*>((char*)P8_SA(b,h)+lds_byte(wr*64+m*16+fr,k*32+fq*8))
; #define P8_LDB(dst,b,h) _Pragma("unroll") for(int n=0;n<2;++n) _Pragma("unroll") for(int k=0;k<2;++k) \
;     dst[n][k]=*reinterpret_cast<const bf16x8*>((char*)P8_SB(b,h)+lds_byte(wc*32+n*16+fr,k*32+fq*8))
; #define P8_MMA(ai,bj,At,Bt) do{__builtin_amdgcn_s_setprio(1); \
;     _Pragma("unroll") for(int m=0;m<4;++m) _Pragma("unroll") for(int n=0;n<2;++n) _Pragma("unroll") for(int k=0;k<2;++k) \
;       acc[ai][bj][m][n]=__builtin_amdgcn_mfma_f32_16x16x32_bf16(At[m][k],Bt[n][k],acc[ai][bj][m][n],0,0,0); \
;     __builtin_amdgcn_s_setprio(0);}while(0)
; #define P8_WAIT_V(n) asm volatile("s_waitcnt vmcnt(" #n ")":::"memory")
; #define P8_WAIT_L(n) asm volatile("s_waitcnt lgkmcnt(" #n ")":::"memory")
; #define P8_BAR __builtin_amdgcn_s_barrier()
; template <class EPI>
; DEVI void gemm8_tile(const bfr* __restrict__ A, const bfr* __restrict__ Bt, int K, int brow, int bcol, int nbrow, int nbcol, char* shmc, EPI epi) {
;     ...
;   { P8_LDB(B0,1,0); P8_LDA(At,1,0); P8_WAIT_V(2); P8_BAR; P8_WAIT_L(0); P8_MMA(0,0,At,B0); P8_BAR;
;     P8_LDB(B1,1,1); P8_WAIT_V(0); P8_BAR; P8_WAIT_L(0); P8_MMA(0,1,At,B1); P8_BAR;
;     P8_LDA(At,1,1); P8_BAR; P8_WAIT_L(0); P8_MMA(1,0,At,B0); P8_MMA(1,1,At,B1); P8_BAR; }
;   if(wr==0)P8_BAR;
	s_waitcnt lgkmcnt(0)
	s_waitcnt lgkmcnt(0)
	v_mfma_f32_16x16x32_bf16 v[72:75], v[36:39], v[4:7], v[124:127]
	v_mfma_f32_16x16x32_bf16 v[120:123], v[40:43], v[8:11], v[72:75]
	v_mfma_f32_16x16x32_bf16 v[72:75], v[36:39], v[12:15], v[212:215]
	v_mfma_f32_16x16x32_bf16 v[104:107], v[40:43], v[24:27], v[72:75]
	v_mfma_f32_16x16x32_bf16 v[72:75], v[44:47], v[4:7], v[116:119]
	v_mfma_f32_16x16x32_bf16 v[124:127], v[56:59], v[8:11], v[72:75]
	v_mfma_f32_16x16x32_bf16 v[72:75], v[44:47], v[12:15], v[112:115]
	v_mfma_f32_16x16x32_bf16 v[108:111], v[56:59], v[24:27], v[72:75]
	v_mfma_f32_16x16x32_bf16 v[72:75], v[68:71], v[4:7], v[216:219]
	v_mfma_f32_16x16x32_bf16 v[112:115], v[200:203], v[8:11], v[72:75]
	v_mfma_f32_16x16x32_bf16 v[72:75], v[68:71], v[12:15], v[220:223]
	v_mfma_f32_16x16x32_bf16 v[100:103], v[200:203], v[24:27], v[72:75]
	v_mfma_f32_16x16x32_bf16 v[72:75], v[204:207], v[4:7], v[224:227]
	v_mfma_f32_16x16x32_bf16 v[116:119], v[208:211], v[8:11], v[72:75]
	v_mfma_f32_16x16x32_bf16 v[72:75], v[204:207], v[12:15], v[96:99]
	v_mfma_f32_16x16x32_bf16 v[96:99], v[208:211], v[24:27], v[72:75]
	s_barrier
	ds_read_b128 v[212:215], v155
	ds_read_b128 v[216:219], v155 offset:1024
	ds_read_b128 v[220:223], v155 offset:2048
	ds_read_b128 v[224:227], v155 offset:3072
	s_waitcnt vmcnt(0)
	s_barrier
	s_waitcnt lgkmcnt(0)
	s_waitcnt lgkmcnt(0)
	v_mfma_f32_16x16x32_bf16 v[72:75], v[36:39], v[212:215], v[92:95]
	v_mfma_f32_16x16x32_bf16 v[36:39], v[36:39], v[220:223], v[176:179]
	v_mfma_f32_16x16x32_bf16 v[88:91], v[40:43], v[216:219], v[72:75]
	v_mfma_f32_16x16x32_bf16 v[72:75], v[40:43], v[224:227], v[36:39]
	v_mfma_f32_16x16x32_bf16 v[36:39], v[44:47], v[212:215], v[84:87]
	v_mfma_f32_16x16x32_bf16 v[92:95], v[56:59], v[216:219], v[36:39]
	v_mfma_f32_16x16x32_bf16 v[36:39], v[44:47], v[220:223], v[80:83]
	v_mfma_f32_16x16x32_bf16 v[76:79], v[56:59], v[224:227], v[36:39]
	v_mfma_f32_16x16x32_bf16 v[36:39], v[68:71], v[212:215], v[180:183]
	v_mfma_f32_16x16x32_bf16 v[80:83], v[200:203], v[216:219], v[36:39]
	v_mfma_f32_16x16x32_bf16 v[36:39], v[68:71], v[220:223], v[184:187]
	v_mfma_f32_16x16x32_bf16 v[68:71], v[200:203], v[224:227], v[36:39]
	v_mfma_f32_16x16x32_bf16 v[36:39], v[204:207], v[212:215], v[188:191]
	v_mfma_f32_16x16x32_bf16 v[84:87], v[208:211], v[216:219], v[36:39]
	v_mfma_f32_16x16x32_bf16 v[36:39], v[204:207], v[220:223], v[64:67]
	v_mfma_f32_16x16x32_bf16 v[64:67], v[208:211], v[224:227], v[36:39]
	s_barrier
	ds_read_b128 v[174:177], v154 offset:49152
	ds_read_b128 v[154:157], v154 offset:50176
	ds_read_b128 v[178:181], v153 offset:49152
	ds_read_b128 v[182:185], v153 offset:50176
	ds_read_b128 v[186:189], v152 offset:49152
	ds_read_b128 v[190:193], v152 offset:50176
	ds_read_b128 v[200:203], v151 offset:49152
	ds_read_b128 v[204:207], v151 offset:50176
	s_barrier
	s_waitcnt lgkmcnt(0)
	s_waitcnt lgkmcnt(0)
	v_mfma_f32_16x16x32_bf16 v[36:39], v[174:177], v[4:7], v[60:63]
	v_mfma_f32_16x16x32_bf16 v[56:59], v[154:157], v[8:11], v[36:39]
	v_mfma_f32_16x16x32_bf16 v[36:39], v[174:177], v[12:15], v[228:231]
	v_mfma_f32_16x16x32_bf16 v[40:43], v[154:157], v[24:27], v[36:39]
	v_mfma_f32_16x16x32_bf16 v[36:39], v[178:181], v[4:7], v[52:55]
	v_mfma_f32_16x16x32_bf16 v[60:63], v[182:185], v[8:11], v[36:39]
	v_mfma_f32_16x16x32_bf16 v[36:39], v[178:181], v[12:15], v[48:51]
	v_mfma_f32_16x16x32_bf16 v[44:47], v[182:185], v[24:27], v[36:39]
	v_mfma_f32_16x16x32_bf16 v[36:39], v[186:189], v[4:7], v[232:235]
	v_mfma_f32_16x16x32_bf16 v[4:7], v[200:203], v[4:7], v[132:135]
	v_mfma_f32_16x16x32_bf16 v[48:51], v[190:193], v[8:11], v[36:39]
	v_mfma_f32_16x16x32_bf16 v[36:39], v[186:189], v[12:15], v[236:239]
	v_mfma_f32_16x16x32_bf16 v[52:55], v[204:207], v[8:11], v[4:7]
	v_mfma_f32_16x16x32_bf16 v[4:7], v[200:203], v[12:15], v[32:35]
	v_mfma_f32_16x16x32_bf16 v[36:39], v[190:193], v[24:27], v[36:39]
	v_mfma_f32_16x16x32_bf16 v[32:35], v[204:207], v[24:27], v[4:7]
	s_setprio 0
	s_setprio 1
	v_mfma_f32_16x16x32_bf16 v[4:7], v[174:177], v[212:215], v[28:31]
	v_mfma_f32_16x16x32_bf16 v[24:27], v[154:157], v[216:219], v[4:7]
	v_mfma_f32_16x16x32_bf16 v[4:7], v[174:177], v[220:223], v[136:139]
	v_mfma_f32_16x16x32_bf16 v[8:11], v[154:157], v[224:227], v[4:7]
	v_mfma_f32_16x16x32_bf16 v[4:7], v[178:181], v[212:215], v[20:23]
	v_mfma_f32_16x16x32_bf16 v[28:31], v[182:185], v[216:219], v[4:7]
	v_mfma_f32_16x16x32_bf16 v[4:7], v[178:181], v[220:223], v[16:19]
	v_mfma_f32_16x16x32_bf16 v[12:15], v[182:185], v[224:227], v[4:7]
	v_mfma_f32_16x16x32_bf16 v[4:7], v[186:189], v[212:215], v[158:161]
	v_mfma_f32_16x16x32_bf16 v[16:19], v[190:193], v[216:219], v[4:7]
	v_mfma_f32_16x16x32_bf16 v[4:7], v[186:189], v[220:223], v[170:173]
	v_mfma_f32_16x16x32_bf16 v[20:23], v[200:203], v[212:215], v[196:199]
	v_mfma_f32_16x16x32_bf16 v[0:3], v[200:203], v[220:223], v[0:3]
	v_mfma_f32_16x16x32_bf16 v[4:7], v[190:193], v[224:227], v[4:7]
	v_mfma_f32_16x16x32_bf16 v[20:23], v[204:207], v[216:219], v[20:23]
	v_mfma_f32_16x16x32_bf16 v[0:3], v[204:207], v[224:227], v[0:3]
	s_setprio 0
	v_cmp_gt_u32_e32 vcc, s57, v142
	s_barrier
	s_and_saveexec_b64 s[0:1], vcc
	s_cbranch_execz .LBB0_69
	s_barrier

; #define P8_STAGE(P,BASE,br,kt) do{const bfr* _ub=(BASE)+((long)(br)*K+(long)(kt)*BK); \
;     __builtin_amdgcn_global_load_lds((const unsigned*)(_ub+so0),(unsigned*)((char*)(P)+wid*1024),16,0,0); \
;     __builtin_amdgcn_global_load_lds((const unsigned*)(_ub+so1),(unsigned*)((char*)(P)+wid*1024+8192),16,0,0);}while(0)
; #define P8_LDA(dst,b,h) _Pragma("unroll") for(int m=0;m<4;++m) _Pragma("unroll") for(int k=0;k<2;++k) \
;     dst[m][k]=*reinterpret_cast<const bf16x8*>((char*)P8_SA(b,h)+lds_byte(wr*64+m*16+fr,k*32+fq*8))
; #define P8_LDB(dst,b,h) _Pragma("unroll") for(int n=0;n<2;++n) _Pragma("unroll") for(int k=0;k<2;++k) \
;     dst[n][k]=*reinterpret_cast<const bf16x8*>((char*)P8_SB(b,h)+lds_byte(wc*32+n*16+fr,k*32+fq*8))
; #define P8_MMA(ai,bj,At,Bt) do{__builtin_amdgcn_s_setprio(1); \
;     _Pragma("unroll") for(int m=0;m<4;++m) _Pragma("unroll") for(int n=0;n<2;++n) _Pragma("unroll") for(int k=0;k<2;++k) \
;       acc[ai][bj][m][n]=__builtin_amdgcn_mfma_f32_16x16x32_bf16(At[m][k],Bt[n][k],acc[ai][bj][m][n],0,0,0); \
;     __builtin_amdgcn_s_setprio(0);}while(0)
; #define P8_WAIT_V(n) asm volatile("s_waitcnt vmcnt(" #n ")":::"memory")
; #define P8_WAIT_L(n) asm volatile("s_waitcnt lgkmcnt(" #n ")":::"memory")
; #define P8_BAR __builtin_amdgcn_s_barrier()
; #define P8_SCHED __builtin_amdgcn_sched_barrier(0)
; template <class EPI>
; DEVI void gemm8_tile(const bfr* __restrict__ A, const bfr* __restrict__ Bt, int K, int brow, int bcol, int nbrow, int nbcol, char* shmc, EPI epi) {
;     ...
;   for(int t=0;t<nt-2;t+=2){
;     P8_LDB(B0,0,0); P8_SCHED; P8_LDA(At,0,0); P8_STAGE(P8_SA(1,1),A,brow+128,t+1);
;     P8_WAIT_L(8); P8_BAR; P8_WAIT_L(0); P8_MMA(0,0,At,B0); P8_BAR; P8_SCHED;
;     P8_LDB(B1,0,1); P8_STAGE(P8_SB(0,0),Bt,bcol,t+2);
;     P8_BAR; P8_WAIT_L(0); P8_MMA(0,1,At,B1); P8_BAR;
;     P8_LDA(At,0,1); P8_STAGE(P8_SA(0,0),A,brow,t+2);
;     P8_BAR; P8_WAIT_L(0); P8_MMA(1,0,At,B0); P8_BAR; P8_SCHED;
;     P8_STAGE(P8_SB(0,1),Bt,bcol+128,t+2);
;     P8_WAIT_V(6); P8_BAR; P8_MMA(1,1,At,B1); P8_BAR;
.LBB0_85:
	ds_read_b128 v[174:177], v157
	ds_read_b128 v[178:181], v157 offset:1024
	ds_read_b128 v[182:185], v157 offset:2048
	ds_read_b128 v[186:189], v157 offset:3072
	v_add_u32_e32 v158, s54, v140
	s_add_i32 m0, s100, 0xc000
	ds_read_b128 v[160:163], v147
	ds_read_b128 v[190:193], v147 offset:1024
	ds_read_b128 v[196:199], v146
	ds_read_b128 v[200:203], v146 offset:1024
	ds_read_b128 v[204:207], v145
	ds_read_b128 v[208:211], v145 offset:1024
	ds_read_b128 v[212:215], v144
	ds_read_b128 v[216:219], v144 offset:1024
	global_load_lds_dwordx4 v158, s[86:87]
	v_add_u32_e32 v158, s54, v138
	s_add_i32 m0, s100, 0xe000
	s_nop 0
	global_load_lds_dwordx4 v158, s[86:87]
	s_waitcnt lgkmcnt(8)
	s_barrier
	s_waitcnt lgkmcnt(0)
	v_mfma_f32_16x16x32_bf16 v[124:127], v[160:163], v[174:177], v[124:127]
	v_mfma_f32_16x16x32_bf16 v[120:123], v[160:163], v[182:185], v[120:123]
	v_mfma_f32_16x16x32_bf16 v[116:119], v[196:199], v[174:177], v[116:119]
	v_mfma_f32_16x16x32_bf16 v[112:115], v[196:199], v[182:185], v[112:115]
	v_mfma_f32_16x16x32_bf16 v[108:111], v[204:207], v[174:177], v[108:111]
	v_mfma_f32_16x16x32_bf16 v[104:107], v[204:207], v[182:185], v[104:107]
	v_mfma_f32_16x16x32_bf16 v[100:103], v[212:215], v[174:177], v[100:103]
	v_mfma_f32_16x16x32_bf16 v[96:99], v[212:215], v[182:185], v[96:99]
	v_mfma_f32_16x16x32_bf16 v[124:127], v[190:193], v[178:181], v[124:127]
	v_mfma_f32_16x16x32_bf16 v[120:123], v[190:193], v[186:189], v[120:123]
	v_mfma_f32_16x16x32_bf16 v[116:119], v[200:203], v[178:181], v[116:119]
	v_mfma_f32_16x16x32_bf16 v[112:115], v[200:203], v[186:189], v[112:115]
	v_mfma_f32_16x16x32_bf16 v[108:111], v[208:211], v[178:181], v[108:111]
	v_mfma_f32_16x16x32_bf16 v[104:107], v[208:211], v[186:189], v[104:107]
	v_mfma_f32_16x16x32_bf16 v[100:103], v[216:219], v[178:181], v[100:103]
	v_mfma_f32_16x16x32_bf16 v[96:99], v[216:219], v[186:189], v[96:99]
	s_barrier
	v_add_u32_e32 v236, s66, v136
	s_add_i32 m0, s100, 0x10000
	ds_read_b128 v[220:223], v155
	ds_read_b128 v[224:227], v155 offset:1024
	ds_read_b128 v[228:231], v155 offset:2048
	ds_read_b128 v[232:235], v155 offset:3072
	global_load_lds_dwordx4 v236, s[86:87]
	v_add_u32_e32 v236, s66, v134
	s_add_i32 m0, s100, 0x12000
	s_nop 0
	global_load_lds_dwordx4 v236, s[86:87]
	s_barrier
	s_waitcnt lgkmcnt(0)
	v_mfma_f32_16x16x32_bf16 v[92:95], v[160:163], v[220:223], v[92:95]
	v_mfma_f32_16x16x32_bf16 v[88:91], v[160:163], v[228:231], v[88:91]
	v_mfma_f32_16x16x32_bf16 v[84:87], v[196:199], v[220:223], v[84:87]
	v_mfma_f32_16x16x32_bf16 v[80:83], v[196:199], v[228:231], v[80:83]
	v_mfma_f32_16x16x32_bf16 v[76:79], v[204:207], v[220:223], v[76:79]
	v_mfma_f32_16x16x32_bf16 v[72:75], v[204:207], v[228:231], v[72:75]
	v_mfma_f32_16x16x32_bf16 v[68:71], v[212:215], v[220:223], v[68:71]
	v_mfma_f32_16x16x32_bf16 v[64:67], v[212:215], v[228:231], v[64:67]
	v_mfma_f32_16x16x32_bf16 v[92:95], v[190:193], v[224:227], v[92:95]
	v_mfma_f32_16x16x32_bf16 v[88:91], v[190:193], v[232:235], v[88:91]
	v_mfma_f32_16x16x32_bf16 v[84:87], v[200:203], v[224:227], v[84:87]
	v_mfma_f32_16x16x32_bf16 v[80:83], v[200:203], v[232:235], v[80:83]
	v_mfma_f32_16x16x32_bf16 v[76:79], v[208:211], v[224:227], v[76:79]
	v_mfma_f32_16x16x32_bf16 v[72:75], v[208:211], v[232:235], v[72:75]
	v_mfma_f32_16x16x32_bf16 v[68:71], v[216:219], v[224:227], v[68:71]
	v_mfma_f32_16x16x32_bf16 v[64:67], v[216:219], v[232:235], v[64:67]
	v_add_u32_e32 v160, s60, v140
	s_mov_b32 m0, s100
	s_barrier
	ds_read_b128 v[190:193], v147 offset:16384
	ds_read_b128 v[196:199], v147 offset:17408
	ds_read_b128 v[200:203], v146 offset:16384
	ds_read_b128 v[204:207], v146 offset:17408
	ds_read_b128 v[208:211], v145 offset:16384
	ds_read_b128 v[212:215], v145 offset:17408
	ds_read_b128 v[216:219], v144 offset:16384
	ds_read_b128 v[236:239], v144 offset:17408
	global_load_lds_dwordx4 v160, s[86:87]
	v_add_u32_e32 v162, s60, v138
	s_add_i32 m0, s100, 0x2000
	s_nop 0
	global_load_lds_dwordx4 v162, s[86:87]
	s_barrier
	s_waitcnt lgkmcnt(0)
	v_mfma_f32_16x16x32_bf16 v[60:63], v[190:193], v[174:177], v[60:63]
	v_mfma_f32_16x16x32_bf16 v[56:59], v[190:193], v[182:185], v[56:59]
	v_mfma_f32_16x16x32_bf16 v[52:55], v[200:203], v[174:177], v[52:55]
	v_mfma_f32_16x16x32_bf16 v[48:51], v[200:203], v[182:185], v[48:51]
	v_mfma_f32_16x16x32_bf16 v[44:47], v[208:211], v[174:177], v[44:47]
	v_mfma_f32_16x16x32_bf16 v[40:43], v[208:211], v[182:185], v[40:43]
	v_mfma_f32_16x16x32_bf16 v[36:39], v[216:219], v[174:177], v[36:39]
	v_mfma_f32_16x16x32_bf16 v[32:35], v[216:219], v[182:185], v[32:35]
	v_mfma_f32_16x16x32_bf16 v[60:63], v[196:199], v[178:181], v[60:63]
	v_mfma_f32_16x16x32_bf16 v[56:59], v[196:199], v[186:189], v[56:59]
	v_mfma_f32_16x16x32_bf16 v[52:55], v[204:207], v[178:181], v[52:55]
	v_mfma_f32_16x16x32_bf16 v[48:51], v[204:207], v[186:189], v[48:51]
	v_mfma_f32_16x16x32_bf16 v[44:47], v[212:215], v[178:181], v[44:47]
	v_mfma_f32_16x16x32_bf16 v[40:43], v[212:215], v[186:189], v[40:43]
	v_mfma_f32_16x16x32_bf16 v[36:39], v[236:239], v[178:181], v[36:39]
	v_mfma_f32_16x16x32_bf16 v[32:35], v[236:239], v[186:189], v[32:35]
	s_barrier
	v_add_u32_e32 v162, s70, v136
	s_add_i32 m0, s100, 0x14000
	v_add_u32_e32 v174, s70, v134
	global_load_lds_dwordx4 v162, s[86:87]
	s_nop 0
	s_add_i32 m0, s100, 0x16000
	s_nop 0
	global_load_lds_dwordx4 v174, s[86:87]
	s_waitcnt vmcnt(6)
	s_barrier
; #define P8_STAGE(P,BASE,br,kt) do{const bfr* _ub=(BASE)+((long)(br)*K+(long)(kt)*BK); \
;     __builtin_amdgcn_global_load_lds((const unsigned*)(_ub+so0),(unsigned*)((char*)(P)+wid*1024),16,0,0); \
;     __builtin_amdgcn_global_load_lds((const unsigned*)(_ub+so1),(unsigned*)((char*)(P)+wid*1024+8192),16,0,0);}while(0)
; #define P8_LDA(dst,b,h) _Pragma("unroll") for(int m=0;m<4;++m) _Pragma("unroll") for(int k=0;k<2;++k) \
;     dst[m][k]=*reinterpret_cast<const bf16x8*>((char*)P8_SA(b,h)+lds_byte(wr*64+m*16+fr,k*32+fq*8))
; #define P8_LDB(dst,b,h) _Pragma("unroll") for(int n=0;n<2;++n) _Pragma("unroll") for(int k=0;k<2;++k) \
;     dst[n][k]=*reinterpret_cast<const bf16x8*>((char*)P8_SB(b,h)+lds_byte(wc*32+n*16+fr,k*32+fq*8))
; #define P8_MMA(ai,bj,At,Bt) do{__builtin_amdgcn_s_setprio(1); \
;     _Pragma("unroll") for(int m=0;m<4;++m) _Pragma("unroll") for(int n=0;n<2;++n) _Pragma("unroll") for(int k=0;k<2;++k) \
;       acc[ai][bj][m][n]=__builtin_amdgcn_mfma_f32_16x16x32_bf16(At[m][k],Bt[n][k],acc[ai][bj][m][n],0,0,0); \
;     __builtin_amdgcn_s_setprio(0);}while(0)
; #define P8_WAIT_V(n) asm volatile("s_waitcnt vmcnt(" #n ")":::"memory")
; #define P8_WAIT_L(n) asm volatile("s_waitcnt lgkmcnt(" #n ")":::"memory")
; #define P8_BAR __builtin_amdgcn_s_barrier()
; #define P8_SCHED __builtin_amdgcn_sched_barrier(0)
; template <class EPI>
; DEVI void gemm8_tile(const bfr* __restrict__ A, const bfr* __restrict__ Bt, int K, int brow, int bcol, int nbrow, int nbcol, char* shmc, EPI epi) {
;     ...
;     P8_WAIT_V(6); P8_BAR; P8_MMA(1,1,At,B1); P8_BAR;
;     P8_LDB(B0,1,0); P8_SCHED; P8_LDA(At,1,0); P8_STAGE(P8_SA(0,1),A,brow+128,t+2);
;     P8_WAIT_L(8); P8_BAR; P8_WAIT_L(0); P8_MMA(0,0,At,B0); P8_BAR; P8_SCHED;
;     P8_LDB(B1,1,1); P8_STAGE(P8_SB(1,0),Bt,bcol,t+3);
;     P8_BAR; P8_WAIT_L(0); P8_MMA(0,1,At,B1); P8_BAR;
;     P8_LDA(At,1,1); P8_STAGE(P8_SA(1,0),A,brow,t+3);
	v_mfma_f32_16x16x32_bf16 v[28:31], v[190:193], v[220:223], v[28:31]
	v_mfma_f32_16x16x32_bf16 v[24:27], v[190:193], v[228:231], v[24:27]
	v_mfma_f32_16x16x32_bf16 v[20:23], v[200:203], v[220:223], v[20:23]
	v_mfma_f32_16x16x32_bf16 v[16:19], v[200:203], v[228:231], v[16:19]
	v_mfma_f32_16x16x32_bf16 v[12:15], v[208:211], v[220:223], v[12:15]
	v_mfma_f32_16x16x32_bf16 v[8:11], v[208:211], v[228:231], v[8:11]
	v_mfma_f32_16x16x32_bf16 v[4:7], v[216:219], v[220:223], v[4:7]
	v_mfma_f32_16x16x32_bf16 v[0:3], v[216:219], v[228:231], v[0:3]
	v_mfma_f32_16x16x32_bf16 v[28:31], v[196:199], v[224:227], v[28:31]
	v_mfma_f32_16x16x32_bf16 v[24:27], v[196:199], v[232:235], v[24:27]
	v_mfma_f32_16x16x32_bf16 v[20:23], v[204:207], v[224:227], v[20:23]
	v_mfma_f32_16x16x32_bf16 v[16:19], v[204:207], v[232:235], v[16:19]
	v_mfma_f32_16x16x32_bf16 v[12:15], v[212:215], v[224:227], v[12:15]
	v_mfma_f32_16x16x32_bf16 v[8:11], v[212:215], v[232:235], v[8:11]
	v_mfma_f32_16x16x32_bf16 v[4:7], v[236:239], v[224:227], v[4:7]
	v_mfma_f32_16x16x32_bf16 v[0:3], v[236:239], v[232:235], v[0:3]
	s_barrier
	ds_read_b128 v[174:177], v149
	ds_read_b128 v[178:181], v149 offset:1024
	ds_read_b128 v[182:185], v149 offset:2048
	ds_read_b128 v[186:189], v149 offset:3072
	v_add_u32_e32 v224, s72, v140
	s_add_i32 m0, s100, 0x4000
	ds_read_b128 v[190:193], v147 offset:32768
	ds_read_b128 v[196:199], v147 offset:33792
	ds_read_b128 v[200:203], v146 offset:32768
	ds_read_b128 v[204:207], v146 offset:33792
	ds_read_b128 v[208:211], v145 offset:32768
	ds_read_b128 v[212:215], v145 offset:33792
	ds_read_b128 v[216:219], v144 offset:32768
	ds_read_b128 v[220:223], v144 offset:33792
	global_load_lds_dwordx4 v224, s[86:87]
	v_add_u32_e32 v224, s72, v138
	s_add_i32 m0, s100, 0x6000
	s_nop 0
	global_load_lds_dwordx4 v224, s[86:87]
	s_waitcnt lgkmcnt(8)
	s_barrier
	s_waitcnt lgkmcnt(0)
	v_mfma_f32_16x16x32_bf16 v[124:127], v[190:193], v[174:177], v[124:127]
	v_mfma_f32_16x16x32_bf16 v[120:123], v[190:193], v[182:185], v[120:123]
	v_mfma_f32_16x16x32_bf16 v[116:119], v[200:203], v[174:177], v[116:119]
	v_mfma_f32_16x16x32_bf16 v[112:115], v[200:203], v[182:185], v[112:115]
	v_mfma_f32_16x16x32_bf16 v[108:111], v[208:211], v[174:177], v[108:111]
	v_mfma_f32_16x16x32_bf16 v[104:107], v[208:211], v[182:185], v[104:107]
	v_mfma_f32_16x16x32_bf16 v[100:103], v[216:219], v[174:177], v[100:103]
	v_mfma_f32_16x16x32_bf16 v[96:99], v[216:219], v[182:185], v[96:99]
	v_mfma_f32_16x16x32_bf16 v[124:127], v[196:199], v[178:181], v[124:127]
	v_mfma_f32_16x16x32_bf16 v[120:123], v[196:199], v[186:189], v[120:123]
	v_mfma_f32_16x16x32_bf16 v[116:119], v[204:207], v[178:181], v[116:119]
	v_mfma_f32_16x16x32_bf16 v[112:115], v[204:207], v[186:189], v[112:115]
	v_mfma_f32_16x16x32_bf16 v[108:111], v[212:215], v[178:181], v[108:111]
	v_mfma_f32_16x16x32_bf16 v[104:107], v[212:215], v[186:189], v[104:107]
	v_mfma_f32_16x16x32_bf16 v[100:103], v[220:223], v[178:181], v[100:103]
	v_mfma_f32_16x16x32_bf16 v[96:99], v[220:223], v[186:189], v[96:99]
	s_barrier
	v_add_u32_e32 v248, s74, v136
	s_add_i32 m0, s100, 0x18000
	ds_read_b128 v[224:227], v148
	ds_read_b128 v[228:231], v148 offset:1024
	ds_read_b128 v[232:235], v148 offset:2048
	ds_read_b128 v[236:239], v148 offset:3072
	global_load_lds_dwordx4 v248, s[86:87]
	v_add_u32_e32 v248, s74, v134
	s_add_i32 m0, s100, 0x1a000
	s_nop 0
	global_load_lds_dwordx4 v248, s[86:87]
	s_barrier
	s_waitcnt lgkmcnt(0)
	v_mfma_f32_16x16x32_bf16 v[92:95], v[190:193], v[224:227], v[92:95]
	v_mfma_f32_16x16x32_bf16 v[88:91], v[190:193], v[232:235], v[88:91]
	v_mfma_f32_16x16x32_bf16 v[84:87], v[200:203], v[224:227], v[84:87]
	v_mfma_f32_16x16x32_bf16 v[80:83], v[200:203], v[232:235], v[80:83]
	v_mfma_f32_16x16x32_bf16 v[76:79], v[208:211], v[224:227], v[76:79]
	v_mfma_f32_16x16x32_bf16 v[72:75], v[208:211], v[232:235], v[72:75]
	v_mfma_f32_16x16x32_bf16 v[68:71], v[216:219], v[224:227], v[68:71]
	v_mfma_f32_16x16x32_bf16 v[64:67], v[216:219], v[232:235], v[64:67]
	v_mfma_f32_16x16x32_bf16 v[92:95], v[196:199], v[228:231], v[92:95]
	v_mfma_f32_16x16x32_bf16 v[88:91], v[196:199], v[236:239], v[88:91]
	v_mfma_f32_16x16x32_bf16 v[84:87], v[204:207], v[228:231], v[84:87]
	v_mfma_f32_16x16x32_bf16 v[80:83], v[204:207], v[236:239], v[80:83]
	v_mfma_f32_16x16x32_bf16 v[76:79], v[212:215], v[228:231], v[76:79]
	v_mfma_f32_16x16x32_bf16 v[72:75], v[212:215], v[236:239], v[72:75]
	v_mfma_f32_16x16x32_bf16 v[68:71], v[220:223], v[228:231], v[68:71]
	v_mfma_f32_16x16x32_bf16 v[64:67], v[220:223], v[236:239], v[64:67]
	v_add_u32_e32 v240, s82, v140
	s_add_i32 m0, s100, 0x8000
	s_barrier
	ds_read_b128 v[190:193], v147 offset:49152
	ds_read_b128 v[196:199], v147 offset:50176
	ds_read_b128 v[200:203], v146 offset:49152
	ds_read_b128 v[204:207], v146 offset:50176
	ds_read_b128 v[208:211], v145 offset:49152
	ds_read_b128 v[212:215], v145 offset:50176
	ds_read_b128 v[216:219], v144 offset:49152
	ds_read_b128 v[220:223], v144 offset:50176
	global_load_lds_dwordx4 v240, s[86:87]
	v_add_u32_e32 v240, s82, v138
	s_add_i32 m0, s100, 0xa000
	s_nop 0
	global_load_lds_dwordx4 v240, s[86:87]
	s_barrier
; #define P8_STAGE(P,BASE,br,kt) do{const bfr* _ub=(BASE)+((long)(br)*K+(long)(kt)*BK); \
;     __builtin_amdgcn_global_load_lds((const unsigned*)(_ub+so0),(unsigned*)((char*)(P)+wid*1024),16,0,0); \
;     __builtin_amdgcn_global_load_lds((const unsigned*)(_ub+so1),(unsigned*)((char*)(P)+wid*1024+8192),16,0,0);}while(0)
; #define P8_LDA(dst,b,h) _Pragma("unroll") for(int m=0;m<4;++m) _Pragma("unroll") for(int k=0;k<2;++k) \
;     dst[m][k]=*reinterpret_cast<const bf16x8*>((char*)P8_SA(b,h)+lds_byte(wr*64+m*16+fr,k*32+fq*8))
; #define P8_LDB(dst,b,h) _Pragma("unroll") for(int n=0;n<2;++n) _Pragma("unroll") for(int k=0;k<2;++k) \
;     dst[n][k]=*reinterpret_cast<const bf16x8*>((char*)P8_SB(b,h)+lds_byte(wc*32+n*16+fr,k*32+fq*8))
; #define P8_MMA(ai,bj,At,Bt) do{__builtin_amdgcn_s_setprio(1); \
;     _Pragma("unroll") for(int m=0;m<4;++m) _Pragma("unroll") for(int n=0;n<2;++n) _Pragma("unroll") for(int k=0;k<2;++k) \
;       acc[ai][bj][m][n]=__builtin_amdgcn_mfma_f32_16x16x32_bf16(At[m][k],Bt[n][k],acc[ai][bj][m][n],0,0,0); \
;     __builtin_amdgcn_s_setprio(0);}while(0)
; #define P8_WAIT_V(n) asm volatile("s_waitcnt vmcnt(" #n ")":::"memory")
; #define P8_WAIT_L(n) asm volatile("s_waitcnt lgkmcnt(" #n ")":::"memory")
; #define P8_BAR __builtin_amdgcn_s_barrier()
; #define P8_SCHED __builtin_amdgcn_sched_barrier(0)
; template <class EPI>
; DEVI void gemm8_tile(const bfr* __restrict__ A, const bfr* __restrict__ Bt, int K, int brow, int bcol, int nbrow, int nbcol, char* shmc, EPI epi) {
;     ...
;     P8_BAR; P8_WAIT_L(0); P8_MMA(1,0,At,B0); P8_BAR; P8_SCHED;
;     P8_STAGE(P8_SB(1,1),Bt,bcol+128,t+3);
;     P8_WAIT_V(6); P8_BAR; P8_MMA(1,1,At,B1); P8_BAR;
;   }
;   { P8_LDB(B0,0,0); P8_LDA(At,0,0); P8_STAGE(P8_SA(1,1),A,brow+128,nt-1);
;     P8_BAR; P8_WAIT_L(0); P8_MMA(0,0,At,B0); P8_BAR;
;     P8_LDB(B1,0,1); P8_BAR; P8_WAIT_L(0); P8_MMA(0,1,At,B1); P8_BAR;
	s_waitcnt lgkmcnt(0)
	v_mfma_f32_16x16x32_bf16 v[60:63], v[190:193], v[174:177], v[60:63]
	v_mfma_f32_16x16x32_bf16 v[56:59], v[190:193], v[182:185], v[56:59]
	v_mfma_f32_16x16x32_bf16 v[52:55], v[200:203], v[174:177], v[52:55]
	v_mfma_f32_16x16x32_bf16 v[48:51], v[200:203], v[182:185], v[48:51]
	v_mfma_f32_16x16x32_bf16 v[44:47], v[208:211], v[174:177], v[44:47]
	v_mfma_f32_16x16x32_bf16 v[40:43], v[208:211], v[182:185], v[40:43]
	v_mfma_f32_16x16x32_bf16 v[36:39], v[216:219], v[174:177], v[36:39]
	v_mfma_f32_16x16x32_bf16 v[32:35], v[216:219], v[182:185], v[32:35]
	v_mfma_f32_16x16x32_bf16 v[60:63], v[196:199], v[178:181], v[60:63]
	v_mfma_f32_16x16x32_bf16 v[56:59], v[196:199], v[186:189], v[56:59]
	v_mfma_f32_16x16x32_bf16 v[52:55], v[204:207], v[178:181], v[52:55]
	v_mfma_f32_16x16x32_bf16 v[48:51], v[204:207], v[186:189], v[48:51]
	v_mfma_f32_16x16x32_bf16 v[44:47], v[212:215], v[178:181], v[44:47]
	v_mfma_f32_16x16x32_bf16 v[40:43], v[212:215], v[186:189], v[40:43]
	v_mfma_f32_16x16x32_bf16 v[36:39], v[220:223], v[178:181], v[36:39]
	v_mfma_f32_16x16x32_bf16 v[32:35], v[220:223], v[186:189], v[32:35]
	s_barrier
	v_add_u32_e32 v174, s78, v136
	s_add_i32 m0, s100, 0x1c000
	s_nop 0
	global_load_lds_dwordx4 v174, s[86:87]
	v_add_u32_e32 v174, s78, v134
	s_add_i32 m0, s100, 0x1e000
	s_nop 0
	global_load_lds_dwordx4 v174, s[86:87]
	s_waitcnt vmcnt(6)
	s_barrier
	v_mfma_f32_16x16x32_bf16 v[28:31], v[190:193], v[224:227], v[28:31]
	v_mfma_f32_16x16x32_bf16 v[24:27], v[190:193], v[232:235], v[24:27]
	v_mfma_f32_16x16x32_bf16 v[20:23], v[200:203], v[224:227], v[20:23]
	v_mfma_f32_16x16x32_bf16 v[16:19], v[200:203], v[232:235], v[16:19]
	v_mfma_f32_16x16x32_bf16 v[12:15], v[208:211], v[224:227], v[12:15]
	v_mfma_f32_16x16x32_bf16 v[8:11], v[208:211], v[232:235], v[8:11]
	v_mfma_f32_16x16x32_bf16 v[4:7], v[216:219], v[224:227], v[4:7]
	v_mfma_f32_16x16x32_bf16 v[0:3], v[216:219], v[232:235], v[0:3]
	v_mfma_f32_16x16x32_bf16 v[28:31], v[196:199], v[228:231], v[28:31]
	v_mfma_f32_16x16x32_bf16 v[24:27], v[196:199], v[236:239], v[24:27]
	v_mfma_f32_16x16x32_bf16 v[20:23], v[204:207], v[228:231], v[20:23]
	v_mfma_f32_16x16x32_bf16 v[16:19], v[204:207], v[236:239], v[16:19]
	v_mfma_f32_16x16x32_bf16 v[12:15], v[212:215], v[228:231], v[12:15]
	v_mfma_f32_16x16x32_bf16 v[8:11], v[212:215], v[236:239], v[8:11]
	v_mfma_f32_16x16x32_bf16 v[4:7], v[220:223], v[228:231], v[4:7]
	v_mfma_f32_16x16x32_bf16 v[0:3], v[220:223], v[236:239], v[0:3]
	s_add_i32 s0, s0, 2
	v_lshl_add_u64 v[134:135], v[134:135], 0, s[80:81]
	v_lshl_add_u64 v[136:137], v[136:137], 0, s[80:81]
	v_lshl_add_u64 v[138:139], v[138:139], 0, s[80:81]
	s_cmp_lt_u32 s0, 28
	v_lshl_add_u64 v[140:141], v[140:141], 0, s[80:81]
	s_barrier
	s_cbranch_scc1 .LBB0_85
	v_add_u32_e32 v171, 0xc000, v143
	v_add_u32_e32 v172, 0xe000, v143
	v_add_u32_e32 v158, 0x10000, v143
	v_add_u32_e32 v159, 0x12000, v143
	v_add_u32_e32 v160, 0x2000, v143
	v_add_u32_e32 v161, 0x14000, v143
	v_add_u32_e32 v162, 0x16000, v143
	v_add_u32_e32 v163, 0x4000, v143
	v_add_u32_e32 v170, 0x6000, v143
	s_or_b32 s0, s8, 0x80
	s_ashr_i32 s1, s0, 31
	s_lshl_b64 s[0:1], s[0:1], 12
	s_add_u32 s0, s28, s0
	s_addc_u32 s1, s29, s1
	ds_read_b128 v[134:137], v157
	ds_read_b128 v[138:141], v157 offset:1024
	ds_read_b128 v[150:153], v157 offset:2048
	ds_read_b128 v[174:177], v157 offset:3072
	ds_read_b128 v[178:181], v147
	ds_read_b128 v[182:185], v147 offset:1024
	ds_read_b128 v[186:189], v146
	ds_read_b128 v[190:193], v146 offset:1024
	ds_read_b128 v[196:199], v145
	ds_read_b128 v[200:203], v145 offset:1024
	ds_read_b128 v[204:207], v144
	ds_read_b128 v[208:211], v144 offset:1024
	v_lshl_add_u64 v[156:157], v[166:167], 1, s[0:1]
	s_mov_b64 s[54:55], 0xf80
	v_lshl_add_u64 v[156:157], v[156:157], 0, s[54:55]
	s_add_i32 m0, s100, 0xc000
	v_lshl_add_u64 v[132:133], v[132:133], 1, s[0:1]
	global_load_lds_dwordx4 v[156:157], off
	v_lshl_add_u64 v[132:133], v[132:133], 0, s[54:55]
	s_add_i32 m0, s100, 0xe000
	s_nop 0
	global_load_lds_dwordx4 v[132:133], off
	s_barrier
	s_waitcnt lgkmcnt(0)
	s_waitcnt lgkmcnt(0)
	v_mfma_f32_16x16x32_bf16 v[124:127], v[178:181], v[134:137], v[124:127]
	v_mfma_f32_16x16x32_bf16 v[116:119], v[186:189], v[134:137], v[116:119]
	v_mfma_f32_16x16x32_bf16 v[112:115], v[186:189], v[150:153], v[112:115]
	v_mfma_f32_16x16x32_bf16 v[96:99], v[204:207], v[150:153], v[96:99]
	v_mfma_f32_16x16x32_bf16 v[124:127], v[182:185], v[138:141], v[124:127]
	v_mfma_f32_16x16x32_bf16 v[120:123], v[178:181], v[150:153], v[120:123]
	v_mfma_f32_16x16x32_bf16 v[116:119], v[190:193], v[138:141], v[116:119]
	v_mfma_f32_16x16x32_bf16 v[112:115], v[190:193], v[174:177], v[112:115]
	v_mfma_f32_16x16x32_bf16 v[108:111], v[196:199], v[134:137], v[108:111]
	v_mfma_f32_16x16x32_bf16 v[104:107], v[196:199], v[150:153], v[104:107]
	v_mfma_f32_16x16x32_bf16 v[100:103], v[204:207], v[134:137], v[100:103]
	v_mfma_f32_16x16x32_bf16 v[96:99], v[208:211], v[174:177], v[96:99]
	v_mfma_f32_16x16x32_bf16 v[212:215], v[182:185], v[174:177], v[120:123]
	v_mfma_f32_16x16x32_bf16 v[216:219], v[200:203], v[138:141], v[108:111]
	v_mfma_f32_16x16x32_bf16 v[220:223], v[200:203], v[174:177], v[104:107]
	v_mfma_f32_16x16x32_bf16 v[224:227], v[208:211], v[138:141], v[100:103]
	s_barrier
	s_nop 0
	ds_read_b128 v[100:103], v155
	ds_read_b128 v[104:107], v155 offset:1024
	ds_read_b128 v[108:111], v155 offset:2048
	ds_read_b128 v[120:123], v155 offset:3072
	s_barrier
; #define P8_LDA(dst,b,h) _Pragma("unroll") for(int m=0;m<4;++m) _Pragma("unroll") for(int k=0;k<2;++k) \
;     dst[m][k]=*reinterpret_cast<const bf16x8*>((char*)P8_SA(b,h)+lds_byte(wr*64+m*16+fr,k*32+fq*8))
; #define P8_LDB(dst,b,h) _Pragma("unroll") for(int n=0;n<2;++n) _Pragma("unroll") for(int k=0;k<2;++k) \
;     dst[n][k]=*reinterpret_cast<const bf16x8*>((char*)P8_SB(b,h)+lds_byte(wc*32+n*16+fr,k*32+fq*8))
; #define P8_MMA(ai,bj,At,Bt) do{__builtin_amdgcn_s_setprio(1); \
;     _Pragma("unroll") for(int m=0;m<4;++m) _Pragma("unroll") for(int n=0;n<2;++n) _Pragma("unroll") for(int k=0;k<2;++k) \
;       acc[ai][bj][m][n]=__builtin_amdgcn_mfma_f32_16x16x32_bf16(At[m][k],Bt[n][k],acc[ai][bj][m][n],0,0,0); \
;     __builtin_amdgcn_s_setprio(0);}while(0)
; #define P8_WAIT_V(n) asm volatile("s_waitcnt vmcnt(" #n ")":::"memory")
; #define P8_WAIT_L(n) asm volatile("s_waitcnt lgkmcnt(" #n ")":::"memory")
; #define P8_BAR __builtin_amdgcn_s_barrier()
; template <class EPI>
; DEVI void gemm8_tile(const bfr* __restrict__ A, const bfr* __restrict__ Bt, int K, int brow, int bcol, int nbrow, int nbcol, char* shmc, EPI epi) {
;     ...
;     P8_LDB(B1,0,1); P8_BAR; P8_WAIT_L(0); P8_MMA(0,1,At,B1); P8_BAR;
;     P8_LDA(At,0,1); P8_WAIT_V(4); P8_BAR; P8_WAIT_L(0); P8_MMA(1,0,At,B0); P8_MMA(1,1,At,B1); P8_BAR; }
;   { P8_LDB(B0,1,0); P8_LDA(At,1,0); P8_WAIT_V(2); P8_BAR; P8_WAIT_L(0); P8_MMA(0,0,At,B0); P8_BAR;
	s_waitcnt lgkmcnt(0)
	s_waitcnt lgkmcnt(0)
	v_mfma_f32_16x16x32_bf16 v[92:95], v[178:181], v[100:103], v[92:95]
	v_mfma_f32_16x16x32_bf16 v[84:87], v[186:189], v[100:103], v[84:87]
	v_mfma_f32_16x16x32_bf16 v[80:83], v[186:189], v[108:111], v[80:83]
	v_mfma_f32_16x16x32_bf16 v[64:67], v[204:207], v[108:111], v[64:67]
	v_mfma_f32_16x16x32_bf16 v[92:95], v[182:185], v[104:107], v[92:95]
	v_mfma_f32_16x16x32_bf16 v[88:91], v[178:181], v[108:111], v[88:91]
	v_mfma_f32_16x16x32_bf16 v[84:87], v[190:193], v[104:107], v[84:87]
	v_mfma_f32_16x16x32_bf16 v[80:83], v[190:193], v[120:123], v[80:83]
	v_mfma_f32_16x16x32_bf16 v[76:79], v[196:199], v[100:103], v[76:79]
	v_mfma_f32_16x16x32_bf16 v[72:75], v[196:199], v[108:111], v[72:75]
	v_mfma_f32_16x16x32_bf16 v[68:71], v[204:207], v[100:103], v[68:71]
	v_mfma_f32_16x16x32_bf16 v[64:67], v[208:211], v[120:123], v[64:67]
	v_mfma_f32_16x16x32_bf16 v[154:157], v[182:185], v[120:123], v[88:91]
	v_mfma_f32_16x16x32_bf16 v[178:181], v[200:203], v[104:107], v[76:79]
	v_mfma_f32_16x16x32_bf16 v[182:185], v[200:203], v[120:123], v[72:75]
	v_mfma_f32_16x16x32_bf16 v[186:189], v[208:211], v[104:107], v[68:71]
	s_barrier
	s_nop 0
	ds_read_b128 v[68:71], v147 offset:16384
	ds_read_b128 v[72:75], v147 offset:17408
	ds_read_b128 v[76:79], v146 offset:16384
	ds_read_b128 v[88:91], v146 offset:17408
	ds_read_b128 v[190:193], v145 offset:16384
	ds_read_b128 v[196:199], v145 offset:17408
	ds_read_b128 v[200:203], v144 offset:16384
	ds_read_b128 v[204:207], v144 offset:17408
	s_waitcnt vmcnt(4)
	s_barrier
	s_waitcnt lgkmcnt(0)
	s_waitcnt lgkmcnt(0)
	v_mfma_f32_16x16x32_bf16 v[60:63], v[68:71], v[134:137], v[60:63]
	v_mfma_f32_16x16x32_bf16 v[52:55], v[76:79], v[134:137], v[52:55]
	v_mfma_f32_16x16x32_bf16 v[48:51], v[76:79], v[150:153], v[48:51]
	v_mfma_f32_16x16x32_bf16 v[32:35], v[200:203], v[150:153], v[32:35]
	v_mfma_f32_16x16x32_bf16 v[60:63], v[72:75], v[138:141], v[60:63]
	v_mfma_f32_16x16x32_bf16 v[56:59], v[68:71], v[150:153], v[56:59]
	v_mfma_f32_16x16x32_bf16 v[52:55], v[88:91], v[138:141], v[52:55]
	v_mfma_f32_16x16x32_bf16 v[48:51], v[88:91], v[174:177], v[48:51]
	v_mfma_f32_16x16x32_bf16 v[44:47], v[190:193], v[134:137], v[44:47]
	v_mfma_f32_16x16x32_bf16 v[40:43], v[190:193], v[150:153], v[40:43]
	v_mfma_f32_16x16x32_bf16 v[36:39], v[200:203], v[134:137], v[36:39]
	v_mfma_f32_16x16x32_bf16 v[32:35], v[204:207], v[174:177], v[32:35]
	v_mfma_f32_16x16x32_bf16 v[208:211], v[72:75], v[174:177], v[56:59]
	v_mfma_f32_16x16x32_bf16 v[228:231], v[196:199], v[138:141], v[44:47]
	v_mfma_f32_16x16x32_bf16 v[232:235], v[196:199], v[174:177], v[40:43]
	v_mfma_f32_16x16x32_bf16 v[132:135], v[204:207], v[138:141], v[36:39]
	s_setprio 0
	s_setprio 1
	v_mfma_f32_16x16x32_bf16 v[28:31], v[68:71], v[100:103], v[28:31]
	v_mfma_f32_16x16x32_bf16 v[20:23], v[76:79], v[100:103], v[20:23]
	v_mfma_f32_16x16x32_bf16 v[16:19], v[76:79], v[108:111], v[16:19]
	v_mfma_f32_16x16x32_bf16 v[0:3], v[200:203], v[108:111], v[0:3]
	v_mfma_f32_16x16x32_bf16 v[28:31], v[72:75], v[104:107], v[28:31]
	v_mfma_f32_16x16x32_bf16 v[24:27], v[68:71], v[108:111], v[24:27]
	v_mfma_f32_16x16x32_bf16 v[20:23], v[88:91], v[104:107], v[20:23]
	v_mfma_f32_16x16x32_bf16 v[16:19], v[88:91], v[120:123], v[16:19]
	v_mfma_f32_16x16x32_bf16 v[12:15], v[190:193], v[100:103], v[12:15]
	v_mfma_f32_16x16x32_bf16 v[8:11], v[190:193], v[108:111], v[8:11]
	v_mfma_f32_16x16x32_bf16 v[4:7], v[200:203], v[100:103], v[4:7]
	v_mfma_f32_16x16x32_bf16 v[0:3], v[204:207], v[120:123], v[0:3]
	v_mfma_f32_16x16x32_bf16 v[136:139], v[72:75], v[120:123], v[24:27]
	v_mfma_f32_16x16x32_bf16 v[150:153], v[196:199], v[104:107], v[12:15]
	v_mfma_f32_16x16x32_bf16 v[172:175], v[196:199], v[120:123], v[8:11]
	v_mfma_f32_16x16x32_bf16 v[190:193], v[204:207], v[104:107], v[4:7]
	s_barrier
	s_nop 0
	ds_read_b128 v[4:7], v149
	ds_read_b128 v[8:11], v149 offset:1024
	ds_read_b128 v[12:15], v149 offset:2048
	ds_read_b128 v[24:27], v149 offset:3072
	ds_read_b128 v[36:39], v147 offset:32768
	ds_read_b128 v[40:43], v147 offset:33792
	ds_read_b128 v[44:47], v146 offset:32768
	ds_read_b128 v[56:59], v146 offset:33792
	ds_read_b128 v[68:71], v145 offset:32768
	ds_read_b128 v[196:199], v145 offset:33792
	ds_read_b128 v[200:203], v144 offset:32768
	ds_read_b128 v[204:207], v144 offset:33792
	s_waitcnt vmcnt(2)
	s_barrier
; #define P8_LDA(dst,b,h) _Pragma("unroll") for(int m=0;m<4;++m) _Pragma("unroll") for(int k=0;k<2;++k) \
;     dst[m][k]=*reinterpret_cast<const bf16x8*>((char*)P8_SA(b,h)+lds_byte(wr*64+m*16+fr,k*32+fq*8))
; #define P8_LDB(dst,b,h) _Pragma("unroll") for(int n=0;n<2;++n) _Pragma("unroll") for(int k=0;k<2;++k) \
;     dst[n][k]=*reinterpret_cast<const bf16x8*>((char*)P8_SB(b,h)+lds_byte(wc*32+n*16+fr,k*32+fq*8))
; #define P8_MMA(ai,bj,At,Bt) do{__builtin_amdgcn_s_setprio(1); \
;     _Pragma("unroll") for(int m=0;m<4;++m) _Pragma("unroll") for(int n=0;n<2;++n) _Pragma("unroll") for(int k=0;k<2;++k) \
;       acc[ai][bj][m][n]=__builtin_amdgcn_mfma_f32_16x16x32_bf16(At[m][k],Bt[n][k],acc[ai][bj][m][n],0,0,0); \
;     __builtin_amdgcn_s_setprio(0);}while(0)
; #define P8_WAIT_V(n) asm volatile("s_waitcnt vmcnt(" #n ")":::"memory")
; #define P8_WAIT_L(n) asm volatile("s_waitcnt lgkmcnt(" #n ")":::"memory")
; #define P8_BAR __builtin_amdgcn_s_barrier()
; template <class EPI>
; DEVI void gemm8_tile(const bfr* __restrict__ A, const bfr* __restrict__ Bt, int K, int brow, int bcol, int nbrow, int nbcol, char* shmc, EPI epi) {
;     ...
;   { P8_LDB(B0,1,0); P8_LDA(At,1,0); P8_WAIT_V(2); P8_BAR; P8_WAIT_L(0); P8_MMA(0,0,At,B0); P8_BAR;
;     P8_LDB(B1,1,1); P8_WAIT_V(0); P8_BAR; P8_WAIT_L(0); P8_MMA(0,1,At,B1); P8_BAR;
;     P8_LDA(At,1,1); P8_BAR; P8_WAIT_L(0); P8_MMA(1,0,At,B0); P8_MMA(1,1,At,B1); P8_BAR; }
;   if(wr==0)P8_BAR;
	s_waitcnt lgkmcnt(0)
	s_waitcnt lgkmcnt(0)
	v_mfma_f32_16x16x32_bf16 v[72:75], v[36:39], v[4:7], v[124:127]
	v_mfma_f32_16x16x32_bf16 v[120:123], v[40:43], v[8:11], v[72:75]
	v_mfma_f32_16x16x32_bf16 v[72:75], v[36:39], v[12:15], v[212:215]
	v_mfma_f32_16x16x32_bf16 v[104:107], v[40:43], v[24:27], v[72:75]
	v_mfma_f32_16x16x32_bf16 v[72:75], v[44:47], v[4:7], v[116:119]
	v_mfma_f32_16x16x32_bf16 v[124:127], v[56:59], v[8:11], v[72:75]
	v_mfma_f32_16x16x32_bf16 v[72:75], v[44:47], v[12:15], v[112:115]
	v_mfma_f32_16x16x32_bf16 v[108:111], v[56:59], v[24:27], v[72:75]
	v_mfma_f32_16x16x32_bf16 v[72:75], v[68:71], v[4:7], v[216:219]
	v_mfma_f32_16x16x32_bf16 v[112:115], v[196:199], v[8:11], v[72:75]
	v_mfma_f32_16x16x32_bf16 v[72:75], v[68:71], v[12:15], v[220:223]
	v_mfma_f32_16x16x32_bf16 v[100:103], v[196:199], v[24:27], v[72:75]
	v_mfma_f32_16x16x32_bf16 v[72:75], v[200:203], v[4:7], v[224:227]
	v_mfma_f32_16x16x32_bf16 v[116:119], v[204:207], v[8:11], v[72:75]
	v_mfma_f32_16x16x32_bf16 v[72:75], v[200:203], v[12:15], v[96:99]
	v_mfma_f32_16x16x32_bf16 v[96:99], v[204:207], v[24:27], v[72:75]
	s_barrier
	ds_read_b128 v[212:215], v148
	ds_read_b128 v[216:219], v148 offset:1024
	ds_read_b128 v[220:223], v148 offset:2048
	ds_read_b128 v[224:227], v148 offset:3072
	s_waitcnt vmcnt(0)
	s_barrier
	s_waitcnt lgkmcnt(0)
	s_waitcnt lgkmcnt(0)
	v_mfma_f32_16x16x32_bf16 v[72:75], v[36:39], v[212:215], v[92:95]
	v_mfma_f32_16x16x32_bf16 v[36:39], v[36:39], v[220:223], v[154:157]
	v_mfma_f32_16x16x32_bf16 v[88:91], v[40:43], v[216:219], v[72:75]
	v_mfma_f32_16x16x32_bf16 v[72:75], v[40:43], v[224:227], v[36:39]
	v_mfma_f32_16x16x32_bf16 v[36:39], v[44:47], v[212:215], v[84:87]
	v_mfma_f32_16x16x32_bf16 v[92:95], v[56:59], v[216:219], v[36:39]
	v_mfma_f32_16x16x32_bf16 v[36:39], v[44:47], v[220:223], v[80:83]
	v_mfma_f32_16x16x32_bf16 v[76:79], v[56:59], v[224:227], v[36:39]
	v_mfma_f32_16x16x32_bf16 v[36:39], v[68:71], v[212:215], v[178:181]
	v_mfma_f32_16x16x32_bf16 v[80:83], v[196:199], v[216:219], v[36:39]
	v_mfma_f32_16x16x32_bf16 v[36:39], v[68:71], v[220:223], v[182:185]
	v_mfma_f32_16x16x32_bf16 v[68:71], v[196:199], v[224:227], v[36:39]
	v_mfma_f32_16x16x32_bf16 v[36:39], v[200:203], v[212:215], v[186:189]
	v_mfma_f32_16x16x32_bf16 v[84:87], v[204:207], v[216:219], v[36:39]
	v_mfma_f32_16x16x32_bf16 v[36:39], v[200:203], v[220:223], v[64:67]
	v_mfma_f32_16x16x32_bf16 v[64:67], v[204:207], v[224:227], v[36:39]
	s_barrier
	ds_read_b128 v[154:157], v147 offset:49152
	ds_read_b128 v[176:179], v147 offset:50176
	ds_read_b128 v[180:183], v146 offset:49152
	ds_read_b128 v[146:149], v146 offset:50176
	ds_read_b128 v[184:187], v145 offset:49152
	ds_read_b128 v[196:199], v145 offset:50176
	ds_read_b128 v[200:203], v144 offset:49152
	ds_read_b128 v[204:207], v144 offset:50176
	s_barrier
	s_waitcnt lgkmcnt(0)
	s_waitcnt lgkmcnt(0)
	v_mfma_f32_16x16x32_bf16 v[36:39], v[154:157], v[4:7], v[60:63]
	v_mfma_f32_16x16x32_bf16 v[56:59], v[176:179], v[8:11], v[36:39]
	v_mfma_f32_16x16x32_bf16 v[36:39], v[154:157], v[12:15], v[208:211]
	v_mfma_f32_16x16x32_bf16 v[40:43], v[176:179], v[24:27], v[36:39]
	v_mfma_f32_16x16x32_bf16 v[36:39], v[180:183], v[4:7], v[52:55]
	v_mfma_f32_16x16x32_bf16 v[60:63], v[146:149], v[8:11], v[36:39]
	v_mfma_f32_16x16x32_bf16 v[36:39], v[180:183], v[12:15], v[48:51]
	v_mfma_f32_16x16x32_bf16 v[44:47], v[146:149], v[24:27], v[36:39]
	v_mfma_f32_16x16x32_bf16 v[36:39], v[184:187], v[4:7], v[228:231]
	v_mfma_f32_16x16x32_bf16 v[4:7], v[200:203], v[4:7], v[132:135]
	v_mfma_f32_16x16x32_bf16 v[48:51], v[196:199], v[8:11], v[36:39]
	v_mfma_f32_16x16x32_bf16 v[36:39], v[184:187], v[12:15], v[232:235]
	v_mfma_f32_16x16x32_bf16 v[52:55], v[204:207], v[8:11], v[4:7]
	v_mfma_f32_16x16x32_bf16 v[4:7], v[200:203], v[12:15], v[32:35]
	v_mfma_f32_16x16x32_bf16 v[36:39], v[196:199], v[24:27], v[36:39]
	v_mfma_f32_16x16x32_bf16 v[32:35], v[204:207], v[24:27], v[4:7]
	s_setprio 0
	s_setprio 1
	v_mfma_f32_16x16x32_bf16 v[4:7], v[154:157], v[212:215], v[28:31]
	v_mfma_f32_16x16x32_bf16 v[24:27], v[176:179], v[216:219], v[4:7]
	v_mfma_f32_16x16x32_bf16 v[4:7], v[154:157], v[220:223], v[136:139]
	v_mfma_f32_16x16x32_bf16 v[8:11], v[176:179], v[224:227], v[4:7]
	v_mfma_f32_16x16x32_bf16 v[4:7], v[180:183], v[212:215], v[20:23]
	v_mfma_f32_16x16x32_bf16 v[28:31], v[146:149], v[216:219], v[4:7]
	v_mfma_f32_16x16x32_bf16 v[4:7], v[180:183], v[220:223], v[16:19]
	v_mfma_f32_16x16x32_bf16 v[12:15], v[146:149], v[224:227], v[4:7]
	v_mfma_f32_16x16x32_bf16 v[4:7], v[184:187], v[212:215], v[150:153]
	v_mfma_f32_16x16x32_bf16 v[16:19], v[196:199], v[216:219], v[4:7]
	v_mfma_f32_16x16x32_bf16 v[4:7], v[184:187], v[220:223], v[172:175]
	v_mfma_f32_16x16x32_bf16 v[20:23], v[200:203], v[212:215], v[190:193]
	v_mfma_f32_16x16x32_bf16 v[0:3], v[200:203], v[220:223], v[0:3]
	v_mfma_f32_16x16x32_bf16 v[4:7], v[196:199], v[224:227], v[4:7]
	v_mfma_f32_16x16x32_bf16 v[20:23], v[204:207], v[216:219], v[20:23]
	v_mfma_f32_16x16x32_bf16 v[0:3], v[204:207], v[224:227], v[0:3]
	s_setprio 0
	v_cmp_gt_u32_e32 vcc, s57, v142
	s_barrier
	s_and_saveexec_b64 s[0:1], vcc
	s_cbranch_execz .LBB0_88
	s_barrier

; #define P8_STAGE(P,BASE,br,kt) do{const bfr* _ub=(BASE)+((long)(br)*K+(long)(kt)*BK); \
;     __builtin_amdgcn_global_load_lds((const unsigned*)(_ub+so0),(unsigned*)((char*)(P)+wid*1024),16,0,0); \
;     __builtin_amdgcn_global_load_lds((const unsigned*)(_ub+so1),(unsigned*)((char*)(P)+wid*1024+8192),16,0,0);}while(0)
; #define P8_LDA(dst,b,h) _Pragma("unroll") for(int m=0;m<4;++m) _Pragma("unroll") for(int k=0;k<2;++k) \
;     dst[m][k]=*reinterpret_cast<const bf16x8*>((char*)P8_SA(b,h)+lds_byte(wr*64+m*16+fr,k*32+fq*8))
; #define P8_LDB(dst,b,h) _Pragma("unroll") for(int n=0;n<2;++n) _Pragma("unroll") for(int k=0;k<2;++k) \
;     dst[n][k]=*reinterpret_cast<const bf16x8*>((char*)P8_SB(b,h)+lds_byte(wc*32+n*16+fr,k*32+fq*8))
; #define P8_MMA(ai,bj,At,Bt) do{__builtin_amdgcn_s_setprio(1); \
;     _Pragma("unroll") for(int m=0;m<4;++m) _Pragma("unroll") for(int n=0;n<2;++n) _Pragma("unroll") for(int k=0;k<2;++k) \
;       acc[ai][bj][m][n]=__builtin_amdgcn_mfma_f32_16x16x32_bf16(At[m][k],Bt[n][k],acc[ai][bj][m][n],0,0,0); \
;     __builtin_amdgcn_s_setprio(0);}while(0)
; #define P8_WAIT_V(n) asm volatile("s_waitcnt vmcnt(" #n ")":::"memory")
; #define P8_WAIT_L(n) asm volatile("s_waitcnt lgkmcnt(" #n ")":::"memory")
; #define P8_BAR __builtin_amdgcn_s_barrier()
; #define P8_SCHED __builtin_amdgcn_sched_barrier(0)
; template <class EPI>
; DEVI void gemm8_tile(const bfr* __restrict__ A, const bfr* __restrict__ Bt, int K, int brow, int bcol, int nbrow, int nbcol, char* shmc, EPI epi) {
;     ...
;   for(int t=0;t<nt-2;t+=2){
;     P8_LDB(B0,0,0); P8_SCHED; P8_LDA(At,0,0); P8_STAGE(P8_SA(1,1),A,brow+128,t+1);
;     P8_WAIT_L(8); P8_BAR; P8_WAIT_L(0); P8_MMA(0,0,At,B0); P8_BAR; P8_SCHED;
;     P8_LDB(B1,0,1); P8_STAGE(P8_SB(0,0),Bt,bcol,t+2);
;     P8_BAR; P8_WAIT_L(0); P8_MMA(0,1,At,B1); P8_BAR;
;     P8_LDA(At,0,1); P8_STAGE(P8_SA(0,0),A,brow,t+2);
;     P8_BAR; P8_WAIT_L(0); P8_MMA(1,0,At,B0); P8_BAR; P8_SCHED;
;     P8_STAGE(P8_SB(0,1),Bt,bcol+128,t+2);
;     P8_WAIT_V(6); P8_BAR; P8_MMA(1,1,At,B1); P8_BAR;
.LBB0_141:
	ds_read_b128 v[174:177], v157
	ds_read_b128 v[178:181], v157 offset:1024
	ds_read_b128 v[182:185], v157 offset:2048
	ds_read_b128 v[186:189], v157 offset:3072
	v_add_u32_e32 v158, s8, v136
	s_add_i32 m0, s100, 0xc000
	ds_read_b128 v[160:163], v147
	ds_read_b128 v[190:193], v147 offset:1024
	ds_read_b128 v[196:199], v146
	ds_read_b128 v[208:211], v146 offset:1024
	ds_read_b128 v[212:215], v145
	ds_read_b128 v[216:219], v145 offset:1024
	ds_read_b128 v[220:223], v144
	ds_read_b128 v[224:227], v144 offset:1024
	global_load_lds_dwordx4 v158, s[86:87]
	v_add_u32_e32 v158, s8, v134
	s_add_i32 m0, s100, 0xe000
	s_nop 0
	global_load_lds_dwordx4 v158, s[86:87]
	s_waitcnt lgkmcnt(8)
	s_barrier
	s_waitcnt lgkmcnt(0)
	v_mfma_f32_16x16x32_bf16 v[124:127], v[160:163], v[174:177], v[124:127]
	v_mfma_f32_16x16x32_bf16 v[120:123], v[160:163], v[182:185], v[120:123]
	v_mfma_f32_16x16x32_bf16 v[116:119], v[196:199], v[174:177], v[116:119]
	v_mfma_f32_16x16x32_bf16 v[112:115], v[196:199], v[182:185], v[112:115]
	v_mfma_f32_16x16x32_bf16 v[108:111], v[212:215], v[174:177], v[108:111]
	v_mfma_f32_16x16x32_bf16 v[104:107], v[212:215], v[182:185], v[104:107]
	v_mfma_f32_16x16x32_bf16 v[100:103], v[220:223], v[174:177], v[100:103]
	v_mfma_f32_16x16x32_bf16 v[96:99], v[220:223], v[182:185], v[96:99]
	v_mfma_f32_16x16x32_bf16 v[124:127], v[190:193], v[178:181], v[124:127]
	v_mfma_f32_16x16x32_bf16 v[120:123], v[190:193], v[186:189], v[120:123]
	v_mfma_f32_16x16x32_bf16 v[116:119], v[208:211], v[178:181], v[116:119]
	v_mfma_f32_16x16x32_bf16 v[112:115], v[208:211], v[186:189], v[112:115]
	v_mfma_f32_16x16x32_bf16 v[108:111], v[216:219], v[178:181], v[108:111]
	v_mfma_f32_16x16x32_bf16 v[104:107], v[216:219], v[186:189], v[104:107]
	v_mfma_f32_16x16x32_bf16 v[100:103], v[224:227], v[178:181], v[100:103]
	v_mfma_f32_16x16x32_bf16 v[96:99], v[224:227], v[186:189], v[96:99]
	s_barrier
	v_add_u32_e32 v206, s66, v140
	s_add_i32 m0, s100, 0x10000
	ds_read_b128 v[228:231], v154
	ds_read_b128 v[232:235], v154 offset:1024
	ds_read_b128 v[236:239], v154 offset:2048
	ds_read_b128 v[240:243], v154 offset:3072
	global_load_lds_dwordx4 v206, s[86:87]
	v_add_u32_e32 v244, s66, v138
	s_add_i32 m0, s100, 0x12000
	s_nop 0
	global_load_lds_dwordx4 v244, s[86:87]
	s_barrier
	s_waitcnt lgkmcnt(0)
	v_mfma_f32_16x16x32_bf16 v[92:95], v[160:163], v[228:231], v[92:95]
	v_mfma_f32_16x16x32_bf16 v[88:91], v[160:163], v[236:239], v[88:91]
	v_mfma_f32_16x16x32_bf16 v[84:87], v[196:199], v[228:231], v[84:87]
	v_mfma_f32_16x16x32_bf16 v[80:83], v[196:199], v[236:239], v[80:83]
	v_mfma_f32_16x16x32_bf16 v[76:79], v[212:215], v[228:231], v[76:79]
	v_mfma_f32_16x16x32_bf16 v[72:75], v[212:215], v[236:239], v[72:75]
	v_mfma_f32_16x16x32_bf16 v[68:71], v[220:223], v[228:231], v[68:71]
	v_mfma_f32_16x16x32_bf16 v[64:67], v[220:223], v[236:239], v[64:67]
	v_mfma_f32_16x16x32_bf16 v[92:95], v[190:193], v[232:235], v[92:95]
	v_mfma_f32_16x16x32_bf16 v[88:91], v[190:193], v[240:243], v[88:91]
	v_mfma_f32_16x16x32_bf16 v[84:87], v[208:211], v[232:235], v[84:87]
	v_mfma_f32_16x16x32_bf16 v[80:83], v[208:211], v[240:243], v[80:83]
	v_mfma_f32_16x16x32_bf16 v[76:79], v[216:219], v[232:235], v[76:79]
	v_mfma_f32_16x16x32_bf16 v[72:75], v[216:219], v[240:243], v[72:75]
	v_mfma_f32_16x16x32_bf16 v[68:71], v[224:227], v[232:235], v[68:71]
	v_mfma_f32_16x16x32_bf16 v[64:67], v[224:227], v[240:243], v[64:67]
	v_add_u32_e32 v160, s54, v136
	s_mov_b32 m0, s100
	s_barrier
	ds_read_b128 v[190:193], v147 offset:16384
	ds_read_b128 v[196:199], v147 offset:17408
	ds_read_b128 v[208:211], v146 offset:16384
	ds_read_b128 v[212:215], v146 offset:17408
	ds_read_b128 v[216:219], v145 offset:16384
	ds_read_b128 v[220:223], v145 offset:17408
	ds_read_b128 v[224:227], v144 offset:16384
	ds_read_b128 v[244:247], v144 offset:17408
	global_load_lds_dwordx4 v160, s[86:87]
	v_add_u32_e32 v162, s54, v134
	s_add_i32 m0, s100, 0x2000
	s_nop 0
	global_load_lds_dwordx4 v162, s[86:87]
	s_barrier
	s_waitcnt lgkmcnt(0)
	v_mfma_f32_16x16x32_bf16 v[60:63], v[190:193], v[174:177], v[60:63]
	v_mfma_f32_16x16x32_bf16 v[56:59], v[190:193], v[182:185], v[56:59]
	v_mfma_f32_16x16x32_bf16 v[52:55], v[208:211], v[174:177], v[52:55]
	v_mfma_f32_16x16x32_bf16 v[48:51], v[208:211], v[182:185], v[48:51]
	v_mfma_f32_16x16x32_bf16 v[44:47], v[216:219], v[174:177], v[44:47]
	v_mfma_f32_16x16x32_bf16 v[40:43], v[216:219], v[182:185], v[40:43]
	v_mfma_f32_16x16x32_bf16 v[36:39], v[224:227], v[174:177], v[36:39]
	v_mfma_f32_16x16x32_bf16 v[32:35], v[224:227], v[182:185], v[32:35]
	v_mfma_f32_16x16x32_bf16 v[60:63], v[196:199], v[178:181], v[60:63]
	v_mfma_f32_16x16x32_bf16 v[56:59], v[196:199], v[186:189], v[56:59]
	v_mfma_f32_16x16x32_bf16 v[52:55], v[212:215], v[178:181], v[52:55]
	v_mfma_f32_16x16x32_bf16 v[48:51], v[212:215], v[186:189], v[48:51]
	v_mfma_f32_16x16x32_bf16 v[44:47], v[220:223], v[178:181], v[44:47]
	v_mfma_f32_16x16x32_bf16 v[40:43], v[220:223], v[186:189], v[40:43]
	v_mfma_f32_16x16x32_bf16 v[36:39], v[244:247], v[178:181], v[36:39]
	v_mfma_f32_16x16x32_bf16 v[32:35], v[244:247], v[186:189], v[32:35]
	s_barrier
	v_add_u32_e32 v162, s60, v140
	s_add_i32 m0, s100, 0x14000
	v_add_u32_e32 v174, s60, v138
	global_load_lds_dwordx4 v162, s[86:87]
	s_nop 0
	s_add_i32 m0, s100, 0x16000
	s_nop 0
	global_load_lds_dwordx4 v174, s[86:87]
	s_waitcnt vmcnt(6)
	s_barrier
; #define P8_STAGE(P,BASE,br,kt) do{const bfr* _ub=(BASE)+((long)(br)*K+(long)(kt)*BK); \
;     __builtin_amdgcn_global_load_lds((const unsigned*)(_ub+so0),(unsigned*)((char*)(P)+wid*1024),16,0,0); \
;     __builtin_amdgcn_global_load_lds((const unsigned*)(_ub+so1),(unsigned*)((char*)(P)+wid*1024+8192),16,0,0);}while(0)
; #define P8_LDA(dst,b,h) _Pragma("unroll") for(int m=0;m<4;++m) _Pragma("unroll") for(int k=0;k<2;++k) \
;     dst[m][k]=*reinterpret_cast<const bf16x8*>((char*)P8_SA(b,h)+lds_byte(wr*64+m*16+fr,k*32+fq*8))
; #define P8_LDB(dst,b,h) _Pragma("unroll") for(int n=0;n<2;++n) _Pragma("unroll") for(int k=0;k<2;++k) \
;     dst[n][k]=*reinterpret_cast<const bf16x8*>((char*)P8_SB(b,h)+lds_byte(wc*32+n*16+fr,k*32+fq*8))
; #define P8_MMA(ai,bj,At,Bt) do{__builtin_amdgcn_s_setprio(1); \
;     _Pragma("unroll") for(int m=0;m<4;++m) _Pragma("unroll") for(int n=0;n<2;++n) _Pragma("unroll") for(int k=0;k<2;++k) \
;       acc[ai][bj][m][n]=__builtin_amdgcn_mfma_f32_16x16x32_bf16(At[m][k],Bt[n][k],acc[ai][bj][m][n],0,0,0); \
;     __builtin_amdgcn_s_setprio(0);}while(0)
; #define P8_WAIT_V(n) asm volatile("s_waitcnt vmcnt(" #n ")":::"memory")
; #define P8_WAIT_L(n) asm volatile("s_waitcnt lgkmcnt(" #n ")":::"memory")
; #define P8_BAR __builtin_amdgcn_s_barrier()
; #define P8_SCHED __builtin_amdgcn_sched_barrier(0)
; template <class EPI>
; DEVI void gemm8_tile(const bfr* __restrict__ A, const bfr* __restrict__ Bt, int K, int brow, int bcol, int nbrow, int nbcol, char* shmc, EPI epi) {
;     ...
;     P8_WAIT_V(6); P8_BAR; P8_MMA(1,1,At,B1); P8_BAR;
;     P8_LDB(B0,1,0); P8_SCHED; P8_LDA(At,1,0); P8_STAGE(P8_SA(0,1),A,brow+128,t+2);
;     P8_WAIT_L(8); P8_BAR; P8_WAIT_L(0); P8_MMA(0,0,At,B0); P8_BAR; P8_SCHED;
;     P8_LDB(B1,1,1); P8_STAGE(P8_SB(1,0),Bt,bcol,t+3);
;     P8_BAR; P8_WAIT_L(0); P8_MMA(0,1,At,B1); P8_BAR;
;     P8_LDA(At,1,1); P8_STAGE(P8_SA(1,0),A,brow,t+3);
	v_mfma_f32_16x16x32_bf16 v[28:31], v[190:193], v[228:231], v[28:31]
	v_mfma_f32_16x16x32_bf16 v[24:27], v[190:193], v[236:239], v[24:27]
	v_mfma_f32_16x16x32_bf16 v[20:23], v[208:211], v[228:231], v[20:23]
	v_mfma_f32_16x16x32_bf16 v[16:19], v[208:211], v[236:239], v[16:19]
	v_mfma_f32_16x16x32_bf16 v[12:15], v[216:219], v[228:231], v[12:15]
	v_mfma_f32_16x16x32_bf16 v[8:11], v[216:219], v[236:239], v[8:11]
	v_mfma_f32_16x16x32_bf16 v[4:7], v[224:227], v[228:231], v[4:7]
	v_mfma_f32_16x16x32_bf16 v[0:3], v[224:227], v[236:239], v[0:3]
	v_mfma_f32_16x16x32_bf16 v[28:31], v[196:199], v[232:235], v[28:31]
	v_mfma_f32_16x16x32_bf16 v[24:27], v[196:199], v[240:243], v[24:27]
	v_mfma_f32_16x16x32_bf16 v[20:23], v[212:215], v[232:235], v[20:23]
	v_mfma_f32_16x16x32_bf16 v[16:19], v[212:215], v[240:243], v[16:19]
	v_mfma_f32_16x16x32_bf16 v[12:15], v[220:223], v[232:235], v[12:15]
	v_mfma_f32_16x16x32_bf16 v[8:11], v[220:223], v[240:243], v[8:11]
	v_mfma_f32_16x16x32_bf16 v[4:7], v[244:247], v[232:235], v[4:7]
	v_mfma_f32_16x16x32_bf16 v[0:3], v[244:247], v[240:243], v[0:3]
	s_barrier
	ds_read_b128 v[174:177], v149
	ds_read_b128 v[178:181], v149 offset:1024
	ds_read_b128 v[182:185], v149 offset:2048
	ds_read_b128 v[186:189], v149 offset:3072
	v_add_u32_e32 v232, s72, v136
	s_add_i32 m0, s100, 0x4000
	ds_read_b128 v[190:193], v147 offset:32768
	ds_read_b128 v[196:199], v147 offset:33792
	ds_read_b128 v[208:211], v146 offset:32768
	ds_read_b128 v[212:215], v146 offset:33792
	ds_read_b128 v[216:219], v145 offset:32768
	ds_read_b128 v[220:223], v145 offset:33792
	ds_read_b128 v[224:227], v144 offset:32768
	ds_read_b128 v[228:231], v144 offset:33792
	global_load_lds_dwordx4 v232, s[86:87]
	v_add_u32_e32 v232, s72, v134
	s_add_i32 m0, s100, 0x6000
	s_nop 0
	global_load_lds_dwordx4 v232, s[86:87]
	s_waitcnt lgkmcnt(8)
	s_barrier
	s_waitcnt lgkmcnt(0)
	v_mfma_f32_16x16x32_bf16 v[124:127], v[190:193], v[174:177], v[124:127]
	v_mfma_f32_16x16x32_bf16 v[120:123], v[190:193], v[182:185], v[120:123]
	v_mfma_f32_16x16x32_bf16 v[116:119], v[208:211], v[174:177], v[116:119]
	v_mfma_f32_16x16x32_bf16 v[112:115], v[208:211], v[182:185], v[112:115]
	v_mfma_f32_16x16x32_bf16 v[108:111], v[216:219], v[174:177], v[108:111]
	v_mfma_f32_16x16x32_bf16 v[104:107], v[216:219], v[182:185], v[104:107]
	v_mfma_f32_16x16x32_bf16 v[100:103], v[224:227], v[174:177], v[100:103]
	v_mfma_f32_16x16x32_bf16 v[96:99], v[224:227], v[182:185], v[96:99]
	v_mfma_f32_16x16x32_bf16 v[124:127], v[196:199], v[178:181], v[124:127]
	v_mfma_f32_16x16x32_bf16 v[120:123], v[196:199], v[186:189], v[120:123]
	v_mfma_f32_16x16x32_bf16 v[116:119], v[212:215], v[178:181], v[116:119]
	v_mfma_f32_16x16x32_bf16 v[112:115], v[212:215], v[186:189], v[112:115]
	v_mfma_f32_16x16x32_bf16 v[108:111], v[220:223], v[178:181], v[108:111]
	v_mfma_f32_16x16x32_bf16 v[104:107], v[220:223], v[186:189], v[104:107]
	v_mfma_f32_16x16x32_bf16 v[100:103], v[228:231], v[178:181], v[100:103]
	v_mfma_f32_16x16x32_bf16 v[96:99], v[228:231], v[186:189], v[96:99]
	s_barrier
	v_add_u32_e32 v248, s74, v140
	s_add_i32 m0, s100, 0x18000
	ds_read_b128 v[232:235], v148
	ds_read_b128 v[236:239], v148 offset:1024
	ds_read_b128 v[240:243], v148 offset:2048
	ds_read_b128 v[244:247], v148 offset:3072
	global_load_lds_dwordx4 v248, s[86:87]
	v_add_u32_e32 v248, s74, v138
	s_add_i32 m0, s100, 0x1a000
	s_nop 0
	global_load_lds_dwordx4 v248, s[86:87]
	s_barrier
	s_waitcnt lgkmcnt(0)
	v_mfma_f32_16x16x32_bf16 v[92:95], v[190:193], v[232:235], v[92:95]
	v_mfma_f32_16x16x32_bf16 v[88:91], v[190:193], v[240:243], v[88:91]
	v_mfma_f32_16x16x32_bf16 v[84:87], v[208:211], v[232:235], v[84:87]
	v_mfma_f32_16x16x32_bf16 v[80:83], v[208:211], v[240:243], v[80:83]
	v_mfma_f32_16x16x32_bf16 v[76:79], v[216:219], v[232:235], v[76:79]
	v_mfma_f32_16x16x32_bf16 v[72:75], v[216:219], v[240:243], v[72:75]
	v_mfma_f32_16x16x32_bf16 v[68:71], v[224:227], v[232:235], v[68:71]
	v_mfma_f32_16x16x32_bf16 v[64:67], v[224:227], v[240:243], v[64:67]
	v_mfma_f32_16x16x32_bf16 v[92:95], v[196:199], v[236:239], v[92:95]
	v_mfma_f32_16x16x32_bf16 v[88:91], v[196:199], v[244:247], v[88:91]
	v_mfma_f32_16x16x32_bf16 v[84:87], v[212:215], v[236:239], v[84:87]
	v_mfma_f32_16x16x32_bf16 v[80:83], v[212:215], v[244:247], v[80:83]
	v_mfma_f32_16x16x32_bf16 v[76:79], v[220:223], v[236:239], v[76:79]
	v_mfma_f32_16x16x32_bf16 v[72:75], v[220:223], v[244:247], v[72:75]
	v_mfma_f32_16x16x32_bf16 v[68:71], v[228:231], v[236:239], v[68:71]
	v_mfma_f32_16x16x32_bf16 v[64:67], v[228:231], v[244:247], v[64:67]
	v_add_u32_e32 v200, s92, v136
	s_add_i32 m0, s100, 0x8000
	s_barrier
	ds_read_b128 v[190:193], v147 offset:49152
	ds_read_b128 v[196:199], v147 offset:50176
	ds_read_b128 v[208:211], v146 offset:49152
	ds_read_b128 v[212:215], v146 offset:50176
	ds_read_b128 v[216:219], v145 offset:49152
	ds_read_b128 v[220:223], v145 offset:50176
	ds_read_b128 v[224:227], v144 offset:49152
	ds_read_b128 v[228:231], v144 offset:50176
	global_load_lds_dwordx4 v200, s[86:87]
	v_add_u32_e32 v200, s92, v134
	s_add_i32 m0, s100, 0xa000
	s_nop 0
	global_load_lds_dwordx4 v200, s[86:87]
	s_barrier
; #define P8_STAGE(P,BASE,br,kt) do{const bfr* _ub=(BASE)+((long)(br)*K+(long)(kt)*BK); \
;     __builtin_amdgcn_global_load_lds((const unsigned*)(_ub+so0),(unsigned*)((char*)(P)+wid*1024),16,0,0); \
;     __builtin_amdgcn_global_load_lds((const unsigned*)(_ub+so1),(unsigned*)((char*)(P)+wid*1024+8192),16,0,0);}while(0)
; #define P8_LDA(dst,b,h) _Pragma("unroll") for(int m=0;m<4;++m) _Pragma("unroll") for(int k=0;k<2;++k) \
;     dst[m][k]=*reinterpret_cast<const bf16x8*>((char*)P8_SA(b,h)+lds_byte(wr*64+m*16+fr,k*32+fq*8))
; #define P8_LDB(dst,b,h) _Pragma("unroll") for(int n=0;n<2;++n) _Pragma("unroll") for(int k=0;k<2;++k) \
;     dst[n][k]=*reinterpret_cast<const bf16x8*>((char*)P8_SB(b,h)+lds_byte(wc*32+n*16+fr,k*32+fq*8))
; #define P8_MMA(ai,bj,At,Bt) do{__builtin_amdgcn_s_setprio(1); \
;     _Pragma("unroll") for(int m=0;m<4;++m) _Pragma("unroll") for(int n=0;n<2;++n) _Pragma("unroll") for(int k=0;k<2;++k) \
;       acc[ai][bj][m][n]=__builtin_amdgcn_mfma_f32_16x16x32_bf16(At[m][k],Bt[n][k],acc[ai][bj][m][n],0,0,0); \
;     __builtin_amdgcn_s_setprio(0);}while(0)
; #define P8_WAIT_V(n) asm volatile("s_waitcnt vmcnt(" #n ")":::"memory")
; #define P8_WAIT_L(n) asm volatile("s_waitcnt lgkmcnt(" #n ")":::"memory")
; #define P8_BAR __builtin_amdgcn_s_barrier()
; #define P8_SCHED __builtin_amdgcn_sched_barrier(0)
; template <class EPI>
; DEVI void gemm8_tile(const bfr* __restrict__ A, const bfr* __restrict__ Bt, int K, int brow, int bcol, int nbrow, int nbcol, char* shmc, EPI epi) {
;     ...
;     P8_BAR; P8_WAIT_L(0); P8_MMA(1,0,At,B0); P8_BAR; P8_SCHED;
;     P8_STAGE(P8_SB(1,1),Bt,bcol+128,t+3);
;     P8_WAIT_V(6); P8_BAR; P8_MMA(1,1,At,B1); P8_BAR;
;   }
;   { P8_LDB(B0,0,0); P8_LDA(At,0,0); P8_STAGE(P8_SA(1,1),A,brow+128,nt-1);
;     P8_BAR; P8_WAIT_L(0); P8_MMA(0,0,At,B0); P8_BAR;
;     P8_LDB(B1,0,1); P8_BAR; P8_WAIT_L(0); P8_MMA(0,1,At,B1); P8_BAR;
	s_waitcnt lgkmcnt(0)
	v_mfma_f32_16x16x32_bf16 v[60:63], v[190:193], v[174:177], v[60:63]
	v_mfma_f32_16x16x32_bf16 v[56:59], v[190:193], v[182:185], v[56:59]
	v_mfma_f32_16x16x32_bf16 v[52:55], v[208:211], v[174:177], v[52:55]
	v_mfma_f32_16x16x32_bf16 v[48:51], v[208:211], v[182:185], v[48:51]
	v_mfma_f32_16x16x32_bf16 v[44:47], v[216:219], v[174:177], v[44:47]
	v_mfma_f32_16x16x32_bf16 v[40:43], v[216:219], v[182:185], v[40:43]
	v_mfma_f32_16x16x32_bf16 v[36:39], v[224:227], v[174:177], v[36:39]
	v_mfma_f32_16x16x32_bf16 v[32:35], v[224:227], v[182:185], v[32:35]
	v_mfma_f32_16x16x32_bf16 v[60:63], v[196:199], v[178:181], v[60:63]
	v_mfma_f32_16x16x32_bf16 v[56:59], v[196:199], v[186:189], v[56:59]
	v_mfma_f32_16x16x32_bf16 v[52:55], v[212:215], v[178:181], v[52:55]
	v_mfma_f32_16x16x32_bf16 v[48:51], v[212:215], v[186:189], v[48:51]
	v_mfma_f32_16x16x32_bf16 v[44:47], v[220:223], v[178:181], v[44:47]
	v_mfma_f32_16x16x32_bf16 v[40:43], v[220:223], v[186:189], v[40:43]
	v_mfma_f32_16x16x32_bf16 v[36:39], v[228:231], v[178:181], v[36:39]
	v_mfma_f32_16x16x32_bf16 v[32:35], v[228:231], v[186:189], v[32:35]
	s_barrier
	v_add_u32_e32 v174, s94, v140
	s_add_i32 m0, s100, 0x1c000
	s_nop 0
	global_load_lds_dwordx4 v174, s[86:87]
	v_add_u32_e32 v174, s94, v138
	s_add_i32 m0, s100, 0x1e000
	s_nop 0
	global_load_lds_dwordx4 v174, s[86:87]
	s_waitcnt vmcnt(6)
	s_barrier
	v_mfma_f32_16x16x32_bf16 v[28:31], v[190:193], v[232:235], v[28:31]
	v_mfma_f32_16x16x32_bf16 v[24:27], v[190:193], v[240:243], v[24:27]
	v_mfma_f32_16x16x32_bf16 v[20:23], v[208:211], v[232:235], v[20:23]
	v_mfma_f32_16x16x32_bf16 v[16:19], v[208:211], v[240:243], v[16:19]
	v_mfma_f32_16x16x32_bf16 v[12:15], v[216:219], v[232:235], v[12:15]
	v_mfma_f32_16x16x32_bf16 v[8:11], v[216:219], v[240:243], v[8:11]
	v_mfma_f32_16x16x32_bf16 v[4:7], v[224:227], v[232:235], v[4:7]
	v_mfma_f32_16x16x32_bf16 v[0:3], v[224:227], v[240:243], v[0:3]
	v_mfma_f32_16x16x32_bf16 v[28:31], v[196:199], v[236:239], v[28:31]
	v_mfma_f32_16x16x32_bf16 v[24:27], v[196:199], v[244:247], v[24:27]
	v_mfma_f32_16x16x32_bf16 v[20:23], v[212:215], v[236:239], v[20:23]
	v_mfma_f32_16x16x32_bf16 v[16:19], v[212:215], v[244:247], v[16:19]
	v_mfma_f32_16x16x32_bf16 v[12:15], v[220:223], v[236:239], v[12:15]
	v_mfma_f32_16x16x32_bf16 v[8:11], v[220:223], v[244:247], v[8:11]
	v_mfma_f32_16x16x32_bf16 v[4:7], v[228:231], v[236:239], v[4:7]
	v_mfma_f32_16x16x32_bf16 v[0:3], v[228:231], v[244:247], v[0:3]
	s_add_i32 s0, s0, 2
	v_lshl_add_u64 v[134:135], v[134:135], 0, s[80:81]
	v_lshl_add_u64 v[136:137], v[136:137], 0, s[80:81]
	v_lshl_add_u64 v[138:139], v[138:139], 0, s[80:81]
	s_cmp_lt_u32 s0, 4
	v_lshl_add_u64 v[140:141], v[140:141], 0, s[80:81]
	s_barrier
	s_cbranch_scc1 .LBB0_141
	v_add_u32_e32 v171, 0xc000, v143
	v_add_u32_e32 v172, 0xe000, v143
	v_add_u32_e32 v158, 0x10000, v143
	v_add_u32_e32 v159, 0x12000, v143
	v_add_u32_e32 v160, 0x2000, v143
	v_add_u32_e32 v161, 0x14000, v143
	v_add_u32_e32 v162, 0x16000, v143
	v_add_u32_e32 v163, 0x4000, v143
	v_add_u32_e32 v170, 0x6000, v143
	s_or_b32 s0, s6, 0x80
	s_ashr_i32 s1, s0, 31
	s_lshl_b64 s[0:1], s[0:1], 10
	s_add_u32 s0, s28, s0
	s_addc_u32 s1, s29, s1
	ds_read_b128 v[134:137], v157
	ds_read_b128 v[138:141], v157 offset:1024
	ds_read_b128 v[150:153], v157 offset:2048
	ds_read_b128 v[174:177], v157 offset:3072
	ds_read_b128 v[178:181], v147
	ds_read_b128 v[182:185], v147 offset:1024
	ds_read_b128 v[186:189], v146
	ds_read_b128 v[190:193], v146 offset:1024
	ds_read_b128 v[196:199], v145
	ds_read_b128 v[208:211], v145 offset:1024
	ds_read_b128 v[212:215], v144
	ds_read_b128 v[216:219], v144 offset:1024
	v_lshl_add_u64 v[156:157], v[166:167], 1, s[0:1]
	s_mov_b64 s[6:7], 0x380
	v_lshl_add_u64 v[156:157], v[156:157], 0, s[6:7]
	s_add_i32 m0, s100, 0xc000
	v_lshl_add_u64 v[132:133], v[132:133], 1, s[0:1]
	global_load_lds_dwordx4 v[156:157], off
	v_lshl_add_u64 v[132:133], v[132:133], 0, s[6:7]
	s_add_i32 m0, s100, 0xe000
	s_nop 0
	global_load_lds_dwordx4 v[132:133], off
	s_barrier
	s_waitcnt lgkmcnt(0)
	s_waitcnt lgkmcnt(0)
	v_mfma_f32_16x16x32_bf16 v[124:127], v[178:181], v[134:137], v[124:127]
	v_mfma_f32_16x16x32_bf16 v[120:123], v[178:181], v[150:153], v[120:123]
	v_mfma_f32_16x16x32_bf16 v[116:119], v[186:189], v[134:137], v[116:119]
	v_mfma_f32_16x16x32_bf16 v[112:115], v[186:189], v[150:153], v[112:115]
	v_mfma_f32_16x16x32_bf16 v[108:111], v[196:199], v[134:137], v[108:111]
	v_mfma_f32_16x16x32_bf16 v[104:107], v[196:199], v[150:153], v[104:107]
	v_mfma_f32_16x16x32_bf16 v[100:103], v[212:215], v[134:137], v[100:103]
	v_mfma_f32_16x16x32_bf16 v[96:99], v[212:215], v[150:153], v[96:99]
	v_mfma_f32_16x16x32_bf16 v[124:127], v[182:185], v[138:141], v[124:127]
	v_mfma_f32_16x16x32_bf16 v[120:123], v[182:185], v[174:177], v[120:123]
	v_mfma_f32_16x16x32_bf16 v[116:119], v[190:193], v[138:141], v[116:119]
	v_mfma_f32_16x16x32_bf16 v[112:115], v[190:193], v[174:177], v[112:115]
	v_mfma_f32_16x16x32_bf16 v[108:111], v[208:211], v[138:141], v[108:111]
	v_mfma_f32_16x16x32_bf16 v[104:107], v[208:211], v[174:177], v[104:107]
	v_mfma_f32_16x16x32_bf16 v[100:103], v[216:219], v[138:141], v[100:103]
	v_mfma_f32_16x16x32_bf16 v[96:99], v[216:219], v[174:177], v[96:99]
	s_barrier
	ds_read_b128 v[220:223], v154
	ds_read_b128 v[224:227], v154 offset:1024
	ds_read_b128 v[228:231], v154 offset:2048
	ds_read_b128 v[154:157], v154 offset:3072
	s_barrier
; #define P8_LDA(dst,b,h) _Pragma("unroll") for(int m=0;m<4;++m) _Pragma("unroll") for(int k=0;k<2;++k) \
;     dst[m][k]=*reinterpret_cast<const bf16x8*>((char*)P8_SA(b,h)+lds_byte(wr*64+m*16+fr,k*32+fq*8))
; #define P8_LDB(dst,b,h) _Pragma("unroll") for(int n=0;n<2;++n) _Pragma("unroll") for(int k=0;k<2;++k) \
;     dst[n][k]=*reinterpret_cast<const bf16x8*>((char*)P8_SB(b,h)+lds_byte(wc*32+n*16+fr,k*32+fq*8))
; #define P8_MMA(ai,bj,At,Bt) do{__builtin_amdgcn_s_setprio(1); \
;     _Pragma("unroll") for(int m=0;m<4;++m) _Pragma("unroll") for(int n=0;n<2;++n) _Pragma("unroll") for(int k=0;k<2;++k) \
;       acc[ai][bj][m][n]=__builtin_amdgcn_mfma_f32_16x16x32_bf16(At[m][k],Bt[n][k],acc[ai][bj][m][n],0,0,0); \
;     __builtin_amdgcn_s_setprio(0);}while(0)
; #define P8_WAIT_V(n) asm volatile("s_waitcnt vmcnt(" #n ")":::"memory")
; #define P8_WAIT_L(n) asm volatile("s_waitcnt lgkmcnt(" #n ")":::"memory")
; #define P8_BAR __builtin_amdgcn_s_barrier()
; template <class EPI>
; DEVI void gemm8_tile(const bfr* __restrict__ A, const bfr* __restrict__ Bt, int K, int brow, int bcol, int nbrow, int nbcol, char* shmc, EPI epi) {
;     ...
;     P8_LDB(B1,0,1); P8_BAR; P8_WAIT_L(0); P8_MMA(0,1,At,B1); P8_BAR;
;     P8_LDA(At,0,1); P8_WAIT_V(4); P8_BAR; P8_WAIT_L(0); P8_MMA(1,0,At,B0); P8_MMA(1,1,At,B1); P8_BAR; }
;   { P8_LDB(B0,1,0); P8_LDA(At,1,0); P8_WAIT_V(2); P8_BAR; P8_WAIT_L(0); P8_MMA(0,0,At,B0); P8_BAR;
	s_waitcnt lgkmcnt(0)
	s_waitcnt lgkmcnt(0)
	v_mfma_f32_16x16x32_bf16 v[88:91], v[178:181], v[228:231], v[88:91]
	v_mfma_f32_16x16x32_bf16 v[76:79], v[196:199], v[220:223], v[76:79]
	v_mfma_f32_16x16x32_bf16 v[72:75], v[196:199], v[228:231], v[72:75]
	v_mfma_f32_16x16x32_bf16 v[68:71], v[212:215], v[220:223], v[68:71]
	v_mfma_f32_16x16x32_bf16 v[64:67], v[212:215], v[228:231], v[64:67]
	v_mfma_f32_16x16x32_bf16 v[92:95], v[178:181], v[220:223], v[92:95]
	v_mfma_f32_16x16x32_bf16 v[178:181], v[182:185], v[154:157], v[88:91]
	v_mfma_f32_16x16x32_bf16 v[84:87], v[186:189], v[220:223], v[84:87]
	v_mfma_f32_16x16x32_bf16 v[80:83], v[186:189], v[228:231], v[80:83]
	v_mfma_f32_16x16x32_bf16 v[76:79], v[208:211], v[224:227], v[76:79]
	v_mfma_f32_16x16x32_bf16 v[72:75], v[208:211], v[154:157], v[72:75]
	v_mfma_f32_16x16x32_bf16 v[68:71], v[216:219], v[224:227], v[68:71]
	v_mfma_f32_16x16x32_bf16 v[64:67], v[216:219], v[154:157], v[64:67]
	v_mfma_f32_16x16x32_bf16 v[232:235], v[182:185], v[224:227], v[92:95]
	v_mfma_f32_16x16x32_bf16 v[182:185], v[190:193], v[224:227], v[84:87]
	v_mfma_f32_16x16x32_bf16 v[186:189], v[190:193], v[154:157], v[80:83]
	s_barrier
	s_nop 0
	ds_read_b128 v[80:83], v147 offset:16384
	ds_read_b128 v[84:87], v147 offset:17408
	ds_read_b128 v[88:91], v146 offset:16384
	ds_read_b128 v[92:95], v146 offset:17408
	ds_read_b128 v[190:193], v145 offset:16384
	ds_read_b128 v[196:199], v145 offset:17408
	ds_read_b128 v[208:211], v144 offset:16384
	ds_read_b128 v[212:215], v144 offset:17408
	s_waitcnt vmcnt(4)
	s_barrier
	s_waitcnt lgkmcnt(0)
	s_waitcnt lgkmcnt(0)
	v_mfma_f32_16x16x32_bf16 v[44:47], v[190:193], v[134:137], v[44:47]
	v_mfma_f32_16x16x32_bf16 v[40:43], v[190:193], v[150:153], v[40:43]
	v_mfma_f32_16x16x32_bf16 v[36:39], v[208:211], v[134:137], v[36:39]
	v_mfma_f32_16x16x32_bf16 v[32:35], v[208:211], v[150:153], v[32:35]
	v_mfma_f32_16x16x32_bf16 v[60:63], v[80:83], v[134:137], v[60:63]
	v_mfma_f32_16x16x32_bf16 v[56:59], v[80:83], v[150:153], v[56:59]
	v_mfma_f32_16x16x32_bf16 v[52:55], v[88:91], v[134:137], v[52:55]
	v_mfma_f32_16x16x32_bf16 v[48:51], v[88:91], v[150:153], v[48:51]
	v_mfma_f32_16x16x32_bf16 v[44:47], v[196:199], v[138:141], v[44:47]
	v_mfma_f32_16x16x32_bf16 v[40:43], v[196:199], v[174:177], v[40:43]
	v_mfma_f32_16x16x32_bf16 v[36:39], v[212:215], v[138:141], v[36:39]
	v_mfma_f32_16x16x32_bf16 v[32:35], v[212:215], v[174:177], v[32:35]
	v_mfma_f32_16x16x32_bf16 v[216:219], v[84:87], v[138:141], v[60:63]
	v_mfma_f32_16x16x32_bf16 v[236:239], v[84:87], v[174:177], v[56:59]
	v_mfma_f32_16x16x32_bf16 v[240:243], v[92:95], v[138:141], v[52:55]
	v_mfma_f32_16x16x32_bf16 v[244:247], v[92:95], v[174:177], v[48:51]
	s_setprio 0
	s_setprio 1
	v_mfma_f32_16x16x32_bf16 v[12:15], v[190:193], v[220:223], v[12:15]
	v_mfma_f32_16x16x32_bf16 v[4:7], v[208:211], v[220:223], v[4:7]
	v_mfma_f32_16x16x32_bf16 v[28:31], v[80:83], v[220:223], v[28:31]
	v_mfma_f32_16x16x32_bf16 v[24:27], v[80:83], v[228:231], v[24:27]
	v_mfma_f32_16x16x32_bf16 v[20:23], v[88:91], v[220:223], v[20:23]
	v_mfma_f32_16x16x32_bf16 v[16:19], v[88:91], v[228:231], v[16:19]
	v_mfma_f32_16x16x32_bf16 v[12:15], v[196:199], v[224:227], v[12:15]
	v_mfma_f32_16x16x32_bf16 v[8:11], v[190:193], v[228:231], v[8:11]
	v_mfma_f32_16x16x32_bf16 v[4:7], v[212:215], v[224:227], v[4:7]
	v_mfma_f32_16x16x32_bf16 v[0:3], v[208:211], v[228:231], v[0:3]
	v_mfma_f32_16x16x32_bf16 v[132:135], v[84:87], v[224:227], v[28:31]
	v_mfma_f32_16x16x32_bf16 v[136:139], v[84:87], v[154:157], v[24:27]
	v_mfma_f32_16x16x32_bf16 v[150:153], v[92:95], v[224:227], v[20:23]
	v_mfma_f32_16x16x32_bf16 v[172:175], v[92:95], v[154:157], v[16:19]
	v_mfma_f32_16x16x32_bf16 v[190:193], v[196:199], v[154:157], v[8:11]
	v_mfma_f32_16x16x32_bf16 v[154:157], v[212:215], v[154:157], v[0:3]
	s_barrier
	s_nop 0
	ds_read_b128 v[0:3], v149
	ds_read_b128 v[8:11], v149 offset:1024
	ds_read_b128 v[196:199], v149 offset:2048
	ds_read_b128 v[208:211], v149 offset:3072
	ds_read_b128 v[16:19], v147 offset:32768
	ds_read_b128 v[20:23], v147 offset:33792
	ds_read_b128 v[24:27], v146 offset:32768
	ds_read_b128 v[48:51], v146 offset:33792
	ds_read_b128 v[212:215], v145 offset:32768
	ds_read_b128 v[220:223], v145 offset:33792
	ds_read_b128 v[224:227], v144 offset:32768
	ds_read_b128 v[228:231], v144 offset:33792
	s_waitcnt vmcnt(2)
	s_barrier
; #define P8_LDA(dst,b,h) _Pragma("unroll") for(int m=0;m<4;++m) _Pragma("unroll") for(int k=0;k<2;++k) \
;     dst[m][k]=*reinterpret_cast<const bf16x8*>((char*)P8_SA(b,h)+lds_byte(wr*64+m*16+fr,k*32+fq*8))
; #define P8_LDB(dst,b,h) _Pragma("unroll") for(int n=0;n<2;++n) _Pragma("unroll") for(int k=0;k<2;++k) \
;     dst[n][k]=*reinterpret_cast<const bf16x8*>((char*)P8_SB(b,h)+lds_byte(wc*32+n*16+fr,k*32+fq*8))
; #define P8_MMA(ai,bj,At,Bt) do{__builtin_amdgcn_s_setprio(1); \
;     _Pragma("unroll") for(int m=0;m<4;++m) _Pragma("unroll") for(int n=0;n<2;++n) _Pragma("unroll") for(int k=0;k<2;++k) \
;       acc[ai][bj][m][n]=__builtin_amdgcn_mfma_f32_16x16x32_bf16(At[m][k],Bt[n][k],acc[ai][bj][m][n],0,0,0); \
;     __builtin_amdgcn_s_setprio(0);}while(0)
; #define P8_WAIT_V(n) asm volatile("s_waitcnt vmcnt(" #n ")":::"memory")
; #define P8_WAIT_L(n) asm volatile("s_waitcnt lgkmcnt(" #n ")":::"memory")
; #define P8_BAR __builtin_amdgcn_s_barrier()
; template <class EPI>
; DEVI void gemm8_tile(const bfr* __restrict__ A, const bfr* __restrict__ Bt, int K, int brow, int bcol, int nbrow, int nbcol, char* shmc, EPI epi) {
;     ...
;   { P8_LDB(B0,1,0); P8_LDA(At,1,0); P8_WAIT_V(2); P8_BAR; P8_WAIT_L(0); P8_MMA(0,0,At,B0); P8_BAR;
;     P8_LDB(B1,1,1); P8_WAIT_V(0); P8_BAR; P8_WAIT_L(0); P8_MMA(0,1,At,B1); P8_BAR;
;     P8_LDA(At,1,1); P8_BAR; P8_WAIT_L(0); P8_MMA(1,0,At,B0); P8_MMA(1,1,At,B1); P8_BAR; }
;   if(wr==0)P8_BAR;
	s_waitcnt lgkmcnt(0)
	s_waitcnt lgkmcnt(0)
	v_mfma_f32_16x16x32_bf16 v[28:31], v[16:19], v[0:3], v[124:127]
	v_mfma_f32_16x16x32_bf16 v[124:127], v[20:23], v[8:11], v[28:31]
	v_mfma_f32_16x16x32_bf16 v[28:31], v[16:19], v[196:199], v[120:123]
	v_mfma_f32_16x16x32_bf16 v[92:95], v[20:23], v[208:211], v[28:31]
	v_mfma_f32_16x16x32_bf16 v[28:31], v[24:27], v[0:3], v[116:119]
	v_mfma_f32_16x16x32_bf16 v[120:123], v[48:51], v[8:11], v[28:31]
	v_mfma_f32_16x16x32_bf16 v[28:31], v[24:27], v[196:199], v[112:115]
	v_mfma_f32_16x16x32_bf16 v[88:91], v[48:51], v[208:211], v[28:31]
	v_mfma_f32_16x16x32_bf16 v[28:31], v[212:215], v[0:3], v[108:111]
	v_mfma_f32_16x16x32_bf16 v[116:119], v[220:223], v[8:11], v[28:31]
	v_mfma_f32_16x16x32_bf16 v[28:31], v[212:215], v[196:199], v[104:107]
	v_mfma_f32_16x16x32_bf16 v[84:87], v[220:223], v[208:211], v[28:31]
	v_mfma_f32_16x16x32_bf16 v[28:31], v[224:227], v[0:3], v[100:103]
	v_mfma_f32_16x16x32_bf16 v[112:115], v[228:231], v[8:11], v[28:31]
	v_mfma_f32_16x16x32_bf16 v[28:31], v[224:227], v[196:199], v[96:99]
	v_mfma_f32_16x16x32_bf16 v[80:83], v[228:231], v[208:211], v[28:31]
	s_barrier
	ds_read_b128 v[248:251], v148
	ds_read_b128 v[200:203], v148 offset:1024
	ds_read_b128 v[204:207], v148 offset:2048
	s_nop 1
	ds_read_b128 v[28:31], v148 offset:3072
	s_waitcnt vmcnt(0)
	s_barrier
	s_waitcnt lgkmcnt(0)
	s_waitcnt lgkmcnt(0)
	v_mfma_f32_16x16x32_bf16 v[52:55], v[16:19], v[248:251], v[232:235]
	v_mfma_f32_16x16x32_bf16 v[16:19], v[16:19], v[204:207], v[178:181]
	v_mfma_f32_16x16x32_bf16 v[176:179], v[20:23], v[28:31], v[16:19]
	v_mfma_f32_16x16x32_bf16 v[16:19], v[24:27], v[248:251], v[182:185]
	v_mfma_f32_16x16x32_bf16 v[56:59], v[48:51], v[200:203], v[16:19]
	v_mfma_f32_16x16x32_bf16 v[16:19], v[24:27], v[204:207], v[186:189]
	v_mfma_f32_16x16x32_bf16 v[24:27], v[48:51], v[28:31], v[16:19]
	v_mfma_f32_16x16x32_bf16 v[16:19], v[212:215], v[248:251], v[76:79]
	v_mfma_f32_16x16x32_bf16 v[60:63], v[20:23], v[200:203], v[52:55]
	v_mfma_f32_16x16x32_bf16 v[52:55], v[220:223], v[200:203], v[16:19]
	v_mfma_f32_16x16x32_bf16 v[16:19], v[212:215], v[204:207], v[72:75]
	v_mfma_f32_16x16x32_bf16 v[20:23], v[220:223], v[28:31], v[16:19]
	v_mfma_f32_16x16x32_bf16 v[16:19], v[224:227], v[248:251], v[68:71]
	v_mfma_f32_16x16x32_bf16 v[48:51], v[228:231], v[200:203], v[16:19]
	v_mfma_f32_16x16x32_bf16 v[16:19], v[224:227], v[204:207], v[64:67]
	v_mfma_f32_16x16x32_bf16 v[16:19], v[228:231], v[28:31], v[16:19]
	s_barrier
	ds_read_b128 v[180:183], v147 offset:49152
	ds_read_b128 v[184:187], v147 offset:50176
	ds_read_b128 v[212:215], v146 offset:49152
	ds_read_b128 v[146:149], v146 offset:50176
	ds_read_b128 v[220:223], v145 offset:49152
	ds_read_b128 v[224:227], v145 offset:50176
	ds_read_b128 v[228:231], v144 offset:49152
	ds_read_b128 v[232:235], v144 offset:50176
	s_barrier
	s_waitcnt lgkmcnt(0)
	s_waitcnt lgkmcnt(0)
	v_mfma_f32_16x16x32_bf16 v[64:67], v[180:183], v[0:3], v[216:219]
	v_mfma_f32_16x16x32_bf16 v[104:107], v[184:187], v[8:11], v[64:67]
	v_mfma_f32_16x16x32_bf16 v[64:67], v[180:183], v[196:199], v[236:239]
	v_mfma_f32_16x16x32_bf16 v[72:75], v[184:187], v[208:211], v[64:67]
	v_mfma_f32_16x16x32_bf16 v[64:67], v[212:215], v[0:3], v[240:243]
	v_mfma_f32_16x16x32_bf16 v[44:47], v[220:223], v[0:3], v[44:47]
	v_mfma_f32_16x16x32_bf16 v[0:3], v[228:231], v[0:3], v[36:39]
	v_mfma_f32_16x16x32_bf16 v[96:99], v[146:149], v[8:11], v[64:67]
	v_mfma_f32_16x16x32_bf16 v[64:67], v[212:215], v[196:199], v[244:247]
	v_mfma_f32_16x16x32_bf16 v[40:43], v[220:223], v[196:199], v[40:43]
	v_mfma_f32_16x16x32_bf16 v[100:103], v[232:235], v[8:11], v[0:3]
	v_mfma_f32_16x16x32_bf16 v[0:3], v[228:231], v[196:199], v[32:35]
	v_mfma_f32_16x16x32_bf16 v[64:67], v[146:149], v[208:211], v[64:67]
	v_mfma_f32_16x16x32_bf16 v[108:111], v[224:227], v[8:11], v[44:47]
	v_mfma_f32_16x16x32_bf16 v[76:79], v[224:227], v[208:211], v[40:43]
	v_mfma_f32_16x16x32_bf16 v[68:71], v[232:235], v[208:211], v[0:3]
	s_setprio 0
	s_setprio 1
	v_mfma_f32_16x16x32_bf16 v[0:3], v[180:183], v[248:251], v[132:135]
	v_mfma_f32_16x16x32_bf16 v[40:43], v[184:187], v[200:203], v[0:3]
	v_mfma_f32_16x16x32_bf16 v[0:3], v[180:183], v[204:207], v[136:139]
	v_mfma_f32_16x16x32_bf16 v[8:11], v[184:187], v[28:31], v[0:3]
	v_mfma_f32_16x16x32_bf16 v[0:3], v[212:215], v[248:251], v[150:153]
	v_mfma_f32_16x16x32_bf16 v[12:15], v[220:223], v[248:251], v[12:15]
	v_mfma_f32_16x16x32_bf16 v[4:7], v[228:231], v[248:251], v[4:7]
	v_mfma_f32_16x16x32_bf16 v[32:35], v[146:149], v[200:203], v[0:3]
	v_mfma_f32_16x16x32_bf16 v[0:3], v[212:215], v[204:207], v[172:175]
	v_mfma_f32_16x16x32_bf16 v[44:47], v[224:227], v[200:203], v[12:15]
	v_mfma_f32_16x16x32_bf16 v[12:15], v[220:223], v[204:207], v[190:193]
	v_mfma_f32_16x16x32_bf16 v[36:39], v[232:235], v[200:203], v[4:7]
	v_mfma_f32_16x16x32_bf16 v[4:7], v[228:231], v[204:207], v[154:157]
	v_mfma_f32_16x16x32_bf16 v[0:3], v[146:149], v[28:31], v[0:3]
	v_mfma_f32_16x16x32_bf16 v[12:15], v[224:227], v[28:31], v[12:15]
	v_mfma_f32_16x16x32_bf16 v[4:7], v[232:235], v[28:31], v[4:7]
	s_setprio 0
	v_cmp_gt_u32_e32 vcc, s57, v142
	s_barrier
	s_and_saveexec_b64 s[0:1], vcc
	s_cbranch_execz .LBB0_144
	s_barrier

; #define P8_STAGE(P,BASE,br,kt) do{const bfr* _ub=(BASE)+((long)(br)*K+(long)(kt)*BK); \
;     __builtin_amdgcn_global_load_lds((const unsigned*)(_ub+so0),(unsigned*)((char*)(P)+wid*1024),16,0,0); \
;     __builtin_amdgcn_global_load_lds((const unsigned*)(_ub+so1),(unsigned*)((char*)(P)+wid*1024+8192),16,0,0);}while(0)
; #define P8_LDA(dst,b,h) _Pragma("unroll") for(int m=0;m<4;++m) _Pragma("unroll") for(int k=0;k<2;++k) \
;     dst[m][k]=*reinterpret_cast<const bf16x8*>((char*)P8_SA(b,h)+lds_byte(wr*64+m*16+fr,k*32+fq*8))
; #define P8_LDB(dst,b,h) _Pragma("unroll") for(int n=0;n<2;++n) _Pragma("unroll") for(int k=0;k<2;++k) \
;     dst[n][k]=*reinterpret_cast<const bf16x8*>((char*)P8_SB(b,h)+lds_byte(wc*32+n*16+fr,k*32+fq*8))
; #define P8_MMA(ai,bj,At,Bt) do{__builtin_amdgcn_s_setprio(1); \
;     _Pragma("unroll") for(int m=0;m<4;++m) _Pragma("unroll") for(int n=0;n<2;++n) _Pragma("unroll") for(int k=0;k<2;++k) \
;       acc[ai][bj][m][n]=__builtin_amdgcn_mfma_f32_16x16x32_bf16(At[m][k],Bt[n][k],acc[ai][bj][m][n],0,0,0); \
;     __builtin_amdgcn_s_setprio(0);}while(0)
; #define P8_WAIT_V(n) asm volatile("s_waitcnt vmcnt(" #n ")":::"memory")
; #define P8_WAIT_L(n) asm volatile("s_waitcnt lgkmcnt(" #n ")":::"memory")
; #define P8_BAR __builtin_amdgcn_s_barrier()
; #define P8_SCHED __builtin_amdgcn_sched_barrier(0)
; template <class EPI>
; DEVI void gemm8_tile(const bfr* __restrict__ A, const bfr* __restrict__ Bt, int K, int brow, int bcol, int nbrow, int nbcol, char* shmc, EPI epi) {
;     ...
;   for(int t=0;t<nt-2;t+=2){
;     P8_LDB(B0,0,0); P8_SCHED; P8_LDA(At,0,0); P8_STAGE(P8_SA(1,1),A,brow+128,t+1);
;     P8_WAIT_L(8); P8_BAR; P8_WAIT_L(0); P8_MMA(0,0,At,B0); P8_BAR; P8_SCHED;
;     P8_LDB(B1,0,1); P8_STAGE(P8_SB(0,0),Bt,bcol,t+2);
;     P8_BAR; P8_WAIT_L(0); P8_MMA(0,1,At,B1); P8_BAR;
;     P8_LDA(At,0,1); P8_STAGE(P8_SA(0,0),A,brow,t+2);
;     P8_BAR; P8_WAIT_L(0); P8_MMA(1,0,At,B0); P8_BAR; P8_SCHED;
;     P8_STAGE(P8_SB(0,1),Bt,bcol+128,t+2);
;     P8_WAIT_V(6); P8_BAR; P8_MMA(1,1,At,B1); P8_BAR;
.LBB0_175:
	ds_read_b128 v[174:177], v157
	ds_read_b128 v[178:181], v157 offset:1024
	ds_read_b128 v[182:185], v157 offset:2048
	ds_read_b128 v[186:189], v157 offset:3072
	v_add_u32_e32 v158, s54, v136
	s_add_i32 m0, s100, 0xc000
	ds_read_b128 v[160:163], v147
	ds_read_b128 v[190:193], v147 offset:1024
	ds_read_b128 v[196:199], v146
	ds_read_b128 v[200:203], v146 offset:1024
	ds_read_b128 v[204:207], v145
	ds_read_b128 v[208:211], v145 offset:1024
	ds_read_b128 v[212:215], v144
	ds_read_b128 v[216:219], v144 offset:1024
	global_load_lds_dwordx4 v158, s[86:87]
	v_add_u32_e32 v158, s54, v134
	s_add_i32 m0, s100, 0xe000
	s_nop 0
	global_load_lds_dwordx4 v158, s[86:87]
	s_waitcnt lgkmcnt(8)
	s_barrier
	s_waitcnt lgkmcnt(0)
	v_mfma_f32_16x16x32_bf16 v[124:127], v[160:163], v[174:177], v[124:127]
	v_mfma_f32_16x16x32_bf16 v[120:123], v[160:163], v[182:185], v[120:123]
	v_mfma_f32_16x16x32_bf16 v[116:119], v[196:199], v[174:177], v[116:119]
	v_mfma_f32_16x16x32_bf16 v[112:115], v[196:199], v[182:185], v[112:115]
	v_mfma_f32_16x16x32_bf16 v[108:111], v[204:207], v[174:177], v[108:111]
	v_mfma_f32_16x16x32_bf16 v[104:107], v[204:207], v[182:185], v[104:107]
	v_mfma_f32_16x16x32_bf16 v[100:103], v[212:215], v[174:177], v[100:103]
	v_mfma_f32_16x16x32_bf16 v[96:99], v[212:215], v[182:185], v[96:99]
	v_mfma_f32_16x16x32_bf16 v[124:127], v[190:193], v[178:181], v[124:127]
	v_mfma_f32_16x16x32_bf16 v[120:123], v[190:193], v[186:189], v[120:123]
	v_mfma_f32_16x16x32_bf16 v[116:119], v[200:203], v[178:181], v[116:119]
	v_mfma_f32_16x16x32_bf16 v[112:115], v[200:203], v[186:189], v[112:115]
	v_mfma_f32_16x16x32_bf16 v[108:111], v[208:211], v[178:181], v[108:111]
	v_mfma_f32_16x16x32_bf16 v[104:107], v[208:211], v[186:189], v[104:107]
	v_mfma_f32_16x16x32_bf16 v[100:103], v[216:219], v[178:181], v[100:103]
	v_mfma_f32_16x16x32_bf16 v[96:99], v[216:219], v[186:189], v[96:99]
	s_barrier
	v_add_u32_e32 v236, s60, v140
	s_add_i32 m0, s100, 0x10000
	ds_read_b128 v[220:223], v154
	ds_read_b128 v[224:227], v154 offset:1024
	ds_read_b128 v[228:231], v154 offset:2048
	ds_read_b128 v[232:235], v154 offset:3072
	global_load_lds_dwordx4 v236, s[86:87]
	v_add_u32_e32 v236, s60, v138
	s_add_i32 m0, s100, 0x12000
	s_nop 0
	global_load_lds_dwordx4 v236, s[86:87]
	s_barrier
	s_waitcnt lgkmcnt(0)
	v_mfma_f32_16x16x32_bf16 v[92:95], v[160:163], v[220:223], v[92:95]
	v_mfma_f32_16x16x32_bf16 v[88:91], v[160:163], v[228:231], v[88:91]
	v_mfma_f32_16x16x32_bf16 v[84:87], v[196:199], v[220:223], v[84:87]
	v_mfma_f32_16x16x32_bf16 v[80:83], v[196:199], v[228:231], v[80:83]
	v_mfma_f32_16x16x32_bf16 v[76:79], v[204:207], v[220:223], v[76:79]
	v_mfma_f32_16x16x32_bf16 v[72:75], v[204:207], v[228:231], v[72:75]
	v_mfma_f32_16x16x32_bf16 v[68:71], v[212:215], v[220:223], v[68:71]
	v_mfma_f32_16x16x32_bf16 v[64:67], v[212:215], v[228:231], v[64:67]
	v_mfma_f32_16x16x32_bf16 v[92:95], v[190:193], v[224:227], v[92:95]
	v_mfma_f32_16x16x32_bf16 v[88:91], v[190:193], v[232:235], v[88:91]
	v_mfma_f32_16x16x32_bf16 v[84:87], v[200:203], v[224:227], v[84:87]
	v_mfma_f32_16x16x32_bf16 v[80:83], v[200:203], v[232:235], v[80:83]
	v_mfma_f32_16x16x32_bf16 v[76:79], v[208:211], v[224:227], v[76:79]
	v_mfma_f32_16x16x32_bf16 v[72:75], v[208:211], v[232:235], v[72:75]
	v_mfma_f32_16x16x32_bf16 v[68:71], v[216:219], v[224:227], v[68:71]
	v_mfma_f32_16x16x32_bf16 v[64:67], v[216:219], v[232:235], v[64:67]
	v_add_u32_e32 v160, s72, v136
	s_mov_b32 m0, s100
	s_barrier
	ds_read_b128 v[190:193], v147 offset:16384
	ds_read_b128 v[196:199], v147 offset:17408
	ds_read_b128 v[200:203], v146 offset:16384
	ds_read_b128 v[204:207], v146 offset:17408
	ds_read_b128 v[208:211], v145 offset:16384
	ds_read_b128 v[212:215], v145 offset:17408
	ds_read_b128 v[216:219], v144 offset:16384
	ds_read_b128 v[236:239], v144 offset:17408
	global_load_lds_dwordx4 v160, s[86:87]
	v_add_u32_e32 v162, s72, v134
	s_add_i32 m0, s100, 0x2000
	s_nop 0
	global_load_lds_dwordx4 v162, s[86:87]
	s_barrier
	s_waitcnt lgkmcnt(0)
	v_mfma_f32_16x16x32_bf16 v[60:63], v[190:193], v[174:177], v[60:63]
	v_mfma_f32_16x16x32_bf16 v[56:59], v[190:193], v[182:185], v[56:59]
	v_mfma_f32_16x16x32_bf16 v[52:55], v[200:203], v[174:177], v[52:55]
	v_mfma_f32_16x16x32_bf16 v[48:51], v[200:203], v[182:185], v[48:51]
	v_mfma_f32_16x16x32_bf16 v[44:47], v[208:211], v[174:177], v[44:47]
	v_mfma_f32_16x16x32_bf16 v[40:43], v[208:211], v[182:185], v[40:43]
	v_mfma_f32_16x16x32_bf16 v[36:39], v[216:219], v[174:177], v[36:39]
	v_mfma_f32_16x16x32_bf16 v[32:35], v[216:219], v[182:185], v[32:35]
	v_mfma_f32_16x16x32_bf16 v[60:63], v[196:199], v[178:181], v[60:63]
	v_mfma_f32_16x16x32_bf16 v[56:59], v[196:199], v[186:189], v[56:59]
	v_mfma_f32_16x16x32_bf16 v[52:55], v[204:207], v[178:181], v[52:55]
	v_mfma_f32_16x16x32_bf16 v[48:51], v[204:207], v[186:189], v[48:51]
	v_mfma_f32_16x16x32_bf16 v[44:47], v[212:215], v[178:181], v[44:47]
	v_mfma_f32_16x16x32_bf16 v[40:43], v[212:215], v[186:189], v[40:43]
	v_mfma_f32_16x16x32_bf16 v[36:39], v[236:239], v[178:181], v[36:39]
	v_mfma_f32_16x16x32_bf16 v[32:35], v[236:239], v[186:189], v[32:35]
	s_barrier
	v_add_u32_e32 v162, s82, v140
	s_add_i32 m0, s100, 0x14000
	v_add_u32_e32 v174, s82, v138
	global_load_lds_dwordx4 v162, s[86:87]
	s_nop 0
	s_add_i32 m0, s100, 0x16000
	s_nop 0
	global_load_lds_dwordx4 v174, s[86:87]
	s_waitcnt vmcnt(6)
	s_barrier
; #define P8_STAGE(P,BASE,br,kt) do{const bfr* _ub=(BASE)+((long)(br)*K+(long)(kt)*BK); \
;     __builtin_amdgcn_global_load_lds((const unsigned*)(_ub+so0),(unsigned*)((char*)(P)+wid*1024),16,0,0); \
;     __builtin_amdgcn_global_load_lds((const unsigned*)(_ub+so1),(unsigned*)((char*)(P)+wid*1024+8192),16,0,0);}while(0)
; #define P8_LDA(dst,b,h) _Pragma("unroll") for(int m=0;m<4;++m) _Pragma("unroll") for(int k=0;k<2;++k) \
;     dst[m][k]=*reinterpret_cast<const bf16x8*>((char*)P8_SA(b,h)+lds_byte(wr*64+m*16+fr,k*32+fq*8))
; #define P8_LDB(dst,b,h) _Pragma("unroll") for(int n=0;n<2;++n) _Pragma("unroll") for(int k=0;k<2;++k) \
;     dst[n][k]=*reinterpret_cast<const bf16x8*>((char*)P8_SB(b,h)+lds_byte(wc*32+n*16+fr,k*32+fq*8))
; #define P8_MMA(ai,bj,At,Bt) do{__builtin_amdgcn_s_setprio(1); \
;     _Pragma("unroll") for(int m=0;m<4;++m) _Pragma("unroll") for(int n=0;n<2;++n) _Pragma("unroll") for(int k=0;k<2;++k) \
;       acc[ai][bj][m][n]=__builtin_amdgcn_mfma_f32_16x16x32_bf16(At[m][k],Bt[n][k],acc[ai][bj][m][n],0,0,0); \
;     __builtin_amdgcn_s_setprio(0);}while(0)
; #define P8_WAIT_V(n) asm volatile("s_waitcnt vmcnt(" #n ")":::"memory")
; #define P8_WAIT_L(n) asm volatile("s_waitcnt lgkmcnt(" #n ")":::"memory")
; #define P8_BAR __builtin_amdgcn_s_barrier()
; #define P8_SCHED __builtin_amdgcn_sched_barrier(0)
; template <class EPI>
; DEVI void gemm8_tile(const bfr* __restrict__ A, const bfr* __restrict__ Bt, int K, int brow, int bcol, int nbrow, int nbcol, char* shmc, EPI epi) {
;     ...
;     P8_WAIT_V(6); P8_BAR; P8_MMA(1,1,At,B1); P8_BAR;
;     P8_LDB(B0,1,0); P8_SCHED; P8_LDA(At,1,0); P8_STAGE(P8_SA(0,1),A,brow+128,t+2);
;     P8_WAIT_L(8); P8_BAR; P8_WAIT_L(0); P8_MMA(0,0,At,B0); P8_BAR; P8_SCHED;
;     P8_LDB(B1,1,1); P8_STAGE(P8_SB(1,0),Bt,bcol,t+3);
;     P8_BAR; P8_WAIT_L(0); P8_MMA(0,1,At,B1); P8_BAR;
;     P8_LDA(At,1,1); P8_STAGE(P8_SA(1,0),A,brow,t+3);
	v_mfma_f32_16x16x32_bf16 v[28:31], v[190:193], v[220:223], v[28:31]
	v_mfma_f32_16x16x32_bf16 v[24:27], v[190:193], v[228:231], v[24:27]
	v_mfma_f32_16x16x32_bf16 v[20:23], v[200:203], v[220:223], v[20:23]
	v_mfma_f32_16x16x32_bf16 v[16:19], v[200:203], v[228:231], v[16:19]
	v_mfma_f32_16x16x32_bf16 v[12:15], v[208:211], v[220:223], v[12:15]
	v_mfma_f32_16x16x32_bf16 v[8:11], v[208:211], v[228:231], v[8:11]
	v_mfma_f32_16x16x32_bf16 v[4:7], v[216:219], v[220:223], v[4:7]
	v_mfma_f32_16x16x32_bf16 v[0:3], v[216:219], v[228:231], v[0:3]
	v_mfma_f32_16x16x32_bf16 v[28:31], v[196:199], v[224:227], v[28:31]
	v_mfma_f32_16x16x32_bf16 v[24:27], v[196:199], v[232:235], v[24:27]
	v_mfma_f32_16x16x32_bf16 v[20:23], v[204:207], v[224:227], v[20:23]
	v_mfma_f32_16x16x32_bf16 v[16:19], v[204:207], v[232:235], v[16:19]
	v_mfma_f32_16x16x32_bf16 v[12:15], v[212:215], v[224:227], v[12:15]
	v_mfma_f32_16x16x32_bf16 v[8:11], v[212:215], v[232:235], v[8:11]
	v_mfma_f32_16x16x32_bf16 v[4:7], v[236:239], v[224:227], v[4:7]
	v_mfma_f32_16x16x32_bf16 v[0:3], v[236:239], v[232:235], v[0:3]
	s_barrier
	ds_read_b128 v[174:177], v149
	ds_read_b128 v[178:181], v149 offset:1024
	ds_read_b128 v[182:185], v149 offset:2048
	ds_read_b128 v[186:189], v149 offset:3072
	v_add_u32_e32 v224, s92, v136
	s_add_i32 m0, s100, 0x4000
	ds_read_b128 v[190:193], v147 offset:32768
	ds_read_b128 v[196:199], v147 offset:33792
	ds_read_b128 v[200:203], v146 offset:32768
	ds_read_b128 v[204:207], v146 offset:33792
	ds_read_b128 v[208:211], v145 offset:32768
	ds_read_b128 v[212:215], v145 offset:33792
	ds_read_b128 v[216:219], v144 offset:32768
	ds_read_b128 v[220:223], v144 offset:33792
	global_load_lds_dwordx4 v224, s[86:87]
	v_add_u32_e32 v224, s92, v134
	s_add_i32 m0, s100, 0x6000
	s_nop 0
	global_load_lds_dwordx4 v224, s[86:87]
	s_waitcnt lgkmcnt(8)
	s_barrier
	s_waitcnt lgkmcnt(0)
	v_mfma_f32_16x16x32_bf16 v[124:127], v[190:193], v[174:177], v[124:127]
	v_mfma_f32_16x16x32_bf16 v[120:123], v[190:193], v[182:185], v[120:123]
	v_mfma_f32_16x16x32_bf16 v[116:119], v[200:203], v[174:177], v[116:119]
	v_mfma_f32_16x16x32_bf16 v[112:115], v[200:203], v[182:185], v[112:115]
	v_mfma_f32_16x16x32_bf16 v[108:111], v[208:211], v[174:177], v[108:111]
	v_mfma_f32_16x16x32_bf16 v[104:107], v[208:211], v[182:185], v[104:107]
	v_mfma_f32_16x16x32_bf16 v[100:103], v[216:219], v[174:177], v[100:103]
	v_mfma_f32_16x16x32_bf16 v[96:99], v[216:219], v[182:185], v[96:99]
	v_mfma_f32_16x16x32_bf16 v[124:127], v[196:199], v[178:181], v[124:127]
	v_mfma_f32_16x16x32_bf16 v[120:123], v[196:199], v[186:189], v[120:123]
	v_mfma_f32_16x16x32_bf16 v[116:119], v[204:207], v[178:181], v[116:119]
	v_mfma_f32_16x16x32_bf16 v[112:115], v[204:207], v[186:189], v[112:115]
	v_mfma_f32_16x16x32_bf16 v[108:111], v[212:215], v[178:181], v[108:111]
	v_mfma_f32_16x16x32_bf16 v[104:107], v[212:215], v[186:189], v[104:107]
	v_mfma_f32_16x16x32_bf16 v[100:103], v[220:223], v[178:181], v[100:103]
	v_mfma_f32_16x16x32_bf16 v[96:99], v[220:223], v[186:189], v[96:99]
	s_barrier
	v_add_u32_e32 v248, s94, v140
	s_add_i32 m0, s100, 0x18000
	ds_read_b128 v[224:227], v148
	ds_read_b128 v[228:231], v148 offset:1024
	ds_read_b128 v[232:235], v148 offset:2048
	ds_read_b128 v[236:239], v148 offset:3072
	global_load_lds_dwordx4 v248, s[86:87]
	v_add_u32_e32 v248, s94, v138
	s_add_i32 m0, s100, 0x1a000
	s_nop 0
	global_load_lds_dwordx4 v248, s[86:87]
	s_barrier
	s_waitcnt lgkmcnt(0)
	v_mfma_f32_16x16x32_bf16 v[92:95], v[190:193], v[224:227], v[92:95]
	v_mfma_f32_16x16x32_bf16 v[88:91], v[190:193], v[232:235], v[88:91]
	v_mfma_f32_16x16x32_bf16 v[84:87], v[200:203], v[224:227], v[84:87]
	v_mfma_f32_16x16x32_bf16 v[80:83], v[200:203], v[232:235], v[80:83]
	v_mfma_f32_16x16x32_bf16 v[76:79], v[208:211], v[224:227], v[76:79]
	v_mfma_f32_16x16x32_bf16 v[72:75], v[208:211], v[232:235], v[72:75]
	v_mfma_f32_16x16x32_bf16 v[68:71], v[216:219], v[224:227], v[68:71]
	v_mfma_f32_16x16x32_bf16 v[64:67], v[216:219], v[232:235], v[64:67]
	v_mfma_f32_16x16x32_bf16 v[92:95], v[196:199], v[228:231], v[92:95]
	v_mfma_f32_16x16x32_bf16 v[88:91], v[196:199], v[236:239], v[88:91]
	v_mfma_f32_16x16x32_bf16 v[84:87], v[204:207], v[228:231], v[84:87]
	v_mfma_f32_16x16x32_bf16 v[80:83], v[204:207], v[236:239], v[80:83]
	v_mfma_f32_16x16x32_bf16 v[76:79], v[212:215], v[228:231], v[76:79]
	v_mfma_f32_16x16x32_bf16 v[72:75], v[212:215], v[236:239], v[72:75]
	v_mfma_f32_16x16x32_bf16 v[68:71], v[220:223], v[228:231], v[68:71]
	v_mfma_f32_16x16x32_bf16 v[64:67], v[220:223], v[236:239], v[64:67]
	v_add_u32_e32 v240, vcc_lo, v136
	s_add_i32 m0, s100, 0x8000
	s_barrier
	ds_read_b128 v[190:193], v147 offset:49152
	ds_read_b128 v[196:199], v147 offset:50176
	ds_read_b128 v[200:203], v146 offset:49152
	ds_read_b128 v[204:207], v146 offset:50176
	ds_read_b128 v[208:211], v145 offset:49152
	ds_read_b128 v[212:215], v145 offset:50176
	ds_read_b128 v[216:219], v144 offset:49152
	ds_read_b128 v[220:223], v144 offset:50176
	global_load_lds_dwordx4 v240, s[86:87]
	v_add_u32_e32 v240, vcc_lo, v134
	s_add_i32 m0, s100, 0xa000
	s_nop 0
	global_load_lds_dwordx4 v240, s[86:87]
	s_barrier
; #define P8_STAGE(P,BASE,br,kt) do{const bfr* _ub=(BASE)+((long)(br)*K+(long)(kt)*BK); \
;     __builtin_amdgcn_global_load_lds((const unsigned*)(_ub+so0),(unsigned*)((char*)(P)+wid*1024),16,0,0); \
;     __builtin_amdgcn_global_load_lds((const unsigned*)(_ub+so1),(unsigned*)((char*)(P)+wid*1024+8192),16,0,0);}while(0)
; #define P8_LDA(dst,b,h) _Pragma("unroll") for(int m=0;m<4;++m) _Pragma("unroll") for(int k=0;k<2;++k) \
;     dst[m][k]=*reinterpret_cast<const bf16x8*>((char*)P8_SA(b,h)+lds_byte(wr*64+m*16+fr,k*32+fq*8))
; #define P8_LDB(dst,b,h) _Pragma("unroll") for(int n=0;n<2;++n) _Pragma("unroll") for(int k=0;k<2;++k) \
;     dst[n][k]=*reinterpret_cast<const bf16x8*>((char*)P8_SB(b,h)+lds_byte(wc*32+n*16+fr,k*32+fq*8))
; #define P8_MMA(ai,bj,At,Bt) do{__builtin_amdgcn_s_setprio(1); \
;     _Pragma("unroll") for(int m=0;m<4;++m) _Pragma("unroll") for(int n=0;n<2;++n) _Pragma("unroll") for(int k=0;k<2;++k) \
;       acc[ai][bj][m][n]=__builtin_amdgcn_mfma_f32_16x16x32_bf16(At[m][k],Bt[n][k],acc[ai][bj][m][n],0,0,0); \
;     __builtin_amdgcn_s_setprio(0);}while(0)
; #define P8_WAIT_V(n) asm volatile("s_waitcnt vmcnt(" #n ")":::"memory")
; #define P8_WAIT_L(n) asm volatile("s_waitcnt lgkmcnt(" #n ")":::"memory")
; #define P8_BAR __builtin_amdgcn_s_barrier()
; #define P8_SCHED __builtin_amdgcn_sched_barrier(0)
; template <class EPI>
; DEVI void gemm8_tile(const bfr* __restrict__ A, const bfr* __restrict__ Bt, int K, int brow, int bcol, int nbrow, int nbcol, char* shmc, EPI epi) {
;     ...
;     P8_BAR; P8_WAIT_L(0); P8_MMA(1,0,At,B0); P8_BAR; P8_SCHED;
;     P8_STAGE(P8_SB(1,1),Bt,bcol+128,t+3);
;     P8_WAIT_V(6); P8_BAR; P8_MMA(1,1,At,B1); P8_BAR;
;   }
;   { P8_LDB(B0,0,0); P8_LDA(At,0,0); P8_STAGE(P8_SA(1,1),A,brow+128,nt-1);
;     P8_BAR; P8_WAIT_L(0); P8_MMA(0,0,At,B0); P8_BAR;
;     P8_LDB(B1,0,1); P8_BAR; P8_WAIT_L(0); P8_MMA(0,1,At,B1); P8_BAR;
	s_waitcnt lgkmcnt(0)
	v_mfma_f32_16x16x32_bf16 v[60:63], v[190:193], v[174:177], v[60:63]
	v_mfma_f32_16x16x32_bf16 v[56:59], v[190:193], v[182:185], v[56:59]
	v_mfma_f32_16x16x32_bf16 v[52:55], v[200:203], v[174:177], v[52:55]
	v_mfma_f32_16x16x32_bf16 v[48:51], v[200:203], v[182:185], v[48:51]
	v_mfma_f32_16x16x32_bf16 v[44:47], v[208:211], v[174:177], v[44:47]
	v_mfma_f32_16x16x32_bf16 v[40:43], v[208:211], v[182:185], v[40:43]
	v_mfma_f32_16x16x32_bf16 v[36:39], v[216:219], v[174:177], v[36:39]
	v_mfma_f32_16x16x32_bf16 v[32:35], v[216:219], v[182:185], v[32:35]
	v_mfma_f32_16x16x32_bf16 v[60:63], v[196:199], v[178:181], v[60:63]
	v_mfma_f32_16x16x32_bf16 v[56:59], v[196:199], v[186:189], v[56:59]
	v_mfma_f32_16x16x32_bf16 v[52:55], v[204:207], v[178:181], v[52:55]
	v_mfma_f32_16x16x32_bf16 v[48:51], v[204:207], v[186:189], v[48:51]
	v_mfma_f32_16x16x32_bf16 v[44:47], v[212:215], v[178:181], v[44:47]
	v_mfma_f32_16x16x32_bf16 v[40:43], v[212:215], v[186:189], v[40:43]
	v_mfma_f32_16x16x32_bf16 v[36:39], v[220:223], v[178:181], v[36:39]
	v_mfma_f32_16x16x32_bf16 v[32:35], v[220:223], v[186:189], v[32:35]
	s_barrier
	v_add_u32_e32 v174, s96, v140
	s_add_i32 m0, s100, 0x1c000
	s_nop 0
	global_load_lds_dwordx4 v174, s[86:87]
	v_add_u32_e32 v174, s96, v138
	s_add_i32 m0, s100, 0x1e000
	s_nop 0
	global_load_lds_dwordx4 v174, s[86:87]
	s_waitcnt vmcnt(6)
	s_barrier
	v_mfma_f32_16x16x32_bf16 v[28:31], v[190:193], v[224:227], v[28:31]
	v_mfma_f32_16x16x32_bf16 v[24:27], v[190:193], v[232:235], v[24:27]
	v_mfma_f32_16x16x32_bf16 v[20:23], v[200:203], v[224:227], v[20:23]
	v_mfma_f32_16x16x32_bf16 v[16:19], v[200:203], v[232:235], v[16:19]
	v_mfma_f32_16x16x32_bf16 v[12:15], v[208:211], v[224:227], v[12:15]
	v_mfma_f32_16x16x32_bf16 v[8:11], v[208:211], v[232:235], v[8:11]
	v_mfma_f32_16x16x32_bf16 v[4:7], v[216:219], v[224:227], v[4:7]
	v_mfma_f32_16x16x32_bf16 v[0:3], v[216:219], v[232:235], v[0:3]
	v_mfma_f32_16x16x32_bf16 v[28:31], v[196:199], v[228:231], v[28:31]
	v_mfma_f32_16x16x32_bf16 v[24:27], v[196:199], v[236:239], v[24:27]
	v_mfma_f32_16x16x32_bf16 v[20:23], v[204:207], v[228:231], v[20:23]
	v_mfma_f32_16x16x32_bf16 v[16:19], v[204:207], v[236:239], v[16:19]
	v_mfma_f32_16x16x32_bf16 v[12:15], v[212:215], v[228:231], v[12:15]
	v_mfma_f32_16x16x32_bf16 v[8:11], v[212:215], v[236:239], v[8:11]
	v_mfma_f32_16x16x32_bf16 v[4:7], v[220:223], v[228:231], v[4:7]
	v_mfma_f32_16x16x32_bf16 v[0:3], v[220:223], v[236:239], v[0:3]
	s_add_i32 s0, s0, 2
	v_lshl_add_u64 v[134:135], v[134:135], 0, s[80:81]
	v_lshl_add_u64 v[136:137], v[136:137], 0, s[80:81]
	v_lshl_add_u64 v[138:139], v[138:139], 0, s[80:81]
	s_cmp_lt_u32 s0, 4
	v_lshl_add_u64 v[140:141], v[140:141], 0, s[80:81]
	s_barrier
	s_cbranch_scc1 .LBB0_175
	v_add_u32_e32 v171, 0xc000, v143
	v_add_u32_e32 v172, 0xe000, v143
	v_add_u32_e32 v158, 0x10000, v143
	v_add_u32_e32 v159, 0x12000, v143
	v_add_u32_e32 v160, 0x2000, v143
	v_add_u32_e32 v161, 0x14000, v143
	v_add_u32_e32 v162, 0x16000, v143
	v_add_u32_e32 v163, 0x4000, v143
	v_add_u32_e32 v170, 0x6000, v143
	s_or_b32 s0, s34, 0x80
	s_ashr_i32 s1, s0, 31
	s_lshl_b64 s[0:1], s[0:1], 10
	s_add_u32 s0, s29, s0
	s_addc_u32 s1, s64, s1
	ds_read_b128 v[134:137], v157
	ds_read_b128 v[138:141], v157 offset:1024
	ds_read_b128 v[150:153], v157 offset:2048
	ds_read_b128 v[174:177], v157 offset:3072
	ds_read_b128 v[178:181], v147
	ds_read_b128 v[182:185], v147 offset:1024
	ds_read_b128 v[186:189], v146
	ds_read_b128 v[190:193], v146 offset:1024
	ds_read_b128 v[196:199], v145
	ds_read_b128 v[200:203], v145 offset:1024
	ds_read_b128 v[204:207], v144
	ds_read_b128 v[208:211], v144 offset:1024
	v_lshl_add_u64 v[156:157], v[166:167], 1, s[0:1]
	s_mov_b64 s[34:35], 0x380
	v_lshl_add_u64 v[156:157], v[156:157], 0, s[34:35]
	s_add_i32 m0, s100, 0xc000
	v_lshl_add_u64 v[132:133], v[132:133], 1, s[0:1]
	global_load_lds_dwordx4 v[156:157], off
	v_lshl_add_u64 v[132:133], v[132:133], 0, s[34:35]
	s_add_i32 m0, s100, 0xe000
	s_nop 0
	global_load_lds_dwordx4 v[132:133], off
	s_barrier
	s_waitcnt lgkmcnt(0)
	s_waitcnt lgkmcnt(0)
	v_mfma_f32_16x16x32_bf16 v[124:127], v[178:181], v[134:137], v[124:127]
	v_mfma_f32_16x16x32_bf16 v[120:123], v[178:181], v[150:153], v[120:123]
	v_mfma_f32_16x16x32_bf16 v[116:119], v[186:189], v[134:137], v[116:119]
	v_mfma_f32_16x16x32_bf16 v[108:111], v[196:199], v[134:137], v[108:111]
	v_mfma_f32_16x16x32_bf16 v[124:127], v[182:185], v[138:141], v[124:127]
	v_mfma_f32_16x16x32_bf16 v[120:123], v[182:185], v[174:177], v[120:123]
	v_mfma_f32_16x16x32_bf16 v[116:119], v[190:193], v[138:141], v[116:119]
	v_mfma_f32_16x16x32_bf16 v[112:115], v[186:189], v[150:153], v[112:115]
	v_mfma_f32_16x16x32_bf16 v[108:111], v[200:203], v[138:141], v[108:111]
	v_mfma_f32_16x16x32_bf16 v[104:107], v[196:199], v[150:153], v[104:107]
	v_mfma_f32_16x16x32_bf16 v[100:103], v[204:207], v[134:137], v[100:103]
	v_mfma_f32_16x16x32_bf16 v[96:99], v[204:207], v[150:153], v[96:99]
	v_mfma_f32_16x16x32_bf16 v[212:215], v[190:193], v[174:177], v[112:115]
	v_mfma_f32_16x16x32_bf16 v[104:107], v[200:203], v[174:177], v[104:107]
	v_mfma_f32_16x16x32_bf16 v[216:219], v[208:211], v[138:141], v[100:103]
	v_mfma_f32_16x16x32_bf16 v[220:223], v[208:211], v[174:177], v[96:99]
	s_barrier
	s_nop 1
	ds_read_b128 v[96:99], v154
	ds_read_b128 v[100:103], v154 offset:1024
	ds_read_b128 v[112:115], v154 offset:2048
	ds_read_b128 v[154:157], v154 offset:3072
	s_barrier
; #define P8_LDA(dst,b,h) _Pragma("unroll") for(int m=0;m<4;++m) _Pragma("unroll") for(int k=0;k<2;++k) \
;     dst[m][k]=*reinterpret_cast<const bf16x8*>((char*)P8_SA(b,h)+lds_byte(wr*64+m*16+fr,k*32+fq*8))
; #define P8_LDB(dst,b,h) _Pragma("unroll") for(int n=0;n<2;++n) _Pragma("unroll") for(int k=0;k<2;++k) \
;     dst[n][k]=*reinterpret_cast<const bf16x8*>((char*)P8_SB(b,h)+lds_byte(wc*32+n*16+fr,k*32+fq*8))
; #define P8_MMA(ai,bj,At,Bt) do{__builtin_amdgcn_s_setprio(1); \
;     _Pragma("unroll") for(int m=0;m<4;++m) _Pragma("unroll") for(int n=0;n<2;++n) _Pragma("unroll") for(int k=0;k<2;++k) \
;       acc[ai][bj][m][n]=__builtin_amdgcn_mfma_f32_16x16x32_bf16(At[m][k],Bt[n][k],acc[ai][bj][m][n],0,0,0); \
;     __builtin_amdgcn_s_setprio(0);}while(0)
; #define P8_WAIT_V(n) asm volatile("s_waitcnt vmcnt(" #n ")":::"memory")
; #define P8_WAIT_L(n) asm volatile("s_waitcnt lgkmcnt(" #n ")":::"memory")
; #define P8_BAR __builtin_amdgcn_s_barrier()
; template <class EPI>
; DEVI void gemm8_tile(const bfr* __restrict__ A, const bfr* __restrict__ Bt, int K, int brow, int bcol, int nbrow, int nbcol, char* shmc, EPI epi) {
;     ...
;     P8_LDB(B1,0,1); P8_BAR; P8_WAIT_L(0); P8_MMA(0,1,At,B1); P8_BAR;
;     P8_LDA(At,0,1); P8_WAIT_V(4); P8_BAR; P8_WAIT_L(0); P8_MMA(1,0,At,B0); P8_MMA(1,1,At,B1); P8_BAR; }
;   { P8_LDB(B0,1,0); P8_LDA(At,1,0); P8_WAIT_V(2); P8_BAR; P8_WAIT_L(0); P8_MMA(0,0,At,B0); P8_BAR;
	s_waitcnt lgkmcnt(0)
	s_waitcnt lgkmcnt(0)
	v_mfma_f32_16x16x32_bf16 v[88:91], v[178:181], v[112:115], v[88:91]
	v_mfma_f32_16x16x32_bf16 v[84:87], v[186:189], v[96:99], v[84:87]
	v_mfma_f32_16x16x32_bf16 v[76:79], v[196:199], v[96:99], v[76:79]
	v_mfma_f32_16x16x32_bf16 v[72:75], v[196:199], v[112:115], v[72:75]
	v_mfma_f32_16x16x32_bf16 v[92:95], v[178:181], v[96:99], v[92:95]
	v_mfma_f32_16x16x32_bf16 v[88:91], v[182:185], v[154:157], v[88:91]
	v_mfma_f32_16x16x32_bf16 v[84:87], v[190:193], v[100:103], v[84:87]
	v_mfma_f32_16x16x32_bf16 v[80:83], v[186:189], v[112:115], v[80:83]
	v_mfma_f32_16x16x32_bf16 v[76:79], v[200:203], v[100:103], v[76:79]
	v_mfma_f32_16x16x32_bf16 v[72:75], v[200:203], v[154:157], v[72:75]
	v_mfma_f32_16x16x32_bf16 v[68:71], v[204:207], v[96:99], v[68:71]
	v_mfma_f32_16x16x32_bf16 v[64:67], v[204:207], v[112:115], v[64:67]
	v_mfma_f32_16x16x32_bf16 v[224:227], v[182:185], v[100:103], v[92:95]
	v_mfma_f32_16x16x32_bf16 v[178:181], v[190:193], v[154:157], v[80:83]
	v_mfma_f32_16x16x32_bf16 v[182:185], v[208:211], v[100:103], v[68:71]
	v_mfma_f32_16x16x32_bf16 v[186:189], v[208:211], v[154:157], v[64:67]
	s_barrier
	s_nop 1
	ds_read_b128 v[64:67], v147 offset:16384
	ds_read_b128 v[68:71], v147 offset:17408
	ds_read_b128 v[80:83], v146 offset:16384
	ds_read_b128 v[92:95], v146 offset:17408
	ds_read_b128 v[190:193], v145 offset:16384
	ds_read_b128 v[196:199], v145 offset:17408
	ds_read_b128 v[200:203], v144 offset:16384
	ds_read_b128 v[204:207], v144 offset:17408
	s_waitcnt vmcnt(4)
	s_barrier
	s_waitcnt lgkmcnt(0)
	s_waitcnt lgkmcnt(0)
	v_mfma_f32_16x16x32_bf16 v[60:63], v[64:67], v[134:137], v[60:63]
	v_mfma_f32_16x16x32_bf16 v[56:59], v[64:67], v[150:153], v[56:59]
	v_mfma_f32_16x16x32_bf16 v[52:55], v[80:83], v[134:137], v[52:55]
	v_mfma_f32_16x16x32_bf16 v[40:43], v[190:193], v[150:153], v[40:43]
	v_mfma_f32_16x16x32_bf16 v[36:39], v[200:203], v[134:137], v[36:39]
	v_mfma_f32_16x16x32_bf16 v[208:211], v[68:71], v[138:141], v[60:63]
	v_mfma_f32_16x16x32_bf16 v[56:59], v[68:71], v[174:177], v[56:59]
	v_mfma_f32_16x16x32_bf16 v[52:55], v[92:95], v[138:141], v[52:55]
	v_mfma_f32_16x16x32_bf16 v[48:51], v[80:83], v[150:153], v[48:51]
	v_mfma_f32_16x16x32_bf16 v[44:47], v[190:193], v[134:137], v[44:47]
	v_mfma_f32_16x16x32_bf16 v[40:43], v[196:199], v[174:177], v[40:43]
	v_mfma_f32_16x16x32_bf16 v[36:39], v[204:207], v[138:141], v[36:39]
	v_mfma_f32_16x16x32_bf16 v[32:35], v[200:203], v[150:153], v[32:35]
	v_mfma_f32_16x16x32_bf16 v[228:231], v[92:95], v[174:177], v[48:51]
	v_mfma_f32_16x16x32_bf16 v[232:235], v[196:199], v[138:141], v[44:47]
	v_mfma_f32_16x16x32_bf16 v[132:135], v[204:207], v[174:177], v[32:35]
	s_setprio 0
	s_setprio 1
	v_mfma_f32_16x16x32_bf16 v[24:27], v[64:67], v[112:115], v[24:27]
	v_mfma_f32_16x16x32_bf16 v[20:23], v[80:83], v[96:99], v[20:23]
	v_mfma_f32_16x16x32_bf16 v[8:11], v[190:193], v[112:115], v[8:11]
	v_mfma_f32_16x16x32_bf16 v[28:31], v[64:67], v[96:99], v[28:31]
	v_mfma_f32_16x16x32_bf16 v[24:27], v[68:71], v[154:157], v[24:27]
	v_mfma_f32_16x16x32_bf16 v[20:23], v[92:95], v[100:103], v[20:23]
	v_mfma_f32_16x16x32_bf16 v[16:19], v[80:83], v[112:115], v[16:19]
	v_mfma_f32_16x16x32_bf16 v[12:15], v[190:193], v[96:99], v[12:15]
	v_mfma_f32_16x16x32_bf16 v[8:11], v[196:199], v[154:157], v[8:11]
	v_mfma_f32_16x16x32_bf16 v[4:7], v[200:203], v[96:99], v[4:7]
	v_mfma_f32_16x16x32_bf16 v[0:3], v[200:203], v[112:115], v[0:3]
	v_mfma_f32_16x16x32_bf16 v[136:139], v[68:71], v[100:103], v[28:31]
	v_mfma_f32_16x16x32_bf16 v[150:153], v[92:95], v[154:157], v[16:19]
	v_mfma_f32_16x16x32_bf16 v[172:175], v[196:199], v[100:103], v[12:15]
	v_mfma_f32_16x16x32_bf16 v[190:193], v[204:207], v[100:103], v[4:7]
	v_mfma_f32_16x16x32_bf16 v[154:157], v[204:207], v[154:157], v[0:3]
	s_barrier
	ds_read_b128 v[4:7], v149
	ds_read_b128 v[196:199], v149 offset:1024
	ds_read_b128 v[200:203], v149 offset:2048
	ds_read_b128 v[204:207], v149 offset:3072
	ds_read_b128 v[0:3], v147 offset:32768
	ds_read_b128 v[12:15], v147 offset:33792
	ds_read_b128 v[16:19], v146 offset:32768
	ds_read_b128 v[32:35], v146 offset:33792
	ds_read_b128 v[236:239], v145 offset:32768
	ds_read_b128 v[240:243], v145 offset:33792
	ds_read_b128 v[244:247], v144 offset:32768
	ds_read_b128 v[248:251], v144 offset:33792
	s_waitcnt vmcnt(2)
	s_barrier
; #define P8_LDA(dst,b,h) _Pragma("unroll") for(int m=0;m<4;++m) _Pragma("unroll") for(int k=0;k<2;++k) \
;     dst[m][k]=*reinterpret_cast<const bf16x8*>((char*)P8_SA(b,h)+lds_byte(wr*64+m*16+fr,k*32+fq*8))
; #define P8_LDB(dst,b,h) _Pragma("unroll") for(int n=0;n<2;++n) _Pragma("unroll") for(int k=0;k<2;++k) \
;     dst[n][k]=*reinterpret_cast<const bf16x8*>((char*)P8_SB(b,h)+lds_byte(wc*32+n*16+fr,k*32+fq*8))
; #define P8_MMA(ai,bj,At,Bt) do{__builtin_amdgcn_s_setprio(1); \
;     _Pragma("unroll") for(int m=0;m<4;++m) _Pragma("unroll") for(int n=0;n<2;++n) _Pragma("unroll") for(int k=0;k<2;++k) \
;       acc[ai][bj][m][n]=__builtin_amdgcn_mfma_f32_16x16x32_bf16(At[m][k],Bt[n][k],acc[ai][bj][m][n],0,0,0); \
;     __builtin_amdgcn_s_setprio(0);}while(0)
; #define P8_WAIT_V(n) asm volatile("s_waitcnt vmcnt(" #n ")":::"memory")
; #define P8_WAIT_L(n) asm volatile("s_waitcnt lgkmcnt(" #n ")":::"memory")
; #define P8_BAR __builtin_amdgcn_s_barrier()
; template <class EPI>
; DEVI void gemm8_tile(const bfr* __restrict__ A, const bfr* __restrict__ Bt, int K, int brow, int bcol, int nbrow, int nbcol, char* shmc, EPI epi) {
;     ...
;   { P8_LDB(B0,1,0); P8_LDA(At,1,0); P8_WAIT_V(2); P8_BAR; P8_WAIT_L(0); P8_MMA(0,0,At,B0); P8_BAR;
;     P8_LDB(B1,1,1); P8_WAIT_V(0); P8_BAR; P8_WAIT_L(0); P8_MMA(0,1,At,B1); P8_BAR;
;     P8_LDA(At,1,1); P8_BAR; P8_WAIT_L(0); P8_MMA(1,0,At,B0); P8_MMA(1,1,At,B1); P8_BAR; }
;   if(wr==0)P8_BAR;
	s_waitcnt lgkmcnt(0)
	s_waitcnt lgkmcnt(0)
	v_mfma_f32_16x16x32_bf16 v[28:31], v[0:3], v[4:7], v[124:127]
	v_mfma_f32_16x16x32_bf16 v[124:127], v[12:15], v[196:199], v[28:31]
	v_mfma_f32_16x16x32_bf16 v[28:31], v[0:3], v[200:203], v[120:123]
	v_mfma_f32_16x16x32_bf16 v[92:95], v[12:15], v[204:207], v[28:31]
	v_mfma_f32_16x16x32_bf16 v[28:31], v[16:19], v[4:7], v[116:119]
	v_mfma_f32_16x16x32_bf16 v[112:115], v[32:35], v[196:199], v[28:31]
	v_mfma_f32_16x16x32_bf16 v[28:31], v[16:19], v[200:203], v[212:215]
	v_mfma_f32_16x16x32_bf16 v[80:83], v[32:35], v[204:207], v[28:31]
	v_mfma_f32_16x16x32_bf16 v[28:31], v[236:239], v[4:7], v[108:111]
	v_mfma_f32_16x16x32_bf16 v[100:103], v[240:243], v[196:199], v[28:31]
	v_mfma_f32_16x16x32_bf16 v[28:31], v[236:239], v[200:203], v[104:107]
	v_mfma_f32_16x16x32_bf16 v[68:71], v[240:243], v[204:207], v[28:31]
	v_mfma_f32_16x16x32_bf16 v[28:31], v[244:247], v[4:7], v[216:219]
	v_mfma_f32_16x16x32_bf16 v[96:99], v[248:251], v[196:199], v[28:31]
	v_mfma_f32_16x16x32_bf16 v[28:31], v[244:247], v[200:203], v[220:223]
	v_mfma_f32_16x16x32_bf16 v[64:67], v[248:251], v[204:207], v[28:31]
	s_barrier
	ds_read_b128 v[212:215], v148
	ds_read_b128 v[216:219], v148 offset:1024
	ds_read_b128 v[220:223], v148 offset:2048
	ds_read_b128 v[104:107], v148 offset:3072
	s_waitcnt vmcnt(0)
	s_barrier
	s_waitcnt lgkmcnt(0)
	s_waitcnt lgkmcnt(0)
	v_mfma_f32_16x16x32_bf16 v[28:31], v[0:3], v[212:215], v[224:227]
	v_mfma_f32_16x16x32_bf16 v[0:3], v[0:3], v[220:223], v[88:91]
	v_mfma_f32_16x16x32_bf16 v[60:63], v[12:15], v[216:219], v[28:31]
	v_mfma_f32_16x16x32_bf16 v[28:31], v[12:15], v[104:107], v[0:3]
	v_mfma_f32_16x16x32_bf16 v[0:3], v[16:19], v[212:215], v[84:87]
	v_mfma_f32_16x16x32_bf16 v[48:51], v[32:35], v[216:219], v[0:3]
	v_mfma_f32_16x16x32_bf16 v[0:3], v[16:19], v[220:223], v[178:181]
	v_mfma_f32_16x16x32_bf16 v[16:19], v[32:35], v[104:107], v[0:3]
	v_mfma_f32_16x16x32_bf16 v[0:3], v[236:239], v[212:215], v[76:79]
	v_mfma_f32_16x16x32_bf16 v[44:47], v[240:243], v[216:219], v[0:3]
	v_mfma_f32_16x16x32_bf16 v[0:3], v[236:239], v[220:223], v[72:75]
	v_mfma_f32_16x16x32_bf16 v[12:15], v[240:243], v[104:107], v[0:3]
	v_mfma_f32_16x16x32_bf16 v[0:3], v[244:247], v[212:215], v[182:185]
	v_mfma_f32_16x16x32_bf16 v[32:35], v[248:251], v[216:219], v[0:3]
	v_mfma_f32_16x16x32_bf16 v[0:3], v[244:247], v[220:223], v[186:189]
	v_mfma_f32_16x16x32_bf16 v[0:3], v[248:251], v[104:107], v[0:3]
	s_barrier
	ds_read_b128 v[176:179], v147 offset:49152
	ds_read_b128 v[180:183], v147 offset:50176
	ds_read_b128 v[184:187], v146 offset:49152
	ds_read_b128 v[146:149], v146 offset:50176
	ds_read_b128 v[224:227], v145 offset:49152
	ds_read_b128 v[236:239], v145 offset:50176
	ds_read_b128 v[240:243], v144 offset:49152
	ds_read_b128 v[244:247], v144 offset:50176
	s_barrier
	s_waitcnt lgkmcnt(0)
	s_waitcnt lgkmcnt(0)
	v_mfma_f32_16x16x32_bf16 v[52:55], v[184:187], v[4:7], v[52:55]
	v_mfma_f32_16x16x32_bf16 v[116:119], v[146:149], v[196:199], v[52:55]
	v_mfma_f32_16x16x32_bf16 v[52:55], v[184:187], v[200:203], v[228:231]
	v_mfma_f32_16x16x32_bf16 v[72:75], v[176:179], v[4:7], v[208:211]
	v_mfma_f32_16x16x32_bf16 v[84:87], v[146:149], v[204:207], v[52:55]
	v_mfma_f32_16x16x32_bf16 v[52:55], v[224:227], v[4:7], v[232:235]
	v_mfma_f32_16x16x32_bf16 v[4:7], v[240:243], v[4:7], v[36:39]
	v_mfma_f32_16x16x32_bf16 v[56:59], v[176:179], v[200:203], v[56:59]
	v_mfma_f32_16x16x32_bf16 v[40:43], v[224:227], v[200:203], v[40:43]
	v_mfma_f32_16x16x32_bf16 v[108:111], v[244:247], v[196:199], v[4:7]
	v_mfma_f32_16x16x32_bf16 v[4:7], v[240:243], v[200:203], v[132:135]
	v_mfma_f32_16x16x32_bf16 v[120:123], v[180:183], v[196:199], v[72:75]
	v_mfma_f32_16x16x32_bf16 v[88:91], v[180:183], v[204:207], v[56:59]
	v_mfma_f32_16x16x32_bf16 v[208:211], v[236:239], v[196:199], v[52:55]
	v_mfma_f32_16x16x32_bf16 v[72:75], v[236:239], v[204:207], v[40:43]
	v_mfma_f32_16x16x32_bf16 v[76:79], v[244:247], v[204:207], v[4:7]
	s_setprio 0
	s_setprio 1
	v_mfma_f32_16x16x32_bf16 v[4:7], v[176:179], v[212:215], v[136:139]
	v_mfma_f32_16x16x32_bf16 v[56:59], v[180:183], v[216:219], v[4:7]
	v_mfma_f32_16x16x32_bf16 v[4:7], v[176:179], v[220:223], v[24:27]
	v_mfma_f32_16x16x32_bf16 v[24:27], v[180:183], v[104:107], v[4:7]
	v_mfma_f32_16x16x32_bf16 v[4:7], v[184:187], v[212:215], v[20:23]
	v_mfma_f32_16x16x32_bf16 v[52:55], v[146:149], v[216:219], v[4:7]
	v_mfma_f32_16x16x32_bf16 v[4:7], v[184:187], v[220:223], v[150:153]
	v_mfma_f32_16x16x32_bf16 v[20:23], v[146:149], v[104:107], v[4:7]
	v_mfma_f32_16x16x32_bf16 v[4:7], v[224:227], v[212:215], v[172:175]
	v_mfma_f32_16x16x32_bf16 v[36:39], v[236:239], v[216:219], v[4:7]
	v_mfma_f32_16x16x32_bf16 v[4:7], v[224:227], v[220:223], v[8:11]
	v_mfma_f32_16x16x32_bf16 v[8:11], v[240:243], v[212:215], v[190:193]
	v_mfma_f32_16x16x32_bf16 v[40:43], v[244:247], v[216:219], v[8:11]
	v_mfma_f32_16x16x32_bf16 v[8:11], v[240:243], v[220:223], v[154:157]
	v_mfma_f32_16x16x32_bf16 v[4:7], v[236:239], v[104:107], v[4:7]
	v_mfma_f32_16x16x32_bf16 v[8:11], v[244:247], v[104:107], v[8:11]
	s_setprio 0
	v_cmp_gt_u32_e32 vcc, s57, v142
	s_barrier
	s_and_saveexec_b64 s[0:1], vcc
	s_cbranch_execz .LBB0_178
	s_barrier

; #define P8_STAGE(P,BASE,br,kt) do{const bfr* _ub=(BASE)+((long)(br)*K+(long)(kt)*BK); \
;     __builtin_amdgcn_global_load_lds((const unsigned*)(_ub+so0),(unsigned*)((char*)(P)+wid*1024),16,0,0); \
;     __builtin_amdgcn_global_load_lds((const unsigned*)(_ub+so1),(unsigned*)((char*)(P)+wid*1024+8192),16,0,0);}while(0)
; #define P8_LDA(dst,b,h) _Pragma("unroll") for(int m=0;m<4;++m) _Pragma("unroll") for(int k=0;k<2;++k) \
;     dst[m][k]=*reinterpret_cast<const bf16x8*>((char*)P8_SA(b,h)+lds_byte(wr*64+m*16+fr,k*32+fq*8))
; #define P8_LDB(dst,b,h) _Pragma("unroll") for(int n=0;n<2;++n) _Pragma("unroll") for(int k=0;k<2;++k) \
;     dst[n][k]=*reinterpret_cast<const bf16x8*>((char*)P8_SB(b,h)+lds_byte(wc*32+n*16+fr,k*32+fq*8))
; #define P8_MMA(ai,bj,At,Bt) do{__builtin_amdgcn_s_setprio(1); \
;     _Pragma("unroll") for(int m=0;m<4;++m) _Pragma("unroll") for(int n=0;n<2;++n) _Pragma("unroll") for(int k=0;k<2;++k) \
;       acc[ai][bj][m][n]=__builtin_amdgcn_mfma_f32_16x16x32_bf16(At[m][k],Bt[n][k],acc[ai][bj][m][n],0,0,0); \
;     __builtin_amdgcn_s_setprio(0);}while(0)
; #define P8_WAIT_V(n) asm volatile("s_waitcnt vmcnt(" #n ")":::"memory")
; #define P8_WAIT_L(n) asm volatile("s_waitcnt lgkmcnt(" #n ")":::"memory")
; #define P8_BAR __builtin_amdgcn_s_barrier()
; #define P8_SCHED __builtin_amdgcn_sched_barrier(0)
; template <class EPI>
; DEVI void gemm8_tile(const bfr* __restrict__ A, const bfr* __restrict__ Bt, int K, int brow, int bcol, int nbrow, int nbcol, char* shmc, EPI epi) {
;     ...
;   for(int t=0;t<nt-2;t+=2){
;     P8_LDB(B0,0,0); P8_SCHED; P8_LDA(At,0,0); P8_STAGE(P8_SA(1,1),A,brow+128,t+1);
;     P8_WAIT_L(8); P8_BAR; P8_WAIT_L(0); P8_MMA(0,0,At,B0); P8_BAR; P8_SCHED;
;     P8_LDB(B1,0,1); P8_STAGE(P8_SB(0,0),Bt,bcol,t+2);
;     P8_BAR; P8_WAIT_L(0); P8_MMA(0,1,At,B1); P8_BAR;
;     P8_LDA(At,0,1); P8_STAGE(P8_SA(0,0),A,brow,t+2);
;     P8_BAR; P8_WAIT_L(0); P8_MMA(1,0,At,B0); P8_BAR; P8_SCHED;
;     P8_STAGE(P8_SB(0,1),Bt,bcol+128,t+2);
;     P8_WAIT_V(6); P8_BAR; P8_MMA(1,1,At,B1); P8_BAR;
.LBB0_221:
	ds_read_b128 v[174:177], v157
	ds_read_b128 v[178:181], v157 offset:1024
	ds_read_b128 v[182:185], v157 offset:2048
	ds_read_b128 v[186:189], v157 offset:3072
	v_add_u32_e32 v158, s54, v136
	s_add_i32 m0, s100, 0xc000
	ds_read_b128 v[160:163], v147
	ds_read_b128 v[190:193], v147 offset:1024
	ds_read_b128 v[196:199], v146
	ds_read_b128 v[208:211], v146 offset:1024
	ds_read_b128 v[212:215], v145
	ds_read_b128 v[216:219], v145 offset:1024
	ds_read_b128 v[220:223], v144
	ds_read_b128 v[224:227], v144 offset:1024
	global_load_lds_dwordx4 v158, s[86:87]
	v_add_u32_e32 v158, s54, v134
	s_add_i32 m0, s100, 0xe000
	s_nop 0
	global_load_lds_dwordx4 v158, s[86:87]
	s_waitcnt lgkmcnt(8)
	s_barrier
	s_waitcnt lgkmcnt(0)
	v_mfma_f32_16x16x32_bf16 v[124:127], v[160:163], v[174:177], v[124:127]
	v_mfma_f32_16x16x32_bf16 v[120:123], v[160:163], v[182:185], v[120:123]
	v_mfma_f32_16x16x32_bf16 v[116:119], v[196:199], v[174:177], v[116:119]
	v_mfma_f32_16x16x32_bf16 v[112:115], v[196:199], v[182:185], v[112:115]
	v_mfma_f32_16x16x32_bf16 v[108:111], v[212:215], v[174:177], v[108:111]
	v_mfma_f32_16x16x32_bf16 v[104:107], v[212:215], v[182:185], v[104:107]
	v_mfma_f32_16x16x32_bf16 v[100:103], v[220:223], v[174:177], v[100:103]
	v_mfma_f32_16x16x32_bf16 v[96:99], v[220:223], v[182:185], v[96:99]
	v_mfma_f32_16x16x32_bf16 v[124:127], v[190:193], v[178:181], v[124:127]
	v_mfma_f32_16x16x32_bf16 v[120:123], v[190:193], v[186:189], v[120:123]
	v_mfma_f32_16x16x32_bf16 v[116:119], v[208:211], v[178:181], v[116:119]
	v_mfma_f32_16x16x32_bf16 v[112:115], v[208:211], v[186:189], v[112:115]
	v_mfma_f32_16x16x32_bf16 v[108:111], v[216:219], v[178:181], v[108:111]
	v_mfma_f32_16x16x32_bf16 v[104:107], v[216:219], v[186:189], v[104:107]
	v_mfma_f32_16x16x32_bf16 v[100:103], v[224:227], v[178:181], v[100:103]
	v_mfma_f32_16x16x32_bf16 v[96:99], v[224:227], v[186:189], v[96:99]
	s_barrier
	v_add_u32_e32 v206, s66, v140
	s_add_i32 m0, s100, 0x10000
	ds_read_b128 v[228:231], v155
	ds_read_b128 v[232:235], v155 offset:1024
	ds_read_b128 v[236:239], v155 offset:2048
	ds_read_b128 v[240:243], v155 offset:3072
	global_load_lds_dwordx4 v206, s[86:87]
	v_add_u32_e32 v244, s66, v138
	s_add_i32 m0, s100, 0x12000
	s_nop 0
	global_load_lds_dwordx4 v244, s[86:87]
	s_barrier
	s_waitcnt lgkmcnt(0)
	v_mfma_f32_16x16x32_bf16 v[92:95], v[160:163], v[228:231], v[92:95]
	v_mfma_f32_16x16x32_bf16 v[88:91], v[160:163], v[236:239], v[88:91]
	v_mfma_f32_16x16x32_bf16 v[84:87], v[196:199], v[228:231], v[84:87]
	v_mfma_f32_16x16x32_bf16 v[80:83], v[196:199], v[236:239], v[80:83]
	v_mfma_f32_16x16x32_bf16 v[76:79], v[212:215], v[228:231], v[76:79]
	v_mfma_f32_16x16x32_bf16 v[72:75], v[212:215], v[236:239], v[72:75]
	v_mfma_f32_16x16x32_bf16 v[68:71], v[220:223], v[228:231], v[68:71]
	v_mfma_f32_16x16x32_bf16 v[64:67], v[220:223], v[236:239], v[64:67]
	v_mfma_f32_16x16x32_bf16 v[92:95], v[190:193], v[232:235], v[92:95]
	v_mfma_f32_16x16x32_bf16 v[88:91], v[190:193], v[240:243], v[88:91]
	v_mfma_f32_16x16x32_bf16 v[84:87], v[208:211], v[232:235], v[84:87]
	v_mfma_f32_16x16x32_bf16 v[80:83], v[208:211], v[240:243], v[80:83]
	v_mfma_f32_16x16x32_bf16 v[76:79], v[216:219], v[232:235], v[76:79]
	v_mfma_f32_16x16x32_bf16 v[72:75], v[216:219], v[240:243], v[72:75]
	v_mfma_f32_16x16x32_bf16 v[68:71], v[224:227], v[232:235], v[68:71]
	v_mfma_f32_16x16x32_bf16 v[64:67], v[224:227], v[240:243], v[64:67]
	v_add_u32_e32 v160, s80, v136
	s_mov_b32 m0, s100
	s_barrier
	ds_read_b128 v[190:193], v147 offset:16384
	ds_read_b128 v[196:199], v147 offset:17408
	ds_read_b128 v[208:211], v146 offset:16384
	ds_read_b128 v[212:215], v146 offset:17408
	ds_read_b128 v[216:219], v145 offset:16384
	ds_read_b128 v[220:223], v145 offset:17408
	ds_read_b128 v[224:227], v144 offset:16384
	ds_read_b128 v[244:247], v144 offset:17408
	global_load_lds_dwordx4 v160, s[86:87]
	v_add_u32_e32 v162, s80, v134
	s_add_i32 m0, s100, 0x2000
	s_nop 0
	global_load_lds_dwordx4 v162, s[86:87]
	s_barrier
	s_waitcnt lgkmcnt(0)
	v_mfma_f32_16x16x32_bf16 v[60:63], v[190:193], v[174:177], v[60:63]
	v_mfma_f32_16x16x32_bf16 v[56:59], v[190:193], v[182:185], v[56:59]
	v_mfma_f32_16x16x32_bf16 v[52:55], v[208:211], v[174:177], v[52:55]
	v_mfma_f32_16x16x32_bf16 v[48:51], v[208:211], v[182:185], v[48:51]
	v_mfma_f32_16x16x32_bf16 v[44:47], v[216:219], v[174:177], v[44:47]
	v_mfma_f32_16x16x32_bf16 v[40:43], v[216:219], v[182:185], v[40:43]
	v_mfma_f32_16x16x32_bf16 v[36:39], v[224:227], v[174:177], v[36:39]
	v_mfma_f32_16x16x32_bf16 v[32:35], v[224:227], v[182:185], v[32:35]
	v_mfma_f32_16x16x32_bf16 v[60:63], v[196:199], v[178:181], v[60:63]
	v_mfma_f32_16x16x32_bf16 v[56:59], v[196:199], v[186:189], v[56:59]
	v_mfma_f32_16x16x32_bf16 v[52:55], v[212:215], v[178:181], v[52:55]
	v_mfma_f32_16x16x32_bf16 v[48:51], v[212:215], v[186:189], v[48:51]
	v_mfma_f32_16x16x32_bf16 v[44:47], v[220:223], v[178:181], v[44:47]
	v_mfma_f32_16x16x32_bf16 v[40:43], v[220:223], v[186:189], v[40:43]
	v_mfma_f32_16x16x32_bf16 v[36:39], v[244:247], v[178:181], v[36:39]
	v_mfma_f32_16x16x32_bf16 v[32:35], v[244:247], v[186:189], v[32:35]
	s_barrier
	v_add_u32_e32 v162, s70, v140
	s_add_i32 m0, s100, 0x14000
	v_add_u32_e32 v174, s70, v138
	global_load_lds_dwordx4 v162, s[86:87]
	s_nop 0
	s_add_i32 m0, s100, 0x16000
	s_nop 0
	global_load_lds_dwordx4 v174, s[86:87]
	s_waitcnt vmcnt(6)
	s_barrier
; #define P8_STAGE(P,BASE,br,kt) do{const bfr* _ub=(BASE)+((long)(br)*K+(long)(kt)*BK); \
;     __builtin_amdgcn_global_load_lds((const unsigned*)(_ub+so0),(unsigned*)((char*)(P)+wid*1024),16,0,0); \
;     __builtin_amdgcn_global_load_lds((const unsigned*)(_ub+so1),(unsigned*)((char*)(P)+wid*1024+8192),16,0,0);}while(0)
; #define P8_LDA(dst,b,h) _Pragma("unroll") for(int m=0;m<4;++m) _Pragma("unroll") for(int k=0;k<2;++k) \
;     dst[m][k]=*reinterpret_cast<const bf16x8*>((char*)P8_SA(b,h)+lds_byte(wr*64+m*16+fr,k*32+fq*8))
; #define P8_LDB(dst,b,h) _Pragma("unroll") for(int n=0;n<2;++n) _Pragma("unroll") for(int k=0;k<2;++k) \
;     dst[n][k]=*reinterpret_cast<const bf16x8*>((char*)P8_SB(b,h)+lds_byte(wc*32+n*16+fr,k*32+fq*8))
; #define P8_MMA(ai,bj,At,Bt) do{__builtin_amdgcn_s_setprio(1); \
;     _Pragma("unroll") for(int m=0;m<4;++m) _Pragma("unroll") for(int n=0;n<2;++n) _Pragma("unroll") for(int k=0;k<2;++k) \
;       acc[ai][bj][m][n]=__builtin_amdgcn_mfma_f32_16x16x32_bf16(At[m][k],Bt[n][k],acc[ai][bj][m][n],0,0,0); \
;     __builtin_amdgcn_s_setprio(0);}while(0)
; #define P8_WAIT_V(n) asm volatile("s_waitcnt vmcnt(" #n ")":::"memory")
; #define P8_WAIT_L(n) asm volatile("s_waitcnt lgkmcnt(" #n ")":::"memory")
; #define P8_BAR __builtin_amdgcn_s_barrier()
; #define P8_SCHED __builtin_amdgcn_sched_barrier(0)
; template <class EPI>
; DEVI void gemm8_tile(const bfr* __restrict__ A, const bfr* __restrict__ Bt, int K, int brow, int bcol, int nbrow, int nbcol, char* shmc, EPI epi) {
;     ...
;     P8_WAIT_V(6); P8_BAR; P8_MMA(1,1,At,B1); P8_BAR;
;     P8_LDB(B0,1,0); P8_SCHED; P8_LDA(At,1,0); P8_STAGE(P8_SA(0,1),A,brow+128,t+2);
;     P8_WAIT_L(8); P8_BAR; P8_WAIT_L(0); P8_MMA(0,0,At,B0); P8_BAR; P8_SCHED;
;     P8_LDB(B1,1,1); P8_STAGE(P8_SB(1,0),Bt,bcol,t+3);
;     P8_BAR; P8_WAIT_L(0); P8_MMA(0,1,At,B1); P8_BAR;
;     P8_LDA(At,1,1); P8_STAGE(P8_SA(1,0),A,brow,t+3);
	v_mfma_f32_16x16x32_bf16 v[28:31], v[190:193], v[228:231], v[28:31]
	v_mfma_f32_16x16x32_bf16 v[24:27], v[190:193], v[236:239], v[24:27]
	v_mfma_f32_16x16x32_bf16 v[20:23], v[208:211], v[228:231], v[20:23]
	v_mfma_f32_16x16x32_bf16 v[16:19], v[208:211], v[236:239], v[16:19]
	v_mfma_f32_16x16x32_bf16 v[12:15], v[216:219], v[228:231], v[12:15]
	v_mfma_f32_16x16x32_bf16 v[8:11], v[216:219], v[236:239], v[8:11]
	v_mfma_f32_16x16x32_bf16 v[4:7], v[224:227], v[228:231], v[4:7]
	v_mfma_f32_16x16x32_bf16 v[0:3], v[224:227], v[236:239], v[0:3]
	v_mfma_f32_16x16x32_bf16 v[28:31], v[196:199], v[232:235], v[28:31]
	v_mfma_f32_16x16x32_bf16 v[24:27], v[196:199], v[240:243], v[24:27]
	v_mfma_f32_16x16x32_bf16 v[20:23], v[212:215], v[232:235], v[20:23]
	v_mfma_f32_16x16x32_bf16 v[16:19], v[212:215], v[240:243], v[16:19]
	v_mfma_f32_16x16x32_bf16 v[12:15], v[220:223], v[232:235], v[12:15]
	v_mfma_f32_16x16x32_bf16 v[8:11], v[220:223], v[240:243], v[8:11]
	v_mfma_f32_16x16x32_bf16 v[4:7], v[244:247], v[232:235], v[4:7]
	v_mfma_f32_16x16x32_bf16 v[0:3], v[244:247], v[240:243], v[0:3]
	s_barrier
	ds_read_b128 v[174:177], v149
	ds_read_b128 v[178:181], v149 offset:1024
	ds_read_b128 v[182:185], v149 offset:2048
	ds_read_b128 v[186:189], v149 offset:3072
	v_add_u32_e32 v232, s60, v136
	s_add_i32 m0, s100, 0x4000
	ds_read_b128 v[190:193], v147 offset:32768
	ds_read_b128 v[196:199], v147 offset:33792
	ds_read_b128 v[208:211], v146 offset:32768
	ds_read_b128 v[212:215], v146 offset:33792
	ds_read_b128 v[216:219], v145 offset:32768
	ds_read_b128 v[220:223], v145 offset:33792
	ds_read_b128 v[224:227], v144 offset:32768
	ds_read_b128 v[228:231], v144 offset:33792
	global_load_lds_dwordx4 v232, s[86:87]
	v_add_u32_e32 v232, s60, v134
	s_add_i32 m0, s100, 0x6000
	s_nop 0
	global_load_lds_dwordx4 v232, s[86:87]
	s_waitcnt lgkmcnt(8)
	s_barrier
	s_waitcnt lgkmcnt(0)
	v_mfma_f32_16x16x32_bf16 v[124:127], v[190:193], v[174:177], v[124:127]
	v_mfma_f32_16x16x32_bf16 v[120:123], v[190:193], v[182:185], v[120:123]
	v_mfma_f32_16x16x32_bf16 v[116:119], v[208:211], v[174:177], v[116:119]
	v_mfma_f32_16x16x32_bf16 v[112:115], v[208:211], v[182:185], v[112:115]
	v_mfma_f32_16x16x32_bf16 v[108:111], v[216:219], v[174:177], v[108:111]
	v_mfma_f32_16x16x32_bf16 v[104:107], v[216:219], v[182:185], v[104:107]
	v_mfma_f32_16x16x32_bf16 v[100:103], v[224:227], v[174:177], v[100:103]
	v_mfma_f32_16x16x32_bf16 v[96:99], v[224:227], v[182:185], v[96:99]
	v_mfma_f32_16x16x32_bf16 v[124:127], v[196:199], v[178:181], v[124:127]
	v_mfma_f32_16x16x32_bf16 v[120:123], v[196:199], v[186:189], v[120:123]
	v_mfma_f32_16x16x32_bf16 v[116:119], v[212:215], v[178:181], v[116:119]
	v_mfma_f32_16x16x32_bf16 v[112:115], v[212:215], v[186:189], v[112:115]
	v_mfma_f32_16x16x32_bf16 v[108:111], v[220:223], v[178:181], v[108:111]
	v_mfma_f32_16x16x32_bf16 v[104:107], v[220:223], v[186:189], v[104:107]
	v_mfma_f32_16x16x32_bf16 v[100:103], v[228:231], v[178:181], v[100:103]
	v_mfma_f32_16x16x32_bf16 v[96:99], v[228:231], v[186:189], v[96:99]
	s_barrier
	v_add_u32_e32 v248, s74, v140
	s_add_i32 m0, s100, 0x18000
	ds_read_b128 v[232:235], v148
	ds_read_b128 v[236:239], v148 offset:1024
	ds_read_b128 v[240:243], v148 offset:2048
	ds_read_b128 v[244:247], v148 offset:3072
	global_load_lds_dwordx4 v248, s[86:87]
	v_add_u32_e32 v248, s74, v138
	s_add_i32 m0, s100, 0x1a000
	s_nop 0
	global_load_lds_dwordx4 v248, s[86:87]
	s_barrier
	s_waitcnt lgkmcnt(0)
	v_mfma_f32_16x16x32_bf16 v[92:95], v[190:193], v[232:235], v[92:95]
	v_mfma_f32_16x16x32_bf16 v[88:91], v[190:193], v[240:243], v[88:91]
	v_mfma_f32_16x16x32_bf16 v[84:87], v[208:211], v[232:235], v[84:87]
	v_mfma_f32_16x16x32_bf16 v[80:83], v[208:211], v[240:243], v[80:83]
	v_mfma_f32_16x16x32_bf16 v[76:79], v[216:219], v[232:235], v[76:79]
	v_mfma_f32_16x16x32_bf16 v[72:75], v[216:219], v[240:243], v[72:75]
	v_mfma_f32_16x16x32_bf16 v[68:71], v[224:227], v[232:235], v[68:71]
	v_mfma_f32_16x16x32_bf16 v[64:67], v[224:227], v[240:243], v[64:67]
	v_mfma_f32_16x16x32_bf16 v[92:95], v[196:199], v[236:239], v[92:95]
	v_mfma_f32_16x16x32_bf16 v[88:91], v[196:199], v[244:247], v[88:91]
	v_mfma_f32_16x16x32_bf16 v[84:87], v[212:215], v[236:239], v[84:87]
	v_mfma_f32_16x16x32_bf16 v[80:83], v[212:215], v[244:247], v[80:83]
	v_mfma_f32_16x16x32_bf16 v[76:79], v[220:223], v[236:239], v[76:79]
	v_mfma_f32_16x16x32_bf16 v[72:75], v[220:223], v[244:247], v[72:75]
	v_mfma_f32_16x16x32_bf16 v[68:71], v[228:231], v[236:239], v[68:71]
	v_mfma_f32_16x16x32_bf16 v[64:67], v[228:231], v[244:247], v[64:67]
	v_add_u32_e32 v200, s72, v136
	s_add_i32 m0, s100, 0x8000
	s_barrier
	ds_read_b128 v[190:193], v147 offset:49152
	ds_read_b128 v[196:199], v147 offset:50176
	ds_read_b128 v[208:211], v146 offset:49152
	ds_read_b128 v[212:215], v146 offset:50176
	ds_read_b128 v[216:219], v145 offset:49152
	ds_read_b128 v[220:223], v145 offset:50176
	ds_read_b128 v[224:227], v144 offset:49152
	ds_read_b128 v[228:231], v144 offset:50176
	global_load_lds_dwordx4 v200, s[86:87]
	v_add_u32_e32 v200, s72, v134
	s_add_i32 m0, s100, 0xa000
	s_nop 0
	global_load_lds_dwordx4 v200, s[86:87]
	s_barrier
; #define P8_STAGE(P,BASE,br,kt) do{const bfr* _ub=(BASE)+((long)(br)*K+(long)(kt)*BK); \
;     __builtin_amdgcn_global_load_lds((const unsigned*)(_ub+so0),(unsigned*)((char*)(P)+wid*1024),16,0,0); \
;     __builtin_amdgcn_global_load_lds((const unsigned*)(_ub+so1),(unsigned*)((char*)(P)+wid*1024+8192),16,0,0);}while(0)
; #define P8_LDA(dst,b,h) _Pragma("unroll") for(int m=0;m<4;++m) _Pragma("unroll") for(int k=0;k<2;++k) \
;     dst[m][k]=*reinterpret_cast<const bf16x8*>((char*)P8_SA(b,h)+lds_byte(wr*64+m*16+fr,k*32+fq*8))
; #define P8_LDB(dst,b,h) _Pragma("unroll") for(int n=0;n<2;++n) _Pragma("unroll") for(int k=0;k<2;++k) \
;     dst[n][k]=*reinterpret_cast<const bf16x8*>((char*)P8_SB(b,h)+lds_byte(wc*32+n*16+fr,k*32+fq*8))
; #define P8_MMA(ai,bj,At,Bt) do{__builtin_amdgcn_s_setprio(1); \
;     _Pragma("unroll") for(int m=0;m<4;++m) _Pragma("unroll") for(int n=0;n<2;++n) _Pragma("unroll") for(int k=0;k<2;++k) \
;       acc[ai][bj][m][n]=__builtin_amdgcn_mfma_f32_16x16x32_bf16(At[m][k],Bt[n][k],acc[ai][bj][m][n],0,0,0); \
;     __builtin_amdgcn_s_setprio(0);}while(0)
; #define P8_WAIT_V(n) asm volatile("s_waitcnt vmcnt(" #n ")":::"memory")
; #define P8_WAIT_L(n) asm volatile("s_waitcnt lgkmcnt(" #n ")":::"memory")
; #define P8_BAR __builtin_amdgcn_s_barrier()
; #define P8_SCHED __builtin_amdgcn_sched_barrier(0)
; template <class EPI>
; DEVI void gemm8_tile(const bfr* __restrict__ A, const bfr* __restrict__ Bt, int K, int brow, int bcol, int nbrow, int nbcol, char* shmc, EPI epi) {
;     ...
;     P8_BAR; P8_WAIT_L(0); P8_MMA(1,0,At,B0); P8_BAR; P8_SCHED;
;     P8_STAGE(P8_SB(1,1),Bt,bcol+128,t+3);
;     P8_WAIT_V(6); P8_BAR; P8_MMA(1,1,At,B1); P8_BAR;
;   }
;   { P8_LDB(B0,0,0); P8_LDA(At,0,0); P8_STAGE(P8_SA(1,1),A,brow+128,nt-1);
;     P8_BAR; P8_WAIT_L(0); P8_MMA(0,0,At,B0); P8_BAR;
;     P8_LDB(B1,0,1); P8_BAR; P8_WAIT_L(0); P8_MMA(0,1,At,B1); P8_BAR;
	s_waitcnt lgkmcnt(0)
	v_mfma_f32_16x16x32_bf16 v[60:63], v[190:193], v[174:177], v[60:63]
	v_mfma_f32_16x16x32_bf16 v[56:59], v[190:193], v[182:185], v[56:59]
	v_mfma_f32_16x16x32_bf16 v[52:55], v[208:211], v[174:177], v[52:55]
	v_mfma_f32_16x16x32_bf16 v[48:51], v[208:211], v[182:185], v[48:51]
	v_mfma_f32_16x16x32_bf16 v[44:47], v[216:219], v[174:177], v[44:47]
	v_mfma_f32_16x16x32_bf16 v[40:43], v[216:219], v[182:185], v[40:43]
	v_mfma_f32_16x16x32_bf16 v[36:39], v[224:227], v[174:177], v[36:39]
	v_mfma_f32_16x16x32_bf16 v[32:35], v[224:227], v[182:185], v[32:35]
	v_mfma_f32_16x16x32_bf16 v[60:63], v[196:199], v[178:181], v[60:63]
	v_mfma_f32_16x16x32_bf16 v[56:59], v[196:199], v[186:189], v[56:59]
	v_mfma_f32_16x16x32_bf16 v[52:55], v[212:215], v[178:181], v[52:55]
	v_mfma_f32_16x16x32_bf16 v[48:51], v[212:215], v[186:189], v[48:51]
	v_mfma_f32_16x16x32_bf16 v[44:47], v[220:223], v[178:181], v[44:47]
	v_mfma_f32_16x16x32_bf16 v[40:43], v[220:223], v[186:189], v[40:43]
	v_mfma_f32_16x16x32_bf16 v[36:39], v[228:231], v[178:181], v[36:39]
	v_mfma_f32_16x16x32_bf16 v[32:35], v[228:231], v[186:189], v[32:35]
	s_barrier
	v_add_u32_e32 v174, s78, v140
	s_add_i32 m0, s100, 0x1c000
	s_nop 0
	global_load_lds_dwordx4 v174, s[86:87]
	v_add_u32_e32 v174, s78, v138
	s_add_i32 m0, s100, 0x1e000
	s_nop 0
	global_load_lds_dwordx4 v174, s[86:87]
	s_waitcnt vmcnt(6)
	s_barrier
	v_mfma_f32_16x16x32_bf16 v[28:31], v[190:193], v[232:235], v[28:31]
	v_mfma_f32_16x16x32_bf16 v[24:27], v[190:193], v[240:243], v[24:27]
	v_mfma_f32_16x16x32_bf16 v[20:23], v[208:211], v[232:235], v[20:23]
	v_mfma_f32_16x16x32_bf16 v[16:19], v[208:211], v[240:243], v[16:19]
	v_mfma_f32_16x16x32_bf16 v[12:15], v[216:219], v[232:235], v[12:15]
	v_mfma_f32_16x16x32_bf16 v[8:11], v[216:219], v[240:243], v[8:11]
	v_mfma_f32_16x16x32_bf16 v[4:7], v[224:227], v[232:235], v[4:7]
	v_mfma_f32_16x16x32_bf16 v[0:3], v[224:227], v[240:243], v[0:3]
	v_mfma_f32_16x16x32_bf16 v[28:31], v[196:199], v[236:239], v[28:31]
	v_mfma_f32_16x16x32_bf16 v[24:27], v[196:199], v[244:247], v[24:27]
	v_mfma_f32_16x16x32_bf16 v[20:23], v[212:215], v[236:239], v[20:23]
	v_mfma_f32_16x16x32_bf16 v[16:19], v[212:215], v[244:247], v[16:19]
	v_mfma_f32_16x16x32_bf16 v[12:15], v[220:223], v[236:239], v[12:15]
	v_mfma_f32_16x16x32_bf16 v[8:11], v[220:223], v[244:247], v[8:11]
	v_mfma_f32_16x16x32_bf16 v[4:7], v[228:231], v[236:239], v[4:7]
	v_mfma_f32_16x16x32_bf16 v[0:3], v[228:231], v[244:247], v[0:3]
	s_add_i32 s0, s0, 2
	v_lshl_add_u64 v[134:135], v[134:135], 0, s[80:81]
	v_lshl_add_u64 v[136:137], v[136:137], 0, s[80:81]
	v_lshl_add_u64 v[138:139], v[138:139], 0, s[80:81]
	s_cmp_lt_u32 s0, 28
	v_lshl_add_u64 v[140:141], v[140:141], 0, s[80:81]
	s_barrier
	s_cbranch_scc1 .LBB0_221
	v_add_u32_e32 v171, 0xc000, v143
	v_add_u32_e32 v172, 0xe000, v143
	v_add_u32_e32 v158, 0x10000, v143
	v_add_u32_e32 v159, 0x12000, v143
	v_add_u32_e32 v160, 0x2000, v143
	v_add_u32_e32 v161, 0x14000, v143
	v_add_u32_e32 v162, 0x16000, v143
	v_add_u32_e32 v163, 0x4000, v143
	v_add_u32_e32 v170, 0x6000, v143
	s_or_b32 s0, s8, 0x80
	s_ashr_i32 s1, s0, 31
	s_lshl_b64 s[0:1], s[0:1], 12
	s_add_u32 s0, s34, s0
	s_addc_u32 s1, s35, s1
	ds_read_b128 v[134:137], v157
	ds_read_b128 v[138:141], v157 offset:1024
	ds_read_b128 v[150:153], v157 offset:2048
	ds_read_b128 v[174:177], v157 offset:3072
	ds_read_b128 v[178:181], v147
	ds_read_b128 v[182:185], v147 offset:1024
	ds_read_b128 v[186:189], v146
	ds_read_b128 v[190:193], v146 offset:1024
	ds_read_b128 v[196:199], v145
	ds_read_b128 v[208:211], v145 offset:1024
	ds_read_b128 v[212:215], v144
	ds_read_b128 v[216:219], v144 offset:1024
	v_lshl_add_u64 v[156:157], v[166:167], 1, s[0:1]
	s_mov_b64 s[54:55], 0xf80
	v_lshl_add_u64 v[156:157], v[156:157], 0, s[54:55]
	s_add_i32 m0, s100, 0xc000
	v_lshl_add_u64 v[132:133], v[132:133], 1, s[0:1]
	global_load_lds_dwordx4 v[156:157], off
	v_lshl_add_u64 v[132:133], v[132:133], 0, s[54:55]
	s_add_i32 m0, s100, 0xe000
	s_nop 0
	global_load_lds_dwordx4 v[132:133], off
	s_barrier
	s_waitcnt lgkmcnt(0)
	s_waitcnt lgkmcnt(0)
	v_mfma_f32_16x16x32_bf16 v[124:127], v[178:181], v[134:137], v[124:127]
	v_mfma_f32_16x16x32_bf16 v[120:123], v[178:181], v[150:153], v[120:123]
	v_mfma_f32_16x16x32_bf16 v[116:119], v[186:189], v[134:137], v[116:119]
	v_mfma_f32_16x16x32_bf16 v[112:115], v[186:189], v[150:153], v[112:115]
	v_mfma_f32_16x16x32_bf16 v[96:99], v[212:215], v[150:153], v[96:99]
	v_mfma_f32_16x16x32_bf16 v[124:127], v[182:185], v[138:141], v[124:127]
	v_mfma_f32_16x16x32_bf16 v[120:123], v[182:185], v[174:177], v[120:123]
	v_mfma_f32_16x16x32_bf16 v[116:119], v[190:193], v[138:141], v[116:119]
	v_mfma_f32_16x16x32_bf16 v[112:115], v[190:193], v[174:177], v[112:115]
	v_mfma_f32_16x16x32_bf16 v[108:111], v[196:199], v[134:137], v[108:111]
	v_mfma_f32_16x16x32_bf16 v[104:107], v[196:199], v[150:153], v[104:107]
	v_mfma_f32_16x16x32_bf16 v[100:103], v[212:215], v[134:137], v[100:103]
	v_mfma_f32_16x16x32_bf16 v[96:99], v[216:219], v[174:177], v[96:99]
	v_mfma_f32_16x16x32_bf16 v[220:223], v[208:211], v[138:141], v[108:111]
	v_mfma_f32_16x16x32_bf16 v[224:227], v[208:211], v[174:177], v[104:107]
	v_mfma_f32_16x16x32_bf16 v[228:231], v[216:219], v[138:141], v[100:103]
	s_barrier
	s_nop 1
	ds_read_b128 v[100:103], v155
	ds_read_b128 v[104:107], v155 offset:1024
	ds_read_b128 v[108:111], v155 offset:2048
	ds_read_b128 v[154:157], v155 offset:3072
	s_barrier
; #define P8_LDA(dst,b,h) _Pragma("unroll") for(int m=0;m<4;++m) _Pragma("unroll") for(int k=0;k<2;++k) \
;     dst[m][k]=*reinterpret_cast<const bf16x8*>((char*)P8_SA(b,h)+lds_byte(wr*64+m*16+fr,k*32+fq*8))
; #define P8_LDB(dst,b,h) _Pragma("unroll") for(int n=0;n<2;++n) _Pragma("unroll") for(int k=0;k<2;++k) \
;     dst[n][k]=*reinterpret_cast<const bf16x8*>((char*)P8_SB(b,h)+lds_byte(wc*32+n*16+fr,k*32+fq*8))
; #define P8_MMA(ai,bj,At,Bt) do{__builtin_amdgcn_s_setprio(1); \
;     _Pragma("unroll") for(int m=0;m<4;++m) _Pragma("unroll") for(int n=0;n<2;++n) _Pragma("unroll") for(int k=0;k<2;++k) \
;       acc[ai][bj][m][n]=__builtin_amdgcn_mfma_f32_16x16x32_bf16(At[m][k],Bt[n][k],acc[ai][bj][m][n],0,0,0); \
;     __builtin_amdgcn_s_setprio(0);}while(0)
; #define P8_WAIT_V(n) asm volatile("s_waitcnt vmcnt(" #n ")":::"memory")
; #define P8_WAIT_L(n) asm volatile("s_waitcnt lgkmcnt(" #n ")":::"memory")
; #define P8_BAR __builtin_amdgcn_s_barrier()
; template <class EPI>
; DEVI void gemm8_tile(const bfr* __restrict__ A, const bfr* __restrict__ Bt, int K, int brow, int bcol, int nbrow, int nbcol, char* shmc, EPI epi) {
;     ...
;     P8_LDB(B1,0,1); P8_BAR; P8_WAIT_L(0); P8_MMA(0,1,At,B1); P8_BAR;
;     P8_LDA(At,0,1); P8_WAIT_V(4); P8_BAR; P8_WAIT_L(0); P8_MMA(1,0,At,B0); P8_MMA(1,1,At,B1); P8_BAR; }
;   { P8_LDB(B0,1,0); P8_LDA(At,1,0); P8_WAIT_V(2); P8_BAR; P8_WAIT_L(0); P8_MMA(0,0,At,B0); P8_BAR;
	s_waitcnt lgkmcnt(0)
	s_waitcnt lgkmcnt(0)
	v_mfma_f32_16x16x32_bf16 v[92:95], v[178:181], v[100:103], v[92:95]
	v_mfma_f32_16x16x32_bf16 v[88:91], v[178:181], v[108:111], v[88:91]
	v_mfma_f32_16x16x32_bf16 v[84:87], v[186:189], v[100:103], v[84:87]
	v_mfma_f32_16x16x32_bf16 v[80:83], v[186:189], v[108:111], v[80:83]
	v_mfma_f32_16x16x32_bf16 v[64:67], v[212:215], v[108:111], v[64:67]
	v_mfma_f32_16x16x32_bf16 v[92:95], v[182:185], v[104:107], v[92:95]
	v_mfma_f32_16x16x32_bf16 v[88:91], v[182:185], v[154:157], v[88:91]
	v_mfma_f32_16x16x32_bf16 v[84:87], v[190:193], v[104:107], v[84:87]
	v_mfma_f32_16x16x32_bf16 v[80:83], v[190:193], v[154:157], v[80:83]
	v_mfma_f32_16x16x32_bf16 v[76:79], v[196:199], v[100:103], v[76:79]
	v_mfma_f32_16x16x32_bf16 v[72:75], v[196:199], v[108:111], v[72:75]
	v_mfma_f32_16x16x32_bf16 v[68:71], v[212:215], v[100:103], v[68:71]
	v_mfma_f32_16x16x32_bf16 v[64:67], v[216:219], v[154:157], v[64:67]
	v_mfma_f32_16x16x32_bf16 v[178:181], v[208:211], v[104:107], v[76:79]
	v_mfma_f32_16x16x32_bf16 v[182:185], v[208:211], v[154:157], v[72:75]
	v_mfma_f32_16x16x32_bf16 v[186:189], v[216:219], v[104:107], v[68:71]
	s_barrier
	s_nop 1
	ds_read_b128 v[68:71], v147 offset:16384
	ds_read_b128 v[72:75], v147 offset:17408
	ds_read_b128 v[76:79], v146 offset:16384
	ds_read_b128 v[190:193], v146 offset:17408
	ds_read_b128 v[196:199], v145 offset:16384
	ds_read_b128 v[208:211], v145 offset:17408
	ds_read_b128 v[212:215], v144 offset:16384
	ds_read_b128 v[216:219], v144 offset:17408
	s_waitcnt vmcnt(4)
	s_barrier
	s_waitcnt lgkmcnt(0)
	s_waitcnt lgkmcnt(0)
	v_mfma_f32_16x16x32_bf16 v[60:63], v[68:71], v[134:137], v[60:63]
	v_mfma_f32_16x16x32_bf16 v[56:59], v[68:71], v[150:153], v[56:59]
	v_mfma_f32_16x16x32_bf16 v[52:55], v[76:79], v[134:137], v[52:55]
	v_mfma_f32_16x16x32_bf16 v[48:51], v[76:79], v[150:153], v[48:51]
	v_mfma_f32_16x16x32_bf16 v[32:35], v[212:215], v[150:153], v[32:35]
	v_mfma_f32_16x16x32_bf16 v[60:63], v[72:75], v[138:141], v[60:63]
	v_mfma_f32_16x16x32_bf16 v[56:59], v[72:75], v[174:177], v[56:59]
	v_mfma_f32_16x16x32_bf16 v[52:55], v[190:193], v[138:141], v[52:55]
	v_mfma_f32_16x16x32_bf16 v[48:51], v[190:193], v[174:177], v[48:51]
	v_mfma_f32_16x16x32_bf16 v[44:47], v[196:199], v[134:137], v[44:47]
	v_mfma_f32_16x16x32_bf16 v[40:43], v[196:199], v[150:153], v[40:43]
	v_mfma_f32_16x16x32_bf16 v[36:39], v[212:215], v[134:137], v[36:39]
	v_mfma_f32_16x16x32_bf16 v[32:35], v[216:219], v[174:177], v[32:35]
	v_mfma_f32_16x16x32_bf16 v[232:235], v[208:211], v[138:141], v[44:47]
	v_mfma_f32_16x16x32_bf16 v[236:239], v[208:211], v[174:177], v[40:43]
	v_mfma_f32_16x16x32_bf16 v[132:135], v[216:219], v[138:141], v[36:39]
	s_setprio 0
	s_setprio 1
	v_mfma_f32_16x16x32_bf16 v[28:31], v[68:71], v[100:103], v[28:31]
	v_mfma_f32_16x16x32_bf16 v[24:27], v[68:71], v[108:111], v[24:27]
	v_mfma_f32_16x16x32_bf16 v[20:23], v[76:79], v[100:103], v[20:23]
	v_mfma_f32_16x16x32_bf16 v[16:19], v[76:79], v[108:111], v[16:19]
	v_mfma_f32_16x16x32_bf16 v[0:3], v[212:215], v[108:111], v[0:3]
	v_mfma_f32_16x16x32_bf16 v[28:31], v[72:75], v[104:107], v[28:31]
	v_mfma_f32_16x16x32_bf16 v[24:27], v[72:75], v[154:157], v[24:27]
	v_mfma_f32_16x16x32_bf16 v[20:23], v[190:193], v[104:107], v[20:23]
	v_mfma_f32_16x16x32_bf16 v[16:19], v[190:193], v[154:157], v[16:19]
	v_mfma_f32_16x16x32_bf16 v[12:15], v[196:199], v[100:103], v[12:15]
	v_mfma_f32_16x16x32_bf16 v[8:11], v[196:199], v[108:111], v[8:11]
	v_mfma_f32_16x16x32_bf16 v[4:7], v[212:215], v[100:103], v[4:7]
	v_mfma_f32_16x16x32_bf16 v[0:3], v[216:219], v[154:157], v[0:3]
	v_mfma_f32_16x16x32_bf16 v[136:139], v[208:211], v[104:107], v[12:15]
	v_mfma_f32_16x16x32_bf16 v[150:153], v[208:211], v[154:157], v[8:11]
	v_mfma_f32_16x16x32_bf16 v[172:175], v[216:219], v[104:107], v[4:7]
	s_barrier
	s_nop 1
	ds_read_b128 v[4:7], v149
	ds_read_b128 v[8:11], v149 offset:1024
	ds_read_b128 v[12:15], v149 offset:2048
	ds_read_b128 v[154:157], v149 offset:3072
	ds_read_b128 v[36:39], v147 offset:32768
	ds_read_b128 v[40:43], v147 offset:33792
	ds_read_b128 v[44:47], v146 offset:32768
	ds_read_b128 v[68:71], v146 offset:33792
	ds_read_b128 v[190:193], v145 offset:32768
	ds_read_b128 v[196:199], v145 offset:33792
	ds_read_b128 v[208:211], v144 offset:32768
	ds_read_b128 v[212:215], v144 offset:33792
	s_waitcnt vmcnt(2)
	s_barrier
; #define P8_LDA(dst,b,h) _Pragma("unroll") for(int m=0;m<4;++m) _Pragma("unroll") for(int k=0;k<2;++k) \
;     dst[m][k]=*reinterpret_cast<const bf16x8*>((char*)P8_SA(b,h)+lds_byte(wr*64+m*16+fr,k*32+fq*8))
; #define P8_LDB(dst,b,h) _Pragma("unroll") for(int n=0;n<2;++n) _Pragma("unroll") for(int k=0;k<2;++k) \
;     dst[n][k]=*reinterpret_cast<const bf16x8*>((char*)P8_SB(b,h)+lds_byte(wc*32+n*16+fr,k*32+fq*8))
; #define P8_MMA(ai,bj,At,Bt) do{__builtin_amdgcn_s_setprio(1); \
;     _Pragma("unroll") for(int m=0;m<4;++m) _Pragma("unroll") for(int n=0;n<2;++n) _Pragma("unroll") for(int k=0;k<2;++k) \
;       acc[ai][bj][m][n]=__builtin_amdgcn_mfma_f32_16x16x32_bf16(At[m][k],Bt[n][k],acc[ai][bj][m][n],0,0,0); \
;     __builtin_amdgcn_s_setprio(0);}while(0)
; #define P8_WAIT_V(n) asm volatile("s_waitcnt vmcnt(" #n ")":::"memory")
; #define P8_WAIT_L(n) asm volatile("s_waitcnt lgkmcnt(" #n ")":::"memory")
; #define P8_BAR __builtin_amdgcn_s_barrier()
; template <class EPI>
; DEVI void gemm8_tile(const bfr* __restrict__ A, const bfr* __restrict__ Bt, int K, int brow, int bcol, int nbrow, int nbcol, char* shmc, EPI epi) {
;     ...
;   { P8_LDB(B0,1,0); P8_LDA(At,1,0); P8_WAIT_V(2); P8_BAR; P8_WAIT_L(0); P8_MMA(0,0,At,B0); P8_BAR;
;     P8_LDB(B1,1,1); P8_WAIT_V(0); P8_BAR; P8_WAIT_L(0); P8_MMA(0,1,At,B1); P8_BAR;
;     P8_LDA(At,1,1); P8_BAR; P8_WAIT_L(0); P8_MMA(1,0,At,B0); P8_MMA(1,1,At,B1); P8_BAR; }
;   if(wr==0)P8_BAR;
	s_waitcnt lgkmcnt(0)
	s_waitcnt lgkmcnt(0)
	v_mfma_f32_16x16x32_bf16 v[72:75], v[36:39], v[4:7], v[124:127]
	v_mfma_f32_16x16x32_bf16 v[124:127], v[40:43], v[8:11], v[72:75]
	v_mfma_f32_16x16x32_bf16 v[72:75], v[36:39], v[12:15], v[120:123]
	v_mfma_f32_16x16x32_bf16 v[108:111], v[40:43], v[154:157], v[72:75]
	v_mfma_f32_16x16x32_bf16 v[72:75], v[44:47], v[4:7], v[116:119]
	v_mfma_f32_16x16x32_bf16 v[120:123], v[68:71], v[8:11], v[72:75]
	v_mfma_f32_16x16x32_bf16 v[72:75], v[44:47], v[12:15], v[112:115]
	v_mfma_f32_16x16x32_bf16 v[104:107], v[68:71], v[154:157], v[72:75]
	v_mfma_f32_16x16x32_bf16 v[72:75], v[190:193], v[4:7], v[220:223]
	v_mfma_f32_16x16x32_bf16 v[116:119], v[196:199], v[8:11], v[72:75]
	v_mfma_f32_16x16x32_bf16 v[72:75], v[190:193], v[12:15], v[224:227]
	v_mfma_f32_16x16x32_bf16 v[100:103], v[196:199], v[154:157], v[72:75]
	v_mfma_f32_16x16x32_bf16 v[72:75], v[208:211], v[4:7], v[228:231]
	v_mfma_f32_16x16x32_bf16 v[112:115], v[212:215], v[8:11], v[72:75]
	v_mfma_f32_16x16x32_bf16 v[72:75], v[208:211], v[12:15], v[96:99]
	v_mfma_f32_16x16x32_bf16 v[96:99], v[212:215], v[154:157], v[72:75]
	s_barrier
	ds_read_b128 v[216:219], v148
	ds_read_b128 v[220:223], v148 offset:1024
	ds_read_b128 v[224:227], v148 offset:2048
	ds_read_b128 v[228:231], v148 offset:3072
	s_waitcnt vmcnt(0)
	s_barrier
	s_waitcnt lgkmcnt(0)
	s_waitcnt lgkmcnt(0)
	v_mfma_f32_16x16x32_bf16 v[72:75], v[36:39], v[216:219], v[92:95]
	v_mfma_f32_16x16x32_bf16 v[36:39], v[36:39], v[224:227], v[88:91]
	v_mfma_f32_16x16x32_bf16 v[76:79], v[40:43], v[228:231], v[36:39]
	v_mfma_f32_16x16x32_bf16 v[36:39], v[44:47], v[216:219], v[84:87]
	v_mfma_f32_16x16x32_bf16 v[88:91], v[68:71], v[220:223], v[36:39]
	v_mfma_f32_16x16x32_bf16 v[36:39], v[44:47], v[224:227], v[80:83]
	v_mfma_f32_16x16x32_bf16 v[92:95], v[40:43], v[220:223], v[72:75]
	v_mfma_f32_16x16x32_bf16 v[72:75], v[68:71], v[228:231], v[36:39]
	v_mfma_f32_16x16x32_bf16 v[36:39], v[190:193], v[216:219], v[178:181]
	v_mfma_f32_16x16x32_bf16 v[84:87], v[196:199], v[220:223], v[36:39]
	v_mfma_f32_16x16x32_bf16 v[36:39], v[190:193], v[224:227], v[182:185]
	v_mfma_f32_16x16x32_bf16 v[68:71], v[196:199], v[228:231], v[36:39]
	v_mfma_f32_16x16x32_bf16 v[36:39], v[208:211], v[216:219], v[186:189]
	v_mfma_f32_16x16x32_bf16 v[80:83], v[212:215], v[220:223], v[36:39]
	v_mfma_f32_16x16x32_bf16 v[36:39], v[208:211], v[224:227], v[64:67]
	v_mfma_f32_16x16x32_bf16 v[64:67], v[212:215], v[228:231], v[36:39]
	s_barrier
	ds_read_b128 v[176:179], v147 offset:49152
	ds_read_b128 v[180:183], v147 offset:50176
	ds_read_b128 v[184:187], v146 offset:49152
	ds_read_b128 v[146:149], v146 offset:50176
	ds_read_b128 v[188:191], v145 offset:49152
	ds_read_b128 v[196:199], v145 offset:50176
	ds_read_b128 v[208:211], v144 offset:49152
	ds_read_b128 v[212:215], v144 offset:50176
	s_barrier
	s_waitcnt lgkmcnt(0)
	s_waitcnt lgkmcnt(0)
	v_mfma_f32_16x16x32_bf16 v[36:39], v[176:179], v[4:7], v[60:63]
	v_mfma_f32_16x16x32_bf16 v[60:63], v[180:183], v[8:11], v[36:39]
	v_mfma_f32_16x16x32_bf16 v[36:39], v[176:179], v[12:15], v[56:59]
	v_mfma_f32_16x16x32_bf16 v[44:47], v[180:183], v[154:157], v[36:39]
	v_mfma_f32_16x16x32_bf16 v[36:39], v[184:187], v[4:7], v[52:55]
	v_mfma_f32_16x16x32_bf16 v[56:59], v[146:149], v[8:11], v[36:39]
	v_mfma_f32_16x16x32_bf16 v[36:39], v[184:187], v[12:15], v[48:51]
	v_mfma_f32_16x16x32_bf16 v[40:43], v[146:149], v[154:157], v[36:39]
	v_mfma_f32_16x16x32_bf16 v[36:39], v[188:191], v[4:7], v[232:235]
	v_mfma_f32_16x16x32_bf16 v[4:7], v[208:211], v[4:7], v[132:135]
	v_mfma_f32_16x16x32_bf16 v[52:55], v[196:199], v[8:11], v[36:39]
	v_mfma_f32_16x16x32_bf16 v[36:39], v[188:191], v[12:15], v[236:239]
	v_mfma_f32_16x16x32_bf16 v[48:51], v[212:215], v[8:11], v[4:7]
	v_mfma_f32_16x16x32_bf16 v[4:7], v[208:211], v[12:15], v[32:35]
	v_mfma_f32_16x16x32_bf16 v[36:39], v[196:199], v[154:157], v[36:39]
	v_mfma_f32_16x16x32_bf16 v[32:35], v[212:215], v[154:157], v[4:7]
	s_setprio 0
	s_setprio 1
	v_mfma_f32_16x16x32_bf16 v[4:7], v[176:179], v[216:219], v[28:31]
	v_mfma_f32_16x16x32_bf16 v[28:31], v[180:183], v[220:223], v[4:7]
	v_mfma_f32_16x16x32_bf16 v[4:7], v[176:179], v[224:227], v[24:27]
	v_mfma_f32_16x16x32_bf16 v[12:15], v[180:183], v[228:231], v[4:7]
	v_mfma_f32_16x16x32_bf16 v[4:7], v[184:187], v[216:219], v[20:23]
	v_mfma_f32_16x16x32_bf16 v[24:27], v[146:149], v[220:223], v[4:7]
	v_mfma_f32_16x16x32_bf16 v[4:7], v[184:187], v[224:227], v[16:19]
	v_mfma_f32_16x16x32_bf16 v[8:11], v[146:149], v[228:231], v[4:7]
	v_mfma_f32_16x16x32_bf16 v[4:7], v[188:191], v[216:219], v[136:139]
	v_mfma_f32_16x16x32_bf16 v[20:23], v[196:199], v[220:223], v[4:7]
	v_mfma_f32_16x16x32_bf16 v[4:7], v[188:191], v[224:227], v[150:153]
	v_mfma_f32_16x16x32_bf16 v[16:19], v[208:211], v[216:219], v[172:175]
	v_mfma_f32_16x16x32_bf16 v[0:3], v[208:211], v[224:227], v[0:3]
	v_mfma_f32_16x16x32_bf16 v[4:7], v[196:199], v[228:231], v[4:7]
	v_mfma_f32_16x16x32_bf16 v[16:19], v[212:215], v[220:223], v[16:19]
	v_mfma_f32_16x16x32_bf16 v[0:3], v[212:215], v[228:231], v[0:3]
	s_setprio 0
	v_cmp_gt_u32_e32 vcc, s57, v142
	s_barrier
	s_and_saveexec_b64 s[0:1], vcc
	s_cbranch_execz .LBB0_224
	s_barrier

; #define P8_STAGE(P,BASE,br,kt) do{const bfr* _ub=(BASE)+((long)(br)*K+(long)(kt)*BK); \
;     __builtin_amdgcn_global_load_lds((const unsigned*)(_ub+so0),(unsigned*)((char*)(P)+wid*1024),16,0,0); \
;     __builtin_amdgcn_global_load_lds((const unsigned*)(_ub+so1),(unsigned*)((char*)(P)+wid*1024+8192),16,0,0);}while(0)
; #define P8_LDA(dst,b,h) _Pragma("unroll") for(int m=0;m<4;++m) _Pragma("unroll") for(int k=0;k<2;++k) \
;     dst[m][k]=*reinterpret_cast<const bf16x8*>((char*)P8_SA(b,h)+lds_byte(wr*64+m*16+fr,k*32+fq*8))
; #define P8_LDB(dst,b,h) _Pragma("unroll") for(int n=0;n<2;++n) _Pragma("unroll") for(int k=0;k<2;++k) \
;     dst[n][k]=*reinterpret_cast<const bf16x8*>((char*)P8_SB(b,h)+lds_byte(wc*32+n*16+fr,k*32+fq*8))
; #define P8_MMA(ai,bj,At,Bt) do{__builtin_amdgcn_s_setprio(1); \
;     _Pragma("unroll") for(int m=0;m<4;++m) _Pragma("unroll") for(int n=0;n<2;++n) _Pragma("unroll") for(int k=0;k<2;++k) \
;       acc[ai][bj][m][n]=__builtin_amdgcn_mfma_f32_16x16x32_bf16(At[m][k],Bt[n][k],acc[ai][bj][m][n],0,0,0); \
;     __builtin_amdgcn_s_setprio(0);}while(0)
; #define P8_WAIT_V(n) asm volatile("s_waitcnt vmcnt(" #n ")":::"memory")
; #define P8_WAIT_L(n) asm volatile("s_waitcnt lgkmcnt(" #n ")":::"memory")
; #define P8_BAR __builtin_amdgcn_s_barrier()
; #define P8_SCHED __builtin_amdgcn_sched_barrier(0)
; template <class EPI>
; DEVI void gemm8_tile(const bfr* __restrict__ A, const bfr* __restrict__ Bt, int K, int brow, int bcol, int nbrow, int nbcol, char* shmc, EPI epi) {
;     ...
;     P8_LDB(B0,0,0); P8_SCHED; P8_LDA(At,0,0); P8_STAGE(P8_SA(1,1),A,brow+128,t+1);
;     P8_WAIT_L(8); P8_BAR; P8_WAIT_L(0); P8_MMA(0,0,At,B0); P8_BAR; P8_SCHED;
;     P8_LDB(B1,0,1); P8_STAGE(P8_SB(0,0),Bt,bcol,t+2);
;     P8_BAR; P8_WAIT_L(0); P8_MMA(0,1,At,B1); P8_BAR;
;     P8_LDA(At,0,1); P8_STAGE(P8_SA(0,0),A,brow,t+2);
;     P8_BAR; P8_WAIT_L(0); P8_MMA(1,0,At,B0); P8_BAR; P8_SCHED;
;     P8_STAGE(P8_SB(0,1),Bt,bcol+128,t+2);
;     P8_WAIT_V(6); P8_BAR; P8_MMA(1,1,At,B1); P8_BAR;
.LBB0_286:
	ds_read_b128 v[174:177], v157
	ds_read_b128 v[178:181], v157 offset:1024
	ds_read_b128 v[182:185], v157 offset:2048
	ds_read_b128 v[186:189], v157 offset:3072
	v_add_u32_e32 v158, s54, v140
	s_add_i32 m0, s100, 0xc000
	ds_read_b128 v[160:163], v147
	ds_read_b128 v[190:193], v147 offset:1024
	ds_read_b128 v[196:199], v146
	ds_read_b128 v[200:203], v146 offset:1024
	ds_read_b128 v[204:207], v145
	ds_read_b128 v[208:211], v145 offset:1024
	ds_read_b128 v[212:215], v144
	ds_read_b128 v[216:219], v144 offset:1024
	global_load_lds_dwordx4 v158, s[86:87]
	v_add_u32_e32 v158, s54, v138
	s_add_i32 m0, s100, 0xe000
	s_nop 0
	global_load_lds_dwordx4 v158, s[86:87]
	s_waitcnt lgkmcnt(8)
	s_barrier
	s_waitcnt lgkmcnt(0)
	v_mfma_f32_16x16x32_bf16 v[124:127], v[160:163], v[174:177], v[124:127]
	v_mfma_f32_16x16x32_bf16 v[120:123], v[160:163], v[182:185], v[120:123]
	v_mfma_f32_16x16x32_bf16 v[116:119], v[196:199], v[174:177], v[116:119]
	v_mfma_f32_16x16x32_bf16 v[112:115], v[196:199], v[182:185], v[112:115]
	v_mfma_f32_16x16x32_bf16 v[108:111], v[204:207], v[174:177], v[108:111]
	v_mfma_f32_16x16x32_bf16 v[104:107], v[204:207], v[182:185], v[104:107]
	v_mfma_f32_16x16x32_bf16 v[100:103], v[212:215], v[174:177], v[100:103]
	v_mfma_f32_16x16x32_bf16 v[96:99], v[212:215], v[182:185], v[96:99]
	v_mfma_f32_16x16x32_bf16 v[124:127], v[190:193], v[178:181], v[124:127]
	v_mfma_f32_16x16x32_bf16 v[120:123], v[190:193], v[186:189], v[120:123]
	v_mfma_f32_16x16x32_bf16 v[116:119], v[200:203], v[178:181], v[116:119]
	v_mfma_f32_16x16x32_bf16 v[112:115], v[200:203], v[186:189], v[112:115]
	v_mfma_f32_16x16x32_bf16 v[108:111], v[208:211], v[178:181], v[108:111]
	v_mfma_f32_16x16x32_bf16 v[104:107], v[208:211], v[186:189], v[104:107]
	v_mfma_f32_16x16x32_bf16 v[100:103], v[216:219], v[178:181], v[100:103]
	v_mfma_f32_16x16x32_bf16 v[96:99], v[216:219], v[186:189], v[96:99]
	s_barrier
	v_add_u32_e32 v236, s66, v136
	s_add_i32 m0, s100, 0x10000
	ds_read_b128 v[220:223], v155
	ds_read_b128 v[224:227], v155 offset:1024
	ds_read_b128 v[228:231], v155 offset:2048
	ds_read_b128 v[232:235], v155 offset:3072
	global_load_lds_dwordx4 v236, s[86:87]
	v_add_u32_e32 v236, s66, v134
	s_add_i32 m0, s100, 0x12000
	s_nop 0
	global_load_lds_dwordx4 v236, s[86:87]
	s_barrier
	s_waitcnt lgkmcnt(0)
	v_mfma_f32_16x16x32_bf16 v[92:95], v[160:163], v[220:223], v[92:95]
	v_mfma_f32_16x16x32_bf16 v[88:91], v[160:163], v[228:231], v[88:91]
	v_mfma_f32_16x16x32_bf16 v[84:87], v[196:199], v[220:223], v[84:87]
	v_mfma_f32_16x16x32_bf16 v[80:83], v[196:199], v[228:231], v[80:83]
	v_mfma_f32_16x16x32_bf16 v[76:79], v[204:207], v[220:223], v[76:79]
	v_mfma_f32_16x16x32_bf16 v[72:75], v[204:207], v[228:231], v[72:75]
	v_mfma_f32_16x16x32_bf16 v[68:71], v[212:215], v[220:223], v[68:71]
	v_mfma_f32_16x16x32_bf16 v[64:67], v[212:215], v[228:231], v[64:67]
	v_mfma_f32_16x16x32_bf16 v[92:95], v[190:193], v[224:227], v[92:95]
	v_mfma_f32_16x16x32_bf16 v[88:91], v[190:193], v[232:235], v[88:91]
	v_mfma_f32_16x16x32_bf16 v[84:87], v[200:203], v[224:227], v[84:87]
	v_mfma_f32_16x16x32_bf16 v[80:83], v[200:203], v[232:235], v[80:83]
	v_mfma_f32_16x16x32_bf16 v[76:79], v[208:211], v[224:227], v[76:79]
	v_mfma_f32_16x16x32_bf16 v[72:75], v[208:211], v[232:235], v[72:75]
	v_mfma_f32_16x16x32_bf16 v[68:71], v[216:219], v[224:227], v[68:71]
	v_mfma_f32_16x16x32_bf16 v[64:67], v[216:219], v[232:235], v[64:67]
	v_add_u32_e32 v160, s60, v140
	s_mov_b32 m0, s100
	s_barrier
	ds_read_b128 v[190:193], v147 offset:16384
	ds_read_b128 v[196:199], v147 offset:17408
	ds_read_b128 v[200:203], v146 offset:16384
	ds_read_b128 v[204:207], v146 offset:17408
	ds_read_b128 v[208:211], v145 offset:16384
	ds_read_b128 v[212:215], v145 offset:17408
	ds_read_b128 v[216:219], v144 offset:16384
	ds_read_b128 v[236:239], v144 offset:17408
	global_load_lds_dwordx4 v160, s[86:87]
	v_add_u32_e32 v162, s60, v138
	s_add_i32 m0, s100, 0x2000
	s_nop 0
	global_load_lds_dwordx4 v162, s[86:87]
	s_barrier
	s_waitcnt lgkmcnt(0)
	v_mfma_f32_16x16x32_bf16 v[60:63], v[190:193], v[174:177], v[60:63]
	v_mfma_f32_16x16x32_bf16 v[56:59], v[190:193], v[182:185], v[56:59]
	v_mfma_f32_16x16x32_bf16 v[52:55], v[200:203], v[174:177], v[52:55]
	v_mfma_f32_16x16x32_bf16 v[48:51], v[200:203], v[182:185], v[48:51]
	v_mfma_f32_16x16x32_bf16 v[44:47], v[208:211], v[174:177], v[44:47]
	v_mfma_f32_16x16x32_bf16 v[40:43], v[208:211], v[182:185], v[40:43]
	v_mfma_f32_16x16x32_bf16 v[36:39], v[216:219], v[174:177], v[36:39]
	v_mfma_f32_16x16x32_bf16 v[32:35], v[216:219], v[182:185], v[32:35]
	v_mfma_f32_16x16x32_bf16 v[60:63], v[196:199], v[178:181], v[60:63]
	v_mfma_f32_16x16x32_bf16 v[56:59], v[196:199], v[186:189], v[56:59]
	v_mfma_f32_16x16x32_bf16 v[52:55], v[204:207], v[178:181], v[52:55]
	v_mfma_f32_16x16x32_bf16 v[48:51], v[204:207], v[186:189], v[48:51]
	v_mfma_f32_16x16x32_bf16 v[44:47], v[212:215], v[178:181], v[44:47]
	v_mfma_f32_16x16x32_bf16 v[40:43], v[212:215], v[186:189], v[40:43]
	v_mfma_f32_16x16x32_bf16 v[36:39], v[236:239], v[178:181], v[36:39]
	v_mfma_f32_16x16x32_bf16 v[32:35], v[236:239], v[186:189], v[32:35]
	s_barrier
	v_add_u32_e32 v162, s70, v136
	s_add_i32 m0, s100, 0x14000
	v_add_u32_e32 v174, s70, v134
	global_load_lds_dwordx4 v162, s[86:87]
	s_nop 0
	s_add_i32 m0, s100, 0x16000
	s_nop 0
	global_load_lds_dwordx4 v174, s[86:87]
	s_waitcnt vmcnt(6)
	s_barrier
; #define P8_STAGE(P,BASE,br,kt) do{const bfr* _ub=(BASE)+((long)(br)*K+(long)(kt)*BK); \
;     __builtin_amdgcn_global_load_lds((const unsigned*)(_ub+so0),(unsigned*)((char*)(P)+wid*1024),16,0,0); \
;     __builtin_amdgcn_global_load_lds((const unsigned*)(_ub+so1),(unsigned*)((char*)(P)+wid*1024+8192),16,0,0);}while(0)
; #define P8_LDA(dst,b,h) _Pragma("unroll") for(int m=0;m<4;++m) _Pragma("unroll") for(int k=0;k<2;++k) \
;     dst[m][k]=*reinterpret_cast<const bf16x8*>((char*)P8_SA(b,h)+lds_byte(wr*64+m*16+fr,k*32+fq*8))
; #define P8_LDB(dst,b,h) _Pragma("unroll") for(int n=0;n<2;++n) _Pragma("unroll") for(int k=0;k<2;++k) \
;     dst[n][k]=*reinterpret_cast<const bf16x8*>((char*)P8_SB(b,h)+lds_byte(wc*32+n*16+fr,k*32+fq*8))
; #define P8_MMA(ai,bj,At,Bt) do{__builtin_amdgcn_s_setprio(1); \
;     _Pragma("unroll") for(int m=0;m<4;++m) _Pragma("unroll") for(int n=0;n<2;++n) _Pragma("unroll") for(int k=0;k<2;++k) \
;       acc[ai][bj][m][n]=__builtin_amdgcn_mfma_f32_16x16x32_bf16(At[m][k],Bt[n][k],acc[ai][bj][m][n],0,0,0); \
;     __builtin_amdgcn_s_setprio(0);}while(0)
; #define P8_WAIT_V(n) asm volatile("s_waitcnt vmcnt(" #n ")":::"memory")
; #define P8_WAIT_L(n) asm volatile("s_waitcnt lgkmcnt(" #n ")":::"memory")
; #define P8_BAR __builtin_amdgcn_s_barrier()
; #define P8_SCHED __builtin_amdgcn_sched_barrier(0)
; template <class EPI>
; DEVI void gemm8_tile(const bfr* __restrict__ A, const bfr* __restrict__ Bt, int K, int brow, int bcol, int nbrow, int nbcol, char* shmc, EPI epi) {
;     ...
;     P8_WAIT_V(6); P8_BAR; P8_MMA(1,1,At,B1); P8_BAR;
;     P8_LDB(B0,1,0); P8_SCHED; P8_LDA(At,1,0); P8_STAGE(P8_SA(0,1),A,brow+128,t+2);
;     P8_WAIT_L(8); P8_BAR; P8_WAIT_L(0); P8_MMA(0,0,At,B0); P8_BAR; P8_SCHED;
;     P8_LDB(B1,1,1); P8_STAGE(P8_SB(1,0),Bt,bcol,t+3);
;     P8_BAR; P8_WAIT_L(0); P8_MMA(0,1,At,B1); P8_BAR;
;     P8_LDA(At,1,1); P8_STAGE(P8_SA(1,0),A,brow,t+3);
;     P8_BAR; P8_WAIT_L(0); P8_MMA(1,0,At,B0); P8_BAR; P8_SCHED;
	v_mfma_f32_16x16x32_bf16 v[28:31], v[190:193], v[220:223], v[28:31]
	v_mfma_f32_16x16x32_bf16 v[24:27], v[190:193], v[228:231], v[24:27]
	v_mfma_f32_16x16x32_bf16 v[20:23], v[200:203], v[220:223], v[20:23]
	v_mfma_f32_16x16x32_bf16 v[16:19], v[200:203], v[228:231], v[16:19]
	v_mfma_f32_16x16x32_bf16 v[12:15], v[208:211], v[220:223], v[12:15]
	v_mfma_f32_16x16x32_bf16 v[8:11], v[208:211], v[228:231], v[8:11]
	v_mfma_f32_16x16x32_bf16 v[4:7], v[216:219], v[220:223], v[4:7]
	v_mfma_f32_16x16x32_bf16 v[0:3], v[216:219], v[228:231], v[0:3]
	v_mfma_f32_16x16x32_bf16 v[28:31], v[196:199], v[224:227], v[28:31]
	v_mfma_f32_16x16x32_bf16 v[24:27], v[196:199], v[232:235], v[24:27]
	v_mfma_f32_16x16x32_bf16 v[20:23], v[204:207], v[224:227], v[20:23]
	v_mfma_f32_16x16x32_bf16 v[16:19], v[204:207], v[232:235], v[16:19]
	v_mfma_f32_16x16x32_bf16 v[12:15], v[212:215], v[224:227], v[12:15]
	v_mfma_f32_16x16x32_bf16 v[8:11], v[212:215], v[232:235], v[8:11]
	v_mfma_f32_16x16x32_bf16 v[4:7], v[236:239], v[224:227], v[4:7]
	v_mfma_f32_16x16x32_bf16 v[0:3], v[236:239], v[232:235], v[0:3]
	s_barrier
	ds_read_b128 v[174:177], v149
	ds_read_b128 v[178:181], v149 offset:1024
	ds_read_b128 v[182:185], v149 offset:2048
	ds_read_b128 v[186:189], v149 offset:3072
	v_add_u32_e32 v224, s82, v140
	s_add_i32 m0, s100, 0x4000
	ds_read_b128 v[190:193], v147 offset:32768
	ds_read_b128 v[196:199], v147 offset:33792
	ds_read_b128 v[200:203], v146 offset:32768
	ds_read_b128 v[204:207], v146 offset:33792
	ds_read_b128 v[208:211], v145 offset:32768
	ds_read_b128 v[212:215], v145 offset:33792
	ds_read_b128 v[216:219], v144 offset:32768
	ds_read_b128 v[220:223], v144 offset:33792
	global_load_lds_dwordx4 v224, s[86:87]
	v_add_u32_e32 v224, s82, v138
	s_add_i32 m0, s100, 0x6000
	s_nop 0
	global_load_lds_dwordx4 v224, s[86:87]
	s_waitcnt lgkmcnt(8)
	s_barrier
	s_waitcnt lgkmcnt(0)
	v_mfma_f32_16x16x32_bf16 v[124:127], v[190:193], v[174:177], v[124:127]
	v_mfma_f32_16x16x32_bf16 v[120:123], v[190:193], v[182:185], v[120:123]
	v_mfma_f32_16x16x32_bf16 v[116:119], v[200:203], v[174:177], v[116:119]
	v_mfma_f32_16x16x32_bf16 v[112:115], v[200:203], v[182:185], v[112:115]
	v_mfma_f32_16x16x32_bf16 v[108:111], v[208:211], v[174:177], v[108:111]
	v_mfma_f32_16x16x32_bf16 v[104:107], v[208:211], v[182:185], v[104:107]
	v_mfma_f32_16x16x32_bf16 v[100:103], v[216:219], v[174:177], v[100:103]
	v_mfma_f32_16x16x32_bf16 v[96:99], v[216:219], v[182:185], v[96:99]
	v_mfma_f32_16x16x32_bf16 v[124:127], v[196:199], v[178:181], v[124:127]
	v_mfma_f32_16x16x32_bf16 v[120:123], v[196:199], v[186:189], v[120:123]
	v_mfma_f32_16x16x32_bf16 v[116:119], v[204:207], v[178:181], v[116:119]
	v_mfma_f32_16x16x32_bf16 v[112:115], v[204:207], v[186:189], v[112:115]
	v_mfma_f32_16x16x32_bf16 v[108:111], v[212:215], v[178:181], v[108:111]
	v_mfma_f32_16x16x32_bf16 v[104:107], v[212:215], v[186:189], v[104:107]
	v_mfma_f32_16x16x32_bf16 v[100:103], v[220:223], v[178:181], v[100:103]
	v_mfma_f32_16x16x32_bf16 v[96:99], v[220:223], v[186:189], v[96:99]
	s_barrier
	v_add_u32_e32 v248, s74, v136
	s_add_i32 m0, s100, 0x18000
	ds_read_b128 v[224:227], v148
	ds_read_b128 v[228:231], v148 offset:1024
	ds_read_b128 v[232:235], v148 offset:2048
	ds_read_b128 v[236:239], v148 offset:3072
	global_load_lds_dwordx4 v248, s[86:87]
	v_add_u32_e32 v248, s74, v134
	s_add_i32 m0, s100, 0x1a000
	s_nop 0
	global_load_lds_dwordx4 v248, s[86:87]
	s_barrier
	s_waitcnt lgkmcnt(0)
	v_mfma_f32_16x16x32_bf16 v[92:95], v[190:193], v[224:227], v[92:95]
	v_mfma_f32_16x16x32_bf16 v[88:91], v[190:193], v[232:235], v[88:91]
	v_mfma_f32_16x16x32_bf16 v[84:87], v[200:203], v[224:227], v[84:87]
	v_mfma_f32_16x16x32_bf16 v[80:83], v[200:203], v[232:235], v[80:83]
	v_mfma_f32_16x16x32_bf16 v[76:79], v[208:211], v[224:227], v[76:79]
	v_mfma_f32_16x16x32_bf16 v[72:75], v[208:211], v[232:235], v[72:75]
	v_mfma_f32_16x16x32_bf16 v[68:71], v[216:219], v[224:227], v[68:71]
	v_mfma_f32_16x16x32_bf16 v[64:67], v[216:219], v[232:235], v[64:67]
	v_mfma_f32_16x16x32_bf16 v[92:95], v[196:199], v[228:231], v[92:95]
	v_mfma_f32_16x16x32_bf16 v[88:91], v[196:199], v[236:239], v[88:91]
	v_mfma_f32_16x16x32_bf16 v[84:87], v[204:207], v[228:231], v[84:87]
	v_mfma_f32_16x16x32_bf16 v[80:83], v[204:207], v[236:239], v[80:83]
	v_mfma_f32_16x16x32_bf16 v[76:79], v[212:215], v[228:231], v[76:79]
	v_mfma_f32_16x16x32_bf16 v[72:75], v[212:215], v[236:239], v[72:75]
	v_mfma_f32_16x16x32_bf16 v[68:71], v[220:223], v[228:231], v[68:71]
	v_mfma_f32_16x16x32_bf16 v[64:67], v[220:223], v[236:239], v[64:67]
	v_add_u32_e32 v240, s92, v140
	s_add_i32 m0, s100, 0x8000
	s_barrier
	ds_read_b128 v[190:193], v147 offset:49152
	ds_read_b128 v[196:199], v147 offset:50176
	ds_read_b128 v[200:203], v146 offset:49152
	ds_read_b128 v[204:207], v146 offset:50176
	ds_read_b128 v[208:211], v145 offset:49152
	ds_read_b128 v[212:215], v145 offset:50176
	ds_read_b128 v[216:219], v144 offset:49152
	ds_read_b128 v[220:223], v144 offset:50176
	global_load_lds_dwordx4 v240, s[86:87]
	v_add_u32_e32 v240, s92, v138
	s_add_i32 m0, s100, 0xa000
	s_nop 0
	global_load_lds_dwordx4 v240, s[86:87]
	s_barrier
; #define P8_STAGE(P,BASE,br,kt) do{const bfr* _ub=(BASE)+((long)(br)*K+(long)(kt)*BK); \
;     __builtin_amdgcn_global_load_lds((const unsigned*)(_ub+so0),(unsigned*)((char*)(P)+wid*1024),16,0,0); \
;     __builtin_amdgcn_global_load_lds((const unsigned*)(_ub+so1),(unsigned*)((char*)(P)+wid*1024+8192),16,0,0);}while(0)
; #define P8_LDA(dst,b,h) _Pragma("unroll") for(int m=0;m<4;++m) _Pragma("unroll") for(int k=0;k<2;++k) \
;     dst[m][k]=*reinterpret_cast<const bf16x8*>((char*)P8_SA(b,h)+lds_byte(wr*64+m*16+fr,k*32+fq*8))
; #define P8_LDB(dst,b,h) _Pragma("unroll") for(int n=0;n<2;++n) _Pragma("unroll") for(int k=0;k<2;++k) \
;     dst[n][k]=*reinterpret_cast<const bf16x8*>((char*)P8_SB(b,h)+lds_byte(wc*32+n*16+fr,k*32+fq*8))
; #define P8_MMA(ai,bj,At,Bt) do{__builtin_amdgcn_s_setprio(1); \
;     _Pragma("unroll") for(int m=0;m<4;++m) _Pragma("unroll") for(int n=0;n<2;++n) _Pragma("unroll") for(int k=0;k<2;++k) \
;       acc[ai][bj][m][n]=__builtin_amdgcn_mfma_f32_16x16x32_bf16(At[m][k],Bt[n][k],acc[ai][bj][m][n],0,0,0); \
;     __builtin_amdgcn_s_setprio(0);}while(0)
; #define P8_WAIT_V(n) asm volatile("s_waitcnt vmcnt(" #n ")":::"memory")
; #define P8_WAIT_L(n) asm volatile("s_waitcnt lgkmcnt(" #n ")":::"memory")
; #define P8_BAR __builtin_amdgcn_s_barrier()
; #define P8_SCHED __builtin_amdgcn_sched_barrier(0)
; template <class EPI>
; DEVI void gemm8_tile(const bfr* __restrict__ A, const bfr* __restrict__ Bt, int K, int brow, int bcol, int nbrow, int nbcol, char* shmc, EPI epi) {
;     ...
;     P8_BAR; P8_WAIT_L(0); P8_MMA(1,0,At,B0); P8_BAR; P8_SCHED;
;     P8_STAGE(P8_SB(1,1),Bt,bcol+128,t+3);
;     P8_WAIT_V(6); P8_BAR; P8_MMA(1,1,At,B1); P8_BAR;
;   }
;   { P8_LDB(B0,0,0); P8_LDA(At,0,0); P8_STAGE(P8_SA(1,1),A,brow+128,nt-1);
;     P8_BAR; P8_WAIT_L(0); P8_MMA(0,0,At,B0); P8_BAR;
;     P8_LDB(B1,0,1); P8_BAR; P8_WAIT_L(0); P8_MMA(0,1,At,B1); P8_BAR;
	s_waitcnt lgkmcnt(0)
	v_mfma_f32_16x16x32_bf16 v[60:63], v[190:193], v[174:177], v[60:63]
	v_mfma_f32_16x16x32_bf16 v[56:59], v[190:193], v[182:185], v[56:59]
	v_mfma_f32_16x16x32_bf16 v[52:55], v[200:203], v[174:177], v[52:55]
	v_mfma_f32_16x16x32_bf16 v[48:51], v[200:203], v[182:185], v[48:51]
	v_mfma_f32_16x16x32_bf16 v[44:47], v[208:211], v[174:177], v[44:47]
	v_mfma_f32_16x16x32_bf16 v[40:43], v[208:211], v[182:185], v[40:43]
	v_mfma_f32_16x16x32_bf16 v[36:39], v[216:219], v[174:177], v[36:39]
	v_mfma_f32_16x16x32_bf16 v[32:35], v[216:219], v[182:185], v[32:35]
	v_mfma_f32_16x16x32_bf16 v[60:63], v[196:199], v[178:181], v[60:63]
	v_mfma_f32_16x16x32_bf16 v[56:59], v[196:199], v[186:189], v[56:59]
	v_mfma_f32_16x16x32_bf16 v[52:55], v[204:207], v[178:181], v[52:55]
	v_mfma_f32_16x16x32_bf16 v[48:51], v[204:207], v[186:189], v[48:51]
	v_mfma_f32_16x16x32_bf16 v[44:47], v[212:215], v[178:181], v[44:47]
	v_mfma_f32_16x16x32_bf16 v[40:43], v[212:215], v[186:189], v[40:43]
	v_mfma_f32_16x16x32_bf16 v[36:39], v[220:223], v[178:181], v[36:39]
	v_mfma_f32_16x16x32_bf16 v[32:35], v[220:223], v[186:189], v[32:35]
	s_barrier
	v_add_u32_e32 v174, s78, v136
	s_add_i32 m0, s100, 0x1c000
	s_nop 0
	global_load_lds_dwordx4 v174, s[86:87]
	v_add_u32_e32 v174, s78, v134
	s_add_i32 m0, s100, 0x1e000
	s_nop 0
	global_load_lds_dwordx4 v174, s[86:87]
	s_waitcnt vmcnt(6)
	s_barrier
	v_mfma_f32_16x16x32_bf16 v[28:31], v[190:193], v[224:227], v[28:31]
	v_mfma_f32_16x16x32_bf16 v[24:27], v[190:193], v[232:235], v[24:27]
	v_mfma_f32_16x16x32_bf16 v[20:23], v[200:203], v[224:227], v[20:23]
	v_mfma_f32_16x16x32_bf16 v[16:19], v[200:203], v[232:235], v[16:19]
	v_mfma_f32_16x16x32_bf16 v[12:15], v[208:211], v[224:227], v[12:15]
	v_mfma_f32_16x16x32_bf16 v[8:11], v[208:211], v[232:235], v[8:11]
	v_mfma_f32_16x16x32_bf16 v[4:7], v[216:219], v[224:227], v[4:7]
	v_mfma_f32_16x16x32_bf16 v[0:3], v[216:219], v[232:235], v[0:3]
	v_mfma_f32_16x16x32_bf16 v[28:31], v[196:199], v[228:231], v[28:31]
	v_mfma_f32_16x16x32_bf16 v[24:27], v[196:199], v[236:239], v[24:27]
	v_mfma_f32_16x16x32_bf16 v[20:23], v[204:207], v[228:231], v[20:23]
	v_mfma_f32_16x16x32_bf16 v[16:19], v[204:207], v[236:239], v[16:19]
	v_mfma_f32_16x16x32_bf16 v[12:15], v[212:215], v[228:231], v[12:15]
	v_mfma_f32_16x16x32_bf16 v[8:11], v[212:215], v[236:239], v[8:11]
	v_mfma_f32_16x16x32_bf16 v[4:7], v[220:223], v[228:231], v[4:7]
	v_mfma_f32_16x16x32_bf16 v[0:3], v[220:223], v[236:239], v[0:3]
	s_add_i32 s0, s0, 2
	v_lshl_add_u64 v[134:135], v[134:135], 0, s[80:81]
	v_lshl_add_u64 v[136:137], v[136:137], 0, s[80:81]
	v_lshl_add_u64 v[138:139], v[138:139], 0, s[80:81]
	s_cmp_lt_u32 s0, 28
	v_lshl_add_u64 v[140:141], v[140:141], 0, s[80:81]
	s_barrier
	s_cbranch_scc1 .LBB0_286
	v_add_u32_e32 v171, 0xc000, v143
	v_add_u32_e32 v172, 0xe000, v143
	v_add_u32_e32 v158, 0x10000, v143
	v_add_u32_e32 v159, 0x12000, v143
	v_add_u32_e32 v160, 0x2000, v143
	v_add_u32_e32 v161, 0x14000, v143
	v_add_u32_e32 v162, 0x16000, v143
	v_add_u32_e32 v163, 0x4000, v143
	v_add_u32_e32 v170, 0x6000, v143
	s_or_b32 s0, s8, 0x80
	s_ashr_i32 s1, s0, 31
	s_lshl_b64 s[0:1], s[0:1], 12
	s_add_u32 s0, s29, s0
	s_addc_u32 s1, s68, s1
	ds_read_b128 v[134:137], v157
	ds_read_b128 v[138:141], v157 offset:1024
	ds_read_b128 v[150:153], v157 offset:2048
	ds_read_b128 v[174:177], v157 offset:3072
	ds_read_b128 v[178:181], v147
	ds_read_b128 v[182:185], v147 offset:1024
	ds_read_b128 v[186:189], v146
	ds_read_b128 v[190:193], v146 offset:1024
	ds_read_b128 v[196:199], v145
	ds_read_b128 v[200:203], v145 offset:1024
	ds_read_b128 v[204:207], v144
	ds_read_b128 v[208:211], v144 offset:1024
	v_lshl_add_u64 v[156:157], v[166:167], 1, s[0:1]
	s_mov_b64 s[54:55], 0xf80
	v_lshl_add_u64 v[156:157], v[156:157], 0, s[54:55]
	s_add_i32 m0, s100, 0xc000
	v_lshl_add_u64 v[132:133], v[132:133], 1, s[0:1]
	global_load_lds_dwordx4 v[156:157], off
	v_lshl_add_u64 v[132:133], v[132:133], 0, s[54:55]
	s_add_i32 m0, s100, 0xe000
	s_nop 0
	global_load_lds_dwordx4 v[132:133], off
	s_barrier
	s_waitcnt lgkmcnt(0)
	s_waitcnt lgkmcnt(0)
	v_mfma_f32_16x16x32_bf16 v[124:127], v[178:181], v[134:137], v[124:127]
	v_mfma_f32_16x16x32_bf16 v[116:119], v[186:189], v[134:137], v[116:119]
	v_mfma_f32_16x16x32_bf16 v[112:115], v[186:189], v[150:153], v[112:115]
	v_mfma_f32_16x16x32_bf16 v[96:99], v[204:207], v[150:153], v[96:99]
	v_mfma_f32_16x16x32_bf16 v[124:127], v[182:185], v[138:141], v[124:127]
	v_mfma_f32_16x16x32_bf16 v[120:123], v[178:181], v[150:153], v[120:123]
	v_mfma_f32_16x16x32_bf16 v[116:119], v[190:193], v[138:141], v[116:119]
	v_mfma_f32_16x16x32_bf16 v[112:115], v[190:193], v[174:177], v[112:115]
	v_mfma_f32_16x16x32_bf16 v[108:111], v[196:199], v[134:137], v[108:111]
	v_mfma_f32_16x16x32_bf16 v[104:107], v[196:199], v[150:153], v[104:107]
	v_mfma_f32_16x16x32_bf16 v[100:103], v[204:207], v[134:137], v[100:103]
	v_mfma_f32_16x16x32_bf16 v[96:99], v[208:211], v[174:177], v[96:99]
	v_mfma_f32_16x16x32_bf16 v[212:215], v[182:185], v[174:177], v[120:123]
	v_mfma_f32_16x16x32_bf16 v[216:219], v[200:203], v[138:141], v[108:111]
	v_mfma_f32_16x16x32_bf16 v[220:223], v[200:203], v[174:177], v[104:107]
	v_mfma_f32_16x16x32_bf16 v[224:227], v[208:211], v[138:141], v[100:103]
	s_barrier
	s_nop 0
	ds_read_b128 v[100:103], v155
	ds_read_b128 v[104:107], v155 offset:1024
	ds_read_b128 v[108:111], v155 offset:2048
	ds_read_b128 v[120:123], v155 offset:3072
	s_barrier
; #define P8_LDA(dst,b,h) _Pragma("unroll") for(int m=0;m<4;++m) _Pragma("unroll") for(int k=0;k<2;++k) \
;     dst[m][k]=*reinterpret_cast<const bf16x8*>((char*)P8_SA(b,h)+lds_byte(wr*64+m*16+fr,k*32+fq*8))
; #define P8_LDB(dst,b,h) _Pragma("unroll") for(int n=0;n<2;++n) _Pragma("unroll") for(int k=0;k<2;++k) \
;     dst[n][k]=*reinterpret_cast<const bf16x8*>((char*)P8_SB(b,h)+lds_byte(wc*32+n*16+fr,k*32+fq*8))
; #define P8_MMA(ai,bj,At,Bt) do{__builtin_amdgcn_s_setprio(1); \
;     _Pragma("unroll") for(int m=0;m<4;++m) _Pragma("unroll") for(int n=0;n<2;++n) _Pragma("unroll") for(int k=0;k<2;++k) \
;       acc[ai][bj][m][n]=__builtin_amdgcn_mfma_f32_16x16x32_bf16(At[m][k],Bt[n][k],acc[ai][bj][m][n],0,0,0); \
;     __builtin_amdgcn_s_setprio(0);}while(0)
; #define P8_WAIT_V(n) asm volatile("s_waitcnt vmcnt(" #n ")":::"memory")
; #define P8_WAIT_L(n) asm volatile("s_waitcnt lgkmcnt(" #n ")":::"memory")
; #define P8_BAR __builtin_amdgcn_s_barrier()
; template <class EPI>
; DEVI void gemm8_tile(const bfr* __restrict__ A, const bfr* __restrict__ Bt, int K, int brow, int bcol, int nbrow, int nbcol, char* shmc, EPI epi) {
;     ...
;     P8_LDB(B1,0,1); P8_BAR; P8_WAIT_L(0); P8_MMA(0,1,At,B1); P8_BAR;
;     P8_LDA(At,0,1); P8_WAIT_V(4); P8_BAR; P8_WAIT_L(0); P8_MMA(1,0,At,B0); P8_MMA(1,1,At,B1); P8_BAR; }
;   { P8_LDB(B0,1,0); P8_LDA(At,1,0); P8_WAIT_V(2); P8_BAR; P8_WAIT_L(0); P8_MMA(0,0,At,B0); P8_BAR;
	s_waitcnt lgkmcnt(0)
	s_waitcnt lgkmcnt(0)
	v_mfma_f32_16x16x32_bf16 v[92:95], v[178:181], v[100:103], v[92:95]
	v_mfma_f32_16x16x32_bf16 v[84:87], v[186:189], v[100:103], v[84:87]
	v_mfma_f32_16x16x32_bf16 v[80:83], v[186:189], v[108:111], v[80:83]
	v_mfma_f32_16x16x32_bf16 v[64:67], v[204:207], v[108:111], v[64:67]
	v_mfma_f32_16x16x32_bf16 v[92:95], v[182:185], v[104:107], v[92:95]
	v_mfma_f32_16x16x32_bf16 v[88:91], v[178:181], v[108:111], v[88:91]
	v_mfma_f32_16x16x32_bf16 v[84:87], v[190:193], v[104:107], v[84:87]
	v_mfma_f32_16x16x32_bf16 v[80:83], v[190:193], v[120:123], v[80:83]
	v_mfma_f32_16x16x32_bf16 v[76:79], v[196:199], v[100:103], v[76:79]
	v_mfma_f32_16x16x32_bf16 v[72:75], v[196:199], v[108:111], v[72:75]
	v_mfma_f32_16x16x32_bf16 v[68:71], v[204:207], v[100:103], v[68:71]
	v_mfma_f32_16x16x32_bf16 v[64:67], v[208:211], v[120:123], v[64:67]
	v_mfma_f32_16x16x32_bf16 v[154:157], v[182:185], v[120:123], v[88:91]
	v_mfma_f32_16x16x32_bf16 v[178:181], v[200:203], v[104:107], v[76:79]
	v_mfma_f32_16x16x32_bf16 v[182:185], v[200:203], v[120:123], v[72:75]
	v_mfma_f32_16x16x32_bf16 v[186:189], v[208:211], v[104:107], v[68:71]
	s_barrier
	s_nop 0
	ds_read_b128 v[68:71], v147 offset:16384
	ds_read_b128 v[72:75], v147 offset:17408
	ds_read_b128 v[76:79], v146 offset:16384
	ds_read_b128 v[88:91], v146 offset:17408
	ds_read_b128 v[190:193], v145 offset:16384
	ds_read_b128 v[196:199], v145 offset:17408
	ds_read_b128 v[200:203], v144 offset:16384
	ds_read_b128 v[204:207], v144 offset:17408
	s_waitcnt vmcnt(4)
	s_barrier
	s_waitcnt lgkmcnt(0)
	s_waitcnt lgkmcnt(0)
	v_mfma_f32_16x16x32_bf16 v[60:63], v[68:71], v[134:137], v[60:63]
	v_mfma_f32_16x16x32_bf16 v[52:55], v[76:79], v[134:137], v[52:55]
	v_mfma_f32_16x16x32_bf16 v[48:51], v[76:79], v[150:153], v[48:51]
	v_mfma_f32_16x16x32_bf16 v[32:35], v[200:203], v[150:153], v[32:35]
	v_mfma_f32_16x16x32_bf16 v[60:63], v[72:75], v[138:141], v[60:63]
	v_mfma_f32_16x16x32_bf16 v[56:59], v[68:71], v[150:153], v[56:59]
	v_mfma_f32_16x16x32_bf16 v[52:55], v[88:91], v[138:141], v[52:55]
	v_mfma_f32_16x16x32_bf16 v[48:51], v[88:91], v[174:177], v[48:51]
	v_mfma_f32_16x16x32_bf16 v[44:47], v[190:193], v[134:137], v[44:47]
	v_mfma_f32_16x16x32_bf16 v[40:43], v[190:193], v[150:153], v[40:43]
	v_mfma_f32_16x16x32_bf16 v[36:39], v[200:203], v[134:137], v[36:39]
	v_mfma_f32_16x16x32_bf16 v[32:35], v[204:207], v[174:177], v[32:35]
	v_mfma_f32_16x16x32_bf16 v[208:211], v[72:75], v[174:177], v[56:59]
	v_mfma_f32_16x16x32_bf16 v[228:231], v[196:199], v[138:141], v[44:47]
	v_mfma_f32_16x16x32_bf16 v[232:235], v[196:199], v[174:177], v[40:43]
	v_mfma_f32_16x16x32_bf16 v[132:135], v[204:207], v[138:141], v[36:39]
	s_setprio 0
	s_setprio 1
	v_mfma_f32_16x16x32_bf16 v[28:31], v[68:71], v[100:103], v[28:31]
	v_mfma_f32_16x16x32_bf16 v[20:23], v[76:79], v[100:103], v[20:23]
	v_mfma_f32_16x16x32_bf16 v[16:19], v[76:79], v[108:111], v[16:19]
	v_mfma_f32_16x16x32_bf16 v[0:3], v[200:203], v[108:111], v[0:3]
	v_mfma_f32_16x16x32_bf16 v[28:31], v[72:75], v[104:107], v[28:31]
	v_mfma_f32_16x16x32_bf16 v[24:27], v[68:71], v[108:111], v[24:27]
	v_mfma_f32_16x16x32_bf16 v[20:23], v[88:91], v[104:107], v[20:23]
	v_mfma_f32_16x16x32_bf16 v[16:19], v[88:91], v[120:123], v[16:19]
	v_mfma_f32_16x16x32_bf16 v[12:15], v[190:193], v[100:103], v[12:15]
	v_mfma_f32_16x16x32_bf16 v[8:11], v[190:193], v[108:111], v[8:11]
	v_mfma_f32_16x16x32_bf16 v[4:7], v[200:203], v[100:103], v[4:7]
	v_mfma_f32_16x16x32_bf16 v[0:3], v[204:207], v[120:123], v[0:3]
	v_mfma_f32_16x16x32_bf16 v[136:139], v[72:75], v[120:123], v[24:27]
	v_mfma_f32_16x16x32_bf16 v[150:153], v[196:199], v[104:107], v[12:15]
	v_mfma_f32_16x16x32_bf16 v[172:175], v[196:199], v[120:123], v[8:11]
	v_mfma_f32_16x16x32_bf16 v[190:193], v[204:207], v[104:107], v[4:7]
	s_barrier
	s_nop 0
	ds_read_b128 v[4:7], v149
	ds_read_b128 v[8:11], v149 offset:1024
	ds_read_b128 v[12:15], v149 offset:2048
	ds_read_b128 v[24:27], v149 offset:3072
	ds_read_b128 v[36:39], v147 offset:32768
	ds_read_b128 v[40:43], v147 offset:33792
	ds_read_b128 v[44:47], v146 offset:32768
	ds_read_b128 v[56:59], v146 offset:33792
	ds_read_b128 v[68:71], v145 offset:32768
	ds_read_b128 v[196:199], v145 offset:33792
	ds_read_b128 v[200:203], v144 offset:32768
	ds_read_b128 v[204:207], v144 offset:33792
	s_waitcnt vmcnt(2)
	s_barrier
; #define P8_LDA(dst,b,h) _Pragma("unroll") for(int m=0;m<4;++m) _Pragma("unroll") for(int k=0;k<2;++k) \
;     dst[m][k]=*reinterpret_cast<const bf16x8*>((char*)P8_SA(b,h)+lds_byte(wr*64+m*16+fr,k*32+fq*8))
; #define P8_LDB(dst,b,h) _Pragma("unroll") for(int n=0;n<2;++n) _Pragma("unroll") for(int k=0;k<2;++k) \
;     dst[n][k]=*reinterpret_cast<const bf16x8*>((char*)P8_SB(b,h)+lds_byte(wc*32+n*16+fr,k*32+fq*8))
; #define P8_MMA(ai,bj,At,Bt) do{__builtin_amdgcn_s_setprio(1); \
;     _Pragma("unroll") for(int m=0;m<4;++m) _Pragma("unroll") for(int n=0;n<2;++n) _Pragma("unroll") for(int k=0;k<2;++k) \
;       acc[ai][bj][m][n]=__builtin_amdgcn_mfma_f32_16x16x32_bf16(At[m][k],Bt[n][k],acc[ai][bj][m][n],0,0,0); \
;     __builtin_amdgcn_s_setprio(0);}while(0)
; #define P8_WAIT_V(n) asm volatile("s_waitcnt vmcnt(" #n ")":::"memory")
; #define P8_WAIT_L(n) asm volatile("s_waitcnt lgkmcnt(" #n ")":::"memory")
; #define P8_BAR __builtin_amdgcn_s_barrier()
; template <class EPI>
; DEVI void gemm8_tile(const bfr* __restrict__ A, const bfr* __restrict__ Bt, int K, int brow, int bcol, int nbrow, int nbcol, char* shmc, EPI epi) {
;     ...
;   { P8_LDB(B0,1,0); P8_LDA(At,1,0); P8_WAIT_V(2); P8_BAR; P8_WAIT_L(0); P8_MMA(0,0,At,B0); P8_BAR;
;     P8_LDB(B1,1,1); P8_WAIT_V(0); P8_BAR; P8_WAIT_L(0); P8_MMA(0,1,At,B1); P8_BAR;
;     P8_LDA(At,1,1); P8_BAR; P8_WAIT_L(0); P8_MMA(1,0,At,B0); P8_MMA(1,1,At,B1); P8_BAR; }
;   if(wr==0)P8_BAR;
	s_waitcnt lgkmcnt(0)
	s_waitcnt lgkmcnt(0)
	v_mfma_f32_16x16x32_bf16 v[72:75], v[36:39], v[4:7], v[124:127]
	v_mfma_f32_16x16x32_bf16 v[120:123], v[40:43], v[8:11], v[72:75]
	v_mfma_f32_16x16x32_bf16 v[72:75], v[36:39], v[12:15], v[212:215]
	v_mfma_f32_16x16x32_bf16 v[104:107], v[40:43], v[24:27], v[72:75]
	v_mfma_f32_16x16x32_bf16 v[72:75], v[44:47], v[4:7], v[116:119]
	v_mfma_f32_16x16x32_bf16 v[124:127], v[56:59], v[8:11], v[72:75]
	v_mfma_f32_16x16x32_bf16 v[72:75], v[44:47], v[12:15], v[112:115]
	v_mfma_f32_16x16x32_bf16 v[108:111], v[56:59], v[24:27], v[72:75]
	v_mfma_f32_16x16x32_bf16 v[72:75], v[68:71], v[4:7], v[216:219]
	v_mfma_f32_16x16x32_bf16 v[112:115], v[196:199], v[8:11], v[72:75]
	v_mfma_f32_16x16x32_bf16 v[72:75], v[68:71], v[12:15], v[220:223]
	v_mfma_f32_16x16x32_bf16 v[100:103], v[196:199], v[24:27], v[72:75]
	v_mfma_f32_16x16x32_bf16 v[72:75], v[200:203], v[4:7], v[224:227]
	v_mfma_f32_16x16x32_bf16 v[116:119], v[204:207], v[8:11], v[72:75]
	v_mfma_f32_16x16x32_bf16 v[72:75], v[200:203], v[12:15], v[96:99]
	v_mfma_f32_16x16x32_bf16 v[96:99], v[204:207], v[24:27], v[72:75]
	s_barrier
	ds_read_b128 v[212:215], v148
	ds_read_b128 v[216:219], v148 offset:1024
	ds_read_b128 v[220:223], v148 offset:2048
	ds_read_b128 v[224:227], v148 offset:3072
	s_waitcnt vmcnt(0)
	s_barrier
	s_waitcnt lgkmcnt(0)
	s_waitcnt lgkmcnt(0)
	v_mfma_f32_16x16x32_bf16 v[72:75], v[36:39], v[212:215], v[92:95]
	v_mfma_f32_16x16x32_bf16 v[36:39], v[36:39], v[220:223], v[154:157]
	v_mfma_f32_16x16x32_bf16 v[88:91], v[40:43], v[216:219], v[72:75]
	v_mfma_f32_16x16x32_bf16 v[72:75], v[40:43], v[224:227], v[36:39]
	v_mfma_f32_16x16x32_bf16 v[36:39], v[44:47], v[212:215], v[84:87]
	v_mfma_f32_16x16x32_bf16 v[92:95], v[56:59], v[216:219], v[36:39]
	v_mfma_f32_16x16x32_bf16 v[36:39], v[44:47], v[220:223], v[80:83]
	v_mfma_f32_16x16x32_bf16 v[76:79], v[56:59], v[224:227], v[36:39]
	v_mfma_f32_16x16x32_bf16 v[36:39], v[68:71], v[212:215], v[178:181]
	v_mfma_f32_16x16x32_bf16 v[80:83], v[196:199], v[216:219], v[36:39]
	v_mfma_f32_16x16x32_bf16 v[36:39], v[68:71], v[220:223], v[182:185]
	v_mfma_f32_16x16x32_bf16 v[68:71], v[196:199], v[224:227], v[36:39]
	v_mfma_f32_16x16x32_bf16 v[36:39], v[200:203], v[212:215], v[186:189]
	v_mfma_f32_16x16x32_bf16 v[84:87], v[204:207], v[216:219], v[36:39]
	v_mfma_f32_16x16x32_bf16 v[36:39], v[200:203], v[220:223], v[64:67]
	v_mfma_f32_16x16x32_bf16 v[64:67], v[204:207], v[224:227], v[36:39]
	s_barrier
	ds_read_b128 v[154:157], v147 offset:49152
	ds_read_b128 v[176:179], v147 offset:50176
	ds_read_b128 v[180:183], v146 offset:49152
	ds_read_b128 v[146:149], v146 offset:50176
	ds_read_b128 v[184:187], v145 offset:49152
	ds_read_b128 v[196:199], v145 offset:50176
	ds_read_b128 v[200:203], v144 offset:49152
	ds_read_b128 v[204:207], v144 offset:50176
	s_barrier
	s_waitcnt lgkmcnt(0)
	s_waitcnt lgkmcnt(0)
	v_mfma_f32_16x16x32_bf16 v[36:39], v[154:157], v[4:7], v[60:63]
	v_mfma_f32_16x16x32_bf16 v[56:59], v[176:179], v[8:11], v[36:39]
	v_mfma_f32_16x16x32_bf16 v[36:39], v[154:157], v[12:15], v[208:211]
	v_mfma_f32_16x16x32_bf16 v[40:43], v[176:179], v[24:27], v[36:39]
	v_mfma_f32_16x16x32_bf16 v[36:39], v[180:183], v[4:7], v[52:55]
	v_mfma_f32_16x16x32_bf16 v[60:63], v[146:149], v[8:11], v[36:39]
	v_mfma_f32_16x16x32_bf16 v[36:39], v[180:183], v[12:15], v[48:51]
	v_mfma_f32_16x16x32_bf16 v[44:47], v[146:149], v[24:27], v[36:39]
	v_mfma_f32_16x16x32_bf16 v[36:39], v[184:187], v[4:7], v[228:231]
	v_mfma_f32_16x16x32_bf16 v[4:7], v[200:203], v[4:7], v[132:135]
	v_mfma_f32_16x16x32_bf16 v[48:51], v[196:199], v[8:11], v[36:39]
	v_mfma_f32_16x16x32_bf16 v[36:39], v[184:187], v[12:15], v[232:235]
	v_mfma_f32_16x16x32_bf16 v[52:55], v[204:207], v[8:11], v[4:7]
	v_mfma_f32_16x16x32_bf16 v[4:7], v[200:203], v[12:15], v[32:35]
	v_mfma_f32_16x16x32_bf16 v[36:39], v[196:199], v[24:27], v[36:39]
	v_mfma_f32_16x16x32_bf16 v[32:35], v[204:207], v[24:27], v[4:7]
	s_setprio 0
	s_setprio 1
	v_mfma_f32_16x16x32_bf16 v[4:7], v[154:157], v[212:215], v[28:31]
	v_mfma_f32_16x16x32_bf16 v[24:27], v[176:179], v[216:219], v[4:7]
	v_mfma_f32_16x16x32_bf16 v[4:7], v[154:157], v[220:223], v[136:139]
	v_mfma_f32_16x16x32_bf16 v[8:11], v[176:179], v[224:227], v[4:7]
	v_mfma_f32_16x16x32_bf16 v[4:7], v[180:183], v[212:215], v[20:23]
	v_mfma_f32_16x16x32_bf16 v[28:31], v[146:149], v[216:219], v[4:7]
	v_mfma_f32_16x16x32_bf16 v[4:7], v[180:183], v[220:223], v[16:19]
	v_mfma_f32_16x16x32_bf16 v[12:15], v[146:149], v[224:227], v[4:7]
	v_mfma_f32_16x16x32_bf16 v[4:7], v[184:187], v[212:215], v[150:153]
	v_mfma_f32_16x16x32_bf16 v[16:19], v[196:199], v[216:219], v[4:7]
	v_mfma_f32_16x16x32_bf16 v[4:7], v[184:187], v[220:223], v[172:175]
	v_mfma_f32_16x16x32_bf16 v[20:23], v[200:203], v[212:215], v[190:193]
	v_mfma_f32_16x16x32_bf16 v[0:3], v[200:203], v[220:223], v[0:3]
	v_mfma_f32_16x16x32_bf16 v[4:7], v[196:199], v[224:227], v[4:7]
	v_mfma_f32_16x16x32_bf16 v[20:23], v[204:207], v[216:219], v[20:23]
	v_mfma_f32_16x16x32_bf16 v[0:3], v[204:207], v[224:227], v[0:3]
	s_setprio 0
	v_cmp_gt_u32_e32 vcc, s57, v142
	s_barrier
	s_and_saveexec_b64 s[0:1], vcc
	s_cbranch_execz .LBB0_289
	s_barrier

; #define P8_STAGE(P,BASE,br,kt) do{const bfr* _ub=(BASE)+((long)(br)*K+(long)(kt)*BK); \
;     __builtin_amdgcn_global_load_lds((const unsigned*)(_ub+so0),(unsigned*)((char*)(P)+wid*1024),16,0,0); \
;     __builtin_amdgcn_global_load_lds((const unsigned*)(_ub+so1),(unsigned*)((char*)(P)+wid*1024+8192),16,0,0);}while(0)
; #define P8_LDA(dst,b,h) _Pragma("unroll") for(int m=0;m<4;++m) _Pragma("unroll") for(int k=0;k<2;++k) \
;     dst[m][k]=*reinterpret_cast<const bf16x8*>((char*)P8_SA(b,h)+lds_byte(wr*64+m*16+fr,k*32+fq*8))
; #define P8_LDB(dst,b,h) _Pragma("unroll") for(int n=0;n<2;++n) _Pragma("unroll") for(int k=0;k<2;++k) \
;     dst[n][k]=*reinterpret_cast<const bf16x8*>((char*)P8_SB(b,h)+lds_byte(wc*32+n*16+fr,k*32+fq*8))
; #define P8_MMA(ai,bj,At,Bt) do{__builtin_amdgcn_s_setprio(1); \
;     _Pragma("unroll") for(int m=0;m<4;++m) _Pragma("unroll") for(int n=0;n<2;++n) _Pragma("unroll") for(int k=0;k<2;++k) \
;       acc[ai][bj][m][n]=__builtin_amdgcn_mfma_f32_16x16x32_bf16(At[m][k],Bt[n][k],acc[ai][bj][m][n],0,0,0); \
;     __builtin_amdgcn_s_setprio(0);}while(0)
; #define P8_WAIT_V(n) asm volatile("s_waitcnt vmcnt(" #n ")":::"memory")
; #define P8_WAIT_L(n) asm volatile("s_waitcnt lgkmcnt(" #n ")":::"memory")
; #define P8_BAR __builtin_amdgcn_s_barrier()
; #define P8_SCHED __builtin_amdgcn_sched_barrier(0)
; template <class EPI>
; DEVI void gemm8_tile(const bfr* __restrict__ A, const bfr* __restrict__ Bt, int K, int brow, int bcol, int nbrow, int nbcol, char* shmc, EPI epi) {
;     ...
;     P8_LDB(B0,0,0); P8_SCHED; P8_LDA(At,0,0); P8_STAGE(P8_SA(1,1),A,brow+128,t+1);
;     P8_WAIT_L(8); P8_BAR; P8_WAIT_L(0); P8_MMA(0,0,At,B0); P8_BAR; P8_SCHED;
;     P8_LDB(B1,0,1); P8_STAGE(P8_SB(0,0),Bt,bcol,t+2);
;     P8_BAR; P8_WAIT_L(0); P8_MMA(0,1,At,B1); P8_BAR;
;     P8_LDA(At,0,1); P8_STAGE(P8_SA(0,0),A,brow,t+2);
;     P8_BAR; P8_WAIT_L(0); P8_MMA(1,0,At,B0); P8_BAR; P8_SCHED;
;     P8_STAGE(P8_SB(0,1),Bt,bcol+128,t+2);
;     P8_WAIT_V(6); P8_BAR; P8_MMA(1,1,At,B1); P8_BAR;
.LBB0_382:
	ds_read_b128 v[174:177], v157
	ds_read_b128 v[178:181], v157 offset:1024
	ds_read_b128 v[182:185], v157 offset:2048
	ds_read_b128 v[186:189], v157 offset:3072
	v_add_u32_e32 v158, s54, v140
	s_add_i32 m0, s100, 0xc000
	ds_read_b128 v[160:163], v147
	ds_read_b128 v[190:193], v147 offset:1024
	ds_read_b128 v[196:199], v146
	ds_read_b128 v[208:211], v146 offset:1024
	ds_read_b128 v[212:215], v145
	ds_read_b128 v[216:219], v145 offset:1024
	ds_read_b128 v[220:223], v144
	ds_read_b128 v[224:227], v144 offset:1024
	global_load_lds_dwordx4 v158, s[86:87]
	v_add_u32_e32 v158, s54, v138
	s_add_i32 m0, s100, 0xe000
	s_nop 0
	global_load_lds_dwordx4 v158, s[86:87]
	s_waitcnt lgkmcnt(8)
	s_barrier
	s_waitcnt lgkmcnt(0)
	v_mfma_f32_16x16x32_bf16 v[124:127], v[160:163], v[174:177], v[124:127]
	v_mfma_f32_16x16x32_bf16 v[120:123], v[160:163], v[182:185], v[120:123]
	v_mfma_f32_16x16x32_bf16 v[116:119], v[196:199], v[174:177], v[116:119]
	v_mfma_f32_16x16x32_bf16 v[112:115], v[196:199], v[182:185], v[112:115]
	v_mfma_f32_16x16x32_bf16 v[108:111], v[212:215], v[174:177], v[108:111]
	v_mfma_f32_16x16x32_bf16 v[104:107], v[212:215], v[182:185], v[104:107]
	v_mfma_f32_16x16x32_bf16 v[100:103], v[220:223], v[174:177], v[100:103]
	v_mfma_f32_16x16x32_bf16 v[96:99], v[220:223], v[182:185], v[96:99]
	v_mfma_f32_16x16x32_bf16 v[124:127], v[190:193], v[178:181], v[124:127]
	v_mfma_f32_16x16x32_bf16 v[120:123], v[190:193], v[186:189], v[120:123]
	v_mfma_f32_16x16x32_bf16 v[116:119], v[208:211], v[178:181], v[116:119]
	v_mfma_f32_16x16x32_bf16 v[112:115], v[208:211], v[186:189], v[112:115]
	v_mfma_f32_16x16x32_bf16 v[108:111], v[216:219], v[178:181], v[108:111]
	v_mfma_f32_16x16x32_bf16 v[104:107], v[216:219], v[186:189], v[104:107]
	v_mfma_f32_16x16x32_bf16 v[100:103], v[224:227], v[178:181], v[100:103]
	v_mfma_f32_16x16x32_bf16 v[96:99], v[224:227], v[186:189], v[96:99]
	s_barrier
	v_add_u32_e32 v206, s60, v136
	s_add_i32 m0, s100, 0x10000
	ds_read_b128 v[228:231], v154
	ds_read_b128 v[232:235], v154 offset:1024
	ds_read_b128 v[236:239], v154 offset:2048
	ds_read_b128 v[240:243], v154 offset:3072
	global_load_lds_dwordx4 v206, s[86:87]
	v_add_u32_e32 v244, s60, v134
	s_add_i32 m0, s100, 0x12000
	s_nop 0
	global_load_lds_dwordx4 v244, s[86:87]
	s_barrier
	s_waitcnt lgkmcnt(0)
	v_mfma_f32_16x16x32_bf16 v[92:95], v[160:163], v[228:231], v[92:95]
	v_mfma_f32_16x16x32_bf16 v[88:91], v[160:163], v[236:239], v[88:91]
	v_mfma_f32_16x16x32_bf16 v[84:87], v[196:199], v[228:231], v[84:87]
	v_mfma_f32_16x16x32_bf16 v[80:83], v[196:199], v[236:239], v[80:83]
	v_mfma_f32_16x16x32_bf16 v[76:79], v[212:215], v[228:231], v[76:79]
	v_mfma_f32_16x16x32_bf16 v[72:75], v[212:215], v[236:239], v[72:75]
	v_mfma_f32_16x16x32_bf16 v[68:71], v[220:223], v[228:231], v[68:71]
	v_mfma_f32_16x16x32_bf16 v[64:67], v[220:223], v[236:239], v[64:67]
	v_mfma_f32_16x16x32_bf16 v[92:95], v[190:193], v[232:235], v[92:95]
	v_mfma_f32_16x16x32_bf16 v[88:91], v[190:193], v[240:243], v[88:91]
	v_mfma_f32_16x16x32_bf16 v[84:87], v[208:211], v[232:235], v[84:87]
	v_mfma_f32_16x16x32_bf16 v[80:83], v[208:211], v[240:243], v[80:83]
	v_mfma_f32_16x16x32_bf16 v[76:79], v[216:219], v[232:235], v[76:79]
	v_mfma_f32_16x16x32_bf16 v[72:75], v[216:219], v[240:243], v[72:75]
	v_mfma_f32_16x16x32_bf16 v[68:71], v[224:227], v[232:235], v[68:71]
	v_mfma_f32_16x16x32_bf16 v[64:67], v[224:227], v[240:243], v[64:67]
	v_add_u32_e32 v160, s82, v140
	s_mov_b32 m0, s100
	s_barrier
	ds_read_b128 v[190:193], v147 offset:16384
	ds_read_b128 v[196:199], v147 offset:17408
	ds_read_b128 v[208:211], v146 offset:16384
	ds_read_b128 v[212:215], v146 offset:17408
	ds_read_b128 v[216:219], v145 offset:16384
	ds_read_b128 v[220:223], v145 offset:17408
	ds_read_b128 v[224:227], v144 offset:16384
	ds_read_b128 v[244:247], v144 offset:17408
	global_load_lds_dwordx4 v160, s[86:87]
	v_add_u32_e32 v162, s82, v138
	s_add_i32 m0, s100, 0x2000
	s_nop 0
	global_load_lds_dwordx4 v162, s[86:87]
	s_barrier
	s_waitcnt lgkmcnt(0)
	v_mfma_f32_16x16x32_bf16 v[60:63], v[190:193], v[174:177], v[60:63]
	v_mfma_f32_16x16x32_bf16 v[56:59], v[190:193], v[182:185], v[56:59]
	v_mfma_f32_16x16x32_bf16 v[52:55], v[208:211], v[174:177], v[52:55]
	v_mfma_f32_16x16x32_bf16 v[48:51], v[208:211], v[182:185], v[48:51]
	v_mfma_f32_16x16x32_bf16 v[44:47], v[216:219], v[174:177], v[44:47]
	v_mfma_f32_16x16x32_bf16 v[40:43], v[216:219], v[182:185], v[40:43]
	v_mfma_f32_16x16x32_bf16 v[36:39], v[224:227], v[174:177], v[36:39]
	v_mfma_f32_16x16x32_bf16 v[32:35], v[224:227], v[182:185], v[32:35]
	v_mfma_f32_16x16x32_bf16 v[60:63], v[196:199], v[178:181], v[60:63]
	v_mfma_f32_16x16x32_bf16 v[56:59], v[196:199], v[186:189], v[56:59]
	v_mfma_f32_16x16x32_bf16 v[52:55], v[212:215], v[178:181], v[52:55]
	v_mfma_f32_16x16x32_bf16 v[48:51], v[212:215], v[186:189], v[48:51]
	v_mfma_f32_16x16x32_bf16 v[44:47], v[220:223], v[178:181], v[44:47]
	v_mfma_f32_16x16x32_bf16 v[40:43], v[220:223], v[186:189], v[40:43]
	v_mfma_f32_16x16x32_bf16 v[36:39], v[244:247], v[178:181], v[36:39]
	v_mfma_f32_16x16x32_bf16 v[32:35], v[244:247], v[186:189], v[32:35]
	s_barrier
	v_add_u32_e32 v162, s92, v136
	s_add_i32 m0, s100, 0x14000
	v_add_u32_e32 v174, s92, v134
	global_load_lds_dwordx4 v162, s[86:87]
	s_nop 0
	s_add_i32 m0, s100, 0x16000
	s_nop 0
	global_load_lds_dwordx4 v174, s[86:87]
	s_waitcnt vmcnt(6)
	s_barrier
; #define P8_STAGE(P,BASE,br,kt) do{const bfr* _ub=(BASE)+((long)(br)*K+(long)(kt)*BK); \
;     __builtin_amdgcn_global_load_lds((const unsigned*)(_ub+so0),(unsigned*)((char*)(P)+wid*1024),16,0,0); \
;     __builtin_amdgcn_global_load_lds((const unsigned*)(_ub+so1),(unsigned*)((char*)(P)+wid*1024+8192),16,0,0);}while(0)
; #define P8_LDA(dst,b,h) _Pragma("unroll") for(int m=0;m<4;++m) _Pragma("unroll") for(int k=0;k<2;++k) \
;     dst[m][k]=*reinterpret_cast<const bf16x8*>((char*)P8_SA(b,h)+lds_byte(wr*64+m*16+fr,k*32+fq*8))
; #define P8_LDB(dst,b,h) _Pragma("unroll") for(int n=0;n<2;++n) _Pragma("unroll") for(int k=0;k<2;++k) \
;     dst[n][k]=*reinterpret_cast<const bf16x8*>((char*)P8_SB(b,h)+lds_byte(wc*32+n*16+fr,k*32+fq*8))
; #define P8_MMA(ai,bj,At,Bt) do{__builtin_amdgcn_s_setprio(1); \
;     _Pragma("unroll") for(int m=0;m<4;++m) _Pragma("unroll") for(int n=0;n<2;++n) _Pragma("unroll") for(int k=0;k<2;++k) \
;       acc[ai][bj][m][n]=__builtin_amdgcn_mfma_f32_16x16x32_bf16(At[m][k],Bt[n][k],acc[ai][bj][m][n],0,0,0); \
;     __builtin_amdgcn_s_setprio(0);}while(0)
; #define P8_WAIT_V(n) asm volatile("s_waitcnt vmcnt(" #n ")":::"memory")
; #define P8_WAIT_L(n) asm volatile("s_waitcnt lgkmcnt(" #n ")":::"memory")
; #define P8_BAR __builtin_amdgcn_s_barrier()
; #define P8_SCHED __builtin_amdgcn_sched_barrier(0)
; template <class EPI>
; DEVI void gemm8_tile(const bfr* __restrict__ A, const bfr* __restrict__ Bt, int K, int brow, int bcol, int nbrow, int nbcol, char* shmc, EPI epi) {
;     ...
;     P8_WAIT_V(6); P8_BAR; P8_MMA(1,1,At,B1); P8_BAR;
;     P8_LDB(B0,1,0); P8_SCHED; P8_LDA(At,1,0); P8_STAGE(P8_SA(0,1),A,brow+128,t+2);
;     P8_WAIT_L(8); P8_BAR; P8_WAIT_L(0); P8_MMA(0,0,At,B0); P8_BAR; P8_SCHED;
;     P8_LDB(B1,1,1); P8_STAGE(P8_SB(1,0),Bt,bcol,t+3);
;     P8_BAR; P8_WAIT_L(0); P8_MMA(0,1,At,B1); P8_BAR;
;     P8_LDA(At,1,1); P8_STAGE(P8_SA(1,0),A,brow,t+3);
;     P8_BAR; P8_WAIT_L(0); P8_MMA(1,0,At,B0); P8_BAR; P8_SCHED;
	v_mfma_f32_16x16x32_bf16 v[28:31], v[190:193], v[228:231], v[28:31]
	v_mfma_f32_16x16x32_bf16 v[24:27], v[190:193], v[236:239], v[24:27]
	v_mfma_f32_16x16x32_bf16 v[20:23], v[208:211], v[228:231], v[20:23]
	v_mfma_f32_16x16x32_bf16 v[16:19], v[208:211], v[236:239], v[16:19]
	v_mfma_f32_16x16x32_bf16 v[12:15], v[216:219], v[228:231], v[12:15]
	v_mfma_f32_16x16x32_bf16 v[8:11], v[216:219], v[236:239], v[8:11]
	v_mfma_f32_16x16x32_bf16 v[4:7], v[224:227], v[228:231], v[4:7]
	v_mfma_f32_16x16x32_bf16 v[0:3], v[224:227], v[236:239], v[0:3]
	v_mfma_f32_16x16x32_bf16 v[28:31], v[196:199], v[232:235], v[28:31]
	v_mfma_f32_16x16x32_bf16 v[24:27], v[196:199], v[240:243], v[24:27]
	v_mfma_f32_16x16x32_bf16 v[20:23], v[212:215], v[232:235], v[20:23]
	v_mfma_f32_16x16x32_bf16 v[16:19], v[212:215], v[240:243], v[16:19]
	v_mfma_f32_16x16x32_bf16 v[12:15], v[220:223], v[232:235], v[12:15]
	v_mfma_f32_16x16x32_bf16 v[8:11], v[220:223], v[240:243], v[8:11]
	v_mfma_f32_16x16x32_bf16 v[4:7], v[244:247], v[232:235], v[4:7]
	v_mfma_f32_16x16x32_bf16 v[0:3], v[244:247], v[240:243], v[0:3]
	s_barrier
	ds_read_b128 v[174:177], v149
	ds_read_b128 v[178:181], v149 offset:1024
	ds_read_b128 v[182:185], v149 offset:2048
	ds_read_b128 v[186:189], v149 offset:3072
	v_add_u32_e32 v232, s94, v140
	s_add_i32 m0, s100, 0x4000
	ds_read_b128 v[190:193], v147 offset:32768
	ds_read_b128 v[196:199], v147 offset:33792
	ds_read_b128 v[208:211], v146 offset:32768
	ds_read_b128 v[212:215], v146 offset:33792
	ds_read_b128 v[216:219], v145 offset:32768
	ds_read_b128 v[220:223], v145 offset:33792
	ds_read_b128 v[224:227], v144 offset:32768
	ds_read_b128 v[228:231], v144 offset:33792
	global_load_lds_dwordx4 v232, s[86:87]
	v_add_u32_e32 v232, s94, v138
	s_add_i32 m0, s100, 0x6000
	s_nop 0
	global_load_lds_dwordx4 v232, s[86:87]
	s_waitcnt lgkmcnt(8)
	s_barrier
	s_waitcnt lgkmcnt(0)
	v_mfma_f32_16x16x32_bf16 v[124:127], v[190:193], v[174:177], v[124:127]
	v_mfma_f32_16x16x32_bf16 v[120:123], v[190:193], v[182:185], v[120:123]
	v_mfma_f32_16x16x32_bf16 v[116:119], v[208:211], v[174:177], v[116:119]
	v_mfma_f32_16x16x32_bf16 v[112:115], v[208:211], v[182:185], v[112:115]
	v_mfma_f32_16x16x32_bf16 v[108:111], v[216:219], v[174:177], v[108:111]
	v_mfma_f32_16x16x32_bf16 v[104:107], v[216:219], v[182:185], v[104:107]
	v_mfma_f32_16x16x32_bf16 v[100:103], v[224:227], v[174:177], v[100:103]
	v_mfma_f32_16x16x32_bf16 v[96:99], v[224:227], v[182:185], v[96:99]
	v_mfma_f32_16x16x32_bf16 v[124:127], v[196:199], v[178:181], v[124:127]
	v_mfma_f32_16x16x32_bf16 v[120:123], v[196:199], v[186:189], v[120:123]
	v_mfma_f32_16x16x32_bf16 v[116:119], v[212:215], v[178:181], v[116:119]
	v_mfma_f32_16x16x32_bf16 v[112:115], v[212:215], v[186:189], v[112:115]
	v_mfma_f32_16x16x32_bf16 v[108:111], v[220:223], v[178:181], v[108:111]
	v_mfma_f32_16x16x32_bf16 v[104:107], v[220:223], v[186:189], v[104:107]
	v_mfma_f32_16x16x32_bf16 v[100:103], v[228:231], v[178:181], v[100:103]
	v_mfma_f32_16x16x32_bf16 v[96:99], v[228:231], v[186:189], v[96:99]
	s_barrier
	v_add_u32_e32 v248, s96, v136
	s_add_i32 m0, s100, 0x18000
	ds_read_b128 v[232:235], v148
	ds_read_b128 v[236:239], v148 offset:1024
	ds_read_b128 v[240:243], v148 offset:2048
	ds_read_b128 v[244:247], v148 offset:3072
	global_load_lds_dwordx4 v248, s[86:87]
	v_add_u32_e32 v248, s96, v134
	s_add_i32 m0, s100, 0x1a000
	s_nop 0
	global_load_lds_dwordx4 v248, s[86:87]
	s_barrier
	s_waitcnt lgkmcnt(0)
	v_mfma_f32_16x16x32_bf16 v[92:95], v[190:193], v[232:235], v[92:95]
	v_mfma_f32_16x16x32_bf16 v[88:91], v[190:193], v[240:243], v[88:91]
	v_mfma_f32_16x16x32_bf16 v[84:87], v[208:211], v[232:235], v[84:87]
	v_mfma_f32_16x16x32_bf16 v[80:83], v[208:211], v[240:243], v[80:83]
	v_mfma_f32_16x16x32_bf16 v[76:79], v[216:219], v[232:235], v[76:79]
	v_mfma_f32_16x16x32_bf16 v[72:75], v[216:219], v[240:243], v[72:75]
	v_mfma_f32_16x16x32_bf16 v[68:71], v[224:227], v[232:235], v[68:71]
	v_mfma_f32_16x16x32_bf16 v[64:67], v[224:227], v[240:243], v[64:67]
	v_mfma_f32_16x16x32_bf16 v[92:95], v[196:199], v[236:239], v[92:95]
	v_mfma_f32_16x16x32_bf16 v[88:91], v[196:199], v[244:247], v[88:91]
	v_mfma_f32_16x16x32_bf16 v[84:87], v[212:215], v[236:239], v[84:87]
	v_mfma_f32_16x16x32_bf16 v[80:83], v[212:215], v[244:247], v[80:83]
	v_mfma_f32_16x16x32_bf16 v[76:79], v[220:223], v[236:239], v[76:79]
	v_mfma_f32_16x16x32_bf16 v[72:75], v[220:223], v[244:247], v[72:75]
	v_mfma_f32_16x16x32_bf16 v[68:71], v[228:231], v[236:239], v[68:71]
	v_mfma_f32_16x16x32_bf16 v[64:67], v[228:231], v[244:247], v[64:67]
	v_add_u32_e32 v200, vcc_lo, v140
	s_add_i32 m0, s100, 0x8000
	s_barrier
	ds_read_b128 v[190:193], v147 offset:49152
	ds_read_b128 v[196:199], v147 offset:50176
	ds_read_b128 v[208:211], v146 offset:49152
	ds_read_b128 v[212:215], v146 offset:50176
	ds_read_b128 v[216:219], v145 offset:49152
	ds_read_b128 v[220:223], v145 offset:50176
	ds_read_b128 v[224:227], v144 offset:49152
	ds_read_b128 v[228:231], v144 offset:50176
	global_load_lds_dwordx4 v200, s[86:87]
	v_add_u32_e32 v200, vcc_lo, v138
	s_add_i32 m0, s100, 0xa000
	s_nop 0
	global_load_lds_dwordx4 v200, s[86:87]
	s_barrier
; #define P8_STAGE(P,BASE,br,kt) do{const bfr* _ub=(BASE)+((long)(br)*K+(long)(kt)*BK); \
;     __builtin_amdgcn_global_load_lds((const unsigned*)(_ub+so0),(unsigned*)((char*)(P)+wid*1024),16,0,0); \
;     __builtin_amdgcn_global_load_lds((const unsigned*)(_ub+so1),(unsigned*)((char*)(P)+wid*1024+8192),16,0,0);}while(0)
; #define P8_LDA(dst,b,h) _Pragma("unroll") for(int m=0;m<4;++m) _Pragma("unroll") for(int k=0;k<2;++k) \
;     dst[m][k]=*reinterpret_cast<const bf16x8*>((char*)P8_SA(b,h)+lds_byte(wr*64+m*16+fr,k*32+fq*8))
; #define P8_LDB(dst,b,h) _Pragma("unroll") for(int n=0;n<2;++n) _Pragma("unroll") for(int k=0;k<2;++k) \
;     dst[n][k]=*reinterpret_cast<const bf16x8*>((char*)P8_SB(b,h)+lds_byte(wc*32+n*16+fr,k*32+fq*8))
; #define P8_MMA(ai,bj,At,Bt) do{__builtin_amdgcn_s_setprio(1); \
;     _Pragma("unroll") for(int m=0;m<4;++m) _Pragma("unroll") for(int n=0;n<2;++n) _Pragma("unroll") for(int k=0;k<2;++k) \
;       acc[ai][bj][m][n]=__builtin_amdgcn_mfma_f32_16x16x32_bf16(At[m][k],Bt[n][k],acc[ai][bj][m][n],0,0,0); \
;     __builtin_amdgcn_s_setprio(0);}while(0)
; #define P8_WAIT_V(n) asm volatile("s_waitcnt vmcnt(" #n ")":::"memory")
; #define P8_WAIT_L(n) asm volatile("s_waitcnt lgkmcnt(" #n ")":::"memory")
; #define P8_BAR __builtin_amdgcn_s_barrier()
; #define P8_SCHED __builtin_amdgcn_sched_barrier(0)
; template <class EPI>
; DEVI void gemm8_tile(const bfr* __restrict__ A, const bfr* __restrict__ Bt, int K, int brow, int bcol, int nbrow, int nbcol, char* shmc, EPI epi) {
;     ...
;     P8_BAR; P8_WAIT_L(0); P8_MMA(1,0,At,B0); P8_BAR; P8_SCHED;
;     P8_STAGE(P8_SB(1,1),Bt,bcol+128,t+3);
;     P8_WAIT_V(6); P8_BAR; P8_MMA(1,1,At,B1); P8_BAR;
;   }
;   { P8_LDB(B0,0,0); P8_LDA(At,0,0); P8_STAGE(P8_SA(1,1),A,brow+128,nt-1);
;     P8_BAR; P8_WAIT_L(0); P8_MMA(0,0,At,B0); P8_BAR;
;     P8_LDB(B1,0,1); P8_BAR; P8_WAIT_L(0); P8_MMA(0,1,At,B1); P8_BAR;
	s_waitcnt lgkmcnt(0)
	v_mfma_f32_16x16x32_bf16 v[60:63], v[190:193], v[174:177], v[60:63]
	v_mfma_f32_16x16x32_bf16 v[56:59], v[190:193], v[182:185], v[56:59]
	v_mfma_f32_16x16x32_bf16 v[52:55], v[208:211], v[174:177], v[52:55]
	v_mfma_f32_16x16x32_bf16 v[48:51], v[208:211], v[182:185], v[48:51]
	v_mfma_f32_16x16x32_bf16 v[44:47], v[216:219], v[174:177], v[44:47]
	v_mfma_f32_16x16x32_bf16 v[40:43], v[216:219], v[182:185], v[40:43]
	v_mfma_f32_16x16x32_bf16 v[36:39], v[224:227], v[174:177], v[36:39]
	v_mfma_f32_16x16x32_bf16 v[32:35], v[224:227], v[182:185], v[32:35]
	v_mfma_f32_16x16x32_bf16 v[60:63], v[196:199], v[178:181], v[60:63]
	v_mfma_f32_16x16x32_bf16 v[56:59], v[196:199], v[186:189], v[56:59]
	v_mfma_f32_16x16x32_bf16 v[52:55], v[212:215], v[178:181], v[52:55]
	v_mfma_f32_16x16x32_bf16 v[48:51], v[212:215], v[186:189], v[48:51]
	v_mfma_f32_16x16x32_bf16 v[44:47], v[220:223], v[178:181], v[44:47]
	v_mfma_f32_16x16x32_bf16 v[40:43], v[220:223], v[186:189], v[40:43]
	v_mfma_f32_16x16x32_bf16 v[36:39], v[228:231], v[178:181], v[36:39]
	v_mfma_f32_16x16x32_bf16 v[32:35], v[228:231], v[186:189], v[32:35]
	s_barrier
	v_add_u32_e32 v174, s28, v136
	s_add_i32 m0, s100, 0x1c000
	s_nop 0
	global_load_lds_dwordx4 v174, s[86:87]
	v_add_u32_e32 v174, s28, v134
	s_add_i32 m0, s100, 0x1e000
	s_nop 0
	global_load_lds_dwordx4 v174, s[86:87]
	s_waitcnt vmcnt(6)
	s_barrier
	v_mfma_f32_16x16x32_bf16 v[28:31], v[190:193], v[232:235], v[28:31]
	v_mfma_f32_16x16x32_bf16 v[24:27], v[190:193], v[240:243], v[24:27]
	v_mfma_f32_16x16x32_bf16 v[20:23], v[208:211], v[232:235], v[20:23]
	v_mfma_f32_16x16x32_bf16 v[16:19], v[208:211], v[240:243], v[16:19]
	v_mfma_f32_16x16x32_bf16 v[12:15], v[216:219], v[232:235], v[12:15]
	v_mfma_f32_16x16x32_bf16 v[8:11], v[216:219], v[240:243], v[8:11]
	v_mfma_f32_16x16x32_bf16 v[4:7], v[224:227], v[232:235], v[4:7]
	v_mfma_f32_16x16x32_bf16 v[0:3], v[224:227], v[240:243], v[0:3]
	v_mfma_f32_16x16x32_bf16 v[28:31], v[196:199], v[236:239], v[28:31]
	v_mfma_f32_16x16x32_bf16 v[24:27], v[196:199], v[244:247], v[24:27]
	v_mfma_f32_16x16x32_bf16 v[20:23], v[212:215], v[236:239], v[20:23]
	v_mfma_f32_16x16x32_bf16 v[16:19], v[212:215], v[244:247], v[16:19]
	v_mfma_f32_16x16x32_bf16 v[12:15], v[220:223], v[236:239], v[12:15]
	v_mfma_f32_16x16x32_bf16 v[8:11], v[220:223], v[244:247], v[8:11]
	v_mfma_f32_16x16x32_bf16 v[4:7], v[228:231], v[236:239], v[4:7]
	v_mfma_f32_16x16x32_bf16 v[0:3], v[228:231], v[244:247], v[0:3]
	s_add_i32 s0, s0, 2
	v_lshl_add_u64 v[134:135], v[134:135], 0, s[80:81]
	v_lshl_add_u64 v[136:137], v[136:137], 0, s[80:81]
	v_lshl_add_u64 v[138:139], v[138:139], 0, s[80:81]
	s_cmpk_lt_u32 s0, 0x7c
	v_lshl_add_u64 v[140:141], v[140:141], 0, s[80:81]
	s_barrier
	s_cbranch_scc1 .LBB0_382
	v_add_u32_e32 v171, 0xc000, v143
	v_add_u32_e32 v172, 0xe000, v143
	v_add_u32_e32 v158, 0x10000, v143
	v_add_u32_e32 v159, 0x12000, v143
	v_add_u32_e32 v160, 0x2000, v143
	v_add_u32_e32 v161, 0x14000, v143
	v_add_u32_e32 v162, 0x16000, v143
	v_add_u32_e32 v163, 0x4000, v143
	v_add_u32_e32 v170, 0x6000, v143
	s_or_b32 s0, s10, 0x80
	s_ashr_i32 s1, s0, 31
	s_lshl_b64 s[0:1], s[0:1], 14
	s_add_u32 s0, s31, s0
	s_addc_u32 s1, s64, s1
	s_add_u32 s0, s0, 0x3f80
	s_addc_u32 s1, s1, 0
	ds_read_b128 v[134:137], v157
	ds_read_b128 v[138:141], v157 offset:1024
	ds_read_b128 v[150:153], v157 offset:2048
	ds_read_b128 v[174:177], v157 offset:3072
	ds_read_b128 v[178:181], v147
	ds_read_b128 v[182:185], v147 offset:1024
	ds_read_b128 v[186:189], v146
	ds_read_b128 v[190:193], v146 offset:1024
	ds_read_b128 v[196:199], v145
	ds_read_b128 v[208:211], v145 offset:1024
	ds_read_b128 v[212:215], v144
	ds_read_b128 v[216:219], v144 offset:1024
	v_lshl_add_u64 v[156:157], v[166:167], 1, s[0:1]
	s_add_i32 m0, s100, 0xc000
	v_lshl_add_u64 v[132:133], v[132:133], 1, s[0:1]
	global_load_lds_dwordx4 v[156:157], off
	s_add_i32 m0, s100, 0xe000
	s_nop 0
	global_load_lds_dwordx4 v[132:133], off
	s_barrier
	s_waitcnt lgkmcnt(0)
	s_waitcnt lgkmcnt(0)
	v_mfma_f32_16x16x32_bf16 v[124:127], v[178:181], v[134:137], v[124:127]
	v_mfma_f32_16x16x32_bf16 v[116:119], v[186:189], v[134:137], v[116:119]
	v_mfma_f32_16x16x32_bf16 v[112:115], v[186:189], v[150:153], v[112:115]
	v_mfma_f32_16x16x32_bf16 v[96:99], v[212:215], v[150:153], v[96:99]
	v_mfma_f32_16x16x32_bf16 v[124:127], v[182:185], v[138:141], v[124:127]
	v_mfma_f32_16x16x32_bf16 v[120:123], v[178:181], v[150:153], v[120:123]
	v_mfma_f32_16x16x32_bf16 v[116:119], v[190:193], v[138:141], v[116:119]
	v_mfma_f32_16x16x32_bf16 v[112:115], v[190:193], v[174:177], v[112:115]
	v_mfma_f32_16x16x32_bf16 v[108:111], v[196:199], v[134:137], v[108:111]
	v_mfma_f32_16x16x32_bf16 v[104:107], v[196:199], v[150:153], v[104:107]
	v_mfma_f32_16x16x32_bf16 v[100:103], v[212:215], v[134:137], v[100:103]
	v_mfma_f32_16x16x32_bf16 v[96:99], v[216:219], v[174:177], v[96:99]
	v_mfma_f32_16x16x32_bf16 v[220:223], v[182:185], v[174:177], v[120:123]
	v_mfma_f32_16x16x32_bf16 v[224:227], v[208:211], v[138:141], v[108:111]
	v_mfma_f32_16x16x32_bf16 v[228:231], v[208:211], v[174:177], v[104:107]
	v_mfma_f32_16x16x32_bf16 v[232:235], v[216:219], v[138:141], v[100:103]
	s_barrier
	s_nop 0
	ds_read_b128 v[100:103], v154
	ds_read_b128 v[104:107], v154 offset:1024
	ds_read_b128 v[108:111], v154 offset:2048
	ds_read_b128 v[120:123], v154 offset:3072
	s_barrier
; #define P8_LDA(dst,b,h) _Pragma("unroll") for(int m=0;m<4;++m) _Pragma("unroll") for(int k=0;k<2;++k) \
;     dst[m][k]=*reinterpret_cast<const bf16x8*>((char*)P8_SA(b,h)+lds_byte(wr*64+m*16+fr,k*32+fq*8))
; #define P8_LDB(dst,b,h) _Pragma("unroll") for(int n=0;n<2;++n) _Pragma("unroll") for(int k=0;k<2;++k) \
;     dst[n][k]=*reinterpret_cast<const bf16x8*>((char*)P8_SB(b,h)+lds_byte(wc*32+n*16+fr,k*32+fq*8))
; #define P8_MMA(ai,bj,At,Bt) do{__builtin_amdgcn_s_setprio(1); \
;     _Pragma("unroll") for(int m=0;m<4;++m) _Pragma("unroll") for(int n=0;n<2;++n) _Pragma("unroll") for(int k=0;k<2;++k) \
;       acc[ai][bj][m][n]=__builtin_amdgcn_mfma_f32_16x16x32_bf16(At[m][k],Bt[n][k],acc[ai][bj][m][n],0,0,0); \
;     __builtin_amdgcn_s_setprio(0);}while(0)
; #define P8_WAIT_V(n) asm volatile("s_waitcnt vmcnt(" #n ")":::"memory")
; #define P8_WAIT_L(n) asm volatile("s_waitcnt lgkmcnt(" #n ")":::"memory")
; #define P8_BAR __builtin_amdgcn_s_barrier()
; template <class EPI>
; DEVI void gemm8_tile(const bfr* __restrict__ A, const bfr* __restrict__ Bt, int K, int brow, int bcol, int nbrow, int nbcol, char* shmc, EPI epi) {
;     ...
;     P8_LDB(B1,0,1); P8_BAR; P8_WAIT_L(0); P8_MMA(0,1,At,B1); P8_BAR;
;     P8_LDA(At,0,1); P8_WAIT_V(4); P8_BAR; P8_WAIT_L(0); P8_MMA(1,0,At,B0); P8_MMA(1,1,At,B1); P8_BAR; }
;   { P8_LDB(B0,1,0); P8_LDA(At,1,0); P8_WAIT_V(2); P8_BAR; P8_WAIT_L(0); P8_MMA(0,0,At,B0); P8_BAR;
	s_waitcnt lgkmcnt(0)
	s_waitcnt lgkmcnt(0)
	v_mfma_f32_16x16x32_bf16 v[92:95], v[178:181], v[100:103], v[92:95]
	v_mfma_f32_16x16x32_bf16 v[84:87], v[186:189], v[100:103], v[84:87]
	v_mfma_f32_16x16x32_bf16 v[80:83], v[186:189], v[108:111], v[80:83]
	v_mfma_f32_16x16x32_bf16 v[64:67], v[212:215], v[108:111], v[64:67]
	v_mfma_f32_16x16x32_bf16 v[92:95], v[182:185], v[104:107], v[92:95]
	v_mfma_f32_16x16x32_bf16 v[88:91], v[178:181], v[108:111], v[88:91]
	v_mfma_f32_16x16x32_bf16 v[84:87], v[190:193], v[104:107], v[84:87]
	v_mfma_f32_16x16x32_bf16 v[80:83], v[190:193], v[120:123], v[80:83]
	v_mfma_f32_16x16x32_bf16 v[76:79], v[196:199], v[100:103], v[76:79]
	v_mfma_f32_16x16x32_bf16 v[72:75], v[196:199], v[108:111], v[72:75]
	v_mfma_f32_16x16x32_bf16 v[68:71], v[212:215], v[100:103], v[68:71]
	v_mfma_f32_16x16x32_bf16 v[64:67], v[216:219], v[120:123], v[64:67]
	v_mfma_f32_16x16x32_bf16 v[154:157], v[182:185], v[120:123], v[88:91]
	v_mfma_f32_16x16x32_bf16 v[178:181], v[208:211], v[104:107], v[76:79]
	v_mfma_f32_16x16x32_bf16 v[182:185], v[208:211], v[120:123], v[72:75]
	v_mfma_f32_16x16x32_bf16 v[186:189], v[216:219], v[104:107], v[68:71]
	s_barrier
	s_nop 0
	ds_read_b128 v[68:71], v147 offset:16384
	ds_read_b128 v[72:75], v147 offset:17408
	ds_read_b128 v[76:79], v146 offset:16384
	ds_read_b128 v[88:91], v146 offset:17408
	ds_read_b128 v[190:193], v145 offset:16384
	ds_read_b128 v[196:199], v145 offset:17408
	ds_read_b128 v[208:211], v144 offset:16384
	ds_read_b128 v[212:215], v144 offset:17408
	s_waitcnt vmcnt(4)
	s_barrier
	s_waitcnt lgkmcnt(0)
	s_waitcnt lgkmcnt(0)
	v_mfma_f32_16x16x32_bf16 v[60:63], v[68:71], v[134:137], v[60:63]
	v_mfma_f32_16x16x32_bf16 v[52:55], v[76:79], v[134:137], v[52:55]
	v_mfma_f32_16x16x32_bf16 v[48:51], v[76:79], v[150:153], v[48:51]
	v_mfma_f32_16x16x32_bf16 v[32:35], v[208:211], v[150:153], v[32:35]
	v_mfma_f32_16x16x32_bf16 v[60:63], v[72:75], v[138:141], v[60:63]
	v_mfma_f32_16x16x32_bf16 v[56:59], v[68:71], v[150:153], v[56:59]
	v_mfma_f32_16x16x32_bf16 v[52:55], v[88:91], v[138:141], v[52:55]
	v_mfma_f32_16x16x32_bf16 v[48:51], v[88:91], v[174:177], v[48:51]
	v_mfma_f32_16x16x32_bf16 v[44:47], v[190:193], v[134:137], v[44:47]
	v_mfma_f32_16x16x32_bf16 v[40:43], v[190:193], v[150:153], v[40:43]
	v_mfma_f32_16x16x32_bf16 v[36:39], v[208:211], v[134:137], v[36:39]
	v_mfma_f32_16x16x32_bf16 v[32:35], v[212:215], v[174:177], v[32:35]
	v_mfma_f32_16x16x32_bf16 v[216:219], v[72:75], v[174:177], v[56:59]
	v_mfma_f32_16x16x32_bf16 v[236:239], v[196:199], v[138:141], v[44:47]
	v_mfma_f32_16x16x32_bf16 v[240:243], v[196:199], v[174:177], v[40:43]
	v_mfma_f32_16x16x32_bf16 v[132:135], v[212:215], v[138:141], v[36:39]
	s_setprio 0
	s_setprio 1
	v_mfma_f32_16x16x32_bf16 v[28:31], v[68:71], v[100:103], v[28:31]
	v_mfma_f32_16x16x32_bf16 v[20:23], v[76:79], v[100:103], v[20:23]
	v_mfma_f32_16x16x32_bf16 v[16:19], v[76:79], v[108:111], v[16:19]
	v_mfma_f32_16x16x32_bf16 v[0:3], v[208:211], v[108:111], v[0:3]
	v_mfma_f32_16x16x32_bf16 v[28:31], v[72:75], v[104:107], v[28:31]
	v_mfma_f32_16x16x32_bf16 v[24:27], v[68:71], v[108:111], v[24:27]
	v_mfma_f32_16x16x32_bf16 v[20:23], v[88:91], v[104:107], v[20:23]
	v_mfma_f32_16x16x32_bf16 v[16:19], v[88:91], v[120:123], v[16:19]
	v_mfma_f32_16x16x32_bf16 v[12:15], v[190:193], v[100:103], v[12:15]
	v_mfma_f32_16x16x32_bf16 v[8:11], v[190:193], v[108:111], v[8:11]
	v_mfma_f32_16x16x32_bf16 v[4:7], v[208:211], v[100:103], v[4:7]
	v_mfma_f32_16x16x32_bf16 v[0:3], v[212:215], v[120:123], v[0:3]
	v_mfma_f32_16x16x32_bf16 v[136:139], v[72:75], v[120:123], v[24:27]
	v_mfma_f32_16x16x32_bf16 v[150:153], v[196:199], v[104:107], v[12:15]
	v_mfma_f32_16x16x32_bf16 v[172:175], v[196:199], v[120:123], v[8:11]
	v_mfma_f32_16x16x32_bf16 v[190:193], v[212:215], v[104:107], v[4:7]
	s_barrier
	s_nop 0
	ds_read_b128 v[4:7], v149
	ds_read_b128 v[8:11], v149 offset:1024
	ds_read_b128 v[12:15], v149 offset:2048
	ds_read_b128 v[24:27], v149 offset:3072
	ds_read_b128 v[36:39], v147 offset:32768
	ds_read_b128 v[40:43], v147 offset:33792
	ds_read_b128 v[44:47], v146 offset:32768
	ds_read_b128 v[56:59], v146 offset:33792
	ds_read_b128 v[68:71], v145 offset:32768
	ds_read_b128 v[196:199], v145 offset:33792
	ds_read_b128 v[208:211], v144 offset:32768
	ds_read_b128 v[212:215], v144 offset:33792
	s_waitcnt vmcnt(2)
	s_barrier
; #define P8_LDA(dst,b,h) _Pragma("unroll") for(int m=0;m<4;++m) _Pragma("unroll") for(int k=0;k<2;++k) \
;     dst[m][k]=*reinterpret_cast<const bf16x8*>((char*)P8_SA(b,h)+lds_byte(wr*64+m*16+fr,k*32+fq*8))
; #define P8_LDB(dst,b,h) _Pragma("unroll") for(int n=0;n<2;++n) _Pragma("unroll") for(int k=0;k<2;++k) \
;     dst[n][k]=*reinterpret_cast<const bf16x8*>((char*)P8_SB(b,h)+lds_byte(wc*32+n*16+fr,k*32+fq*8))
; #define P8_MMA(ai,bj,At,Bt) do{__builtin_amdgcn_s_setprio(1); \
;     _Pragma("unroll") for(int m=0;m<4;++m) _Pragma("unroll") for(int n=0;n<2;++n) _Pragma("unroll") for(int k=0;k<2;++k) \
;       acc[ai][bj][m][n]=__builtin_amdgcn_mfma_f32_16x16x32_bf16(At[m][k],Bt[n][k],acc[ai][bj][m][n],0,0,0); \
;     __builtin_amdgcn_s_setprio(0);}while(0)
; #define P8_WAIT_V(n) asm volatile("s_waitcnt vmcnt(" #n ")":::"memory")
; #define P8_WAIT_L(n) asm volatile("s_waitcnt lgkmcnt(" #n ")":::"memory")
; #define P8_BAR __builtin_amdgcn_s_barrier()
; template <class EPI>
; DEVI void gemm8_tile(const bfr* __restrict__ A, const bfr* __restrict__ Bt, int K, int brow, int bcol, int nbrow, int nbcol, char* shmc, EPI epi) {
;     ...
;   { P8_LDB(B0,1,0); P8_LDA(At,1,0); P8_WAIT_V(2); P8_BAR; P8_WAIT_L(0); P8_MMA(0,0,At,B0); P8_BAR;
;     P8_LDB(B1,1,1); P8_WAIT_V(0); P8_BAR; P8_WAIT_L(0); P8_MMA(0,1,At,B1); P8_BAR;
;     P8_LDA(At,1,1); P8_BAR; P8_WAIT_L(0); P8_MMA(1,0,At,B0); P8_MMA(1,1,At,B1); P8_BAR; }
;   if(wr==0)P8_BAR;
	s_waitcnt lgkmcnt(0)
	s_waitcnt lgkmcnt(0)
	v_mfma_f32_16x16x32_bf16 v[72:75], v[36:39], v[4:7], v[124:127]
	v_mfma_f32_16x16x32_bf16 v[120:123], v[40:43], v[8:11], v[72:75]
	v_mfma_f32_16x16x32_bf16 v[72:75], v[36:39], v[12:15], v[220:223]
	v_mfma_f32_16x16x32_bf16 v[104:107], v[40:43], v[24:27], v[72:75]
	v_mfma_f32_16x16x32_bf16 v[72:75], v[44:47], v[4:7], v[116:119]
	v_mfma_f32_16x16x32_bf16 v[124:127], v[56:59], v[8:11], v[72:75]
	v_mfma_f32_16x16x32_bf16 v[72:75], v[44:47], v[12:15], v[112:115]
	v_mfma_f32_16x16x32_bf16 v[108:111], v[56:59], v[24:27], v[72:75]
	v_mfma_f32_16x16x32_bf16 v[72:75], v[68:71], v[4:7], v[224:227]
	v_mfma_f32_16x16x32_bf16 v[112:115], v[196:199], v[8:11], v[72:75]
	v_mfma_f32_16x16x32_bf16 v[72:75], v[68:71], v[12:15], v[228:231]
	v_mfma_f32_16x16x32_bf16 v[100:103], v[196:199], v[24:27], v[72:75]
	v_mfma_f32_16x16x32_bf16 v[72:75], v[208:211], v[4:7], v[232:235]
	v_mfma_f32_16x16x32_bf16 v[116:119], v[212:215], v[8:11], v[72:75]
	v_mfma_f32_16x16x32_bf16 v[72:75], v[208:211], v[12:15], v[96:99]
	v_mfma_f32_16x16x32_bf16 v[96:99], v[212:215], v[24:27], v[72:75]
	s_barrier
	ds_read_b128 v[220:223], v148
	ds_read_b128 v[224:227], v148 offset:1024
	ds_read_b128 v[228:231], v148 offset:2048
	ds_read_b128 v[232:235], v148 offset:3072
	s_waitcnt vmcnt(0)
	s_barrier
	s_waitcnt lgkmcnt(0)
	s_waitcnt lgkmcnt(0)
	v_mfma_f32_16x16x32_bf16 v[72:75], v[36:39], v[220:223], v[92:95]
	v_mfma_f32_16x16x32_bf16 v[36:39], v[36:39], v[228:231], v[154:157]
	v_mfma_f32_16x16x32_bf16 v[88:91], v[40:43], v[224:227], v[72:75]
	v_mfma_f32_16x16x32_bf16 v[72:75], v[40:43], v[232:235], v[36:39]
	v_mfma_f32_16x16x32_bf16 v[36:39], v[44:47], v[220:223], v[84:87]
	v_mfma_f32_16x16x32_bf16 v[92:95], v[56:59], v[224:227], v[36:39]
	v_mfma_f32_16x16x32_bf16 v[36:39], v[44:47], v[228:231], v[80:83]
	v_mfma_f32_16x16x32_bf16 v[76:79], v[56:59], v[232:235], v[36:39]
	v_mfma_f32_16x16x32_bf16 v[36:39], v[68:71], v[220:223], v[178:181]
	v_mfma_f32_16x16x32_bf16 v[80:83], v[196:199], v[224:227], v[36:39]
	v_mfma_f32_16x16x32_bf16 v[36:39], v[68:71], v[228:231], v[182:185]
	v_mfma_f32_16x16x32_bf16 v[68:71], v[196:199], v[232:235], v[36:39]
	v_mfma_f32_16x16x32_bf16 v[36:39], v[208:211], v[220:223], v[186:189]
	v_mfma_f32_16x16x32_bf16 v[84:87], v[212:215], v[224:227], v[36:39]
	v_mfma_f32_16x16x32_bf16 v[36:39], v[208:211], v[228:231], v[64:67]
	v_mfma_f32_16x16x32_bf16 v[64:67], v[212:215], v[232:235], v[36:39]
	s_barrier
	ds_read_b128 v[154:157], v147 offset:49152
	ds_read_b128 v[176:179], v147 offset:50176
	ds_read_b128 v[180:183], v146 offset:49152
	ds_read_b128 v[146:149], v146 offset:50176
	ds_read_b128 v[184:187], v145 offset:49152
	ds_read_b128 v[196:199], v145 offset:50176
	ds_read_b128 v[208:211], v144 offset:49152
	ds_read_b128 v[212:215], v144 offset:50176
	s_barrier
	s_waitcnt lgkmcnt(0)
	s_waitcnt lgkmcnt(0)
	v_mfma_f32_16x16x32_bf16 v[36:39], v[154:157], v[4:7], v[60:63]
	v_mfma_f32_16x16x32_bf16 v[56:59], v[176:179], v[8:11], v[36:39]
	v_mfma_f32_16x16x32_bf16 v[36:39], v[154:157], v[12:15], v[216:219]
	v_mfma_f32_16x16x32_bf16 v[40:43], v[176:179], v[24:27], v[36:39]
	v_mfma_f32_16x16x32_bf16 v[36:39], v[180:183], v[4:7], v[52:55]
	v_mfma_f32_16x16x32_bf16 v[60:63], v[146:149], v[8:11], v[36:39]
	v_mfma_f32_16x16x32_bf16 v[36:39], v[180:183], v[12:15], v[48:51]
	v_mfma_f32_16x16x32_bf16 v[44:47], v[146:149], v[24:27], v[36:39]
	v_mfma_f32_16x16x32_bf16 v[36:39], v[184:187], v[4:7], v[236:239]
	v_mfma_f32_16x16x32_bf16 v[4:7], v[208:211], v[4:7], v[132:135]
	v_mfma_f32_16x16x32_bf16 v[48:51], v[196:199], v[8:11], v[36:39]
	v_mfma_f32_16x16x32_bf16 v[36:39], v[184:187], v[12:15], v[240:243]
	v_mfma_f32_16x16x32_bf16 v[52:55], v[212:215], v[8:11], v[4:7]
	v_mfma_f32_16x16x32_bf16 v[4:7], v[208:211], v[12:15], v[32:35]
	v_mfma_f32_16x16x32_bf16 v[36:39], v[196:199], v[24:27], v[36:39]
	v_mfma_f32_16x16x32_bf16 v[32:35], v[212:215], v[24:27], v[4:7]
	s_setprio 0
	s_setprio 1
	v_mfma_f32_16x16x32_bf16 v[4:7], v[154:157], v[220:223], v[28:31]
	v_mfma_f32_16x16x32_bf16 v[24:27], v[176:179], v[224:227], v[4:7]
	v_mfma_f32_16x16x32_bf16 v[4:7], v[154:157], v[228:231], v[136:139]
	v_mfma_f32_16x16x32_bf16 v[8:11], v[176:179], v[232:235], v[4:7]
	v_mfma_f32_16x16x32_bf16 v[4:7], v[180:183], v[220:223], v[20:23]
	v_mfma_f32_16x16x32_bf16 v[28:31], v[146:149], v[224:227], v[4:7]
	v_mfma_f32_16x16x32_bf16 v[4:7], v[180:183], v[228:231], v[16:19]
	v_mfma_f32_16x16x32_bf16 v[12:15], v[146:149], v[232:235], v[4:7]
	v_mfma_f32_16x16x32_bf16 v[4:7], v[184:187], v[220:223], v[150:153]
	v_mfma_f32_16x16x32_bf16 v[16:19], v[196:199], v[224:227], v[4:7]
	v_mfma_f32_16x16x32_bf16 v[4:7], v[184:187], v[228:231], v[172:175]
	v_mfma_f32_16x16x32_bf16 v[20:23], v[208:211], v[220:223], v[190:193]
	v_mfma_f32_16x16x32_bf16 v[0:3], v[208:211], v[228:231], v[0:3]
	v_mfma_f32_16x16x32_bf16 v[4:7], v[196:199], v[232:235], v[4:7]
	v_mfma_f32_16x16x32_bf16 v[20:23], v[212:215], v[224:227], v[20:23]
	v_mfma_f32_16x16x32_bf16 v[0:3], v[212:215], v[232:235], v[0:3]
	s_setprio 0
	v_cmp_gt_u32_e32 vcc, s57, v142
	s_barrier
	s_and_saveexec_b64 s[0:1], vcc
	s_cbranch_execz .LBB0_385
	s_barrier

; #define P8_STAGE(P,BASE,br,kt) do{const bfr* _ub=(BASE)+((long)(br)*K+(long)(kt)*BK); \
;     __builtin_amdgcn_global_load_lds((const unsigned*)(_ub+so0),(unsigned*)((char*)(P)+wid*1024),16,0,0); \
;     __builtin_amdgcn_global_load_lds((const unsigned*)(_ub+so1),(unsigned*)((char*)(P)+wid*1024+8192),16,0,0);}while(0)
; #define P8_LDA(dst,b,h) _Pragma("unroll") for(int m=0;m<4;++m) _Pragma("unroll") for(int k=0;k<2;++k) \
;     dst[m][k]=*reinterpret_cast<const bf16x8*>((char*)P8_SA(b,h)+lds_byte(wr*64+m*16+fr,k*32+fq*8))
; #define P8_LDB(dst,b,h) _Pragma("unroll") for(int n=0;n<2;++n) _Pragma("unroll") for(int k=0;k<2;++k) \
;     dst[n][k]=*reinterpret_cast<const bf16x8*>((char*)P8_SB(b,h)+lds_byte(wc*32+n*16+fr,k*32+fq*8))
; #define P8_MMA(ai,bj,At,Bt) do{__builtin_amdgcn_s_setprio(1); \
;     _Pragma("unroll") for(int m=0;m<4;++m) _Pragma("unroll") for(int n=0;n<2;++n) _Pragma("unroll") for(int k=0;k<2;++k) \
;       acc[ai][bj][m][n]=__builtin_amdgcn_mfma_f32_16x16x32_bf16(At[m][k],Bt[n][k],acc[ai][bj][m][n],0,0,0); \
;     __builtin_amdgcn_s_setprio(0);}while(0)
; #define P8_WAIT_V(n) asm volatile("s_waitcnt vmcnt(" #n ")":::"memory")
; #define P8_WAIT_L(n) asm volatile("s_waitcnt lgkmcnt(" #n ")":::"memory")
; #define P8_BAR __builtin_amdgcn_s_barrier()
; #define P8_SCHED __builtin_amdgcn_sched_barrier(0)
; template <class EPI>
; DEVI void gemm8_tile(const bfr* __restrict__ A, const bfr* __restrict__ Bt, int K, int brow, int bcol, int nbrow, int nbcol, char* shmc, EPI epi) {
;     ...
;     P8_LDB(B0,0,0); P8_SCHED; P8_LDA(At,0,0); P8_STAGE(P8_SA(1,1),A,brow+128,t+1);
;     P8_WAIT_L(8); P8_BAR; P8_WAIT_L(0); P8_MMA(0,0,At,B0); P8_BAR; P8_SCHED;
;     P8_LDB(B1,0,1); P8_STAGE(P8_SB(0,0),Bt,bcol,t+2);
;     P8_BAR; P8_WAIT_L(0); P8_MMA(0,1,At,B1); P8_BAR;
;     P8_LDA(At,0,1); P8_STAGE(P8_SA(0,0),A,brow,t+2);
;     P8_BAR; P8_WAIT_L(0); P8_MMA(1,0,At,B0); P8_BAR; P8_SCHED;
;     P8_STAGE(P8_SB(0,1),Bt,bcol+128,t+2);
;     P8_WAIT_V(6); P8_BAR; P8_MMA(1,1,At,B1); P8_BAR;
.LBB0_401:
	ds_read_b128 v[174:177], v157
	ds_read_b128 v[178:181], v157 offset:1024
	ds_read_b128 v[182:185], v157 offset:2048
	ds_read_b128 v[186:189], v157 offset:3072
	v_add_u32_e32 v158, s54, v136
	s_add_i32 m0, s100, 0xc000
	ds_read_b128 v[160:163], v147
	ds_read_b128 v[190:193], v147 offset:1024
	ds_read_b128 v[196:199], v146
	ds_read_b128 v[208:211], v146 offset:1024
	ds_read_b128 v[212:215], v145
	ds_read_b128 v[216:219], v145 offset:1024
	ds_read_b128 v[220:223], v144
	ds_read_b128 v[224:227], v144 offset:1024
	global_load_lds_dwordx4 v158, s[86:87]
	v_add_u32_e32 v158, s54, v134
	s_add_i32 m0, s100, 0xe000
	s_nop 0
	global_load_lds_dwordx4 v158, s[86:87]
	s_waitcnt lgkmcnt(8)
	s_barrier
	s_waitcnt lgkmcnt(0)
	v_mfma_f32_16x16x32_bf16 v[124:127], v[160:163], v[174:177], v[124:127]
	v_mfma_f32_16x16x32_bf16 v[120:123], v[160:163], v[182:185], v[120:123]
	v_mfma_f32_16x16x32_bf16 v[116:119], v[196:199], v[174:177], v[116:119]
	v_mfma_f32_16x16x32_bf16 v[112:115], v[196:199], v[182:185], v[112:115]
	v_mfma_f32_16x16x32_bf16 v[108:111], v[212:215], v[174:177], v[108:111]
	v_mfma_f32_16x16x32_bf16 v[104:107], v[212:215], v[182:185], v[104:107]
	v_mfma_f32_16x16x32_bf16 v[100:103], v[220:223], v[174:177], v[100:103]
	v_mfma_f32_16x16x32_bf16 v[96:99], v[220:223], v[182:185], v[96:99]
	v_mfma_f32_16x16x32_bf16 v[124:127], v[190:193], v[178:181], v[124:127]
	v_mfma_f32_16x16x32_bf16 v[120:123], v[190:193], v[186:189], v[120:123]
	v_mfma_f32_16x16x32_bf16 v[116:119], v[208:211], v[178:181], v[116:119]
	v_mfma_f32_16x16x32_bf16 v[112:115], v[208:211], v[186:189], v[112:115]
	v_mfma_f32_16x16x32_bf16 v[108:111], v[216:219], v[178:181], v[108:111]
	v_mfma_f32_16x16x32_bf16 v[104:107], v[216:219], v[186:189], v[104:107]
	v_mfma_f32_16x16x32_bf16 v[100:103], v[224:227], v[178:181], v[100:103]
	v_mfma_f32_16x16x32_bf16 v[96:99], v[224:227], v[186:189], v[96:99]
	s_barrier
	v_add_u32_e32 v206, s66, v140
	s_add_i32 m0, s100, 0x10000
	ds_read_b128 v[228:231], v155
	ds_read_b128 v[232:235], v155 offset:1024
	ds_read_b128 v[236:239], v155 offset:2048
	ds_read_b128 v[240:243], v155 offset:3072
	global_load_lds_dwordx4 v206, s[86:87]
	v_add_u32_e32 v244, s66, v138
	s_add_i32 m0, s100, 0x12000
	s_nop 0
	global_load_lds_dwordx4 v244, s[86:87]
	s_barrier
	s_waitcnt lgkmcnt(0)
	v_mfma_f32_16x16x32_bf16 v[92:95], v[160:163], v[228:231], v[92:95]
	v_mfma_f32_16x16x32_bf16 v[88:91], v[160:163], v[236:239], v[88:91]
	v_mfma_f32_16x16x32_bf16 v[84:87], v[196:199], v[228:231], v[84:87]
	v_mfma_f32_16x16x32_bf16 v[80:83], v[196:199], v[236:239], v[80:83]
	v_mfma_f32_16x16x32_bf16 v[76:79], v[212:215], v[228:231], v[76:79]
	v_mfma_f32_16x16x32_bf16 v[72:75], v[212:215], v[236:239], v[72:75]
	v_mfma_f32_16x16x32_bf16 v[68:71], v[220:223], v[228:231], v[68:71]
	v_mfma_f32_16x16x32_bf16 v[64:67], v[220:223], v[236:239], v[64:67]
	v_mfma_f32_16x16x32_bf16 v[92:95], v[190:193], v[232:235], v[92:95]
	v_mfma_f32_16x16x32_bf16 v[88:91], v[190:193], v[240:243], v[88:91]
	v_mfma_f32_16x16x32_bf16 v[84:87], v[208:211], v[232:235], v[84:87]
	v_mfma_f32_16x16x32_bf16 v[80:83], v[208:211], v[240:243], v[80:83]
	v_mfma_f32_16x16x32_bf16 v[76:79], v[216:219], v[232:235], v[76:79]
	v_mfma_f32_16x16x32_bf16 v[72:75], v[216:219], v[240:243], v[72:75]
	v_mfma_f32_16x16x32_bf16 v[68:71], v[224:227], v[232:235], v[68:71]
	v_mfma_f32_16x16x32_bf16 v[64:67], v[224:227], v[240:243], v[64:67]
	v_add_u32_e32 v160, s60, v136
	s_mov_b32 m0, s100
	s_barrier
	ds_read_b128 v[190:193], v147 offset:16384
	ds_read_b128 v[196:199], v147 offset:17408
	ds_read_b128 v[208:211], v146 offset:16384
	ds_read_b128 v[212:215], v146 offset:17408
	ds_read_b128 v[216:219], v145 offset:16384
	ds_read_b128 v[220:223], v145 offset:17408
	ds_read_b128 v[224:227], v144 offset:16384
	ds_read_b128 v[244:247], v144 offset:17408
	global_load_lds_dwordx4 v160, s[86:87]
	v_add_u32_e32 v162, s60, v134
	s_add_i32 m0, s100, 0x2000
	s_nop 0
	global_load_lds_dwordx4 v162, s[86:87]
	s_barrier
	s_waitcnt lgkmcnt(0)
	v_mfma_f32_16x16x32_bf16 v[60:63], v[190:193], v[174:177], v[60:63]
	v_mfma_f32_16x16x32_bf16 v[56:59], v[190:193], v[182:185], v[56:59]
	v_mfma_f32_16x16x32_bf16 v[52:55], v[208:211], v[174:177], v[52:55]
	v_mfma_f32_16x16x32_bf16 v[48:51], v[208:211], v[182:185], v[48:51]
	v_mfma_f32_16x16x32_bf16 v[44:47], v[216:219], v[174:177], v[44:47]
	v_mfma_f32_16x16x32_bf16 v[40:43], v[216:219], v[182:185], v[40:43]
	v_mfma_f32_16x16x32_bf16 v[36:39], v[224:227], v[174:177], v[36:39]
	v_mfma_f32_16x16x32_bf16 v[32:35], v[224:227], v[182:185], v[32:35]
	v_mfma_f32_16x16x32_bf16 v[60:63], v[196:199], v[178:181], v[60:63]
	v_mfma_f32_16x16x32_bf16 v[56:59], v[196:199], v[186:189], v[56:59]
	v_mfma_f32_16x16x32_bf16 v[52:55], v[212:215], v[178:181], v[52:55]
	v_mfma_f32_16x16x32_bf16 v[48:51], v[212:215], v[186:189], v[48:51]
	v_mfma_f32_16x16x32_bf16 v[44:47], v[220:223], v[178:181], v[44:47]
	v_mfma_f32_16x16x32_bf16 v[40:43], v[220:223], v[186:189], v[40:43]
	v_mfma_f32_16x16x32_bf16 v[36:39], v[244:247], v[178:181], v[36:39]
	v_mfma_f32_16x16x32_bf16 v[32:35], v[244:247], v[186:189], v[32:35]
	s_barrier
	v_add_u32_e32 v162, s70, v140
	s_add_i32 m0, s100, 0x14000
	v_add_u32_e32 v174, s70, v138
	global_load_lds_dwordx4 v162, s[86:87]
	s_nop 0
	s_add_i32 m0, s100, 0x16000
	s_nop 0
	global_load_lds_dwordx4 v174, s[86:87]
	s_waitcnt vmcnt(6)
	s_barrier
; #define P8_STAGE(P,BASE,br,kt) do{const bfr* _ub=(BASE)+((long)(br)*K+(long)(kt)*BK); \
;     __builtin_amdgcn_global_load_lds((const unsigned*)(_ub+so0),(unsigned*)((char*)(P)+wid*1024),16,0,0); \
;     __builtin_amdgcn_global_load_lds((const unsigned*)(_ub+so1),(unsigned*)((char*)(P)+wid*1024+8192),16,0,0);}while(0)
; #define P8_LDA(dst,b,h) _Pragma("unroll") for(int m=0;m<4;++m) _Pragma("unroll") for(int k=0;k<2;++k) \
;     dst[m][k]=*reinterpret_cast<const bf16x8*>((char*)P8_SA(b,h)+lds_byte(wr*64+m*16+fr,k*32+fq*8))
; #define P8_LDB(dst,b,h) _Pragma("unroll") for(int n=0;n<2;++n) _Pragma("unroll") for(int k=0;k<2;++k) \
;     dst[n][k]=*reinterpret_cast<const bf16x8*>((char*)P8_SB(b,h)+lds_byte(wc*32+n*16+fr,k*32+fq*8))
; #define P8_MMA(ai,bj,At,Bt) do{__builtin_amdgcn_s_setprio(1); \
;     _Pragma("unroll") for(int m=0;m<4;++m) _Pragma("unroll") for(int n=0;n<2;++n) _Pragma("unroll") for(int k=0;k<2;++k) \
;       acc[ai][bj][m][n]=__builtin_amdgcn_mfma_f32_16x16x32_bf16(At[m][k],Bt[n][k],acc[ai][bj][m][n],0,0,0); \
;     __builtin_amdgcn_s_setprio(0);}while(0)
; #define P8_WAIT_V(n) asm volatile("s_waitcnt vmcnt(" #n ")":::"memory")
; #define P8_WAIT_L(n) asm volatile("s_waitcnt lgkmcnt(" #n ")":::"memory")
; #define P8_BAR __builtin_amdgcn_s_barrier()
; #define P8_SCHED __builtin_amdgcn_sched_barrier(0)
; template <class EPI>
; DEVI void gemm8_tile(const bfr* __restrict__ A, const bfr* __restrict__ Bt, int K, int brow, int bcol, int nbrow, int nbcol, char* shmc, EPI epi) {
;     ...
;     P8_WAIT_V(6); P8_BAR; P8_MMA(1,1,At,B1); P8_BAR;
;     P8_LDB(B0,1,0); P8_SCHED; P8_LDA(At,1,0); P8_STAGE(P8_SA(0,1),A,brow+128,t+2);
;     P8_WAIT_L(8); P8_BAR; P8_WAIT_L(0); P8_MMA(0,0,At,B0); P8_BAR; P8_SCHED;
;     P8_LDB(B1,1,1); P8_STAGE(P8_SB(1,0),Bt,bcol,t+3);
;     P8_BAR; P8_WAIT_L(0); P8_MMA(0,1,At,B1); P8_BAR;
;     P8_LDA(At,1,1); P8_STAGE(P8_SA(1,0),A,brow,t+3);
;     P8_BAR; P8_WAIT_L(0); P8_MMA(1,0,At,B0); P8_BAR; P8_SCHED;
	v_mfma_f32_16x16x32_bf16 v[28:31], v[190:193], v[228:231], v[28:31]
	v_mfma_f32_16x16x32_bf16 v[24:27], v[190:193], v[236:239], v[24:27]
	v_mfma_f32_16x16x32_bf16 v[20:23], v[208:211], v[228:231], v[20:23]
	v_mfma_f32_16x16x32_bf16 v[16:19], v[208:211], v[236:239], v[16:19]
	v_mfma_f32_16x16x32_bf16 v[12:15], v[216:219], v[228:231], v[12:15]
	v_mfma_f32_16x16x32_bf16 v[8:11], v[216:219], v[236:239], v[8:11]
	v_mfma_f32_16x16x32_bf16 v[4:7], v[224:227], v[228:231], v[4:7]
	v_mfma_f32_16x16x32_bf16 v[0:3], v[224:227], v[236:239], v[0:3]
	v_mfma_f32_16x16x32_bf16 v[28:31], v[196:199], v[232:235], v[28:31]
	v_mfma_f32_16x16x32_bf16 v[24:27], v[196:199], v[240:243], v[24:27]
	v_mfma_f32_16x16x32_bf16 v[20:23], v[212:215], v[232:235], v[20:23]
	v_mfma_f32_16x16x32_bf16 v[16:19], v[212:215], v[240:243], v[16:19]
	v_mfma_f32_16x16x32_bf16 v[12:15], v[220:223], v[232:235], v[12:15]
	v_mfma_f32_16x16x32_bf16 v[8:11], v[220:223], v[240:243], v[8:11]
	v_mfma_f32_16x16x32_bf16 v[4:7], v[244:247], v[232:235], v[4:7]
	v_mfma_f32_16x16x32_bf16 v[0:3], v[244:247], v[240:243], v[0:3]
	s_barrier
	ds_read_b128 v[174:177], v149
	ds_read_b128 v[178:181], v149 offset:1024
	ds_read_b128 v[182:185], v149 offset:2048
	ds_read_b128 v[186:189], v149 offset:3072
	v_add_u32_e32 v232, s68, v136
	s_add_i32 m0, s100, 0x4000
	ds_read_b128 v[190:193], v147 offset:32768
	ds_read_b128 v[196:199], v147 offset:33792
	ds_read_b128 v[208:211], v146 offset:32768
	ds_read_b128 v[212:215], v146 offset:33792
	ds_read_b128 v[216:219], v145 offset:32768
	ds_read_b128 v[220:223], v145 offset:33792
	ds_read_b128 v[224:227], v144 offset:32768
	ds_read_b128 v[228:231], v144 offset:33792
	global_load_lds_dwordx4 v232, s[86:87]
	v_add_u32_e32 v232, s68, v134
	s_add_i32 m0, s100, 0x6000
	s_nop 0
	global_load_lds_dwordx4 v232, s[86:87]
	s_waitcnt lgkmcnt(8)
	s_barrier
	s_waitcnt lgkmcnt(0)
	v_mfma_f32_16x16x32_bf16 v[124:127], v[190:193], v[174:177], v[124:127]
	v_mfma_f32_16x16x32_bf16 v[120:123], v[190:193], v[182:185], v[120:123]
	v_mfma_f32_16x16x32_bf16 v[116:119], v[208:211], v[174:177], v[116:119]
	v_mfma_f32_16x16x32_bf16 v[112:115], v[208:211], v[182:185], v[112:115]
	v_mfma_f32_16x16x32_bf16 v[108:111], v[216:219], v[174:177], v[108:111]
	v_mfma_f32_16x16x32_bf16 v[104:107], v[216:219], v[182:185], v[104:107]
	v_mfma_f32_16x16x32_bf16 v[100:103], v[224:227], v[174:177], v[100:103]
	v_mfma_f32_16x16x32_bf16 v[96:99], v[224:227], v[182:185], v[96:99]
	v_mfma_f32_16x16x32_bf16 v[124:127], v[196:199], v[178:181], v[124:127]
	v_mfma_f32_16x16x32_bf16 v[120:123], v[196:199], v[186:189], v[120:123]
	v_mfma_f32_16x16x32_bf16 v[116:119], v[212:215], v[178:181], v[116:119]
	v_mfma_f32_16x16x32_bf16 v[112:115], v[212:215], v[186:189], v[112:115]
	v_mfma_f32_16x16x32_bf16 v[108:111], v[220:223], v[178:181], v[108:111]
	v_mfma_f32_16x16x32_bf16 v[104:107], v[220:223], v[186:189], v[104:107]
	v_mfma_f32_16x16x32_bf16 v[100:103], v[228:231], v[178:181], v[100:103]
	v_mfma_f32_16x16x32_bf16 v[96:99], v[228:231], v[186:189], v[96:99]
	s_barrier
	v_add_u32_e32 v248, s74, v140
	s_add_i32 m0, s100, 0x18000
	ds_read_b128 v[232:235], v148
	ds_read_b128 v[236:239], v148 offset:1024
	ds_read_b128 v[240:243], v148 offset:2048
	ds_read_b128 v[244:247], v148 offset:3072
	global_load_lds_dwordx4 v248, s[86:87]
	v_add_u32_e32 v248, s74, v138
	s_add_i32 m0, s100, 0x1a000
	s_nop 0
	global_load_lds_dwordx4 v248, s[86:87]
	s_barrier
	s_waitcnt lgkmcnt(0)
	v_mfma_f32_16x16x32_bf16 v[92:95], v[190:193], v[232:235], v[92:95]
	v_mfma_f32_16x16x32_bf16 v[88:91], v[190:193], v[240:243], v[88:91]
	v_mfma_f32_16x16x32_bf16 v[84:87], v[208:211], v[232:235], v[84:87]
	v_mfma_f32_16x16x32_bf16 v[80:83], v[208:211], v[240:243], v[80:83]
	v_mfma_f32_16x16x32_bf16 v[76:79], v[216:219], v[232:235], v[76:79]
	v_mfma_f32_16x16x32_bf16 v[72:75], v[216:219], v[240:243], v[72:75]
	v_mfma_f32_16x16x32_bf16 v[68:71], v[224:227], v[232:235], v[68:71]
	v_mfma_f32_16x16x32_bf16 v[64:67], v[224:227], v[240:243], v[64:67]
	v_mfma_f32_16x16x32_bf16 v[92:95], v[196:199], v[236:239], v[92:95]
	v_mfma_f32_16x16x32_bf16 v[88:91], v[196:199], v[244:247], v[88:91]
	v_mfma_f32_16x16x32_bf16 v[84:87], v[212:215], v[236:239], v[84:87]
	v_mfma_f32_16x16x32_bf16 v[80:83], v[212:215], v[244:247], v[80:83]
	v_mfma_f32_16x16x32_bf16 v[76:79], v[220:223], v[236:239], v[76:79]
	v_mfma_f32_16x16x32_bf16 v[72:75], v[220:223], v[244:247], v[72:75]
	v_mfma_f32_16x16x32_bf16 v[68:71], v[228:231], v[236:239], v[68:71]
	v_mfma_f32_16x16x32_bf16 v[64:67], v[228:231], v[244:247], v[64:67]
	v_add_u32_e32 v200, s72, v136
	s_add_i32 m0, s100, 0x8000
	s_barrier
	ds_read_b128 v[190:193], v147 offset:49152
	ds_read_b128 v[196:199], v147 offset:50176
	ds_read_b128 v[208:211], v146 offset:49152
	ds_read_b128 v[212:215], v146 offset:50176
	ds_read_b128 v[216:219], v145 offset:49152
	ds_read_b128 v[220:223], v145 offset:50176
	ds_read_b128 v[224:227], v144 offset:49152
	ds_read_b128 v[228:231], v144 offset:50176
	global_load_lds_dwordx4 v200, s[86:87]
	v_add_u32_e32 v200, s72, v134
	s_add_i32 m0, s100, 0xa000
	s_nop 0
	global_load_lds_dwordx4 v200, s[86:87]
	s_barrier
; #define P8_STAGE(P,BASE,br,kt) do{const bfr* _ub=(BASE)+((long)(br)*K+(long)(kt)*BK); \
;     __builtin_amdgcn_global_load_lds((const unsigned*)(_ub+so0),(unsigned*)((char*)(P)+wid*1024),16,0,0); \
;     __builtin_amdgcn_global_load_lds((const unsigned*)(_ub+so1),(unsigned*)((char*)(P)+wid*1024+8192),16,0,0);}while(0)
; #define P8_LDA(dst,b,h) _Pragma("unroll") for(int m=0;m<4;++m) _Pragma("unroll") for(int k=0;k<2;++k) \
;     dst[m][k]=*reinterpret_cast<const bf16x8*>((char*)P8_SA(b,h)+lds_byte(wr*64+m*16+fr,k*32+fq*8))
; #define P8_LDB(dst,b,h) _Pragma("unroll") for(int n=0;n<2;++n) _Pragma("unroll") for(int k=0;k<2;++k) \
;     dst[n][k]=*reinterpret_cast<const bf16x8*>((char*)P8_SB(b,h)+lds_byte(wc*32+n*16+fr,k*32+fq*8))
; #define P8_MMA(ai,bj,At,Bt) do{__builtin_amdgcn_s_setprio(1); \
;     _Pragma("unroll") for(int m=0;m<4;++m) _Pragma("unroll") for(int n=0;n<2;++n) _Pragma("unroll") for(int k=0;k<2;++k) \
;       acc[ai][bj][m][n]=__builtin_amdgcn_mfma_f32_16x16x32_bf16(At[m][k],Bt[n][k],acc[ai][bj][m][n],0,0,0); \
;     __builtin_amdgcn_s_setprio(0);}while(0)
; #define P8_WAIT_V(n) asm volatile("s_waitcnt vmcnt(" #n ")":::"memory")
; #define P8_WAIT_L(n) asm volatile("s_waitcnt lgkmcnt(" #n ")":::"memory")
; #define P8_BAR __builtin_amdgcn_s_barrier()
; #define P8_SCHED __builtin_amdgcn_sched_barrier(0)
; template <class EPI>
; DEVI void gemm8_tile(const bfr* __restrict__ A, const bfr* __restrict__ Bt, int K, int brow, int bcol, int nbrow, int nbcol, char* shmc, EPI epi) {
;     ...
;     P8_BAR; P8_WAIT_L(0); P8_MMA(1,0,At,B0); P8_BAR; P8_SCHED;
;     P8_STAGE(P8_SB(1,1),Bt,bcol+128,t+3);
;     P8_WAIT_V(6); P8_BAR; P8_MMA(1,1,At,B1); P8_BAR;
;   }
;   { P8_LDB(B0,0,0); P8_LDA(At,0,0); P8_STAGE(P8_SA(1,1),A,brow+128,nt-1);
;     P8_BAR; P8_WAIT_L(0); P8_MMA(0,0,At,B0); P8_BAR;
;     P8_LDB(B1,0,1); P8_BAR; P8_WAIT_L(0); P8_MMA(0,1,At,B1); P8_BAR;
	s_waitcnt lgkmcnt(0)
	v_mfma_f32_16x16x32_bf16 v[60:63], v[190:193], v[174:177], v[60:63]
	v_mfma_f32_16x16x32_bf16 v[56:59], v[190:193], v[182:185], v[56:59]
	v_mfma_f32_16x16x32_bf16 v[52:55], v[208:211], v[174:177], v[52:55]
	v_mfma_f32_16x16x32_bf16 v[48:51], v[208:211], v[182:185], v[48:51]
	v_mfma_f32_16x16x32_bf16 v[44:47], v[216:219], v[174:177], v[44:47]
	v_mfma_f32_16x16x32_bf16 v[40:43], v[216:219], v[182:185], v[40:43]
	v_mfma_f32_16x16x32_bf16 v[36:39], v[224:227], v[174:177], v[36:39]
	v_mfma_f32_16x16x32_bf16 v[32:35], v[224:227], v[182:185], v[32:35]
	v_mfma_f32_16x16x32_bf16 v[60:63], v[196:199], v[178:181], v[60:63]
	v_mfma_f32_16x16x32_bf16 v[56:59], v[196:199], v[186:189], v[56:59]
	v_mfma_f32_16x16x32_bf16 v[52:55], v[212:215], v[178:181], v[52:55]
	v_mfma_f32_16x16x32_bf16 v[48:51], v[212:215], v[186:189], v[48:51]
	v_mfma_f32_16x16x32_bf16 v[44:47], v[220:223], v[178:181], v[44:47]
	v_mfma_f32_16x16x32_bf16 v[40:43], v[220:223], v[186:189], v[40:43]
	v_mfma_f32_16x16x32_bf16 v[36:39], v[228:231], v[178:181], v[36:39]
	v_mfma_f32_16x16x32_bf16 v[32:35], v[228:231], v[186:189], v[32:35]
	s_barrier
	v_add_u32_e32 v174, s78, v140
	s_add_i32 m0, s100, 0x1c000
	s_nop 0
	global_load_lds_dwordx4 v174, s[86:87]
	v_add_u32_e32 v174, s78, v138
	s_add_i32 m0, s100, 0x1e000
	s_nop 0
	global_load_lds_dwordx4 v174, s[86:87]
	s_waitcnt vmcnt(6)
	s_barrier
	v_mfma_f32_16x16x32_bf16 v[28:31], v[190:193], v[232:235], v[28:31]
	v_mfma_f32_16x16x32_bf16 v[24:27], v[190:193], v[240:243], v[24:27]
	v_mfma_f32_16x16x32_bf16 v[20:23], v[208:211], v[232:235], v[20:23]
	v_mfma_f32_16x16x32_bf16 v[16:19], v[208:211], v[240:243], v[16:19]
	v_mfma_f32_16x16x32_bf16 v[12:15], v[216:219], v[232:235], v[12:15]
	v_mfma_f32_16x16x32_bf16 v[8:11], v[216:219], v[240:243], v[8:11]
	v_mfma_f32_16x16x32_bf16 v[4:7], v[224:227], v[232:235], v[4:7]
	v_mfma_f32_16x16x32_bf16 v[0:3], v[224:227], v[240:243], v[0:3]
	v_mfma_f32_16x16x32_bf16 v[28:31], v[196:199], v[236:239], v[28:31]
	v_mfma_f32_16x16x32_bf16 v[24:27], v[196:199], v[244:247], v[24:27]
	v_mfma_f32_16x16x32_bf16 v[20:23], v[212:215], v[236:239], v[20:23]
	v_mfma_f32_16x16x32_bf16 v[16:19], v[212:215], v[244:247], v[16:19]
	v_mfma_f32_16x16x32_bf16 v[12:15], v[220:223], v[236:239], v[12:15]
	v_mfma_f32_16x16x32_bf16 v[8:11], v[220:223], v[244:247], v[8:11]
	v_mfma_f32_16x16x32_bf16 v[4:7], v[228:231], v[236:239], v[4:7]
	v_mfma_f32_16x16x32_bf16 v[0:3], v[228:231], v[244:247], v[0:3]
	s_add_i32 s0, s0, 2
	v_lshl_add_u64 v[134:135], v[134:135], 0, s[80:81]
	v_lshl_add_u64 v[136:137], v[136:137], 0, s[80:81]
	v_lshl_add_u64 v[138:139], v[138:139], 0, s[80:81]
	s_cmp_lt_u32 s0, 28
	v_lshl_add_u64 v[140:141], v[140:141], 0, s[80:81]
	s_barrier
	s_cbranch_scc1 .LBB0_401
	v_add_u32_e32 v171, 0xc000, v143
	v_add_u32_e32 v172, 0xe000, v143
	v_add_u32_e32 v158, 0x10000, v143
	v_add_u32_e32 v159, 0x12000, v143
	v_add_u32_e32 v160, 0x2000, v143
	v_add_u32_e32 v161, 0x14000, v143
	v_add_u32_e32 v162, 0x16000, v143
	v_add_u32_e32 v163, 0x4000, v143
	v_add_u32_e32 v170, 0x6000, v143
	s_or_b32 s0, s34, 0x80
	s_ashr_i32 s1, s0, 31
	s_lshl_b64 s[0:1], s[0:1], 12
	s_add_u32 s0, s31, s0
	s_addc_u32 s1, s64, s1
	ds_read_b128 v[134:137], v157
	ds_read_b128 v[138:141], v157 offset:1024
	ds_read_b128 v[150:153], v157 offset:2048
	ds_read_b128 v[174:177], v157 offset:3072
	ds_read_b128 v[178:181], v147
	ds_read_b128 v[182:185], v147 offset:1024
	ds_read_b128 v[186:189], v146
	ds_read_b128 v[190:193], v146 offset:1024
	ds_read_b128 v[196:199], v145
	ds_read_b128 v[208:211], v145 offset:1024
	ds_read_b128 v[212:215], v144
	ds_read_b128 v[216:219], v144 offset:1024
	v_lshl_add_u64 v[156:157], v[166:167], 1, s[0:1]
	s_mov_b64 s[54:55], 0xf80
	v_lshl_add_u64 v[156:157], v[156:157], 0, s[54:55]
	s_add_i32 m0, s100, 0xc000
	v_lshl_add_u64 v[132:133], v[132:133], 1, s[0:1]
	global_load_lds_dwordx4 v[156:157], off
	v_lshl_add_u64 v[132:133], v[132:133], 0, s[54:55]
	s_add_i32 m0, s100, 0xe000
	s_nop 0
	global_load_lds_dwordx4 v[132:133], off
	s_barrier
	s_waitcnt lgkmcnt(0)
	s_waitcnt lgkmcnt(0)
	v_mfma_f32_16x16x32_bf16 v[124:127], v[178:181], v[134:137], v[124:127]
	v_mfma_f32_16x16x32_bf16 v[116:119], v[186:189], v[134:137], v[116:119]
	v_mfma_f32_16x16x32_bf16 v[112:115], v[186:189], v[150:153], v[112:115]
	v_mfma_f32_16x16x32_bf16 v[100:103], v[212:215], v[134:137], v[100:103]
	v_mfma_f32_16x16x32_bf16 v[124:127], v[182:185], v[138:141], v[124:127]
	v_mfma_f32_16x16x32_bf16 v[120:123], v[178:181], v[150:153], v[120:123]
	v_mfma_f32_16x16x32_bf16 v[116:119], v[190:193], v[138:141], v[116:119]
	v_mfma_f32_16x16x32_bf16 v[112:115], v[190:193], v[174:177], v[112:115]
	v_mfma_f32_16x16x32_bf16 v[108:111], v[196:199], v[134:137], v[108:111]
	v_mfma_f32_16x16x32_bf16 v[104:107], v[196:199], v[150:153], v[104:107]
	v_mfma_f32_16x16x32_bf16 v[100:103], v[216:219], v[138:141], v[100:103]
	v_mfma_f32_16x16x32_bf16 v[96:99], v[212:215], v[150:153], v[96:99]
	v_mfma_f32_16x16x32_bf16 v[220:223], v[182:185], v[174:177], v[120:123]
	v_mfma_f32_16x16x32_bf16 v[224:227], v[208:211], v[138:141], v[108:111]
	v_mfma_f32_16x16x32_bf16 v[228:231], v[208:211], v[174:177], v[104:107]
	v_mfma_f32_16x16x32_bf16 v[232:235], v[216:219], v[174:177], v[96:99]
	s_barrier
	s_nop 1
	ds_read_b128 v[96:99], v155
	ds_read_b128 v[104:107], v155 offset:1024
	ds_read_b128 v[108:111], v155 offset:2048
	ds_read_b128 v[120:123], v155 offset:3072
	s_barrier
; #define P8_LDA(dst,b,h) _Pragma("unroll") for(int m=0;m<4;++m) _Pragma("unroll") for(int k=0;k<2;++k) \
;     dst[m][k]=*reinterpret_cast<const bf16x8*>((char*)P8_SA(b,h)+lds_byte(wr*64+m*16+fr,k*32+fq*8))
; #define P8_LDB(dst,b,h) _Pragma("unroll") for(int n=0;n<2;++n) _Pragma("unroll") for(int k=0;k<2;++k) \
;     dst[n][k]=*reinterpret_cast<const bf16x8*>((char*)P8_SB(b,h)+lds_byte(wc*32+n*16+fr,k*32+fq*8))
; #define P8_MMA(ai,bj,At,Bt) do{__builtin_amdgcn_s_setprio(1); \
;     _Pragma("unroll") for(int m=0;m<4;++m) _Pragma("unroll") for(int n=0;n<2;++n) _Pragma("unroll") for(int k=0;k<2;++k) \
;       acc[ai][bj][m][n]=__builtin_amdgcn_mfma_f32_16x16x32_bf16(At[m][k],Bt[n][k],acc[ai][bj][m][n],0,0,0); \
;     __builtin_amdgcn_s_setprio(0);}while(0)
; #define P8_WAIT_V(n) asm volatile("s_waitcnt vmcnt(" #n ")":::"memory")
; #define P8_WAIT_L(n) asm volatile("s_waitcnt lgkmcnt(" #n ")":::"memory")
; #define P8_BAR __builtin_amdgcn_s_barrier()
; template <class EPI>
; DEVI void gemm8_tile(const bfr* __restrict__ A, const bfr* __restrict__ Bt, int K, int brow, int bcol, int nbrow, int nbcol, char* shmc, EPI epi) {
;     ...
;     P8_LDB(B1,0,1); P8_BAR; P8_WAIT_L(0); P8_MMA(0,1,At,B1); P8_BAR;
;     P8_LDA(At,0,1); P8_WAIT_V(4); P8_BAR; P8_WAIT_L(0); P8_MMA(1,0,At,B0); P8_MMA(1,1,At,B1); P8_BAR; }
;   { P8_LDB(B0,1,0); P8_LDA(At,1,0); P8_WAIT_V(2); P8_BAR; P8_WAIT_L(0); P8_MMA(0,0,At,B0); P8_BAR;
	s_waitcnt lgkmcnt(0)
	s_waitcnt lgkmcnt(0)
	v_mfma_f32_16x16x32_bf16 v[92:95], v[178:181], v[96:99], v[92:95]
	v_mfma_f32_16x16x32_bf16 v[84:87], v[186:189], v[96:99], v[84:87]
	v_mfma_f32_16x16x32_bf16 v[80:83], v[186:189], v[108:111], v[80:83]
	v_mfma_f32_16x16x32_bf16 v[68:71], v[212:215], v[96:99], v[68:71]
	v_mfma_f32_16x16x32_bf16 v[92:95], v[182:185], v[104:107], v[92:95]
	v_mfma_f32_16x16x32_bf16 v[88:91], v[178:181], v[108:111], v[88:91]
	v_mfma_f32_16x16x32_bf16 v[84:87], v[190:193], v[104:107], v[84:87]
	v_mfma_f32_16x16x32_bf16 v[80:83], v[190:193], v[120:123], v[80:83]
	v_mfma_f32_16x16x32_bf16 v[76:79], v[196:199], v[96:99], v[76:79]
	v_mfma_f32_16x16x32_bf16 v[72:75], v[196:199], v[108:111], v[72:75]
	v_mfma_f32_16x16x32_bf16 v[68:71], v[216:219], v[104:107], v[68:71]
	v_mfma_f32_16x16x32_bf16 v[64:67], v[212:215], v[108:111], v[64:67]
	v_mfma_f32_16x16x32_bf16 v[154:157], v[182:185], v[120:123], v[88:91]
	v_mfma_f32_16x16x32_bf16 v[178:181], v[208:211], v[104:107], v[76:79]
	v_mfma_f32_16x16x32_bf16 v[182:185], v[208:211], v[120:123], v[72:75]
	v_mfma_f32_16x16x32_bf16 v[186:189], v[216:219], v[120:123], v[64:67]
	s_barrier
	s_nop 1
	ds_read_b128 v[64:67], v147 offset:16384
	ds_read_b128 v[72:75], v147 offset:17408
	ds_read_b128 v[76:79], v146 offset:16384
	ds_read_b128 v[88:91], v146 offset:17408
	ds_read_b128 v[190:193], v145 offset:16384
	ds_read_b128 v[196:199], v145 offset:17408
	ds_read_b128 v[208:211], v144 offset:16384
	ds_read_b128 v[212:215], v144 offset:17408
	s_waitcnt vmcnt(4)
	s_barrier
	s_waitcnt lgkmcnt(0)
	s_waitcnt lgkmcnt(0)
	v_mfma_f32_16x16x32_bf16 v[60:63], v[64:67], v[134:137], v[60:63]
	v_mfma_f32_16x16x32_bf16 v[52:55], v[76:79], v[134:137], v[52:55]
	v_mfma_f32_16x16x32_bf16 v[48:51], v[76:79], v[150:153], v[48:51]
	v_mfma_f32_16x16x32_bf16 v[36:39], v[208:211], v[134:137], v[36:39]
	v_mfma_f32_16x16x32_bf16 v[60:63], v[72:75], v[138:141], v[60:63]
	v_mfma_f32_16x16x32_bf16 v[56:59], v[64:67], v[150:153], v[56:59]
	v_mfma_f32_16x16x32_bf16 v[52:55], v[88:91], v[138:141], v[52:55]
	v_mfma_f32_16x16x32_bf16 v[48:51], v[88:91], v[174:177], v[48:51]
	v_mfma_f32_16x16x32_bf16 v[44:47], v[190:193], v[134:137], v[44:47]
	v_mfma_f32_16x16x32_bf16 v[40:43], v[190:193], v[150:153], v[40:43]
	v_mfma_f32_16x16x32_bf16 v[36:39], v[212:215], v[138:141], v[36:39]
	v_mfma_f32_16x16x32_bf16 v[32:35], v[208:211], v[150:153], v[32:35]
	v_mfma_f32_16x16x32_bf16 v[216:219], v[72:75], v[174:177], v[56:59]
	v_mfma_f32_16x16x32_bf16 v[236:239], v[196:199], v[138:141], v[44:47]
	v_mfma_f32_16x16x32_bf16 v[240:243], v[196:199], v[174:177], v[40:43]
	v_mfma_f32_16x16x32_bf16 v[132:135], v[212:215], v[174:177], v[32:35]
	s_setprio 0
	s_setprio 1
	v_mfma_f32_16x16x32_bf16 v[28:31], v[64:67], v[96:99], v[28:31]
	v_mfma_f32_16x16x32_bf16 v[20:23], v[76:79], v[96:99], v[20:23]
	v_mfma_f32_16x16x32_bf16 v[16:19], v[76:79], v[108:111], v[16:19]
	v_mfma_f32_16x16x32_bf16 v[4:7], v[208:211], v[96:99], v[4:7]
	v_mfma_f32_16x16x32_bf16 v[28:31], v[72:75], v[104:107], v[28:31]
	v_mfma_f32_16x16x32_bf16 v[24:27], v[64:67], v[108:111], v[24:27]
	v_mfma_f32_16x16x32_bf16 v[20:23], v[88:91], v[104:107], v[20:23]
	v_mfma_f32_16x16x32_bf16 v[16:19], v[88:91], v[120:123], v[16:19]
	v_mfma_f32_16x16x32_bf16 v[12:15], v[190:193], v[96:99], v[12:15]
	v_mfma_f32_16x16x32_bf16 v[8:11], v[190:193], v[108:111], v[8:11]
	v_mfma_f32_16x16x32_bf16 v[4:7], v[212:215], v[104:107], v[4:7]
	v_mfma_f32_16x16x32_bf16 v[0:3], v[208:211], v[108:111], v[0:3]
	v_mfma_f32_16x16x32_bf16 v[136:139], v[72:75], v[120:123], v[24:27]
	v_mfma_f32_16x16x32_bf16 v[150:153], v[196:199], v[104:107], v[12:15]
	v_mfma_f32_16x16x32_bf16 v[172:175], v[196:199], v[120:123], v[8:11]
	v_mfma_f32_16x16x32_bf16 v[190:193], v[212:215], v[120:123], v[0:3]
	s_barrier
	s_nop 1
	ds_read_b128 v[0:3], v149
	ds_read_b128 v[8:11], v149 offset:1024
	ds_read_b128 v[12:15], v149 offset:2048
	ds_read_b128 v[24:27], v149 offset:3072
	ds_read_b128 v[32:35], v147 offset:32768
	ds_read_b128 v[40:43], v147 offset:33792
	ds_read_b128 v[44:47], v146 offset:32768
	ds_read_b128 v[56:59], v146 offset:33792
	ds_read_b128 v[64:67], v145 offset:32768
	ds_read_b128 v[196:199], v145 offset:33792
	ds_read_b128 v[208:211], v144 offset:32768
	ds_read_b128 v[212:215], v144 offset:33792
	s_waitcnt vmcnt(2)
	s_barrier
; #define P8_LDA(dst,b,h) _Pragma("unroll") for(int m=0;m<4;++m) _Pragma("unroll") for(int k=0;k<2;++k) \
;     dst[m][k]=*reinterpret_cast<const bf16x8*>((char*)P8_SA(b,h)+lds_byte(wr*64+m*16+fr,k*32+fq*8))
; #define P8_LDB(dst,b,h) _Pragma("unroll") for(int n=0;n<2;++n) _Pragma("unroll") for(int k=0;k<2;++k) \
;     dst[n][k]=*reinterpret_cast<const bf16x8*>((char*)P8_SB(b,h)+lds_byte(wc*32+n*16+fr,k*32+fq*8))
; #define P8_MMA(ai,bj,At,Bt) do{__builtin_amdgcn_s_setprio(1); \
;     _Pragma("unroll") for(int m=0;m<4;++m) _Pragma("unroll") for(int n=0;n<2;++n) _Pragma("unroll") for(int k=0;k<2;++k) \
;       acc[ai][bj][m][n]=__builtin_amdgcn_mfma_f32_16x16x32_bf16(At[m][k],Bt[n][k],acc[ai][bj][m][n],0,0,0); \
;     __builtin_amdgcn_s_setprio(0);}while(0)
; #define P8_WAIT_V(n) asm volatile("s_waitcnt vmcnt(" #n ")":::"memory")
; #define P8_WAIT_L(n) asm volatile("s_waitcnt lgkmcnt(" #n ")":::"memory")
; #define P8_BAR __builtin_amdgcn_s_barrier()
; template <class EPI>
; DEVI void gemm8_tile(const bfr* __restrict__ A, const bfr* __restrict__ Bt, int K, int brow, int bcol, int nbrow, int nbcol, char* shmc, EPI epi) {
;     ...
;   { P8_LDB(B0,1,0); P8_LDA(At,1,0); P8_WAIT_V(2); P8_BAR; P8_WAIT_L(0); P8_MMA(0,0,At,B0); P8_BAR;
;     P8_LDB(B1,1,1); P8_WAIT_V(0); P8_BAR; P8_WAIT_L(0); P8_MMA(0,1,At,B1); P8_BAR;
;     P8_LDA(At,1,1); P8_BAR; P8_WAIT_L(0); P8_MMA(1,0,At,B0); P8_MMA(1,1,At,B1); P8_BAR; }
;   if(wr==0)P8_BAR;
	s_waitcnt lgkmcnt(0)
	s_waitcnt lgkmcnt(0)
	v_mfma_f32_16x16x32_bf16 v[72:75], v[32:35], v[0:3], v[124:127]
	v_mfma_f32_16x16x32_bf16 v[120:123], v[40:43], v[8:11], v[72:75]
	v_mfma_f32_16x16x32_bf16 v[72:75], v[32:35], v[12:15], v[220:223]
	v_mfma_f32_16x16x32_bf16 v[104:107], v[40:43], v[24:27], v[72:75]
	v_mfma_f32_16x16x32_bf16 v[72:75], v[44:47], v[0:3], v[116:119]
	v_mfma_f32_16x16x32_bf16 v[124:127], v[56:59], v[8:11], v[72:75]
	v_mfma_f32_16x16x32_bf16 v[72:75], v[44:47], v[12:15], v[112:115]
	v_mfma_f32_16x16x32_bf16 v[108:111], v[56:59], v[24:27], v[72:75]
	v_mfma_f32_16x16x32_bf16 v[72:75], v[64:67], v[0:3], v[224:227]
	v_mfma_f32_16x16x32_bf16 v[112:115], v[196:199], v[8:11], v[72:75]
	v_mfma_f32_16x16x32_bf16 v[72:75], v[64:67], v[12:15], v[228:231]
	v_mfma_f32_16x16x32_bf16 v[96:99], v[196:199], v[24:27], v[72:75]
	v_mfma_f32_16x16x32_bf16 v[72:75], v[208:211], v[0:3], v[100:103]
	v_mfma_f32_16x16x32_bf16 v[116:119], v[212:215], v[8:11], v[72:75]
	v_mfma_f32_16x16x32_bf16 v[72:75], v[208:211], v[12:15], v[232:235]
	v_mfma_f32_16x16x32_bf16 v[100:103], v[212:215], v[24:27], v[72:75]
	s_barrier
	ds_read_b128 v[220:223], v148
	ds_read_b128 v[224:227], v148 offset:1024
	ds_read_b128 v[228:231], v148 offset:2048
	ds_read_b128 v[232:235], v148 offset:3072
	s_waitcnt vmcnt(0)
	s_barrier
	s_waitcnt lgkmcnt(0)
	s_waitcnt lgkmcnt(0)
	v_mfma_f32_16x16x32_bf16 v[72:75], v[32:35], v[220:223], v[92:95]
	v_mfma_f32_16x16x32_bf16 v[32:35], v[32:35], v[228:231], v[154:157]
	v_mfma_f32_16x16x32_bf16 v[88:91], v[40:43], v[224:227], v[72:75]
	v_mfma_f32_16x16x32_bf16 v[72:75], v[40:43], v[232:235], v[32:35]
	v_mfma_f32_16x16x32_bf16 v[32:35], v[44:47], v[220:223], v[84:87]
	v_mfma_f32_16x16x32_bf16 v[92:95], v[56:59], v[224:227], v[32:35]
	v_mfma_f32_16x16x32_bf16 v[32:35], v[44:47], v[228:231], v[80:83]
	v_mfma_f32_16x16x32_bf16 v[76:79], v[56:59], v[232:235], v[32:35]
	v_mfma_f32_16x16x32_bf16 v[32:35], v[64:67], v[220:223], v[178:181]
	v_mfma_f32_16x16x32_bf16 v[80:83], v[196:199], v[224:227], v[32:35]
	v_mfma_f32_16x16x32_bf16 v[32:35], v[64:67], v[228:231], v[182:185]
	v_mfma_f32_16x16x32_bf16 v[64:67], v[196:199], v[232:235], v[32:35]
	v_mfma_f32_16x16x32_bf16 v[32:35], v[208:211], v[220:223], v[68:71]
	v_mfma_f32_16x16x32_bf16 v[84:87], v[212:215], v[224:227], v[32:35]
	v_mfma_f32_16x16x32_bf16 v[32:35], v[208:211], v[228:231], v[186:189]
	v_mfma_f32_16x16x32_bf16 v[68:71], v[212:215], v[232:235], v[32:35]
	s_barrier
	ds_read_b128 v[154:157], v147 offset:49152
	ds_read_b128 v[176:179], v147 offset:50176
	ds_read_b128 v[180:183], v146 offset:49152
	ds_read_b128 v[146:149], v146 offset:50176
	ds_read_b128 v[184:187], v145 offset:49152
	ds_read_b128 v[196:199], v145 offset:50176
	ds_read_b128 v[208:211], v144 offset:49152
	ds_read_b128 v[212:215], v144 offset:50176
	s_barrier
	s_waitcnt lgkmcnt(0)
	s_waitcnt lgkmcnt(0)
	v_mfma_f32_16x16x32_bf16 v[32:35], v[154:157], v[0:3], v[60:63]
	v_mfma_f32_16x16x32_bf16 v[56:59], v[176:179], v[8:11], v[32:35]
	v_mfma_f32_16x16x32_bf16 v[32:35], v[154:157], v[12:15], v[216:219]
	v_mfma_f32_16x16x32_bf16 v[40:43], v[176:179], v[24:27], v[32:35]
	v_mfma_f32_16x16x32_bf16 v[32:35], v[180:183], v[0:3], v[52:55]
	v_mfma_f32_16x16x32_bf16 v[60:63], v[146:149], v[8:11], v[32:35]
	v_mfma_f32_16x16x32_bf16 v[32:35], v[180:183], v[12:15], v[48:51]
	v_mfma_f32_16x16x32_bf16 v[44:47], v[146:149], v[24:27], v[32:35]
	v_mfma_f32_16x16x32_bf16 v[32:35], v[184:187], v[0:3], v[236:239]
	v_mfma_f32_16x16x32_bf16 v[0:3], v[208:211], v[0:3], v[36:39]
	v_mfma_f32_16x16x32_bf16 v[48:51], v[196:199], v[8:11], v[32:35]
	v_mfma_f32_16x16x32_bf16 v[32:35], v[184:187], v[12:15], v[240:243]
	v_mfma_f32_16x16x32_bf16 v[52:55], v[212:215], v[8:11], v[0:3]
	v_mfma_f32_16x16x32_bf16 v[0:3], v[208:211], v[12:15], v[132:135]
	v_mfma_f32_16x16x32_bf16 v[32:35], v[196:199], v[24:27], v[32:35]
	v_mfma_f32_16x16x32_bf16 v[36:39], v[212:215], v[24:27], v[0:3]
	s_setprio 0
	s_setprio 1
	v_mfma_f32_16x16x32_bf16 v[0:3], v[154:157], v[220:223], v[28:31]
	v_mfma_f32_16x16x32_bf16 v[24:27], v[176:179], v[224:227], v[0:3]
	v_mfma_f32_16x16x32_bf16 v[0:3], v[154:157], v[228:231], v[136:139]
	v_mfma_f32_16x16x32_bf16 v[8:11], v[176:179], v[232:235], v[0:3]
	v_mfma_f32_16x16x32_bf16 v[0:3], v[180:183], v[220:223], v[20:23]
	v_mfma_f32_16x16x32_bf16 v[28:31], v[146:149], v[224:227], v[0:3]
	v_mfma_f32_16x16x32_bf16 v[0:3], v[180:183], v[228:231], v[16:19]
	v_mfma_f32_16x16x32_bf16 v[12:15], v[146:149], v[232:235], v[0:3]
	v_mfma_f32_16x16x32_bf16 v[0:3], v[184:187], v[220:223], v[150:153]
	v_mfma_f32_16x16x32_bf16 v[4:7], v[208:211], v[220:223], v[4:7]
	v_mfma_f32_16x16x32_bf16 v[16:19], v[196:199], v[224:227], v[0:3]
	v_mfma_f32_16x16x32_bf16 v[0:3], v[184:187], v[228:231], v[172:175]
	v_mfma_f32_16x16x32_bf16 v[20:23], v[212:215], v[224:227], v[4:7]
	v_mfma_f32_16x16x32_bf16 v[4:7], v[208:211], v[228:231], v[190:193]
	v_mfma_f32_16x16x32_bf16 v[0:3], v[196:199], v[232:235], v[0:3]
	v_mfma_f32_16x16x32_bf16 v[4:7], v[212:215], v[232:235], v[4:7]
	s_setprio 0
	v_cmp_gt_u32_e32 vcc, s57, v142
	s_barrier
	s_and_saveexec_b64 s[0:1], vcc
	s_cbranch_execz .LBB0_404
	s_barrier
